# weight conversion (prologue and in-attention conversion items): 796 of the integer round-to-nearest-even bf16 sequences (bfe, add3, lshr, and_or) replaced by v_cvt_pk_bf16_f32, same rounding with deno
# speedup vs baseline: 1.0143x; 1.0051x over previous
.LBB0_15:
	s_waitcnt vmcnt(14)
	v_mov_b32_e32 v40, v42
	s_waitcnt vmcnt(12)
	v_mov_b32_e32 v41, v46
	v_pk_mul_f32 v[40:41], v[40:41], v[92:93]
	v_lshlrev_b32_e32 v84, 11, v86
	v_bfe_u32 v42, v40, 16, 1
	v_add3_u32 v42, v40, v42, s50
	v_bfe_u32 v40, v41, 16, 1
	v_add3_u32 v46, v41, v40, s50
	s_waitcnt vmcnt(10)
	v_mov_b32_e32 v40, v50
	s_waitcnt vmcnt(8)
	v_mov_b32_e32 v41, v58
	v_pk_mul_f32 v[40:41], v[40:41], v[80:81]
	s_lshl_b32 s8, s8, 1
	v_bfe_u32 v50, v40, 16, 1
	v_add3_u32 v50, v40, v50, s50
	v_bfe_u32 v40, v41, 16, 1
	v_add3_u32 v58, v41, v40, s50
	v_mov_b32_e32 v40, v54
	v_mov_b32_e32 v41, v62
	v_pk_mul_f32 v[40:41], v[40:41], v[74:75]
	v_mov_b32_e32 v94, 1.0
	v_bfe_u32 v54, v41, 16, 1
	v_add3_u32 v54, v41, v54, s50
	v_bfe_u32 v41, v40, 16, 1
	v_add3_u32 v62, v40, v41, s50
	v_mov_b32_e32 v40, v66
	v_mov_b32_e32 v41, v70
	v_pk_mul_f32 v[40:41], v[40:41], v[78:79]
	v_lshrrev_b32_e32 v54, 16, v54
	v_bfe_u32 v66, v41, 16, 1
	v_add3_u32 v41, v41, v66, s50
	v_bfe_u32 v66, v40, 16, 1
	v_add3_u32 v40, v40, v66, s50
	v_lshrrev_b32_e32 v41, 16, v41
	v_and_or_b32 v103, v46, s51, v41
	v_lshrrev_b32_e32 v40, 16, v40
	v_mov_b32_e32 v46, v43
	v_and_or_b32 v102, v42, s51, v40
	v_pk_mul_f32 v[42:43], v[46:47], v[92:93]
	v_and_or_b32 v105, v58, s51, v54
	v_bfe_u32 v46, v42, 16, 1
	v_add3_u32 v46, v42, v46, s50
	v_bfe_u32 v42, v43, 16, 1
	v_mov_b32_e32 v58, v51
	v_lshrrev_b32_e32 v62, 16, v62
	v_add3_u32 v47, v43, v42, s50
	v_pk_mul_f32 v[42:43], v[58:59], v[80:81]
	v_and_or_b32 v104, v50, s51, v62
	v_bfe_u32 v50, v42, 16, 1
	v_add3_u32 v50, v42, v50, s50
	v_bfe_u32 v42, v43, 16, 1
	v_mov_b32_e32 v62, v55
	s_waitcnt lgkmcnt(0)
	v_lshl_add_u64 v[40:41], s[24:25], 0, v[84:85]
	v_add3_u32 v51, v43, v42, s50
	v_pk_mul_f32 v[42:43], v[62:63], v[74:75]
	v_lshl_add_u64 v[40:41], v[40:41], 0, s[8:9]
	v_lshlrev_b32_e32 v84, 1, v82
	v_bfe_u32 v54, v43, 16, 1
	v_lshl_add_u64 v[86:87], v[40:41], 0, v[84:85]
	v_add3_u32 v54, v43, v54, s50
	v_bfe_u32 v43, v42, 16, 1
	v_add_co_u32_e32 v40, vcc, s52, v86
	v_add3_u32 v55, v42, v43, s50
	s_nop 0
	v_addc_co_u32_e32 v41, vcc, 0, v87, vcc
	v_lshrrev_b32_e32 v55, 16, v55
	v_lshrrev_b32_e32 v54, 16, v54
	global_store_dwordx4 v[40:41], v[102:105], off offset:-4096
	v_mov_b32_e32 v70, v67
	v_pk_mul_f32 v[42:43], v[70:71], v[78:79]
	v_and_or_b32 v105, v51, s51, v54
	v_and_or_b32 v104, v50, s51, v55
	v_mov_b32_e32 v50, v44
	v_mov_b32_e32 v51, v48
	v_pk_mul_f32 v[50:51], v[50:51], v[92:93]
	v_bfe_u32 v58, v43, 16, 1
	v_bfe_u32 v44, v50, 16, 1
	v_bfe_u32 v48, v51, 16, 1
	v_add3_u32 v44, v50, v44, s50
	v_add3_u32 v48, v51, v48, s50
	v_mov_b32_e32 v50, v52
	v_mov_b32_e32 v51, v60
	v_pk_mul_f32 v[50:51], v[50:51], v[80:81]
	v_add3_u32 v43, v43, v58, s50
	v_bfe_u32 v52, v50, 16, 1
	v_bfe_u32 v58, v42, 16, 1
	v_add3_u32 v52, v50, v52, s50
	v_bfe_u32 v50, v51, 16, 1
	v_add3_u32 v42, v42, v58, s50
	v_add3_u32 v54, v51, v50, s50
	v_mov_b32_e32 v50, v56
	v_mov_b32_e32 v51, v64
	v_lshrrev_b32_e32 v43, 16, v43
	v_lshrrev_b32_e32 v42, 16, v42
	v_pk_mul_f32 v[50:51], v[50:51], v[74:75]
	v_and_or_b32 v103, v47, s51, v43
	v_and_or_b32 v102, v46, s51, v42
	v_mov_b32_e32 v42, v68
	v_mov_b32_e32 v43, v72
	v_bfe_u32 v55, v51, 16, 1
	v_pk_mul_f32 v[42:43], v[42:43], v[78:79]
	v_add3_u32 v51, v51, v55, s50
	v_bfe_u32 v55, v50, 16, 1
	v_add3_u32 v50, v50, v55, s50
	v_bfe_u32 v55, v43, 16, 1
	v_add3_u32 v43, v43, v55, s50
	v_bfe_u32 v55, v42, 16, 1
	v_add3_u32 v42, v42, v55, s50
	v_lshrrev_b32_e32 v43, 16, v43
	v_and_or_b32 v67, v48, s51, v43
	v_lshrrev_b32_e32 v42, 16, v42
	v_mov_b32_e32 v48, v45
	v_mov_b32_e32 v60, v53
	v_mov_b32_e32 v72, v69
	v_lshrrev_b32_e32 v50, 16, v50
	v_lshrrev_b32_e32 v51, 16, v51
	v_and_or_b32 v66, v44, s51, v42
	v_pk_mul_f32 v[42:43], v[48:49], v[92:93]
	v_mov_b32_e32 v64, v57
	v_pk_mul_f32 v[48:49], v[60:61], v[80:81]
	v_pk_mul_f32 v[46:47], v[72:73], v[78:79]
	v_and_or_b32 v69, v54, s51, v51
	v_and_or_b32 v68, v52, s51, v50
	v_pk_mul_f32 v[44:45], v[64:65], v[74:75]
	v_cvt_pk_bf16_f32 v45, v45, v49
	v_cvt_pk_bf16_f32 v44, v44, v48
	v_cvt_pk_bf16_f32 v43, v47, v43
	v_cvt_pk_bf16_f32 v42, v46, v42
	global_store_dwordx4 v[40:41], v[42:45], off offset:2048
	s_waitcnt vmcnt(5)
	v_mov_b32_e32 v46, v26
	s_waitcnt vmcnt(3)
	v_mov_b32_e32 v47, v34
	v_mov_b32_e32 v42, v10
	v_mov_b32_e32 v43, v18
	v_pk_mul_f32 v[42:43], v[42:43], v[2:3]
	v_mov_b32_e32 v44, v6
	v_mov_b32_e32 v45, v14
	v_pk_mul_f32 v[46:47], v[46:47], v[38:39]
	v_mov_b32_e32 v48, v22
	s_waitcnt vmcnt(2)
	v_mov_b32_e32 v49, v30
	v_pk_mul_f32 v[44:45], v[44:45], v[76:77]
	v_pk_mul_f32 v[48:49], v[48:49], v[4:5]
	v_bfe_u32 v22, v42, 16, 1
	v_bfe_u32 v18, v44, 16, 1
	v_add3_u32 v22, v42, v22, s50
	v_add3_u32 v18, v44, v18, s50
	v_lshrrev_b32_e32 v22, 16, v22
	v_cvt_pk_bf16_f32 v44, v46, v48
	v_cvt_pk_bf16_f32 v43, v43, v45
	v_and_or_b32 v42, v18, s51, v22
	v_mov_b32_e32 v18, v11
	v_mov_b32_e32 v14, v7
	v_mov_b32_e32 v30, v23
	v_cvt_pk_bf16_f32 v45, v47, v49
	v_pk_mul_f32 v[10:11], v[18:19], v[2:3]
	v_pk_mul_f32 v[6:7], v[14:15], v[76:77]
	v_mov_b32_e32 v34, v27
	v_pk_mul_f32 v[18:19], v[30:31], v[4:5]
	v_pk_mul_f32 v[14:15], v[34:35], v[38:39]
	v_lshl_add_u64 v[86:87], v[86:87], 0, s[6:7]
	global_store_dwordx4 v[86:87], v[42:45], off offset:32
	global_store_dwordx4 v[86:87], v[102:105], off offset:2048
	global_store_dwordx4 v[40:41], v[66:69], off
	v_cvt_pk_bf16_f32 v45, v15, v19
	v_cvt_pk_bf16_f32 v44, v14, v18
	v_cvt_pk_bf16_f32 v43, v11, v7
	v_cvt_pk_bf16_f32 v42, v10, v6
	v_mov_b32_e32 v10, v8
	v_mov_b32_e32 v11, v16
	v_mov_b32_e32 v18, v24
	v_mov_b32_e32 v19, v32
	v_mov_b32_e32 v6, v12
	v_mov_b32_e32 v7, v20
	v_pk_mul_f32 v[10:11], v[10:11], v[76:77]
	v_pk_mul_f32 v[18:19], v[18:19], v[4:5]
	v_pk_mul_f32 v[6:7], v[6:7], v[2:3]
	v_mov_b32_e32 v14, v28
	v_mov_b32_e32 v15, v36
	v_bfe_u32 v12, v18, 16, 1
	v_bfe_u32 v16, v11, 16, 1
	v_pk_mul_f32 v[14:15], v[14:15], v[38:39]
	v_bfe_u32 v8, v19, 16, 1
	v_bfe_u32 v20, v10, 16, 1
	v_add3_u32 v11, v11, v16, s50
	v_add3_u32 v12, v18, v12, s50
	v_bfe_u32 v16, v6, 16, 1
	v_bfe_u32 v18, v7, 16, 1
	v_add3_u32 v10, v10, v20, s50
	v_add3_u32 v8, v19, v8, s50
	v_bfe_u32 v19, v14, 16, 1
	v_bfe_u32 v20, v15, 16, 1
	v_add3_u32 v7, v7, v18, s50
	v_add3_u32 v6, v6, v16, s50
	v_add3_u32 v15, v15, v20, s50
	v_add3_u32 v14, v14, v19, s50
	v_lshrrev_b32_e32 v6, 16, v6
	v_lshrrev_b32_e32 v7, 16, v7
	v_mov_b32_e32 v16, v9
	v_mov_b32_e32 v32, v25
	global_store_dwordx4 v[86:87], v[42:45], off offset:2080
	v_lshrrev_b32_e32 v14, 16, v14
	v_lshrrev_b32_e32 v15, 16, v15
	v_and_or_b32 v43, v11, s51, v7
	v_and_or_b32 v42, v10, s51, v6
	v_mov_b32_e32 v20, v13
	v_pk_mul_f32 v[6:7], v[16:17], v[76:77]
	v_mov_b32_e32 v36, v29
	v_pk_mul_f32 v[4:5], v[32:33], v[4:5]
	v_and_or_b32 v45, v8, s51, v15
	v_and_or_b32 v44, v12, s51, v14
	v_pk_mul_f32 v[2:3], v[20:21], v[2:3]
	v_pk_mul_f32 v[8:9], v[36:37], v[38:39]
	v_cvt_pk_bf16_f32 v5, v9, v5
	v_cvt_pk_bf16_f32 v4, v8, v4
	v_cvt_pk_bf16_f32 v3, v3, v7
	v_cvt_pk_bf16_f32 v2, v2, v6
	global_store_dwordx4 v[40:41], v[2:5], off offset:2080
	global_store_dwordx4 v[40:41], v[42:45], off offset:32
	v_mov_b32_e32 v74, 1.0
	v_or_b32_e32 v2, 32, v97
	v_add_co_u32_e32 v4, vcc, s53, v88
	v_mad_u64_u32 v[2:3], s[24:25], v2, s44, v[90:91]
	s_nop 0
	v_addc_co_u32_e32 v5, vcc, 0, v89, vcc
	global_load_dwordx4 v[46:49], v[2:3], off nt
	global_load_dwordx4 v[42:45], v[4:5], off nt
	v_add_co_u32_e32 v2, vcc, s54, v88
	v_mov_b32_e32 v75, 1.0
	s_nop 0
	v_addc_co_u32_e32 v3, vcc, 0, v89, vcc
	v_add_co_u32_e32 v4, vcc, s55, v88
	v_mov_b32_e32 v95, 1.0
	s_nop 0
	v_addc_co_u32_e32 v5, vcc, 0, v89, vcc
	global_load_dwordx4 v[54:57], v[2:3], off nt
	global_load_dwordx4 v[50:53], v[4:5], off nt
	v_add_co_u32_e32 v2, vcc, s56, v88
	v_mov_b32_e32 v78, 1.0
	s_nop 0
	v_addc_co_u32_e32 v3, vcc, 0, v89, vcc
	v_add_co_u32_e32 v4, vcc, 0x6f000, v88
	v_mov_b32_e32 v92, 1.0
	s_nop 0
	v_addc_co_u32_e32 v5, vcc, 0, v89, vcc
	global_load_dwordx4 v[62:65], v[2:3], off nt
	global_load_dwordx4 v[58:61], v[4:5], off nt
	v_add_co_u32_e32 v2, vcc, 0x72000, v88
	v_mov_b32_e32 v79, 1.0
	s_nop 0
	v_addc_co_u32_e32 v3, vcc, 0, v89, vcc
	v_add_co_u32_e32 v4, vcc, 0x75000, v88
	v_mov_b32_e32 v93, 1.0
	s_nop 0
	v_addc_co_u32_e32 v5, vcc, 0, v89, vcc
	global_load_dwordx4 v[70:73], v[2:3], off nt
	global_load_dwordx4 v[66:69], v[4:5], off nt
	v_mov_b32_e32 v2, 1.0
	s_and_b64 vcc, exec, s[4:5]
	s_cbranch_vccnz .LBB0_17
	global_load_dwordx4 v[74:77], v96, s[10:11] offset:128
	global_load_dwordx4 v[78:81], v96, s[10:11] offset:144
	s_waitcnt vmcnt(1)
	v_mov_b32_e32 v94, v75
	v_mov_b32_e32 v75, v76
	v_mov_b32_e32 v95, v77
	s_waitcnt vmcnt(0)
	v_mov_b32_e32 v92, v79
	v_mov_b32_e32 v79, v80
	v_mov_b32_e32 v93, v81

.LBB0_19:
	s_waitcnt vmcnt(14)
	v_mov_b32_e32 v40, v42
	s_waitcnt vmcnt(12)
	v_mov_b32_e32 v41, v50
	v_pk_mul_f32 v[40:41], v[40:41], v[94:95]
	s_mov_b64 s[4:5], 0
	v_bfe_u32 v42, v40, 16, 1
	v_add3_u32 v42, v40, v42, s50
	v_bfe_u32 v40, v41, 16, 1
	v_add3_u32 v50, v41, v40, s50
	s_waitcnt vmcnt(10)
	v_mov_b32_e32 v40, v58
	s_waitcnt vmcnt(8)
	v_mov_b32_e32 v41, v66
	v_pk_mul_f32 v[40:41], v[40:41], v[92:93]
	s_nop 0
	v_bfe_u32 v58, v40, 16, 1
	v_add3_u32 v58, v40, v58, s50
	v_bfe_u32 v40, v41, 16, 1
	v_add3_u32 v66, v41, v40, s50
	v_mov_b32_e32 v40, v62
	v_mov_b32_e32 v41, v70
	v_pk_mul_f32 v[40:41], v[40:41], v[78:79]
	s_nop 0
	v_bfe_u32 v62, v41, 16, 1
	v_add3_u32 v62, v41, v62, s50
	v_bfe_u32 v41, v40, 16, 1
	v_add3_u32 v70, v40, v41, s50
	v_mov_b32_e32 v40, v46
	v_mov_b32_e32 v41, v54
	v_pk_mul_f32 v[40:41], v[40:41], v[74:75]
	v_lshrrev_b32_e32 v54, 16, v62
	v_bfe_u32 v46, v41, 16, 1
	v_add3_u32 v41, v41, v46, s50
	v_bfe_u32 v46, v40, 16, 1
	v_add3_u32 v40, v40, v46, s50
	v_lshrrev_b32_e32 v41, 16, v41
	v_and_or_b32 v89, v50, s51, v41
	v_lshrrev_b32_e32 v40, 16, v40
	v_mov_b32_e32 v50, v43
	v_and_or_b32 v88, v42, s51, v40
	v_pk_mul_f32 v[40:41], v[50:51], v[94:95]
	v_lshrrev_b32_e32 v46, 16, v70
	v_bfe_u32 v42, v40, 16, 1
	v_and_or_b32 v91, v66, s51, v54
	v_and_or_b32 v90, v58, s51, v46
	v_add3_u32 v46, v40, v42, s50
	v_bfe_u32 v40, v41, 16, 1
	v_mov_b32_e32 v66, v59
	v_add3_u32 v50, v41, v40, s50
	v_pk_mul_f32 v[40:41], v[66:67], v[92:93]
	v_mov_b32_e32 v70, v63
	v_bfe_u32 v42, v40, 16, 1
	v_add3_u32 v42, v40, v42, s50
	v_bfe_u32 v40, v41, 16, 1
	v_add3_u32 v43, v41, v40, s50
	v_pk_mul_f32 v[40:41], v[70:71], v[78:79]
	v_mov_b32_e32 v54, v47
	v_bfe_u32 v51, v41, 16, 1
	v_add3_u32 v51, v41, v51, s50
	v_bfe_u32 v41, v40, 16, 1
	v_add3_u32 v58, v40, v41, s50
	v_pk_mul_f32 v[40:41], v[54:55], v[74:75]
	v_lshrrev_b32_e32 v51, 16, v51
	v_bfe_u32 v47, v41, 16, 1
	v_add3_u32 v41, v41, v47, s50
	v_bfe_u32 v47, v40, 16, 1
	v_add3_u32 v40, v40, v47, s50
	v_lshrrev_b32_e32 v47, 16, v58
	v_lshrrev_b32_e32 v41, 16, v41
	v_lshrrev_b32_e32 v40, 16, v40
	v_and_or_b32 v43, v43, s51, v51
	v_and_or_b32 v42, v42, s51, v47
	v_and_or_b32 v41, v50, s51, v41
	v_and_or_b32 v40, v46, s51, v40
	global_store_dwordx4 v[86:87], v[40:43], off offset:2112
	global_store_dwordx4 v[86:87], v[88:91], off offset:64
	s_nop 0
	v_mov_b32_e32 v40, v44
	v_mov_b32_e32 v41, v52
	v_pk_mul_f32 v[40:41], v[40:41], v[94:95]
	v_mov_b32_e32 v52, v45
	v_bfe_u32 v42, v40, 16, 1
	v_add3_u32 v44, v40, v42, s50
	v_bfe_u32 v40, v41, 16, 1
	v_add3_u32 v46, v41, v40, s50
	v_mov_b32_e32 v40, v60
	v_mov_b32_e32 v41, v68
	v_pk_mul_f32 v[40:41], v[40:41], v[92:93]
	v_mov_b32_e32 v68, v61
	v_bfe_u32 v42, v40, 16, 1
	v_add3_u32 v42, v40, v42, s50
	v_bfe_u32 v40, v41, 16, 1
	v_add3_u32 v43, v41, v40, s50
	v_mov_b32_e32 v40, v64
	v_mov_b32_e32 v41, v72
	v_pk_mul_f32 v[40:41], v[40:41], v[78:79]
	v_mov_b32_e32 v72, v65
	v_bfe_u32 v47, v41, 16, 1
	v_add3_u32 v47, v41, v47, s50
	v_bfe_u32 v41, v40, 16, 1
	v_add3_u32 v50, v40, v41, s50
	v_mov_b32_e32 v40, v48
	v_mov_b32_e32 v41, v56
	v_pk_mul_f32 v[40:41], v[40:41], v[74:75]
	v_lshrrev_b32_e32 v47, 16, v47
	v_bfe_u32 v48, v41, 16, 1
	v_add3_u32 v41, v41, v48, s50
	v_bfe_u32 v48, v40, 16, 1
	v_add3_u32 v40, v40, v48, s50
	v_lshrrev_b32_e32 v41, 16, v41
	v_lshrrev_b32_e32 v48, 16, v50
	v_and_or_b32 v41, v46, s51, v41
	v_lshrrev_b32_e32 v40, 16, v40
	v_add_co_u32_e32 v46, vcc, s57, v86
	v_and_or_b32 v43, v43, s51, v47
	v_and_or_b32 v42, v42, s51, v48
	v_and_or_b32 v40, v44, s51, v40
	v_addc_co_u32_e32 v47, vcc, 0, v87, vcc
	global_store_dwordx4 v[46:47], v[40:43], off offset:64
	v_mov_b32_e32 v56, v49
	v_pk_mul_f32 v[48:49], v[68:69], v[92:93]
	v_pk_mul_f32 v[42:43], v[52:53], v[94:95]
	v_pk_mul_f32 v[40:41], v[56:57], v[74:75]
	v_pk_mul_f32 v[44:45], v[72:73], v[78:79]
	v_bfe_u32 v50, v49, 16, 1
	v_bfe_u32 v51, v48, 16, 1
	v_bfe_u32 v52, v43, 16, 1
	v_bfe_u32 v53, v42, 16, 1
	v_add3_u32 v53, v42, v53, s50
	v_add3_u32 v52, v43, v52, s50
	v_add3_u32 v42, v48, v51, s50
	v_add3_u32 v43, v49, v50, s50
	v_bfe_u32 v48, v40, 16, 1
	v_bfe_u32 v49, v41, 16, 1
	v_bfe_u32 v50, v44, 16, 1
	v_bfe_u32 v51, v45, 16, 1
	v_add3_u32 v45, v45, v51, s50
	v_add3_u32 v44, v44, v50, s50
	v_add3_u32 v41, v41, v49, s50
	v_add3_u32 v40, v40, v48, s50
	v_lshrrev_b32_e32 v40, 16, v40
	v_lshrrev_b32_e32 v41, 16, v41
	v_lshrrev_b32_e32 v44, 16, v44
	v_lshrrev_b32_e32 v45, 16, v45
	v_and_or_b32 v43, v43, s51, v45
	v_and_or_b32 v42, v42, s51, v44
	v_and_or_b32 v41, v52, s51, v41
	v_and_or_b32 v40, v53, s51, v40
	global_store_dwordx4 v[46:47], v[40:43], off offset:2112
	s_waitcnt vmcnt(7)
	v_mov_b32_e32 v44, v26
	s_waitcnt vmcnt(5)
	v_mov_b32_e32 v45, v34
	v_mov_b32_e32 v40, v10
	v_mov_b32_e32 v41, v18
	v_pk_mul_f32 v[40:41], v[40:41], v[2:3]
	v_mov_b32_e32 v42, v6
	v_mov_b32_e32 v43, v14
	v_pk_mul_f32 v[44:45], v[44:45], v[38:39]
	v_mov_b32_e32 v48, v22
	s_waitcnt vmcnt(4)
	v_mov_b32_e32 v49, v30
	v_pk_mul_f32 v[42:43], v[42:43], v[76:77]
	v_pk_mul_f32 v[48:49], v[48:49], v[4:5]
	v_bfe_u32 v22, v40, 16, 1
	v_bfe_u32 v18, v42, 16, 1
	v_add3_u32 v22, v40, v22, s50
	v_add3_u32 v18, v42, v18, s50
	v_lshrrev_b32_e32 v22, 16, v22
	v_cvt_pk_bf16_f32 v42, v44, v48
	v_cvt_pk_bf16_f32 v41, v41, v43
	v_and_or_b32 v40, v18, s51, v22
	v_mov_b32_e32 v18, v11
	v_mov_b32_e32 v14, v7
	v_mov_b32_e32 v30, v23
	v_cvt_pk_bf16_f32 v43, v45, v49
	v_pk_mul_f32 v[10:11], v[18:19], v[2:3]
	v_pk_mul_f32 v[6:7], v[14:15], v[76:77]
	v_mov_b32_e32 v34, v27
	v_pk_mul_f32 v[18:19], v[30:31], v[4:5]
	v_pk_mul_f32 v[14:15], v[34:35], v[38:39]
	global_store_dwordx4 v[86:87], v[40:43], off offset:96
	s_nop 1
	v_cvt_pk_bf16_f32 v43, v15, v19
	v_cvt_pk_bf16_f32 v42, v14, v18
	v_cvt_pk_bf16_f32 v41, v11, v7
	v_cvt_pk_bf16_f32 v40, v10, v6
	v_mov_b32_e32 v10, v8
	v_mov_b32_e32 v11, v16
	v_mov_b32_e32 v18, v24
	v_mov_b32_e32 v19, v32
	v_mov_b32_e32 v6, v12
	v_mov_b32_e32 v7, v20
	v_pk_mul_f32 v[10:11], v[10:11], v[76:77]
	v_pk_mul_f32 v[18:19], v[18:19], v[4:5]
	v_pk_mul_f32 v[6:7], v[6:7], v[2:3]
	v_mov_b32_e32 v14, v28
	v_mov_b32_e32 v15, v36
	v_bfe_u32 v12, v18, 16, 1
	v_bfe_u32 v16, v11, 16, 1
	v_pk_mul_f32 v[14:15], v[14:15], v[38:39]
	v_bfe_u32 v8, v19, 16, 1
	v_bfe_u32 v20, v10, 16, 1
	v_add3_u32 v11, v11, v16, s50
	v_add3_u32 v12, v18, v12, s50
	v_bfe_u32 v16, v6, 16, 1
	v_bfe_u32 v18, v7, 16, 1
	v_add3_u32 v10, v10, v20, s50
	v_add3_u32 v8, v19, v8, s50
	v_bfe_u32 v19, v14, 16, 1
	v_bfe_u32 v20, v15, 16, 1
	v_add3_u32 v7, v7, v18, s50
	v_add3_u32 v6, v6, v16, s50
	v_add3_u32 v15, v15, v20, s50
	v_add3_u32 v14, v14, v19, s50
	v_lshrrev_b32_e32 v6, 16, v6
	v_lshrrev_b32_e32 v7, 16, v7
	v_mov_b32_e32 v16, v9
	v_mov_b32_e32 v32, v25
	global_store_dwordx4 v[86:87], v[40:43], off offset:2144
	v_lshrrev_b32_e32 v14, 16, v14
	v_lshrrev_b32_e32 v15, 16, v15
	v_and_or_b32 v41, v11, s51, v7
	v_and_or_b32 v40, v10, s51, v6
	v_mov_b32_e32 v20, v13
	v_pk_mul_f32 v[6:7], v[16:17], v[76:77]
	v_mov_b32_e32 v36, v29
	v_pk_mul_f32 v[4:5], v[32:33], v[4:5]
	v_and_or_b32 v43, v8, s51, v15
	v_and_or_b32 v42, v12, s51, v14
	v_pk_mul_f32 v[2:3], v[20:21], v[2:3]
	v_pk_mul_f32 v[8:9], v[36:37], v[38:39]
	v_cvt_pk_bf16_f32 v5, v9, v5
	v_cvt_pk_bf16_f32 v4, v8, v4
	v_cvt_pk_bf16_f32 v3, v3, v7
	v_cvt_pk_bf16_f32 v2, v2, v6
	global_store_dwordx4 v[46:47], v[40:43], off offset:96
	global_store_dwordx4 v[46:47], v[2:5], off offset:2144
.LBB0_20:
	s_mov_b32 s8, 0
	s_and_b64 vcc, exec, s[4:5]
	s_cbranch_vccz .LBB0_22
	s_mov_b64 s[4:5], s[0:1]
	s_mov_b64 s[10:11], s[0:1]
	s_load_dwordx2 s[4:5], s[4:5], 0x18
	s_load_dwordx2 s[10:11], s[10:11], 0xa8
	s_and_b32 s8, s42, 0x380
	v_or_b32_e32 v4, s8, v83
	v_mul_u32_u24_e32 v2, 0xb00, v4
	s_and_b32 s24, s29, 0x7ffc0
	v_lshlrev_b32_e32 v84, 1, v2
	s_waitcnt lgkmcnt(0)
	v_lshl_add_u64 v[2:3], s[10:11], 0, v[84:85]
	s_lshl_b32 s8, s24, 1
	v_lshl_add_u64 v[2:3], v[2:3], 0, s[8:9]
	v_lshlrev_b32_e32 v84, 1, v82
	v_lshl_add_u64 v[76:77], v[2:3], 0, v[84:85]
	v_or_b32_e32 v5, s24, v82
	v_lshlrev_b32_e32 v84, 2, v4
	v_lshl_add_u64 v[2:3], s[4:5], 0, v[84:85]
	v_lshlrev_b32_e32 v84, 12, v5
	v_lshl_add_u64 v[10:11], v[2:3], 0, v[84:85]
	v_add_co_u32_e32 v2, vcc, s58, v10
	global_load_dwordx4 v[6:9], v[10:11], off nt
	s_nop 0
	v_addc_co_u32_e32 v3, vcc, 0, v11, vcc
	global_load_dwordx4 v[12:15], v[2:3], off offset:-4096 nt
	global_load_dwordx4 v[16:19], v[2:3], off nt
	v_add_co_u32_e32 v2, vcc, s59, v10
	s_mov_b32 s8, 4
	s_nop 0
	v_addc_co_u32_e32 v3, vcc, 0, v11, vcc
	global_load_dwordx4 v[20:23], v[2:3], off offset:-4096 nt
	global_load_dwordx4 v[24:27], v[2:3], off nt
	v_add_co_u32_e32 v2, vcc, s45, v10
	s_waitcnt vmcnt(4)
	v_addc_co_u32_e32 v3, vcc, 0, v11, vcc
	global_load_dwordx4 v[28:31], v[2:3], off offset:-4096 nt
	global_load_dwordx4 v[32:35], v[2:3], off nt
	v_add_co_u32_e32 v2, vcc, s60, v10
	s_nop 0
	v_addc_co_u32_e32 v3, vcc, 0, v11, vcc
	global_load_dwordx4 v[36:39], v[2:3], off nt
	v_add_co_u32_e32 v4, vcc, s64, v76
	s_waitcnt vmcnt(6)
	v_addc_co_u32_e32 v5, vcc, 0, v77, vcc
	v_add_co_u32_e32 v44, vcc, s61, v10
	s_waitcnt vmcnt(5)
	v_addc_co_u32_e32 v45, vcc, 0, v11, vcc
	v_add_co_u32_e32 v52, vcc, s62, v10
	s_waitcnt vmcnt(3)
	v_addc_co_u32_e32 v53, vcc, 0, v11, vcc
	v_add_co_u32_e32 v60, vcc, s48, v10
	s_nop 0
	v_addc_co_u32_e32 v61, vcc, 0, v11, vcc
	v_add_co_u32_e32 v68, vcc, s63, v10
	s_nop 0
	v_addc_co_u32_e32 v69, vcc, 0, v11, vcc
	global_load_dwordx4 v[40:43], v[44:45], off offset:-4096 nt
	s_nop 0
	global_load_dwordx4 v[44:47], v[44:45], off nt
	s_nop 0
	global_load_dwordx4 v[48:51], v[52:53], off offset:-4096 nt
	s_nop 0
	global_load_dwordx4 v[52:55], v[52:53], off nt
	s_nop 0
	global_load_dwordx4 v[56:59], v[60:61], off offset:-4096 nt
	s_nop 0
	global_load_dwordx4 v[60:63], v[60:61], off nt
	s_nop 0
	global_load_dwordx4 v[64:67], v[68:69], off offset:-4096 nt
	s_nop 0
	global_load_dwordx4 v[68:71], v[68:69], off nt
	v_cvt_pk_bf16_f32 v72, v6, v12
	v_cvt_pk_bf16_f32 v73, v16, v20
	v_bfe_u32 v6, v8, 16, 1
	v_add3_u32 v6, v8, v6, s50
	v_lshrrev_b32_e32 v6, 16, v6
	v_lshl_add_u64 v[2:3], v[76:77], 0, s[14:15]
	s_waitcnt vmcnt(10)
	s_waitcnt vmcnt(9)
	v_cvt_pk_bf16_f32 v74, v24, v28
	v_cvt_pk_bf16_f32 v12, v9, v15
	s_waitcnt vmcnt(8)
	v_cvt_pk_bf16_f32 v75, v32, v36
	global_store_dwordx4 v[4:5], v[72:75], off
	s_nop 1
	v_cvt_pk_bf16_f32 v72, v7, v13
	s_nop 1
	v_cvt_pk_bf16_f32 v73, v17, v21
	v_cvt_pk_bf16_f32 v74, v25, v29
	v_cvt_pk_bf16_f32 v75, v33, v37
	v_add_co_u32_e32 v4, vcc, s65, v76
	v_bfe_u32 v7, v14, 16, 1
	s_nop 0
	v_addc_co_u32_e32 v5, vcc, 0, v77, vcc
	v_add3_u32 v7, v14, v7, s50
	global_store_dwordx4 v[4:5], v[72:75], off offset:1536
	s_nop 1
	v_and_or_b32 v72, v7, s51, v6
	s_nop 1
	v_cvt_pk_bf16_f32 v73, v18, v22
	v_cvt_pk_bf16_f32 v13, v19, v23
	v_cvt_pk_bf16_f32 v74, v26, v30
	v_cvt_pk_bf16_f32 v14, v27, v31
	v_cvt_pk_bf16_f32 v75, v34, v38
	v_add_co_u32_e32 v6, vcc, s66, v76
	v_addc_co_u32_e32 v7, vcc, 0, v77, vcc
	v_cvt_pk_bf16_f32 v15, v35, v39
	v_add_co_u32_e32 v8, vcc, s67, v76
	s_waitcnt vmcnt(2)
	v_addc_co_u32_e32 v9, vcc, 0, v77, vcc
	global_store_dwordx4 v[8:9], v[12:15], off offset:512
	global_store_dwordx4 v[6:7], v[72:75], off offset:3072
	s_nop 1
	v_cvt_pk_bf16_f32 v12, v40, v44
	v_cvt_pk_bf16_f32 v13, v48, v52
	v_cvt_pk_bf16_f32 v14, v56, v60
	v_cvt_pk_bf16_f32 v15, v64, v68
	global_store_dwordx4 v[2:3], v[12:15], off offset:32
	s_nop 1
	v_cvt_pk_bf16_f32 v12, v41, v45
	s_nop 1
	v_cvt_pk_bf16_f32 v13, v49, v53
	v_cvt_pk_bf16_f32 v14, v57, v61
	v_cvt_pk_bf16_f32 v15, v65, v69
	global_store_dwordx4 v[4:5], v[12:15], off offset:1568
	s_nop 1
	v_cvt_pk_bf16_f32 v12, v42, v46
	s_nop 1
	v_cvt_pk_bf16_f32 v13, v50, v54
	v_cvt_pk_bf16_f32 v14, v58, v62
	v_cvt_pk_bf16_f32 v15, v66, v70
	global_store_dwordx4 v[6:7], v[12:15], off offset:3104
	s_nop 1
	v_cvt_pk_bf16_f32 v12, v43, v47
	s_nop 1
	v_cvt_pk_bf16_f32 v13, v51, v55
	v_cvt_pk_bf16_f32 v14, v59, v63
	v_cvt_pk_bf16_f32 v15, v67, v71
	v_add_co_u32_e32 v16, vcc, s68, v10
	global_store_dwordx4 v[8:9], v[12:15], off offset:544
	s_nop 0
	v_addc_co_u32_e32 v17, vcc, 0, v11, vcc
	global_load_dwordx4 v[12:15], v[16:17], off offset:-4096 nt
	s_nop 0
	global_load_dwordx4 v[16:19], v[16:17], off nt
	v_add_co_u32_e32 v24, vcc, s69, v10
	s_nop 1
	v_addc_co_u32_e32 v25, vcc, 0, v11, vcc
	global_load_dwordx4 v[20:23], v[24:25], off offset:-4096 nt
	s_nop 0
	global_load_dwordx4 v[24:27], v[24:25], off nt
	v_add_co_u32_e32 v32, vcc, s70, v10
	s_nop 1
	v_addc_co_u32_e32 v33, vcc, 0, v11, vcc
	global_load_dwordx4 v[28:31], v[32:33], off offset:-4096 nt
	s_nop 0
	global_load_dwordx4 v[32:35], v[32:33], off nt
	v_add_co_u32_e32 v40, vcc, s71, v10
	s_nop 1
	v_addc_co_u32_e32 v41, vcc, 0, v11, vcc
	global_load_dwordx4 v[36:39], v[40:41], off offset:-4096 nt
	s_nop 0
	global_load_dwordx4 v[40:43], v[40:41], off nt
	v_add_co_u32_e32 v48, vcc, s72, v10
	s_nop 1
	v_addc_co_u32_e32 v49, vcc, 0, v11, vcc
	global_load_dwordx4 v[44:47], v[48:49], off offset:-4096 nt
	s_nop 0
	global_load_dwordx4 v[48:51], v[48:49], off nt
	v_add_co_u32_e32 v56, vcc, s49, v10
	s_nop 1
	v_addc_co_u32_e32 v57, vcc, 0, v11, vcc
	global_load_dwordx4 v[52:55], v[56:57], off offset:-4096 nt
	s_nop 0
	global_load_dwordx4 v[56:59], v[56:57], off nt
	v_add_co_u32_e32 v64, vcc, s73, v10
	s_nop 1
	v_addc_co_u32_e32 v65, vcc, 0, v11, vcc
	global_load_dwordx4 v[60:63], v[64:65], off offset:-4096 nt
	s_nop 0
	global_load_dwordx4 v[64:67], v[64:65], off nt
	v_add_co_u32_e32 v10, vcc, s74, v10
	s_nop 1
	v_addc_co_u32_e32 v11, vcc, 0, v11, vcc
	global_load_dwordx4 v[68:71], v[10:11], off offset:-4096 nt
	global_load_dwordx4 v[72:75], v[10:11], off nt
	s_waitcnt vmcnt(15)
	s_waitcnt vmcnt(14)
	v_cvt_pk_bf16_f32 v76, v12, v16
	s_waitcnt vmcnt(13)
	s_waitcnt vmcnt(12)
	v_cvt_pk_bf16_f32 v77, v20, v24
	s_waitcnt vmcnt(11)
	s_waitcnt vmcnt(10)
	v_cvt_pk_bf16_f32 v78, v28, v32
	s_waitcnt vmcnt(9)
	s_waitcnt vmcnt(8)
	v_cvt_pk_bf16_f32 v79, v36, v40
	v_cvt_pk_bf16_f32 v10, v13, v17
	v_cvt_pk_bf16_f32 v11, v21, v25
	v_cvt_pk_bf16_f32 v12, v29, v33
	v_cvt_pk_bf16_f32 v13, v37, v41
	global_store_dwordx4 v[4:5], v[10:13], off offset:1600
	global_store_dwordx4 v[2:3], v[76:79], off offset:64
	s_nop 0
	v_cvt_pk_bf16_f32 v10, v14, v18
	v_cvt_pk_bf16_f32 v11, v22, v26
	v_cvt_pk_bf16_f32 v12, v30, v34
	v_cvt_pk_bf16_f32 v13, v38, v42
	global_store_dwordx4 v[6:7], v[10:13], off offset:3136
	s_nop 1
	v_cvt_pk_bf16_f32 v10, v15, v19
	s_nop 1
	v_cvt_pk_bf16_f32 v11, v23, v27
	v_cvt_pk_bf16_f32 v12, v31, v35
	v_cvt_pk_bf16_f32 v13, v39, v43
	global_store_dwordx4 v[8:9], v[10:13], off offset:576
	s_waitcnt vmcnt(4)
	s_nop 1
	v_cvt_pk_bf16_f32 v10, v44, v48
	v_cvt_pk_bf16_f32 v11, v52, v56
	v_cvt_pk_bf16_f32 v12, v60, v64
	v_cvt_pk_bf16_f32 v13, v68, v72
	global_store_dwordx4 v[2:3], v[10:13], off offset:96
	s_nop 1
	v_cvt_pk_bf16_f32 v10, v45, v49
	s_nop 1
	v_cvt_pk_bf16_f32 v11, v53, v57
	v_cvt_pk_bf16_f32 v12, v61, v65
	v_cvt_pk_bf16_f32 v13, v69, v73
	v_cvt_pk_bf16_f32 v2, v46, v50
	global_store_dwordx4 v[4:5], v[10:13], off offset:1632
	v_cvt_pk_bf16_f32 v3, v54, v58
	v_cvt_pk_bf16_f32 v4, v62, v66
	v_cvt_pk_bf16_f32 v5, v70, v74
	global_store_dwordx4 v[6:7], v[2:5], off offset:3168
	s_nop 1
	v_cvt_pk_bf16_f32 v2, v47, v51
	s_nop 1
	v_cvt_pk_bf16_f32 v3, v55, v59
	v_cvt_pk_bf16_f32 v4, v63, v67
	v_cvt_pk_bf16_f32 v5, v71, v75
	global_store_dwordx4 v[8:9], v[2:5], off offset:608

.LBB0_37:
	s_waitcnt vmcnt(14)
	v_mov_b32_e32 v40, v42
	s_waitcnt vmcnt(12)
	v_mov_b32_e32 v41, v50
	v_pk_mul_f32 v[40:41], v[40:41], v[98:99]
	v_add_co_u32_e32 v88, vcc, s57, v86
	v_bfe_u32 v42, v40, 16, 1
	v_add3_u32 v42, v40, v42, s50
	v_bfe_u32 v40, v41, 16, 1
	v_add3_u32 v50, v41, v40, s50
	s_waitcnt vmcnt(10)
	v_mov_b32_e32 v40, v54
	s_waitcnt vmcnt(8)
	v_mov_b32_e32 v41, v66
	v_pk_mul_f32 v[40:41], v[40:41], v[96:97]
	v_addc_co_u32_e32 v89, vcc, 0, v87, vcc
	v_bfe_u32 v54, v40, 16, 1
	v_add3_u32 v54, v40, v54, s50
	v_bfe_u32 v40, v41, 16, 1
	v_add3_u32 v66, v41, v40, s50
	v_mov_b32_e32 v40, v62
	v_mov_b32_e32 v41, v70
	v_pk_mul_f32 v[40:41], v[40:41], v[78:79]
	s_and_b64 vcc, exec, s[4:5]
	v_bfe_u32 v62, v41, 16, 1
	v_add3_u32 v62, v41, v62, s50
	v_bfe_u32 v41, v40, 16, 1
	v_add3_u32 v70, v40, v41, s50
	v_mov_b32_e32 v40, v46
	v_mov_b32_e32 v41, v58
	v_pk_mul_f32 v[40:41], v[40:41], v[74:75]
	v_lshrrev_b32_e32 v58, 16, v62
	v_bfe_u32 v46, v41, 16, 1
	v_add3_u32 v41, v41, v46, s50
	v_bfe_u32 v46, v40, 16, 1
	v_add3_u32 v40, v40, v46, s50
	v_lshrrev_b32_e32 v41, 16, v41
	v_and_or_b32 v103, v50, s51, v41
	v_lshrrev_b32_e32 v40, 16, v40
	v_mov_b32_e32 v50, v43
	v_and_or_b32 v102, v42, s51, v40
	v_pk_mul_f32 v[40:41], v[50:51], v[98:99]
	v_lshrrev_b32_e32 v46, 16, v70
	v_bfe_u32 v42, v40, 16, 1
	v_and_or_b32 v105, v66, s51, v58
	v_and_or_b32 v104, v54, s51, v46
	v_add3_u32 v46, v40, v42, s50
	v_bfe_u32 v40, v41, 16, 1
	v_mov_b32_e32 v66, v55
	v_add3_u32 v50, v41, v40, s50
	v_pk_mul_f32 v[40:41], v[66:67], v[96:97]
	v_mov_b32_e32 v70, v63
	v_bfe_u32 v42, v40, 16, 1
	v_add3_u32 v42, v40, v42, s50
	v_bfe_u32 v40, v41, 16, 1
	v_add3_u32 v43, v41, v40, s50
	v_pk_mul_f32 v[40:41], v[70:71], v[78:79]
	v_mov_b32_e32 v58, v47
	v_bfe_u32 v51, v41, 16, 1
	v_add3_u32 v51, v41, v51, s50
	v_bfe_u32 v41, v40, 16, 1
	v_add3_u32 v54, v40, v41, s50
	v_pk_mul_f32 v[40:41], v[58:59], v[74:75]
	v_lshrrev_b32_e32 v51, 16, v51
	v_bfe_u32 v47, v41, 16, 1
	v_add3_u32 v41, v41, v47, s50
	v_bfe_u32 v47, v40, 16, 1
	v_add3_u32 v40, v40, v47, s50
	v_lshrrev_b32_e32 v47, 16, v54
	v_lshrrev_b32_e32 v41, 16, v41
	v_lshrrev_b32_e32 v40, 16, v40
	v_and_or_b32 v43, v43, s51, v51
	v_and_or_b32 v42, v42, s51, v47
	v_and_or_b32 v41, v50, s51, v41
	v_and_or_b32 v40, v46, s51, v40
	global_store_dwordx4 v[86:87], v[40:43], off offset:2048
	global_store_dwordx4 v[86:87], v[102:105], off
	s_nop 0
	v_mov_b32_e32 v40, v44
	v_mov_b32_e32 v41, v52
	v_pk_mul_f32 v[40:41], v[40:41], v[98:99]
	v_mov_b32_e32 v52, v45
	v_bfe_u32 v42, v40, 16, 1
	v_add3_u32 v44, v40, v42, s50
	v_bfe_u32 v40, v41, 16, 1
	v_add3_u32 v46, v41, v40, s50
	v_mov_b32_e32 v40, v56
	v_mov_b32_e32 v41, v68
	v_pk_mul_f32 v[40:41], v[40:41], v[96:97]
	v_mov_b32_e32 v68, v57
	v_bfe_u32 v42, v40, 16, 1
	v_add3_u32 v42, v40, v42, s50
	v_bfe_u32 v40, v41, 16, 1
	v_add3_u32 v43, v41, v40, s50
	v_mov_b32_e32 v40, v64
	v_mov_b32_e32 v41, v72
	v_pk_mul_f32 v[40:41], v[40:41], v[78:79]
	v_mov_b32_e32 v72, v65
	v_bfe_u32 v47, v41, 16, 1
	v_add3_u32 v47, v41, v47, s50
	v_bfe_u32 v41, v40, 16, 1
	v_add3_u32 v50, v40, v41, s50
	v_mov_b32_e32 v40, v48
	v_mov_b32_e32 v41, v60
	v_pk_mul_f32 v[40:41], v[40:41], v[74:75]
	v_lshrrev_b32_e32 v47, 16, v47
	v_bfe_u32 v48, v41, 16, 1
	v_add3_u32 v41, v41, v48, s50
	v_bfe_u32 v48, v40, 16, 1
	v_add3_u32 v40, v40, v48, s50
	v_lshrrev_b32_e32 v48, 16, v50
	v_lshrrev_b32_e32 v41, 16, v41
	v_lshrrev_b32_e32 v40, 16, v40
	v_and_or_b32 v43, v43, s51, v47
	v_and_or_b32 v42, v42, s51, v48
	v_and_or_b32 v41, v46, s51, v41
	v_and_or_b32 v40, v44, s51, v40
	global_store_dwordx4 v[88:89], v[40:43], off
	v_mov_b32_e32 v60, v49
	v_pk_mul_f32 v[46:47], v[68:69], v[96:97]
	v_pk_mul_f32 v[42:43], v[52:53], v[98:99]
	v_pk_mul_f32 v[40:41], v[60:61], v[74:75]
	v_pk_mul_f32 v[44:45], v[72:73], v[78:79]
	v_bfe_u32 v48, v47, 16, 1
	v_bfe_u32 v49, v46, 16, 1
	v_bfe_u32 v50, v43, 16, 1
	v_bfe_u32 v51, v42, 16, 1
	v_add3_u32 v51, v42, v51, s50
	v_add3_u32 v50, v43, v50, s50
	v_add3_u32 v42, v46, v49, s50
	v_add3_u32 v43, v47, v48, s50
	v_bfe_u32 v46, v40, 16, 1
	v_bfe_u32 v47, v41, 16, 1
	v_bfe_u32 v48, v44, 16, 1
	v_bfe_u32 v49, v45, 16, 1
	v_add3_u32 v45, v45, v49, s50
	v_add3_u32 v44, v44, v48, s50
	v_add3_u32 v41, v41, v47, s50
	v_add3_u32 v40, v40, v46, s50
	v_lshrrev_b32_e32 v40, 16, v40
	v_lshrrev_b32_e32 v41, 16, v41
	v_lshrrev_b32_e32 v44, 16, v44
	v_lshrrev_b32_e32 v45, 16, v45
	v_and_or_b32 v43, v43, s51, v45
	v_and_or_b32 v42, v42, s51, v44
	v_and_or_b32 v41, v50, s51, v41
	v_and_or_b32 v40, v51, s51, v40
	global_store_dwordx4 v[88:89], v[40:43], off offset:2048
	s_waitcnt vmcnt(7)
	v_mov_b32_e32 v44, v26
	s_waitcnt vmcnt(5)
	v_mov_b32_e32 v45, v34
	v_mov_b32_e32 v40, v10
	v_mov_b32_e32 v41, v22
	v_pk_mul_f32 v[40:41], v[40:41], v[2:3]
	v_mov_b32_e32 v42, v6
	v_mov_b32_e32 v43, v14
	v_pk_mul_f32 v[44:45], v[44:45], v[38:39]
	v_mov_b32_e32 v46, v18
	s_waitcnt vmcnt(4)
	v_mov_b32_e32 v47, v30
	v_pk_mul_f32 v[42:43], v[42:43], v[76:77]
	v_pk_mul_f32 v[46:47], v[46:47], v[4:5]
	v_bfe_u32 v22, v40, 16, 1
	v_bfe_u32 v18, v42, 16, 1
	v_add3_u32 v22, v40, v22, s50
	v_add3_u32 v18, v42, v18, s50
	v_lshrrev_b32_e32 v22, 16, v22
	v_cvt_pk_bf16_f32 v42, v44, v46
	v_cvt_pk_bf16_f32 v41, v41, v43
	v_mov_b32_e32 v14, v7
	v_mov_b32_e32 v30, v19
	v_cvt_pk_bf16_f32 v43, v45, v47
	v_and_or_b32 v40, v18, s51, v22
	v_mov_b32_e32 v22, v11
	v_pk_mul_f32 v[6:7], v[14:15], v[76:77]
	v_mov_b32_e32 v34, v27
	v_pk_mul_f32 v[18:19], v[30:31], v[4:5]
	v_pk_mul_f32 v[10:11], v[22:23], v[2:3]
	v_pk_mul_f32 v[14:15], v[34:35], v[38:39]
	global_store_dwordx4 v[86:87], v[40:43], off offset:32
	v_mov_b32_e32 v74, 1.0
	v_mov_b32_e32 v98, 1.0
	v_cvt_pk_bf16_f32 v43, v15, v19
	v_cvt_pk_bf16_f32 v42, v14, v18
	v_cvt_pk_bf16_f32 v41, v11, v7
	v_cvt_pk_bf16_f32 v40, v10, v6
	v_mov_b32_e32 v10, v8
	v_mov_b32_e32 v11, v16
	v_mov_b32_e32 v18, v20
	v_mov_b32_e32 v19, v32
	v_mov_b32_e32 v6, v12
	v_mov_b32_e32 v7, v24
	v_pk_mul_f32 v[10:11], v[10:11], v[76:77]
	v_pk_mul_f32 v[18:19], v[18:19], v[4:5]
	v_pk_mul_f32 v[6:7], v[6:7], v[2:3]
	v_mov_b32_e32 v14, v28
	v_mov_b32_e32 v15, v36
	v_bfe_u32 v12, v18, 16, 1
	v_bfe_u32 v16, v11, 16, 1
	v_pk_mul_f32 v[14:15], v[14:15], v[38:39]
	v_bfe_u32 v8, v19, 16, 1
	v_bfe_u32 v20, v10, 16, 1
	v_add3_u32 v11, v11, v16, s50
	v_add3_u32 v12, v18, v12, s50
	v_bfe_u32 v16, v6, 16, 1
	v_bfe_u32 v18, v7, 16, 1
	v_add3_u32 v10, v10, v20, s50
	v_add3_u32 v8, v19, v8, s50
	v_bfe_u32 v19, v14, 16, 1
	v_bfe_u32 v20, v15, 16, 1
	v_add3_u32 v7, v7, v18, s50
	v_add3_u32 v6, v6, v16, s50
	v_add3_u32 v15, v15, v20, s50
	v_add3_u32 v14, v14, v19, s50
	v_lshrrev_b32_e32 v6, 16, v6
	v_lshrrev_b32_e32 v7, 16, v7
	v_mov_b32_e32 v16, v9
	v_mov_b32_e32 v32, v21
	global_store_dwordx4 v[86:87], v[40:43], off offset:2080
	v_lshrrev_b32_e32 v14, 16, v14
	v_lshrrev_b32_e32 v15, 16, v15
	v_and_or_b32 v41, v11, s51, v7
	v_and_or_b32 v40, v10, s51, v6
	v_mov_b32_e32 v24, v13
	v_pk_mul_f32 v[6:7], v[16:17], v[76:77]
	v_mov_b32_e32 v36, v29
	v_pk_mul_f32 v[4:5], v[32:33], v[4:5]
	v_and_or_b32 v43, v8, s51, v15
	v_and_or_b32 v42, v12, s51, v14
	v_pk_mul_f32 v[2:3], v[24:25], v[2:3]
	v_pk_mul_f32 v[8:9], v[36:37], v[38:39]
	v_cvt_pk_bf16_f32 v5, v9, v5
	v_cvt_pk_bf16_f32 v4, v8, v4
	v_cvt_pk_bf16_f32 v3, v3, v7
	v_cvt_pk_bf16_f32 v2, v2, v6
	global_store_dwordx4 v[88:89], v[2:5], off offset:2080
	global_store_dwordx4 v[88:89], v[40:43], off offset:32
	v_mov_b32_e32 v75, 1.0
	v_or_b32_e32 v2, 32, v90
	v_mad_i64_i32 v[2:3], s[10:11], v2, s75, v[92:93]
	v_or_b32_e32 v4, 33, v90
	v_mad_i64_i32 v[4:5], s[10:11], v4, s75, v[92:93]
	global_load_dwordx4 v[46:49], v[2:3], off nt
	global_load_dwordx4 v[42:45], v[4:5], off nt
	v_or_b32_e32 v2, 34, v90
	v_mad_i64_i32 v[2:3], s[10:11], v2, s75, v[92:93]
	v_or_b32_e32 v4, 35, v90
	v_mad_i64_i32 v[4:5], s[10:11], v4, s75, v[92:93]
	global_load_dwordx4 v[58:61], v[2:3], off nt
	global_load_dwordx4 v[50:53], v[4:5], off nt
	v_or_b32_e32 v2, 36, v90
	v_mad_i64_i32 v[2:3], s[10:11], v2, s75, v[92:93]
	v_or_b32_e32 v4, 37, v90
	v_mad_i64_i32 v[4:5], s[10:11], v4, s75, v[92:93]
	global_load_dwordx4 v[62:65], v[2:3], off nt
	global_load_dwordx4 v[54:57], v[4:5], off nt
	v_or_b32_e32 v2, 38, v90
	v_mad_i64_i32 v[2:3], s[10:11], v2, s75, v[92:93]
	v_or_b32_e32 v4, 39, v90
	v_mad_i64_i32 v[4:5], s[10:11], v4, s75, v[92:93]
	global_load_dwordx4 v[70:73], v[2:3], off nt
	global_load_dwordx4 v[66:69], v[4:5], off nt
	v_mov_b32_e32 v2, 1.0
	v_mov_b32_e32 v99, 1.0
	v_mov_b32_e32 v78, 1.0
	v_mov_b32_e32 v96, 1.0
	v_mov_b32_e32 v79, 1.0
	v_mov_b32_e32 v97, 1.0
	s_cbranch_vccnz .LBB0_39
	global_load_dwordx4 v[74:77], v[94:95], off offset:128
	global_load_dwordx4 v[78:81], v[94:95], off offset:144
	s_waitcnt vmcnt(1)
	v_mov_b32_e32 v98, v75
	v_mov_b32_e32 v75, v76
	v_mov_b32_e32 v99, v77
	s_waitcnt vmcnt(0)
	v_mov_b32_e32 v96, v79
	v_mov_b32_e32 v79, v80
	v_mov_b32_e32 v97, v81

.LBB0_41:
	s_waitcnt vmcnt(14)
	v_mov_b32_e32 v4, v42
	s_waitcnt vmcnt(12)
	v_mov_b32_e32 v5, v50
	v_pk_mul_f32 v[4:5], v[4:5], v[98:99]
	s_mov_b64 s[26:27], 0
	v_bfe_u32 v32, v4, 16, 1
	v_add3_u32 v32, v4, v32, s50
	v_bfe_u32 v4, v5, 16, 1
	v_add3_u32 v33, v5, v4, s50
	s_waitcnt vmcnt(10)
	v_mov_b32_e32 v4, v54
	s_waitcnt vmcnt(8)
	v_mov_b32_e32 v5, v66
	v_pk_mul_f32 v[4:5], v[4:5], v[96:97]
	v_mov_b32_e32 v66, v55
	v_bfe_u32 v42, v4, 16, 1
	v_add3_u32 v42, v4, v42, s50
	v_bfe_u32 v4, v5, 16, 1
	v_add3_u32 v50, v5, v4, s50
	v_mov_b32_e32 v4, v62
	v_mov_b32_e32 v5, v70
	v_pk_mul_f32 v[4:5], v[4:5], v[78:79]
	v_mov_b32_e32 v70, v63
	v_bfe_u32 v54, v5, 16, 1
	v_add3_u32 v54, v5, v54, s50
	v_bfe_u32 v5, v4, 16, 1
	v_add3_u32 v62, v4, v5, s50
	v_mov_b32_e32 v4, v46
	v_mov_b32_e32 v5, v58
	v_pk_mul_f32 v[4:5], v[4:5], v[74:75]
	v_lshrrev_b32_e32 v54, 16, v54
	v_bfe_u32 v46, v5, 16, 1
	v_add3_u32 v5, v5, v46, s50
	v_bfe_u32 v46, v4, 16, 1
	v_add3_u32 v4, v4, v46, s50
	v_and_or_b32 v93, v50, s51, v54
	v_lshrrev_b32_e32 v5, 16, v5
	v_lshrrev_b32_e32 v4, 16, v4
	v_mov_b32_e32 v50, v43
	v_and_or_b32 v91, v33, s51, v5
	v_and_or_b32 v90, v32, s51, v4
	v_pk_mul_f32 v[4:5], v[50:51], v[98:99]
	v_lshrrev_b32_e32 v46, 16, v62
	v_bfe_u32 v32, v4, 16, 1
	v_add3_u32 v32, v4, v32, s50
	v_bfe_u32 v4, v5, 16, 1
	v_add3_u32 v33, v5, v4, s50
	v_pk_mul_f32 v[4:5], v[66:67], v[96:97]
	v_and_or_b32 v92, v42, s51, v46
	v_bfe_u32 v42, v4, 16, 1
	v_add3_u32 v42, v4, v42, s50
	v_bfe_u32 v4, v5, 16, 1
	v_add3_u32 v43, v5, v4, s50
	v_pk_mul_f32 v[4:5], v[70:71], v[78:79]
	v_mov_b32_e32 v58, v47
	v_bfe_u32 v46, v5, 16, 1
	v_add3_u32 v46, v5, v46, s50
	v_bfe_u32 v5, v4, 16, 1
	v_add3_u32 v50, v4, v5, s50
	v_pk_mul_f32 v[4:5], v[58:59], v[74:75]
	global_store_dwordx4 v[86:87], v[90:93], off offset:64
	v_bfe_u32 v47, v5, 16, 1
	v_add3_u32 v5, v5, v47, s50
	v_bfe_u32 v47, v4, 16, 1
	v_add3_u32 v4, v4, v47, s50
	v_lshrrev_b32_e32 v5, 16, v5
	v_lshrrev_b32_e32 v4, 16, v4
	v_and_or_b32 v91, v33, s51, v5
	v_and_or_b32 v90, v32, s51, v4
	v_mov_b32_e32 v4, v44
	v_mov_b32_e32 v5, v52
	v_pk_mul_f32 v[4:5], v[4:5], v[98:99]
	v_lshrrev_b32_e32 v47, 16, v50
	v_bfe_u32 v32, v4, 16, 1
	v_add3_u32 v32, v4, v32, s50
	v_bfe_u32 v4, v5, 16, 1
	v_add3_u32 v33, v5, v4, s50
	v_mov_b32_e32 v4, v56
	v_mov_b32_e32 v5, v68
	v_pk_mul_f32 v[4:5], v[4:5], v[96:97]
	v_and_or_b32 v92, v42, s51, v47
	v_bfe_u32 v42, v4, 16, 1
	v_lshrrev_b32_e32 v46, 16, v46
	v_add3_u32 v42, v4, v42, s50
	v_bfe_u32 v4, v5, 16, 1
	v_and_or_b32 v93, v43, s51, v46
	v_add3_u32 v43, v5, v4, s50
	v_mov_b32_e32 v4, v64
	v_mov_b32_e32 v5, v72
	v_pk_mul_f32 v[4:5], v[4:5], v[78:79]
	v_mov_b32_e32 v52, v45
	v_bfe_u32 v44, v5, 16, 1
	v_add3_u32 v44, v5, v44, s50
	v_bfe_u32 v5, v4, 16, 1
	v_add3_u32 v46, v4, v5, s50
	v_mov_b32_e32 v4, v48
	v_mov_b32_e32 v5, v60
	v_pk_mul_f32 v[4:5], v[4:5], v[74:75]
	v_lshrrev_b32_e32 v44, 16, v44
	v_bfe_u32 v47, v5, 16, 1
	v_add3_u32 v5, v5, v47, s50
	v_bfe_u32 v47, v4, 16, 1
	v_add3_u32 v4, v4, v47, s50
	v_lshrrev_b32_e32 v5, 16, v5
	v_lshrrev_b32_e32 v4, 16, v4
	v_mov_b32_e32 v68, v57
	global_store_dwordx4 v[86:87], v[90:93], off offset:2112
	v_lshrrev_b32_e32 v46, 16, v46
	v_mov_b32_e32 v60, v49
	v_and_or_b32 v93, v43, s51, v44
	v_and_or_b32 v91, v33, s51, v5
	v_and_or_b32 v90, v32, s51, v4
	v_pk_mul_f32 v[32:33], v[52:53], v[98:99]
	v_mov_b32_e32 v72, v65
	v_pk_mul_f32 v[44:45], v[68:69], v[96:97]
	v_and_or_b32 v92, v42, s51, v46
	v_pk_mul_f32 v[4:5], v[60:61], v[74:75]
	v_pk_mul_f32 v[42:43], v[72:73], v[78:79]
	v_cvt_pk_bf16_f32 v45, v43, v45
	v_cvt_pk_bf16_f32 v44, v42, v44
	v_cvt_pk_bf16_f32 v43, v5, v33
	v_cvt_pk_bf16_f32 v42, v4, v32
	s_waitcnt vmcnt(8)
	v_mov_b32_e32 v32, v22
	s_waitcnt vmcnt(6)
	v_mov_b32_e32 v33, v34
	global_store_dwordx4 v[88:89], v[42:45], off offset:2112
	v_pk_mul_f32 v[32:33], v[32:33], v[80:81]
	v_mov_b32_e32 v4, v26
	s_waitcnt vmcnt(6)
	v_mov_b32_e32 v42, v18
	s_waitcnt vmcnt(4)
	v_mov_b32_e32 v43, v10
	v_mov_b32_e32 v5, v38
	v_pk_mul_f32 v[42:43], v[42:43], v[30:31]
	v_mov_b32_e32 v44, v14
	s_waitcnt vmcnt(3)
	v_mov_b32_e32 v45, v6
	v_pk_mul_f32 v[4:5], v[4:5], v[2:3]
	v_pk_mul_f32 v[44:45], v[44:45], v[76:77]
	v_bfe_u32 v18, v32, 16, 1
	v_add3_u32 v18, v32, v18, s50
	v_bfe_u32 v22, v4, 16, 1
	v_add3_u32 v4, v4, v22, s50
	v_cvt_pk_bf16_f32 v45, v43, v45
	v_mov_b32_e32 v34, v23
	v_mov_b32_e32 v6, v15
	v_lshrrev_b32_e32 v4, 16, v4
	v_cvt_pk_bf16_f32 v44, v42, v44
	v_mov_b32_e32 v38, v27
	v_pk_mul_f32 v[22:23], v[34:35], v[80:81]
	v_mov_b32_e32 v10, v19
	v_pk_mul_f32 v[6:7], v[6:7], v[76:77]
	v_cvt_pk_bf16_f32 v43, v5, v33
	v_and_or_b32 v42, v18, s51, v4
	v_pk_mul_f32 v[4:5], v[38:39], v[2:3]
	v_pk_mul_f32 v[10:11], v[10:11], v[30:31]
	v_cvt_pk_bf16_f32 v7, v11, v7
	v_cvt_pk_bf16_f32 v6, v10, v6
	v_cvt_pk_bf16_f32 v5, v5, v23
	v_cvt_pk_bf16_f32 v4, v4, v22
	global_store_dwordx4 v[86:87], v[4:7], off offset:2144
	v_mov_b32_e32 v14, v16
	v_mov_b32_e32 v15, v8
	v_mov_b32_e32 v6, v24
	v_mov_b32_e32 v7, v36
	v_mov_b32_e32 v4, v28
	v_mov_b32_e32 v5, v40
	v_pk_mul_f32 v[6:7], v[6:7], v[80:81]
	v_mov_b32_e32 v10, v20
	v_mov_b32_e32 v11, v12
	v_pk_mul_f32 v[14:15], v[14:15], v[76:77]
	v_pk_mul_f32 v[4:5], v[4:5], v[2:3]
	v_pk_mul_f32 v[10:11], v[10:11], v[30:31]
	v_bfe_u32 v8, v15, 16, 1
	v_bfe_u32 v12, v14, 16, 1
	v_bfe_u32 v16, v7, 16, 1
	v_bfe_u32 v18, v6, 16, 1
	v_add3_u32 v18, v6, v18, s50
	v_add3_u32 v16, v7, v16, s50
	v_add3_u32 v6, v14, v12, s50
	v_add3_u32 v7, v15, v8, s50
	v_bfe_u32 v8, v4, 16, 1
	v_bfe_u32 v12, v5, 16, 1
	v_bfe_u32 v14, v10, 16, 1
	v_bfe_u32 v15, v11, 16, 1
	v_add3_u32 v11, v11, v15, s50
	v_add3_u32 v10, v10, v14, s50
	v_add3_u32 v5, v5, v12, s50
	v_add3_u32 v4, v4, v8, s50
	v_lshrrev_b32_e32 v4, 16, v4
	v_lshrrev_b32_e32 v5, 16, v5
	v_lshrrev_b32_e32 v8, 16, v10
	v_lshrrev_b32_e32 v10, 16, v11
	v_mov_b32_e32 v40, v29
	v_and_or_b32 v7, v7, s51, v10
	v_and_or_b32 v6, v6, s51, v8
	v_and_or_b32 v5, v16, s51, v5
	v_and_or_b32 v4, v18, s51, v4
	v_pk_mul_f32 v[2:3], v[40:41], v[2:3]
	v_mov_b32_e32 v36, v25
	global_store_dwordx4 v[88:89], v[4:7], off offset:96
	v_mov_b32_e32 v16, v21
	v_mov_b32_e32 v8, v13
	v_pk_mul_f32 v[4:5], v[36:37], v[80:81]
	v_and_b32_sdwa v6, v3, v100 dst_sel:DWORD dst_unused:UNUSED_PAD src0_sel:WORD_1 src1_sel:DWORD
	v_and_b32_sdwa v7, v2, v100 dst_sel:DWORD dst_unused:UNUSED_PAD src0_sel:WORD_1 src1_sel:DWORD
	v_add3_u32 v2, v2, v7, s50
	v_add3_u32 v3, v3, v6, s50
	v_and_b32_sdwa v6, v5, v100 dst_sel:DWORD dst_unused:UNUSED_PAD src0_sel:WORD_1 src1_sel:DWORD
	v_and_b32_sdwa v7, v4, v100 dst_sel:DWORD dst_unused:UNUSED_PAD src0_sel:WORD_1 src1_sel:DWORD
	v_add3_u32 v5, v5, v6, s50
	v_add3_u32 v4, v4, v7, s50
	v_and_b32_e32 v5, 0xffff0000, v5
	v_and_b32_e32 v4, 0xffff0000, v4
	v_or_b32_sdwa v3, v5, v3 dst_sel:DWORD dst_unused:UNUSED_PAD src0_sel:DWORD src1_sel:WORD_1
	v_or_b32_sdwa v2, v4, v2 dst_sel:DWORD dst_unused:UNUSED_PAD src0_sel:DWORD src1_sel:WORD_1
	v_mov_b32_e32 v4, v30
	v_mov_b32_e32 v5, v76
	v_pk_mul_f32 v[4:5], v[16:17], v[4:5]
	v_mov_b32_e32 v76, v31
	v_and_b32_sdwa v6, v5, v100 dst_sel:DWORD dst_unused:UNUSED_PAD src0_sel:WORD_1 src1_sel:DWORD
	v_and_b32_sdwa v7, v4, v100 dst_sel:DWORD dst_unused:UNUSED_PAD src0_sel:WORD_1 src1_sel:DWORD
	v_add3_u32 v5, v5, v6, s50
	v_add3_u32 v4, v4, v7, s50
	v_pk_mul_f32 v[6:7], v[8:9], v[76:77]
	v_lshrrev_b32_e32 v4, 16, v4
	v_and_b32_sdwa v8, v6, v100 dst_sel:DWORD dst_unused:UNUSED_PAD src0_sel:WORD_1 src1_sel:DWORD
	v_and_or_b32 v4, v5, s51, v4
	v_and_b32_sdwa v5, v7, v100 dst_sel:DWORD dst_unused:UNUSED_PAD src0_sel:WORD_1 src1_sel:DWORD
	v_add3_u32 v6, v6, v8, s50
	v_add3_u32 v5, v7, v5, s50
	v_lshrrev_b32_e32 v6, 16, v6
	v_and_or_b32 v5, v5, s51, v6
	global_store_dwordx4 v[88:89], v[90:93], off offset:64
	global_store_dwordx4 v[86:87], v[42:45], off offset:96

.Lx_A_body:
	s_waitcnt lgkmcnt(0)
	v_mul_f32_e32 v2, v15, v15
	v_mul_f32_e32 v30, v17, v17
	v_mul_f32_e32 v31, v19, v19
	v_mul_f32_e32 v32, v21, v21
	v_mul_f32_e32 v33, v23, v23
	v_mul_f32_e32 v34, v25, v25
	v_fmac_f32_e32 v2, v14, v14
	v_fmac_f32_e32 v30, v16, v16
	v_fmac_f32_e32 v31, v18, v18
	v_fmac_f32_e32 v32, v20, v20
	v_mul_f32_e32 v35, v27, v27
	v_mul_f32_e32 v36, v29, v29
	v_fmac_f32_e32 v33, v22, v22
	v_fmac_f32_e32 v34, v24, v24
	v_add_f32_e32 v2, v2, v30
	v_add_f32_e32 v30, v31, v32
	v_fmac_f32_e32 v35, v26, v26
	v_fmac_f32_e32 v36, v28, v28
	v_add_f32_e32 v31, v33, v34
	v_add_f32_e32 v2, v2, v30
	v_add_f32_e32 v32, v35, v36
	v_add_f32_e32 v2, v2, v31
	v_add_f32_e32 v2, v2, v32
	ds_bpermute_b32 v30, v8, v2
	s_waitcnt lgkmcnt(0)
	v_add_f32_e32 v2, v2, v30
	ds_bpermute_b32 v30, v9, v2
	s_waitcnt lgkmcnt(0)
	v_add_f32_e32 v2, v2, v30
	ds_bpermute_b32 v30, v10, v2
	s_waitcnt lgkmcnt(0)
	v_add_f32_e32 v2, v2, v30
	ds_bpermute_b32 v30, v11, v2
	v_cvt_pk_bf16_f32 v14, v14, v15
	s_waitcnt lgkmcnt(0)
	v_add_f32_e32 v2, v2, v30
	v_cvt_pk_bf16_f32 v15, v16, v17
	v_cvt_pk_bf16_f32 v17, v20, v21
	v_mov_b32_e32 v21, v2
	s_nop 1
	v_permlane16_swap_b32_e32 v21, v2
	s_waitcnt lgkmcnt(0)
	v_add_f32_e32 v2, v2, v21
	v_cvt_pk_bf16_f32 v16, v18, v19
	v_cvt_pk_bf16_f32 v18, v22, v23
	v_cvt_pk_bf16_f32 v19, v24, v25
	global_store_dwordx2 v[4:5], v[14:15], off offset:-1536
	global_store_dwordx2 v[4:5], v[16:17], off offset:-1024
	global_store_dwordx2 v[4:5], v[18:19], off offset:-512
	v_mov_b32_e32 v14, v2
	s_nop 1
	v_permlane32_swap_b32_e32 v14, v2
	v_cvt_pk_bf16_f32 v20, v26, v27
	v_cvt_pk_bf16_f32 v21, v28, v29
	global_store_dwordx2 v[4:5], v[20:21], off
	s_and_saveexec_b64 s[24:25], vcc
	s_cbranch_execz .Lx_A_latch
	s_waitcnt lgkmcnt(0)
	v_add_f32_e32 v2, v2, v14
	global_store_dword v3, v2, s[4:5]
	s_branch .Lx_A_latch

.Lx_B_body:
	s_waitcnt lgkmcnt(0)
	v_mul_f32_e32 v2, v53, v53
	v_mul_f32_e32 v30, v55, v55
	v_mul_f32_e32 v31, v57, v57
	v_mul_f32_e32 v32, v59, v59
	v_mul_f32_e32 v33, v61, v61
	v_mul_f32_e32 v34, v63, v63
	v_fmac_f32_e32 v2, v52, v52
	v_fmac_f32_e32 v30, v54, v54
	v_fmac_f32_e32 v31, v56, v56
	v_fmac_f32_e32 v32, v58, v58
	v_mul_f32_e32 v35, v65, v65
	v_mul_f32_e32 v36, v67, v67
	v_fmac_f32_e32 v33, v60, v60
	v_fmac_f32_e32 v34, v62, v62
	v_add_f32_e32 v2, v2, v30
	v_add_f32_e32 v30, v31, v32
	v_fmac_f32_e32 v35, v64, v64
	v_fmac_f32_e32 v36, v66, v66
	v_add_f32_e32 v31, v33, v34
	v_add_f32_e32 v2, v2, v30
	v_add_f32_e32 v32, v35, v36
	v_add_f32_e32 v2, v2, v31
	v_add_f32_e32 v2, v2, v32
	ds_bpermute_b32 v30, v8, v2
	s_waitcnt lgkmcnt(0)
	v_add_f32_e32 v2, v2, v30
	ds_bpermute_b32 v30, v9, v2
	s_waitcnt lgkmcnt(0)
	v_add_f32_e32 v2, v2, v30
	ds_bpermute_b32 v30, v10, v2
	s_waitcnt lgkmcnt(0)
	v_add_f32_e32 v2, v2, v30
	ds_bpermute_b32 v30, v11, v2
	v_cvt_pk_bf16_f32 v52, v52, v53
	s_waitcnt lgkmcnt(0)
	v_add_f32_e32 v2, v2, v30
	v_cvt_pk_bf16_f32 v53, v54, v55
	v_cvt_pk_bf16_f32 v55, v58, v59
	v_mov_b32_e32 v59, v2
	s_nop 1
	v_permlane16_swap_b32_e32 v59, v2
	s_waitcnt lgkmcnt(0)
	v_add_f32_e32 v2, v2, v59
	v_cvt_pk_bf16_f32 v54, v56, v57
	v_cvt_pk_bf16_f32 v56, v60, v61
	v_cvt_pk_bf16_f32 v57, v62, v63
	global_store_dwordx2 v[4:5], v[52:53], off offset:-1536
	global_store_dwordx2 v[4:5], v[54:55], off offset:-1024
	global_store_dwordx2 v[4:5], v[56:57], off offset:-512
	v_mov_b32_e32 v52, v2
	s_nop 1
	v_permlane32_swap_b32_e32 v52, v2
	v_cvt_pk_bf16_f32 v58, v64, v65
	v_cvt_pk_bf16_f32 v59, v66, v67
	global_store_dwordx2 v[4:5], v[58:59], off
	s_and_saveexec_b64 s[24:25], vcc
	s_cbranch_execz .Lx_B_latch
	s_waitcnt lgkmcnt(0)
	v_add_f32_e32 v2, v2, v52
	global_store_dword v3, v2, s[4:5]
	s_branch .Lx_B_latch

.LBB0_482:
	v_or_b32_e32 v2, s24, v155
	v_mul_u32_u24_e32 v2, 0x300, v2
	v_lshlrev_b32_e32 v2, 1, v2
	v_lshl_add_u64 v[42:43], s[60:61], 0, v[2:3]
	s_lshl_b32 s24, s64, 1
	v_lshl_add_u64 v[42:43], v[42:43], 0, s[24:25]
	v_lshlrev_b32_e32 v2, 1, v116
	v_lshl_add_u64 v[100:101], v[42:43], 0, v[2:3]
	s_waitcnt vmcnt(15)
	v_mov_b32_e32 v42, v48
	s_waitcnt vmcnt(13)
	v_mov_b32_e32 v43, v56
	v_pk_mul_f32 v[42:43], v[42:43], v[76:77]
	v_mov_b32_e32 v96, v44
	s_waitcnt vmcnt(12)
	v_mov_b32_e32 v97, v52
	s_waitcnt vmcnt(11)
	v_mov_b32_e32 v98, v64
	s_waitcnt vmcnt(9)
	v_mov_b32_e32 v99, v72
	v_pk_mul_f32 v[96:97], v[96:97], v[92:93]
	v_pk_mul_f32 v[98:99], v[98:99], v[80:81]
	v_mov_b32_e32 v102, v60
	s_waitcnt vmcnt(8)
	v_mov_b32_e32 v103, v68
	v_bfe_u32 v56, v42, 16, 1
	v_pk_mul_f32 v[102:103], v[102:103], v[90:91]
	v_bfe_u32 v52, v96, 16, 1
	v_bfe_u32 v68, v99, 16, 1
	v_add3_u32 v42, v42, v56, s76
	v_bfe_u32 v2, v103, 16, 1
	v_add3_u32 v52, v96, v52, s76
	v_add3_u32 v68, v99, v68, s76
	v_lshrrev_b32_e32 v42, 16, v42
	s_mov_b32 s24, 0x5180000
	v_add3_u32 v2, v103, v2, s76
	v_lshrrev_b32_e32 v60, 16, v68
	v_and_or_b32 v96, v52, s77, v42
	v_add_co_u32_e32 v42, vcc, s24, v100
	v_mov_b32_e32 v52, v45
	v_mov_b32_e32 v68, v61
	v_and_or_b32 v99, v2, s77, v60
	v_cvt_pk_bf16_f32 v98, v98, v102
	v_cvt_pk_bf16_f32 v97, v43, v97
	v_addc_co_u32_e32 v43, vcc, 0, v101, vcc
	v_mov_b32_e32 v56, v49
	v_pk_mul_f32 v[44:45], v[52:53], v[92:93]
	v_mov_b32_e32 v72, v65
	v_pk_mul_f32 v[52:53], v[68:69], v[90:91]
	global_store_dwordx4 v[42:43], v[96:99], off
	v_pk_mul_f32 v[42:43], v[56:57], v[76:77]
	v_pk_mul_f32 v[48:49], v[72:73], v[80:81]
	v_bfe_u32 v2, v53, 16, 1
	v_bfe_u32 v56, v52, 16, 1
	v_bfe_u32 v57, v45, 16, 1
	v_bfe_u32 v60, v44, 16, 1
	v_add3_u32 v60, v44, v60, s76
	v_add3_u32 v57, v45, v57, s76
	v_add3_u32 v44, v52, v56, s76
	v_add3_u32 v2, v53, v2, s76
	v_bfe_u32 v45, v42, 16, 1
	v_bfe_u32 v52, v43, 16, 1
	v_bfe_u32 v53, v48, 16, 1
	v_bfe_u32 v56, v49, 16, 1
	v_add3_u32 v49, v49, v56, s76
	v_add3_u32 v48, v48, v53, s76
	v_add3_u32 v43, v43, v52, s76
	v_add3_u32 v42, v42, v45, s76
	s_mov_b64 s[60:61], 0x5180000
	v_lshrrev_b32_e32 v42, 16, v42
	v_lshrrev_b32_e32 v43, 16, v43
	v_lshrrev_b32_e32 v48, 16, v48
	v_lshrrev_b32_e32 v45, 16, v49
	v_lshl_add_u64 v[84:85], v[100:101], 0, s[60:61]
	v_and_or_b32 v45, v2, s77, v45
	v_and_or_b32 v44, v44, s77, v48
	v_and_or_b32 v43, v57, s77, v43
	v_and_or_b32 v42, v60, s77, v42
	global_store_dwordx4 v[84:85], v[42:45], off offset:1536
	v_mov_b32_e32 v52, v62
	v_mov_b32_e32 v53, v70
	v_mov_b32_e32 v44, v46
	v_mov_b32_e32 v45, v54
	v_mov_b32_e32 v42, v50
	v_mov_b32_e32 v43, v58
	v_pk_mul_f32 v[44:45], v[44:45], v[92:93]
	v_mov_b32_e32 v48, v66
	v_mov_b32_e32 v49, v74
	v_pk_mul_f32 v[52:53], v[52:53], v[90:91]
	v_pk_mul_f32 v[42:43], v[42:43], v[76:77]
	v_pk_mul_f32 v[48:49], v[48:49], v[80:81]
	v_bfe_u32 v50, v45, 16, 1
	v_bfe_u32 v54, v44, 16, 1
	v_add3_u32 v54, v44, v54, s76
	v_add3_u32 v50, v45, v50, s76
	v_bfe_u32 v45, v42, 16, 1
	v_bfe_u32 v46, v43, 16, 1
	v_add3_u32 v43, v43, v46, s76
	v_add3_u32 v42, v42, v45, s76
	v_lshrrev_b32_e32 v42, 16, v42
	v_lshrrev_b32_e32 v43, 16, v43
	v_mov_b32_e32 v70, v63
	v_cvt_pk_bf16_f32 v45, v49, v53
	v_cvt_pk_bf16_f32 v44, v48, v52
	v_and_or_b32 v43, v50, s77, v43
	v_and_or_b32 v42, v54, s77, v42
	v_mov_b32_e32 v54, v47
	v_mov_b32_e32 v74, v67
	v_pk_mul_f32 v[48:49], v[70:71], v[90:91]
	global_store_dwordx4 v[84:85], v[42:45], off offset:3072
	v_mov_b32_e32 v58, v51
	v_pk_mul_f32 v[46:47], v[74:75], v[80:81]
	v_pk_mul_f32 v[44:45], v[54:55], v[92:93]
	v_bfe_u32 v2, v49, 16, 1
	v_pk_mul_f32 v[42:43], v[58:59], v[76:77]
	v_bfe_u32 v50, v48, 16, 1
	v_bfe_u32 v51, v45, 16, 1
	v_bfe_u32 v52, v44, 16, 1
	v_add3_u32 v2, v49, v2, s76
	v_bfe_u32 v49, v46, 16, 1
	v_add3_u32 v52, v44, v52, s76
	v_add3_u32 v51, v45, v51, s76
	v_add3_u32 v44, v48, v50, s76
	v_bfe_u32 v45, v42, 16, 1
	v_bfe_u32 v48, v43, 16, 1
	v_bfe_u32 v50, v47, 16, 1
	v_add3_u32 v46, v46, v49, s76
	v_add3_u32 v47, v47, v50, s76
	v_add3_u32 v43, v43, v48, s76
	v_add3_u32 v42, v42, v45, s76
	v_lshrrev_b32_e32 v46, 16, v46
	s_mov_b32 s24, 0x5181000
	v_lshrrev_b32_e32 v42, 16, v42
	v_lshrrev_b32_e32 v43, 16, v43
	v_lshrrev_b32_e32 v45, 16, v47
	v_and_or_b32 v44, v44, s77, v46
	v_add_co_u32_e32 v46, vcc, s24, v100
	v_and_or_b32 v45, v2, s77, v45
	v_and_or_b32 v43, v51, s77, v43
	v_and_or_b32 v42, v52, s77, v42
	v_addc_co_u32_e32 v47, vcc, 0, v101, vcc
	global_store_dwordx4 v[46:47], v[42:45], off offset:512
	s_waitcnt vmcnt(7)
	v_mov_b32_e32 v48, v28
	s_waitcnt vmcnt(5)
	v_mov_b32_e32 v49, v36
	v_mov_b32_e32 v42, v12
	v_mov_b32_e32 v43, v20
	v_pk_mul_f32 v[42:43], v[42:43], v[4:5]
	v_mov_b32_e32 v44, v8
	v_mov_b32_e32 v45, v16
	v_pk_mul_f32 v[48:49], v[48:49], v[40:41]
	v_mov_b32_e32 v50, v24
	s_waitcnt vmcnt(4)
	v_mov_b32_e32 v51, v32
	v_pk_mul_f32 v[44:45], v[44:45], v[82:83]
	v_pk_mul_f32 v[50:51], v[50:51], v[78:79]
	v_bfe_u32 v24, v43, 16, 1
	v_bfe_u32 v12, v45, 16, 1
	v_add3_u32 v24, v43, v24, s76
	v_add3_u32 v12, v45, v12, s76
	v_lshrrev_b32_e32 v24, 16, v24
	v_cvt_pk_bf16_f32 v45, v49, v51
	v_cvt_pk_bf16_f32 v42, v42, v44
	v_mov_b32_e32 v20, v13
	v_mov_b32_e32 v32, v25
	v_and_or_b32 v43, v12, s77, v24
	v_pk_mul_f32 v[12:13], v[20:21], v[4:5]
	v_mov_b32_e32 v16, v9
	v_pk_mul_f32 v[20:21], v[32:33], v[78:79]
	v_cvt_pk_bf16_f32 v44, v48, v50
	v_pk_mul_f32 v[8:9], v[16:17], v[82:83]
	v_mov_b32_e32 v36, v29
	v_bfe_u32 v2, v21, 16, 1
	v_pk_mul_f32 v[16:17], v[36:37], v[40:41]
	v_add3_u32 v2, v21, v2, s76
	v_bfe_u32 v28, v17, 16, 1
	global_store_dwordx4 v[84:85], v[42:45], off offset:32
	v_add3_u32 v17, v17, v28, s76
	s_nop 1
	v_cvt_pk_bf16_f32 v43, v13, v9
	v_cvt_pk_bf16_f32 v42, v12, v8
	v_mov_b32_e32 v12, v10
	v_mov_b32_e32 v13, v18
	v_lshrrev_b32_e32 v17, 16, v17
	v_cvt_pk_bf16_f32 v44, v16, v20
	v_mov_b32_e32 v8, v14
	v_mov_b32_e32 v9, v22
	v_pk_mul_f32 v[12:13], v[12:13], v[82:83]
	v_mov_b32_e32 v20, v26
	v_mov_b32_e32 v21, v34
	v_and_or_b32 v45, v2, s77, v17
	v_pk_mul_f32 v[8:9], v[8:9], v[4:5]
	v_mov_b32_e32 v16, v30
	v_mov_b32_e32 v17, v38
	v_pk_mul_f32 v[20:21], v[20:21], v[78:79]
	v_bfe_u32 v14, v13, 16, 1
	v_bfe_u32 v18, v12, 16, 1
	v_pk_mul_f32 v[16:17], v[16:17], v[40:41]
	v_add3_u32 v12, v12, v18, s76
	v_add3_u32 v13, v13, v14, s76
	v_bfe_u32 v14, v8, 16, 1
	v_bfe_u32 v18, v9, 16, 1
	v_add3_u32 v9, v9, v18, s76
	v_add3_u32 v8, v8, v14, s76
	v_lshrrev_b32_e32 v8, 16, v8
	v_lshrrev_b32_e32 v9, 16, v9
	v_mov_b32_e32 v34, v27
	global_store_dwordx4 v[84:85], v[42:45], off offset:1568
	s_nop 1
	v_and_or_b32 v43, v13, s77, v9
	s_nop 1
	v_and_or_b32 v42, v12, s77, v8
	v_mov_b32_e32 v22, v15
	v_pk_mul_f32 v[12:13], v[34:35], v[78:79]
	v_cvt_pk_bf16_f32 v45, v17, v21
	v_pk_mul_f32 v[4:5], v[22:23], v[4:5]
	v_mov_b32_e32 v18, v11
	v_cvt_pk_bf16_f32 v44, v16, v20
	v_pk_mul_f32 v[8:9], v[18:19], v[82:83]
	v_mov_b32_e32 v38, v31
	s_mov_b64 s[62:63], 0x18000
	v_pk_mul_f32 v[10:11], v[38:39], v[40:41]
	v_lshl_add_u64 v[6:7], v[86:87], 0, s[62:63]
	s_mov_b32 s24, 0x18000
	v_cvt_pk_bf16_f32 v8, v4, v8
	v_add_co_u32_e32 v4, vcc, s24, v6
	v_cvt_pk_bf16_f32 v9, v5, v9
	v_addc_co_u32_e32 v5, vcc, 0, v7, vcc
	v_cvt_pk_bf16_f32 v11, v11, v13
	v_cvt_pk_bf16_f32 v10, v10, v12
	v_add_co_u32_e32 v6, vcc, s78, v86
	global_store_dwordx4 v[84:85], v[42:45], off offset:3104
	global_store_dwordx4 v[46:47], v[8:11], off offset:544
	v_addc_co_u32_e32 v7, vcc, 0, v87, vcc
	global_load_dwordx4 v[48:51], v[4:5], off nt
	global_load_dwordx4 v[44:47], v[6:7], off offset:2048 nt
	v_add_co_u32_e32 v4, vcc, s79, v86
	s_mov_b32 s24, 0x34000
	s_nop 0
	v_addc_co_u32_e32 v5, vcc, 0, v87, vcc
	v_add_co_u32_e32 v6, vcc, s24, v86
	s_mov_b32 s24, 0x36000
	s_nop 0
	v_addc_co_u32_e32 v7, vcc, 0, v87, vcc
	global_load_dwordx4 v[56:59], v[4:5], off nt
	global_load_dwordx4 v[52:55], v[6:7], off offset:2048 nt
	v_add_co_u32_e32 v4, vcc, s24, v86
	v_mov_b32_e32 v76, 1.0
	s_nop 0
	v_addc_co_u32_e32 v5, vcc, 0, v87, vcc
	v_add_co_u32_e32 v6, vcc, 0x37000, v86
	v_mov_b32_e32 v92, 1.0
	s_nop 0
	v_addc_co_u32_e32 v7, vcc, 0, v87, vcc
	global_load_dwordx4 v[64:67], v[4:5], off nt
	global_load_dwordx4 v[60:63], v[6:7], off offset:2048 nt
	v_add_co_u32_e32 v4, vcc, 0x39000, v86
	v_mov_b32_e32 v77, 1.0
	s_nop 0
	v_addc_co_u32_e32 v5, vcc, 0, v87, vcc
	v_add_co_u32_e32 v6, vcc, 0x3a000, v86
	v_mov_b32_e32 v93, 1.0
	s_nop 0
	v_addc_co_u32_e32 v7, vcc, 0, v87, vcc
	global_load_dwordx4 v[72:75], v[4:5], off nt
	global_load_dwordx4 v[68:71], v[6:7], off offset:2048 nt
	v_mov_b32_e32 v4, 1.0
	s_and_b64 vcc, exec, s[16:17]
	v_mov_b32_e32 v80, 1.0
	v_mov_b32_e32 v90, 1.0
	v_mov_b32_e32 v81, 1.0
	v_mov_b32_e32 v91, 1.0
	s_cbranch_vccnz .LBB0_484
	global_load_dwordx4 v[76:79], v94, s[26:27] offset:128
	global_load_dwordx4 v[80:83], v94, s[26:27] offset:144
	s_waitcnt vmcnt(1)
	v_mov_b32_e32 v92, v77
	v_mov_b32_e32 v77, v78
	v_mov_b32_e32 v93, v79
	s_waitcnt vmcnt(0)
	v_mov_b32_e32 v90, v81
	v_mov_b32_e32 v81, v82
	v_mov_b32_e32 v91, v83

.LBB0_486:
	s_waitcnt vmcnt(15)
	v_mov_b32_e32 v42, v48
	s_waitcnt vmcnt(13)
	v_mov_b32_e32 v43, v56
	v_pk_mul_f32 v[42:43], v[42:43], v[76:77]
	v_mov_b32_e32 v82, v44
	s_waitcnt vmcnt(12)
	v_mov_b32_e32 v83, v52
	s_waitcnt vmcnt(11)
	v_mov_b32_e32 v86, v64
	s_waitcnt vmcnt(9)
	v_mov_b32_e32 v87, v72
	v_pk_mul_f32 v[82:83], v[82:83], v[92:93]
	v_pk_mul_f32 v[86:87], v[86:87], v[80:81]
	v_mov_b32_e32 v88, v60
	s_waitcnt vmcnt(8)
	v_mov_b32_e32 v89, v68
	v_bfe_u32 v56, v42, 16, 1
	v_pk_mul_f32 v[88:89], v[88:89], v[90:91]
	v_bfe_u32 v52, v82, 16, 1
	v_bfe_u32 v64, v86, 16, 1
	v_add3_u32 v42, v42, v56, s76
	v_bfe_u32 v44, v88, 16, 1
	v_add3_u32 v52, v82, v52, s76
	v_add3_u32 v64, v86, v64, s76
	v_lshrrev_b32_e32 v42, 16, v42
	v_add3_u32 v44, v88, v44, s76
	v_lshrrev_b32_e32 v56, 16, v64
	v_and_or_b32 v86, v52, s77, v42
	v_mov_b32_e32 v52, v45
	v_mov_b32_e32 v68, v61
	v_and_or_b32 v88, v44, s77, v56
	v_mov_b32_e32 v56, v49
	v_pk_mul_f32 v[44:45], v[52:53], v[92:93]
	v_mov_b32_e32 v72, v65
	v_pk_mul_f32 v[52:53], v[68:69], v[90:91]
	v_cvt_pk_bf16_f32 v89, v87, v89
	v_cvt_pk_bf16_f32 v87, v43, v83
	v_pk_mul_f32 v[42:43], v[56:57], v[76:77]
	v_pk_mul_f32 v[48:49], v[72:73], v[80:81]
	v_bfe_u32 v2, v53, 16, 1
	v_bfe_u32 v56, v52, 16, 1
	v_bfe_u32 v57, v45, 16, 1
	v_bfe_u32 v60, v44, 16, 1
	v_add3_u32 v60, v44, v60, s76
	v_add3_u32 v57, v45, v57, s76
	v_add3_u32 v44, v52, v56, s76
	v_add3_u32 v2, v53, v2, s76
	v_bfe_u32 v45, v42, 16, 1
	v_bfe_u32 v52, v43, 16, 1
	v_bfe_u32 v53, v48, 16, 1
	v_bfe_u32 v56, v49, 16, 1
	v_add3_u32 v49, v49, v56, s76
	v_add3_u32 v48, v48, v53, s76
	v_add3_u32 v43, v43, v52, s76
	v_add3_u32 v42, v42, v45, s76
	v_lshrrev_b32_e32 v42, 16, v42
	v_lshrrev_b32_e32 v43, 16, v43
	v_lshrrev_b32_e32 v48, 16, v48
	v_lshrrev_b32_e32 v45, 16, v49
	v_and_or_b32 v45, v2, s77, v45
	v_and_or_b32 v44, v44, s77, v48
	v_and_or_b32 v43, v57, s77, v43
	v_and_or_b32 v42, v60, s77, v42
	global_store_dwordx4 v[84:85], v[42:45], off offset:1600
	v_mov_b32_e32 v52, v62
	v_mov_b32_e32 v53, v70
	v_mov_b32_e32 v44, v46
	v_mov_b32_e32 v45, v54
	v_mov_b32_e32 v42, v50
	v_mov_b32_e32 v43, v58
	v_pk_mul_f32 v[44:45], v[44:45], v[92:93]
	v_mov_b32_e32 v48, v66
	v_mov_b32_e32 v49, v74
	v_pk_mul_f32 v[52:53], v[52:53], v[90:91]
	v_pk_mul_f32 v[42:43], v[42:43], v[76:77]
	v_pk_mul_f32 v[48:49], v[48:49], v[80:81]
	v_bfe_u32 v50, v45, 16, 1
	v_bfe_u32 v54, v44, 16, 1
	v_add3_u32 v54, v44, v54, s76
	v_add3_u32 v50, v45, v50, s76
	v_bfe_u32 v45, v42, 16, 1
	v_bfe_u32 v46, v43, 16, 1
	v_add3_u32 v43, v43, v46, s76
	v_add3_u32 v42, v42, v45, s76
	v_lshrrev_b32_e32 v42, 16, v42
	v_lshrrev_b32_e32 v43, 16, v43
	v_mov_b32_e32 v70, v63
	v_cvt_pk_bf16_f32 v45, v49, v53
	v_cvt_pk_bf16_f32 v44, v48, v52
	v_and_or_b32 v43, v50, s77, v43
	v_and_or_b32 v42, v54, s77, v42
	v_mov_b32_e32 v54, v47
	v_mov_b32_e32 v74, v67
	v_pk_mul_f32 v[48:49], v[70:71], v[90:91]
	global_store_dwordx4 v[84:85], v[42:45], off offset:3136
	v_mov_b32_e32 v58, v51
	v_pk_mul_f32 v[46:47], v[74:75], v[80:81]
	v_pk_mul_f32 v[44:45], v[54:55], v[92:93]
	v_bfe_u32 v2, v49, 16, 1
	v_pk_mul_f32 v[42:43], v[58:59], v[76:77]
	v_bfe_u32 v50, v48, 16, 1
	v_bfe_u32 v51, v45, 16, 1
	v_bfe_u32 v52, v44, 16, 1
	v_add3_u32 v2, v49, v2, s76
	v_bfe_u32 v49, v46, 16, 1
	v_add3_u32 v52, v44, v52, s76
	v_add3_u32 v51, v45, v51, s76
	v_add3_u32 v44, v48, v50, s76
	v_bfe_u32 v45, v42, 16, 1
	v_bfe_u32 v48, v43, 16, 1
	v_bfe_u32 v50, v47, 16, 1
	v_add3_u32 v46, v46, v49, s76
	v_add3_u32 v47, v47, v50, s76
	v_add3_u32 v43, v43, v48, s76
	v_add3_u32 v42, v42, v45, s76
	v_lshrrev_b32_e32 v46, 16, v46
	v_lshrrev_b32_e32 v42, 16, v42
	v_lshrrev_b32_e32 v43, 16, v43
	v_lshrrev_b32_e32 v45, 16, v47
	v_and_or_b32 v44, v44, s77, v46
	v_add_co_u32_e32 v46, vcc, s69, v84
	v_and_or_b32 v45, v2, s77, v45
	v_and_or_b32 v43, v51, s77, v43
	v_and_or_b32 v42, v52, s77, v42
	v_addc_co_u32_e32 v47, vcc, 0, v85, vcc
	global_store_dwordx4 v[46:47], v[42:45], off offset:576
	s_waitcnt vmcnt(6)
	v_mov_b32_e32 v48, v28
	s_waitcnt vmcnt(4)
	v_mov_b32_e32 v49, v36
	v_mov_b32_e32 v42, v12
	v_mov_b32_e32 v43, v20
	v_pk_mul_f32 v[42:43], v[42:43], v[4:5]
	v_mov_b32_e32 v44, v8
	v_mov_b32_e32 v45, v16
	v_pk_mul_f32 v[48:49], v[48:49], v[40:41]
	v_mov_b32_e32 v50, v24
	s_waitcnt vmcnt(3)
	v_mov_b32_e32 v51, v32
	v_pk_mul_f32 v[44:45], v[44:45], v[78:79]
	v_pk_mul_f32 v[50:51], v[50:51], v[6:7]
	v_bfe_u32 v24, v43, 16, 1
	v_bfe_u32 v12, v45, 16, 1
	v_add3_u32 v24, v43, v24, s76
	v_add3_u32 v12, v45, v12, s76
	v_lshrrev_b32_e32 v24, 16, v24
	v_cvt_pk_bf16_f32 v45, v49, v51
	v_cvt_pk_bf16_f32 v42, v42, v44
	v_mov_b32_e32 v20, v13
	v_mov_b32_e32 v32, v25
	v_and_or_b32 v43, v12, s77, v24
	v_pk_mul_f32 v[12:13], v[20:21], v[4:5]
	v_mov_b32_e32 v16, v9
	v_pk_mul_f32 v[20:21], v[32:33], v[6:7]
	v_cvt_pk_bf16_f32 v44, v48, v50
	v_pk_mul_f32 v[8:9], v[16:17], v[78:79]
	v_mov_b32_e32 v36, v29
	v_bfe_u32 v2, v21, 16, 1
	v_pk_mul_f32 v[16:17], v[36:37], v[40:41]
	v_add3_u32 v2, v21, v2, s76
	v_bfe_u32 v28, v17, 16, 1
	global_store_dwordx4 v[84:85], v[42:45], off offset:96
	v_add3_u32 v17, v17, v28, s76
	s_nop 1
	v_cvt_pk_bf16_f32 v43, v13, v9
	v_cvt_pk_bf16_f32 v42, v12, v8
	v_mov_b32_e32 v12, v10
	v_mov_b32_e32 v13, v18
	v_lshrrev_b32_e32 v17, 16, v17
	v_cvt_pk_bf16_f32 v44, v16, v20
	v_mov_b32_e32 v8, v14
	v_mov_b32_e32 v9, v22
	v_pk_mul_f32 v[12:13], v[12:13], v[78:79]
	v_mov_b32_e32 v20, v26
	v_mov_b32_e32 v21, v34
	v_and_or_b32 v45, v2, s77, v17
	v_pk_mul_f32 v[8:9], v[8:9], v[4:5]
	v_mov_b32_e32 v16, v30
	v_mov_b32_e32 v17, v38
	v_pk_mul_f32 v[20:21], v[20:21], v[6:7]
	v_bfe_u32 v14, v13, 16, 1
	v_bfe_u32 v18, v12, 16, 1
	v_pk_mul_f32 v[16:17], v[16:17], v[40:41]
	v_add3_u32 v12, v12, v18, s76
	v_add3_u32 v13, v13, v14, s76
	v_bfe_u32 v14, v8, 16, 1
	v_bfe_u32 v18, v9, 16, 1
	v_add3_u32 v9, v9, v18, s76
	v_add3_u32 v8, v8, v14, s76
	v_lshrrev_b32_e32 v8, 16, v8
	v_lshrrev_b32_e32 v9, 16, v9
	v_mov_b32_e32 v18, v11
	v_mov_b32_e32 v34, v27
	global_store_dwordx4 v[84:85], v[42:45], off offset:1632
	s_nop 1
	v_and_or_b32 v43, v13, s77, v9
	s_nop 1
	v_and_or_b32 v42, v12, s77, v8
	v_mov_b32_e32 v22, v15
	v_pk_mul_f32 v[8:9], v[18:19], v[78:79]
	v_mov_b32_e32 v38, v31
	v_pk_mul_f32 v[6:7], v[34:35], v[6:7]
	v_cvt_pk_bf16_f32 v45, v17, v21
	v_cvt_pk_bf16_f32 v44, v16, v20
	v_pk_mul_f32 v[4:5], v[22:23], v[4:5]
	v_pk_mul_f32 v[10:11], v[38:39], v[40:41]
	v_bfe_u32 v2, v7, 16, 1
	v_bfe_u32 v14, v8, 16, 1
	v_add3_u32 v8, v8, v14, s76
	v_add3_u32 v2, v7, v2, s76
	v_bfe_u32 v7, v4, 16, 1
	v_bfe_u32 v14, v11, 16, 1
	v_add3_u32 v11, v11, v14, s76
	v_add3_u32 v4, v4, v7, s76
	v_lshrrev_b32_e32 v4, 16, v4
	v_lshrrev_b32_e32 v7, 16, v11
	v_and_or_b32 v7, v2, s77, v7
	v_cvt_pk_bf16_f32 v6, v10, v6
	v_cvt_pk_bf16_f32 v5, v5, v9
	v_and_or_b32 v4, v8, s77, v4
	global_store_dwordx4 v[84:85], v[86:89], off offset:64
	global_store_dwordx4 v[84:85], v[42:45], off offset:3168
	global_store_dwordx4 v[46:47], v[4:7], off offset:608
	s_mov_b64 s[16:17], 0
.LBB0_487:
	s_and_b64 vcc, exec, s[16:17]
	s_cbranch_vccz .LBB0_489
	s_mov_b64 s[16:17], s[0:1]
	s_load_dwordx2 s[26:27], s[16:17], 0x78
	s_mov_b64 s[16:17], s[0:1]
	s_load_dwordx2 s[60:61], s[16:17], 0xa8
	s_mov_b64 s[16:17], s[0:1]
	s_load_dwordx2 s[16:17], s[16:17], 0x20
	s_waitcnt lgkmcnt(0)
	s_add_u32 s16, s16, 0x1000
	s_addc_u32 s17, s17, 0
	s_add_i32 s24, s23, 32
	s_and_b32 s62, s24, 0xff
	s_mulk_i32 s62, 0xab
	s_lshr_b32 s62, s62, 10
	s_mul_i32 s63, s62, 6
	s_sub_i32 s24, s24, s63
	s_and_b32 s24, s24, 0xff
	v_lshl_or_b32 v6, s24, 7, v155
	v_lshlrev_b32_e32 v2, 11, v6
	v_lshl_add_u64 v[4:5], s[60:61], 0, v[2:3]
	s_lshl_b32 s24, s62, 7
	v_lshl_add_u64 v[4:5], v[4:5], 0, s[24:25]
	v_lshlrev_b32_e32 v2, 1, v116
	s_waitcnt vmcnt(4)
	v_lshl_add_u64 v[96:97], v[4:5], 0, v[2:3]
	v_lshl_or_b32 v78, s62, 6, v116
	v_lshlrev_b32_e32 v2, 2, v6
	v_lshl_add_u64 v[76:77], s[26:27], 0, v[2:3]
	v_mul_u32_u24_e32 v2, 0x300, v78
	v_lshlrev_b32_e32 v2, 2, v2
	v_mad_u64_u32 v[4:5], s[26:27], v78, s68, v[76:77]
	v_lshl_add_u64 v[74:75], v[76:77], 0, v[2:3]
	global_load_dwordx4 v[48:51], v[4:5], off nt
	global_load_dwordx4 v[44:47], v[74:75], off offset:3072 nt
	v_add_co_u32_e32 v4, vcc, s69, v74
	s_movk_i32 s24, 0x3000
	s_nop 0
	v_addc_co_u32_e32 v5, vcc, 0, v75, vcc
	v_add_co_u32_e32 v6, vcc, s81, v74
	v_lshlrev_b32_e32 v2, 2, v78
	s_nop 0
	v_addc_co_u32_e32 v7, vcc, 0, v75, vcc
	global_load_dwordx4 v[56:59], v[4:5], off offset:2048 nt
	global_load_dwordx4 v[52:55], v[6:7], off offset:1024 nt
	v_add_co_u32_e32 v4, vcc, s24, v74
	global_load_dwordx4 v[60:63], v2, s[16:17] offset:16
	global_load_dwordx4 v[68:71], v2, s[16:17]
	v_addc_co_u32_e32 v5, vcc, 0, v75, vcc
	global_load_dwordx4 v[80:83], v[4:5], off nt
	global_load_dwordx4 v[64:67], v[4:5], off offset:3072 nt
	v_add_co_u32_e32 v4, vcc, s70, v74
	s_mov_b32 s24, 0xc000
	s_nop 0
	v_addc_co_u32_e32 v5, vcc, 0, v75, vcc
	global_load_dwordx4 v[84:87], v[4:5], off offset:2048 nt
	v_add_co_u32_e32 v4, vcc, s82, v74
	v_or_b32_e32 v2, 16, v78
	s_nop 0
	v_addc_co_u32_e32 v5, vcc, 0, v75, vcc
	global_load_dwordx4 v[88:91], v[4:5], off offset:1024 nt
	v_add_co_u32_e32 v14, vcc, s24, v74
	s_mov_b32 s24, 0xd000
	s_nop 0
	v_addc_co_u32_e32 v15, vcc, 0, v75, vcc
	v_add_co_u32_e32 v16, vcc, s24, v74
	s_mov_b32 s24, 0xe000
	s_nop 0
	v_addc_co_u32_e32 v17, vcc, 0, v75, vcc
	v_add_co_u32_e32 v18, vcc, s24, v74
	s_mov_b32 s24, 0xf000
	s_nop 0
	v_addc_co_u32_e32 v19, vcc, 0, v75, vcc
	v_add_co_u32_e32 v28, vcc, s24, v74
	s_mov_b32 s24, 0x10000
	s_nop 0
	v_addc_co_u32_e32 v29, vcc, 0, v75, vcc
	v_add_co_u32_e32 v30, vcc, s24, v74
	v_lshlrev_b32_e32 v8, 2, v2
	s_mov_b64 s[26:27], 0x5000000
	v_addc_co_u32_e32 v31, vcc, 0, v75, vcc
	global_load_dwordx4 v[4:7], v8, s[16:17] offset:16
	s_nop 0
	global_load_dwordx4 v[8:11], v8, s[16:17]
	v_lshl_add_u64 v[72:73], v[96:97], 0, s[26:27]
	v_mad_u64_u32 v[12:13], s[26:27], v2, s68, v[76:77]
	v_add_co_u32_e32 v92, vcc, s83, v74
	s_mov_b32 s24, 0x5001000
	s_nop 0
	v_addc_co_u32_e32 v93, vcc, 0, v75, vcc
	global_load_dwordx4 v[20:23], v[12:13], off nt
	global_load_dwordx4 v[32:35], v[14:15], off offset:3072 nt
	global_load_dwordx4 v[40:43], v[16:17], off offset:2048 nt
	global_load_dwordx4 v[36:39], v[18:19], off offset:1024 nt
	global_load_dwordx4 v[24:27], v[28:29], off nt
	s_nop 0
	global_load_dwordx4 v[12:15], v[28:29], off offset:3072 nt
	s_nop 0
	global_load_dwordx4 v[28:31], v[30:31], off offset:2048 nt
	s_nop 0
	global_load_dwordx4 v[16:19], v[92:93], off offset:1024 nt
	s_waitcnt vmcnt(19)
	v_mov_b32_e32 v92, v48
	s_waitcnt vmcnt(18)
	v_mov_b32_e32 v94, v44
	s_waitcnt vmcnt(17)
	v_mov_b32_e32 v93, v56
	s_waitcnt vmcnt(16)
	v_mov_b32_e32 v95, v52
	s_waitcnt vmcnt(15)
	v_mov_b32_e32 v101, v62
	v_mov_b32_e32 v62, v61
	s_waitcnt vmcnt(14)
	v_mov_b32_e32 v98, v68
	v_mov_b32_e32 v99, v70
	s_waitcnt vmcnt(12)
	v_mov_b32_e32 v102, v64
	v_mov_b32_e32 v70, v69
	v_mov_b32_e32 v100, v60
	v_pk_mul_f32 v[92:93], v[92:93], v[98:99]
	v_pk_mul_f32 v[68:69], v[94:95], v[70:71]
	v_mov_b32_e32 v94, v80
	s_waitcnt vmcnt(11)
	v_mov_b32_e32 v95, v84
	v_pk_mul_f32 v[94:95], v[94:95], v[100:101]
	v_bfe_u32 v56, v94, 16, 1
	s_waitcnt vmcnt(10)
	v_mov_b32_e32 v103, v88
	v_pk_mul_f32 v[60:61], v[102:103], v[62:63]
	v_add3_u32 v56, v94, v56, s76
	v_bfe_u32 v44, v60, 16, 1
	v_add3_u32 v44, v60, v44, s76
	v_lshrrev_b32_e32 v56, 16, v56
	v_cvt_pk_bf16_f32 v92, v92, v68
	v_mov_b32_e32 v52, v45
	v_and_or_b32 v94, v44, s77, v56
	v_mov_b32_e32 v56, v49
	v_pk_mul_f32 v[44:45], v[52:53], v[70:71]
	v_mov_b32_e32 v88, v65
	v_cvt_pk_bf16_f32 v93, v93, v69
	v_pk_mul_f32 v[48:49], v[56:57], v[98:99]
	v_mov_b32_e32 v84, v81
	v_pk_mul_f32 v[56:57], v[88:89], v[62:63]
	v_cvt_pk_bf16_f32 v95, v95, v61
	v_pk_mul_f32 v[52:53], v[84:85], v[100:101]
	v_bfe_u32 v2, v57, 16, 1
	v_add_co_u32_e32 v60, vcc, s24, v96
	v_add3_u32 v2, v57, v2, s76
	v_bfe_u32 v64, v53, 16, 1
	v_addc_co_u32_e32 v61, vcc, 0, v97, vcc
	v_add3_u32 v53, v53, v64, s76
	global_store_dwordx4 v[60:61], v[92:95], off offset:-4096
	v_lshrrev_b32_e32 v53, 16, v53
	s_nop 1
	v_cvt_pk_bf16_f32 v93, v49, v45
	v_cvt_pk_bf16_f32 v92, v48, v44
	v_mov_b32_e32 v48, v46
	v_mov_b32_e32 v49, v54
	v_and_or_b32 v95, v2, s77, v53
	v_cvt_pk_bf16_f32 v94, v52, v56
	v_pk_mul_f32 v[48:49], v[48:49], v[70:71]
	v_mov_b32_e32 v52, v82
	v_mov_b32_e32 v53, v86
	v_mov_b32_e32 v56, v66
	v_mov_b32_e32 v57, v90
	v_mov_b32_e32 v44, v50
	v_mov_b32_e32 v45, v58
	v_pk_mul_f32 v[52:53], v[52:53], v[100:101]
	v_pk_mul_f32 v[56:57], v[56:57], v[62:63]
	v_bfe_u32 v50, v49, 16, 1
	v_pk_mul_f32 v[44:45], v[44:45], v[98:99]
	v_bfe_u32 v2, v57, 16, 1
	v_bfe_u32 v46, v56, 16, 1
	v_add3_u32 v49, v49, v50, s76
	v_bfe_u32 v50, v52, 16, 1
	v_add3_u32 v46, v56, v46, s76
	v_add3_u32 v2, v57, v2, s76
	v_bfe_u32 v54, v53, 16, 1
	v_bfe_u32 v57, v45, 16, 1
	v_add3_u32 v50, v52, v50, s76
	v_add3_u32 v53, v53, v54, s76
	v_add3_u32 v45, v45, v57, s76
	v_lshrrev_b32_e32 v50, 16, v50
	v_mov_b32_e32 v54, v47
	v_mov_b32_e32 v90, v67
	global_store_dwordx4 v[72:73], v[92:95], off offset:2048
	v_lshrrev_b32_e32 v52, 16, v53
	v_lshrrev_b32_e32 v45, 16, v45
	v_and_or_b32 v94, v46, s77, v50
	v_mov_b32_e32 v58, v51
	v_pk_mul_f32 v[46:47], v[54:55], v[70:71]
	v_mov_b32_e32 v86, v83
	v_pk_mul_f32 v[50:51], v[90:91], v[62:63]
	v_and_or_b32 v95, v2, s77, v52
	v_and_or_b32 v93, v49, s77, v45
	v_cvt_pk_bf16_f32 v92, v44, v48
	v_pk_mul_f32 v[44:45], v[58:59], v[98:99]
	v_pk_mul_f32 v[48:49], v[86:87], v[100:101]
	v_bfe_u32 v2, v51, 16, 1
	v_bfe_u32 v52, v50, 16, 1
	v_bfe_u32 v53, v47, 16, 1
	v_bfe_u32 v54, v46, 16, 1
	v_add3_u32 v50, v50, v52, s76
	v_add3_u32 v2, v51, v2, s76
	v_add3_u32 v51, v46, v54, s76
	v_add3_u32 v52, v47, v53, s76
	v_bfe_u32 v46, v48, 16, 1
	v_bfe_u32 v47, v49, 16, 1
	v_bfe_u32 v53, v44, 16, 1
	v_bfe_u32 v54, v45, 16, 1
	v_add3_u32 v47, v49, v47, s76
	v_add3_u32 v46, v48, v46, s76
	v_add3_u32 v45, v45, v54, s76
	v_add3_u32 v44, v44, v53, s76
	v_lshrrev_b32_e32 v46, 16, v46
	v_lshrrev_b32_e32 v47, 16, v47
	v_lshrrev_b32_e32 v44, 16, v44
	v_lshrrev_b32_e32 v45, 16, v45
	v_and_or_b32 v47, v2, s77, v47
	v_and_or_b32 v46, v50, s77, v46
	v_and_or_b32 v45, v52, s77, v45
	v_and_or_b32 v44, v51, s77, v44
	global_store_dwordx4 v[60:61], v[44:47], off offset:2048
	s_waitcnt vmcnt(11)
	v_mov_b32_e32 v49, v10
	v_mov_b32_e32 v10, v9
	s_waitcnt vmcnt(9)
	v_mov_b32_e32 v46, v32
	s_waitcnt vmcnt(7)
	v_mov_b32_e32 v47, v36
	v_mov_b32_e32 v44, v20
	v_mov_b32_e32 v45, v40
	v_mov_b32_e32 v48, v8
	v_pk_mul_f32 v[8:9], v[46:47], v[10:11]
	v_mov_b32_e32 v51, v6
	s_waitcnt vmcnt(5)
	v_mov_b32_e32 v52, v12
	s_waitcnt vmcnt(3)
	v_mov_b32_e32 v53, v16
	v_mov_b32_e32 v6, v5
	v_pk_mul_f32 v[44:45], v[44:45], v[48:49]
	v_mov_b32_e32 v46, v24
	v_mov_b32_e32 v47, v28
	v_mov_b32_e32 v50, v4
	v_pk_mul_f32 v[4:5], v[52:53], v[6:7]
	v_bfe_u32 v16, v9, 16, 1
	v_pk_mul_f32 v[46:47], v[46:47], v[50:51]
	v_bfe_u32 v2, v5, 16, 1
	v_add3_u32 v9, v9, v16, s76
	v_bfe_u32 v20, v45, 16, 1
	v_add3_u32 v2, v5, v2, s76
	v_bfe_u32 v12, v47, 16, 1
	v_add3_u32 v20, v45, v20, s76
	v_add3_u32 v12, v47, v12, s76
	v_lshrrev_b32_e32 v20, 16, v20
	v_mov_b32_e32 v36, v33
	v_lshrrev_b32_e32 v12, 16, v12
	v_and_or_b32 v45, v9, s77, v20
	v_cvt_pk_bf16_f32 v44, v44, v8
	v_mov_b32_e32 v40, v21
	v_pk_mul_f32 v[8:9], v[36:37], v[10:11]
	v_mov_b32_e32 v16, v13
	v_and_or_b32 v47, v2, s77, v12
	v_cvt_pk_bf16_f32 v46, v46, v4
	v_pk_mul_f32 v[4:5], v[40:41], v[48:49]
	v_mov_b32_e32 v28, v25
	v_pk_mul_f32 v[12:13], v[16:17], v[6:7]
	v_pk_mul_f32 v[20:21], v[28:29], v[50:51]
	v_bfe_u32 v16, v12, 16, 1
	v_bfe_u32 v2, v13, 16, 1
	v_add3_u32 v12, v12, v16, s76
	v_bfe_u32 v16, v21, 16, 1
	v_add3_u32 v2, v13, v2, s76
	v_bfe_u32 v13, v20, 16, 1
	v_add3_u32 v16, v21, v16, s76
	global_store_dwordx4 v[72:73], v[44:47], off offset:32
	v_add3_u32 v13, v20, v13, s76
	v_lshrrev_b32_e32 v16, 16, v16
	v_cvt_pk_bf16_f32 v45, v5, v9
	v_cvt_pk_bf16_f32 v44, v4, v8
	v_mov_b32_e32 v8, v34
	v_mov_b32_e32 v9, v38
	v_lshrrev_b32_e32 v13, 16, v13
	v_and_or_b32 v47, v2, s77, v16
	v_mov_b32_e32 v4, v22
	v_mov_b32_e32 v5, v42
	v_pk_mul_f32 v[8:9], v[8:9], v[10:11]
	v_mov_b32_e32 v16, v14
	v_mov_b32_e32 v17, v18
	v_and_or_b32 v46, v12, s77, v13
	v_pk_mul_f32 v[4:5], v[4:5], v[48:49]
	v_mov_b32_e32 v12, v26
	v_mov_b32_e32 v13, v30
	v_pk_mul_f32 v[16:17], v[16:17], v[6:7]
	v_bfe_u32 v18, v9, 16, 1
	v_bfe_u32 v20, v8, 16, 1
	v_pk_mul_f32 v[12:13], v[12:13], v[50:51]
	v_add3_u32 v8, v8, v20, s76
	v_add3_u32 v9, v9, v18, s76
	v_bfe_u32 v18, v4, 16, 1
	v_bfe_u32 v20, v5, 16, 1
	v_add3_u32 v5, v5, v20, s76
	v_add3_u32 v4, v4, v18, s76
	v_lshrrev_b32_e32 v4, 16, v4
	v_lshrrev_b32_e32 v5, 16, v5
	v_mov_b32_e32 v38, v35
	v_mov_b32_e32 v18, v15
	global_store_dwordx4 v[72:73], v[44:47], off offset:2080
	s_nop 1
	v_and_or_b32 v45, v9, s77, v5
	s_nop 1
	v_and_or_b32 v44, v8, s77, v4
	v_mov_b32_e32 v42, v23
	v_pk_mul_f32 v[8:9], v[38:39], v[10:11]
	v_mov_b32_e32 v30, v27
	v_pk_mul_f32 v[6:7], v[18:19], v[6:7]
	v_cvt_pk_bf16_f32 v47, v13, v17
	v_cvt_pk_bf16_f32 v46, v12, v16
	v_pk_mul_f32 v[4:5], v[42:43], v[48:49]
	v_pk_mul_f32 v[10:11], v[30:31], v[50:51]
	v_bfe_u32 v2, v7, 16, 1
	v_bfe_u32 v12, v6, 16, 1
	v_add3_u32 v6, v6, v12, s76
	v_add3_u32 v2, v7, v2, s76
	v_bfe_u32 v7, v10, 16, 1
	v_bfe_u32 v12, v11, 16, 1
	v_add3_u32 v11, v11, v12, s76
	v_add3_u32 v7, v10, v7, s76
	v_lshrrev_b32_e32 v10, 16, v7
	v_lshrrev_b32_e32 v7, 16, v11
	v_and_or_b32 v7, v2, s77, v7
	v_and_or_b32 v6, v6, s77, v10
	v_cvt_pk_bf16_f32 v5, v5, v9
	v_cvt_pk_bf16_f32 v4, v4, v8
	s_mov_b32 s24, 0x18000
	global_store_dwordx4 v[60:61], v[4:7], off offset:2080
	v_or_b32_e32 v2, 32, v78
	global_store_dwordx4 v[60:61], v[92:95], off
	v_add_co_u32_e32 v6, vcc, s24, v74
	global_store_dwordx4 v[60:61], v[44:47], off offset:32
	v_mad_u64_u32 v[4:5], s[26:27], v2, s68, v[76:77]
	v_addc_co_u32_e32 v7, vcc, 0, v75, vcc
	s_mov_b32 s24, 0x19000
	global_load_dwordx4 v[44:47], v[4:5], off nt
	global_load_dwordx4 v[48:51], v[6:7], off offset:3072 nt
	v_add_co_u32_e32 v4, vcc, s24, v74
	s_mov_b32 s24, 0x1a000
	s_nop 0
	v_addc_co_u32_e32 v5, vcc, 0, v75, vcc
	v_add_co_u32_e32 v6, vcc, s24, v74
	s_mov_b32 s24, 0x1b000
	s_nop 0
	v_addc_co_u32_e32 v7, vcc, 0, v75, vcc
	global_load_dwordx4 v[52:55], v[4:5], off offset:2048 nt
	global_load_dwordx4 v[56:59], v[6:7], off offset:1024 nt
	v_add_co_u32_e32 v4, vcc, s24, v74
	v_lshlrev_b32_e32 v2, 2, v2
	s_nop 0
	v_addc_co_u32_e32 v5, vcc, 0, v75, vcc
	s_mov_b32 s24, 0x1c000
	global_load_dwordx4 v[62:65], v2, s[16:17] offset:16
	global_load_dwordx4 v[66:69], v2, s[16:17]
	global_load_dwordx4 v[80:83], v[4:5], off nt
	global_load_dwordx4 v[84:87], v[4:5], off offset:3072 nt
	v_add_co_u32_e32 v4, vcc, s24, v74
	s_mov_b32 s24, 0x1d000
	s_nop 0
	v_addc_co_u32_e32 v5, vcc, 0, v75, vcc
	global_load_dwordx4 v[88:91], v[4:5], off offset:2048 nt
	v_add_co_u32_e32 v4, vcc, s24, v74
	s_mov_b32 s24, 0x24000
	s_nop 0
	v_addc_co_u32_e32 v5, vcc, 0, v75, vcc
	global_load_dwordx4 v[92:95], v[4:5], off offset:1024 nt
	v_add_co_u32_e32 v6, vcc, s24, v74
	s_mov_b32 s24, 0x26000
	s_nop 0
	v_addc_co_u32_e32 v7, vcc, 0, v75, vcc
	v_add_co_u32_e32 v12, vcc, s84, v74
	v_or_b32_e32 v2, 48, v78
	s_nop 0
	v_addc_co_u32_e32 v13, vcc, 0, v75, vcc
	v_add_co_u32_e32 v14, vcc, s24, v74
	s_mov_b32 s24, 0x28000
	s_nop 0
	v_addc_co_u32_e32 v15, vcc, 0, v75, vcc
	v_add_co_u32_e32 v16, vcc, s85, v74
	v_mad_u64_u32 v[4:5], s[26:27], v2, s68, v[76:77]
	s_nop 0
	v_addc_co_u32_e32 v17, vcc, 0, v75, vcc
	v_add_co_u32_e32 v28, vcc, s24, v74
	s_mov_b32 s24, 0x29000
	s_nop 0
	v_addc_co_u32_e32 v29, vcc, 0, v75, vcc
	v_add_co_u32_e32 v30, vcc, s24, v74
	v_lshlrev_b32_e32 v2, 2, v2
	s_nop 0
	v_addc_co_u32_e32 v31, vcc, 0, v75, vcc
	global_load_dwordx4 v[8:11], v[4:5], off nt
	s_nop 0
	global_load_dwordx4 v[4:7], v[6:7], off offset:3072 nt
	s_nop 0
	global_load_dwordx4 v[20:23], v[12:13], off offset:2048 nt
	s_nop 0
	global_load_dwordx4 v[12:15], v[14:15], off offset:1024 nt
	s_nop 0
	global_load_dwordx4 v[24:27], v[16:17], off nt
	s_nop 0
	global_load_dwordx4 v[16:19], v[16:17], off offset:3072 nt
	s_nop 0
	global_load_dwordx4 v[32:35], v[28:29], off offset:2048 nt
	s_nop 0
	global_load_dwordx4 v[28:31], v[30:31], off offset:1024 nt
	s_nop 0
	global_load_dwordx4 v[36:39], v2, s[16:17] offset:16
	global_load_dwordx4 v[40:43], v2, s[16:17]
	s_waitcnt vmcnt(19)
	v_mov_b32_e32 v70, v44
	s_waitcnt vmcnt(18)
	v_mov_b32_e32 v74, v48
	s_waitcnt vmcnt(17)
	v_mov_b32_e32 v71, v52
	s_waitcnt vmcnt(16)
	v_mov_b32_e32 v75, v56
	s_waitcnt vmcnt(15)
	v_mov_b32_e32 v96, v62
	s_waitcnt vmcnt(14)
	v_mov_b32_e32 v79, v68
	v_mov_b32_e32 v68, v67
	v_mov_b32_e32 v78, v66
	v_pk_mul_f32 v[66:67], v[74:75], v[68:69]
	s_waitcnt vmcnt(13)
	v_mov_b32_e32 v74, v80
	v_mov_b32_e32 v97, v64
	s_waitcnt vmcnt(12)
	v_mov_b32_e32 v76, v84
	s_waitcnt vmcnt(11)
	v_mov_b32_e32 v75, v88
	v_mov_b32_e32 v64, v63
	v_pk_mul_f32 v[74:75], v[74:75], v[96:97]
	v_pk_mul_f32 v[70:71], v[70:71], v[78:79]
	v_bfe_u32 v56, v74, 16, 1
	s_waitcnt vmcnt(10)
	v_mov_b32_e32 v77, v92
	v_pk_mul_f32 v[62:63], v[76:77], v[64:65]
	v_bfe_u32 v2, v63, 16, 1
	v_bfe_u32 v44, v62, 16, 1
	v_add3_u32 v2, v63, v2, s76
	v_add3_u32 v56, v74, v56, s76
	v_add3_u32 v44, v62, v44, s76
	v_lshrrev_b32_e32 v56, 16, v56
	v_bfe_u32 v62, v75, 16, 1
	v_and_or_b32 v76, v44, s77, v56
	v_mov_b32_e32 v56, v49
	v_add3_u32 v62, v75, v62, s76
	v_cvt_pk_bf16_f32 v75, v71, v67
	v_cvt_pk_bf16_f32 v74, v70, v66
	v_mov_b32_e32 v52, v45
	v_pk_mul_f32 v[48:49], v[56:57], v[68:69]
	v_mov_b32_e32 v92, v85
	v_lshrrev_b32_e32 v62, 16, v62
	v_pk_mul_f32 v[44:45], v[52:53], v[78:79]
	v_mov_b32_e32 v88, v81
	v_pk_mul_f32 v[56:57], v[92:93], v[64:65]
	v_and_or_b32 v77, v2, s77, v62
	v_pk_mul_f32 v[52:53], v[88:89], v[96:97]
	v_bfe_u32 v2, v57, 16, 1
	v_add3_u32 v2, v57, v2, s76
	v_bfe_u32 v62, v53, 16, 1
	v_add3_u32 v53, v53, v62, s76
	global_store_dwordx4 v[72:73], v[74:77], off offset:64
	v_lshrrev_b32_e32 v53, 16, v53
	s_nop 1
	v_cvt_pk_bf16_f32 v75, v45, v49
	v_cvt_pk_bf16_f32 v74, v44, v48
	v_mov_b32_e32 v48, v50
	v_mov_b32_e32 v49, v58
	v_and_or_b32 v77, v2, s77, v53
	v_cvt_pk_bf16_f32 v76, v52, v56
	v_pk_mul_f32 v[48:49], v[48:49], v[68:69]
	v_mov_b32_e32 v52, v82
	v_mov_b32_e32 v53, v90
	v_mov_b32_e32 v56, v86
	v_mov_b32_e32 v57, v94
	v_mov_b32_e32 v44, v46
	v_mov_b32_e32 v45, v54
	v_pk_mul_f32 v[52:53], v[52:53], v[96:97]
	v_pk_mul_f32 v[56:57], v[56:57], v[64:65]
	v_bfe_u32 v50, v49, 16, 1
	v_pk_mul_f32 v[44:45], v[44:45], v[78:79]
	v_bfe_u32 v2, v57, 16, 1
	v_bfe_u32 v46, v56, 16, 1
	v_bfe_u32 v54, v48, 16, 1
	v_add3_u32 v49, v49, v50, s76
	v_bfe_u32 v50, v52, 16, 1
	v_add3_u32 v48, v48, v54, s76
	v_add3_u32 v46, v56, v46, s76
	v_add3_u32 v2, v57, v2, s76
	v_bfe_u32 v54, v53, 16, 1
	v_bfe_u32 v56, v44, 16, 1
	v_bfe_u32 v57, v45, 16, 1
	v_add3_u32 v50, v52, v50, s76
	v_add3_u32 v53, v53, v54, s76
	v_add3_u32 v45, v45, v57, s76
	v_add3_u32 v44, v44, v56, s76
	v_lshrrev_b32_e32 v50, 16, v50
	v_mov_b32_e32 v58, v51
	v_mov_b32_e32 v94, v87
	global_store_dwordx4 v[72:73], v[74:77], off offset:2112
	v_lshrrev_b32_e32 v52, 16, v53
	v_lshrrev_b32_e32 v44, 16, v44
	v_lshrrev_b32_e32 v45, 16, v45
	v_and_or_b32 v76, v46, s77, v50
	v_mov_b32_e32 v54, v47
	v_pk_mul_f32 v[46:47], v[58:59], v[68:69]
	v_mov_b32_e32 v90, v83
	v_pk_mul_f32 v[50:51], v[94:95], v[64:65]
	v_and_or_b32 v77, v2, s77, v52
	v_and_or_b32 v75, v49, s77, v45
	v_and_or_b32 v74, v48, s77, v44
	v_pk_mul_f32 v[44:45], v[54:55], v[78:79]
	v_pk_mul_f32 v[48:49], v[90:91], v[96:97]
	v_bfe_u32 v2, v51, 16, 1
	v_bfe_u32 v52, v50, 16, 1
	v_bfe_u32 v53, v47, 16, 1
	v_bfe_u32 v54, v46, 16, 1
	v_add3_u32 v54, v46, v54, s76
	v_add3_u32 v53, v47, v53, s76
	v_add3_u32 v46, v50, v52, s76
	v_add3_u32 v2, v51, v2, s76
	v_bfe_u32 v47, v48, 16, 1
	v_bfe_u32 v50, v49, 16, 1
	v_bfe_u32 v51, v44, 16, 1
	v_bfe_u32 v52, v45, 16, 1
	v_add3_u32 v49, v49, v50, s76
	v_add3_u32 v47, v48, v47, s76
	v_add3_u32 v45, v45, v52, s76
	v_add3_u32 v44, v44, v51, s76
	v_lshrrev_b32_e32 v48, 16, v47
	v_lshrrev_b32_e32 v47, 16, v49
	v_lshrrev_b32_e32 v44, 16, v44
	v_lshrrev_b32_e32 v45, 16, v45
	v_and_or_b32 v47, v2, s77, v47
	v_and_or_b32 v46, v46, s77, v48
	v_and_or_b32 v45, v53, s77, v45
	v_and_or_b32 v44, v54, s77, v44
	global_store_dwordx4 v[60:61], v[44:47], off offset:2112
	s_waitcnt vmcnt(3)
	v_mov_b32_e32 v48, v40
	v_mov_b32_e32 v49, v42
	v_mov_b32_e32 v44, v8
	v_mov_b32_e32 v45, v20
	v_mov_b32_e32 v46, v4
	v_mov_b32_e32 v47, v12
	v_mov_b32_e32 v42, v41
	v_pk_mul_f32 v[44:45], v[44:45], v[48:49]
	v_pk_mul_f32 v[40:41], v[46:47], v[42:43]
	v_mov_b32_e32 v46, v24
	v_mov_b32_e32 v47, v32
	v_mov_b32_e32 v50, v36
	v_mov_b32_e32 v51, v38
	v_pk_mul_f32 v[46:47], v[46:47], v[50:51]
	v_mov_b32_e32 v52, v16
	v_mov_b32_e32 v53, v28
	v_mov_b32_e32 v38, v37
	v_pk_mul_f32 v[36:37], v[52:53], v[38:39]
	v_cvt_pk_bf16_f32 v44, v44, v40
	v_mov_b32_e32 v12, v5
	v_cvt_pk_bf16_f32 v47, v47, v37
	v_cvt_pk_bf16_f32 v46, v46, v36
	v_cvt_pk_bf16_f32 v45, v45, v41
	v_mov_b32_e32 v20, v9
	v_pk_mul_f32 v[4:5], v[12:13], v[42:43]
	v_mov_b32_e32 v28, v17
	v_pk_mul_f32 v[8:9], v[20:21], v[48:49]
	v_mov_b32_e32 v32, v25
	v_pk_mul_f32 v[16:17], v[28:29], v[38:39]
	v_pk_mul_f32 v[12:13], v[32:33], v[50:51]
	v_bfe_u32 v2, v17, 16, 1
	v_add3_u32 v2, v17, v2, s76
	v_bfe_u32 v20, v13, 16, 1
	v_add3_u32 v13, v13, v20, s76
	global_store_dwordx4 v[72:73], v[44:47], off offset:96
	v_lshrrev_b32_e32 v13, 16, v13
	s_nop 1
	v_cvt_pk_bf16_f32 v45, v9, v5
	v_cvt_pk_bf16_f32 v44, v8, v4
	v_mov_b32_e32 v8, v6
	v_mov_b32_e32 v9, v14
	v_and_or_b32 v47, v2, s77, v13
	v_cvt_pk_bf16_f32 v46, v12, v16
	v_pk_mul_f32 v[8:9], v[8:9], v[42:43]
	v_mov_b32_e32 v12, v26
	v_mov_b32_e32 v13, v34
	v_mov_b32_e32 v16, v18
	v_mov_b32_e32 v17, v30
	v_mov_b32_e32 v4, v10
	v_mov_b32_e32 v5, v22
	v_pk_mul_f32 v[12:13], v[12:13], v[50:51]
	v_pk_mul_f32 v[16:17], v[16:17], v[38:39]
	v_bfe_u32 v10, v9, 16, 1
	v_pk_mul_f32 v[4:5], v[4:5], v[48:49]
	v_bfe_u32 v2, v17, 16, 1
	v_bfe_u32 v6, v16, 16, 1
	v_add3_u32 v9, v9, v10, s76
	v_bfe_u32 v10, v12, 16, 1
	v_add3_u32 v6, v16, v6, s76
	v_add3_u32 v2, v17, v2, s76
	v_bfe_u32 v14, v13, 16, 1
	v_bfe_u32 v17, v5, 16, 1
	v_add3_u32 v10, v12, v10, s76
	v_add3_u32 v13, v13, v14, s76
	v_add3_u32 v5, v5, v17, s76
	v_lshrrev_b32_e32 v10, 16, v10
	v_mov_b32_e32 v14, v7
	v_mov_b32_e32 v30, v19
	global_store_dwordx4 v[72:73], v[44:47], off offset:2144
	v_lshrrev_b32_e32 v12, 16, v13
	v_lshrrev_b32_e32 v5, 16, v5
	v_and_or_b32 v46, v6, s77, v10
	v_mov_b32_e32 v22, v11
	v_pk_mul_f32 v[6:7], v[14:15], v[42:43]
	v_mov_b32_e32 v34, v27
	v_pk_mul_f32 v[10:11], v[30:31], v[38:39]
	v_and_or_b32 v47, v2, s77, v12
	v_and_or_b32 v45, v9, s77, v5
	v_cvt_pk_bf16_f32 v44, v4, v8
	v_pk_mul_f32 v[4:5], v[22:23], v[48:49]
	v_pk_mul_f32 v[8:9], v[34:35], v[50:51]
	v_bfe_u32 v2, v11, 16, 1
	v_bfe_u32 v12, v10, 16, 1
	v_bfe_u32 v13, v7, 16, 1
	v_bfe_u32 v14, v6, 16, 1
	v_add3_u32 v14, v6, v14, s76
	v_add3_u32 v13, v7, v13, s76
	v_add3_u32 v6, v10, v12, s76
	v_add3_u32 v2, v11, v2, s76
	v_bfe_u32 v7, v8, 16, 1
	v_bfe_u32 v10, v9, 16, 1
	v_bfe_u32 v11, v4, 16, 1
	v_bfe_u32 v12, v5, 16, 1
	v_add3_u32 v9, v9, v10, s76
	v_add3_u32 v7, v8, v7, s76
	v_add3_u32 v5, v5, v12, s76
	v_add3_u32 v4, v4, v11, s76
	v_lshrrev_b32_e32 v8, 16, v7
	v_lshrrev_b32_e32 v7, 16, v9
	v_lshrrev_b32_e32 v4, 16, v4
	v_lshrrev_b32_e32 v5, 16, v5
	v_and_or_b32 v7, v2, s77, v7
	v_and_or_b32 v6, v6, s77, v8
	v_and_or_b32 v5, v13, s77, v5
	v_and_or_b32 v4, v14, s77, v4
	global_store_dwordx4 v[60:61], v[74:77], off offset:64
	global_store_dwordx4 v[60:61], v[44:47], off offset:96
	global_store_dwordx4 v[60:61], v[4:7], off offset:2144

.LBB0_495:
	v_lshlrev_b32_e32 v2, 9, v84
	s_waitcnt vmcnt(15)
	v_mov_b32_e32 v82, v44
	s_waitcnt vmcnt(13)
	v_mov_b32_e32 v83, v52
	s_waitcnt vmcnt(11)
	v_mov_b32_e32 v98, v60
	s_waitcnt vmcnt(9)
	v_mov_b32_e32 v99, v68
	s_waitcnt lgkmcnt(0)
	v_lshl_add_u64 v[42:43], s[62:63], 0, v[2:3]
	s_lshl_b32 s24, s24, 1
	v_pk_mul_f32 v[82:83], v[82:83], v[76:77]
	v_mov_b32_e32 v96, v48
	v_mov_b32_e32 v97, v56
	v_pk_mul_f32 v[98:99], v[98:99], v[80:81]
	v_mov_b32_e32 v100, v64
	s_waitcnt vmcnt(8)
	v_mov_b32_e32 v101, v72
	v_lshl_add_u64 v[42:43], v[42:43], 0, s[24:25]
	v_lshlrev_b32_e32 v2, 1, v116
	v_pk_mul_f32 v[96:97], v[96:97], v[92:93]
	v_pk_mul_f32 v[100:101], v[100:101], v[90:91]
	v_lshl_add_u64 v[42:43], v[42:43], 0, v[2:3]
	s_mov_b64 s[60:61], 0x4f00000
	s_mov_b32 s24, 0x4f00000
	v_lshl_add_u64 v[84:85], v[42:43], 0, s[60:61]
	v_add_co_u32_e32 v42, vcc, s24, v42
	v_cvt_pk_bf16_f32 v99, v99, v101
	v_cvt_pk_bf16_f32 v98, v98, v100
	v_cvt_pk_bf16_f32 v97, v83, v97
	v_cvt_pk_bf16_f32 v96, v82, v96
	v_addc_co_u32_e32 v43, vcc, 0, v43, vcc
	v_mov_b32_e32 v52, v45
	v_mov_b32_e32 v56, v49
	v_mov_b32_e32 v72, v65
	global_store_dwordx4 v[42:43], v[96:99], off
	v_pk_mul_f32 v[42:43], v[52:53], v[76:77]
	v_pk_mul_f32 v[44:45], v[56:57], v[92:93]
	v_mov_b32_e32 v68, v61
	v_pk_mul_f32 v[52:53], v[72:73], v[90:91]
	v_pk_mul_f32 v[48:49], v[68:69], v[80:81]
	v_bfe_u32 v2, v53, 16, 1
	v_bfe_u32 v56, v52, 16, 1
	v_bfe_u32 v57, v45, 16, 1
	v_bfe_u32 v60, v44, 16, 1
	v_add3_u32 v60, v44, v60, s76
	v_add3_u32 v57, v45, v57, s76
	v_add3_u32 v44, v52, v56, s76
	v_add3_u32 v2, v53, v2, s76
	v_bfe_u32 v45, v42, 16, 1
	v_bfe_u32 v52, v43, 16, 1
	v_bfe_u32 v53, v48, 16, 1
	v_bfe_u32 v56, v49, 16, 1
	v_add3_u32 v49, v49, v56, s76
	v_add3_u32 v48, v48, v53, s76
	v_add3_u32 v43, v43, v52, s76
	v_add3_u32 v42, v42, v45, s76
	v_lshrrev_b32_e32 v42, 16, v42
	v_lshrrev_b32_e32 v43, 16, v43
	v_lshrrev_b32_e32 v48, 16, v48
	v_lshrrev_b32_e32 v45, 16, v49
	v_and_or_b32 v45, v2, s77, v45
	v_and_or_b32 v44, v44, s77, v48
	v_and_or_b32 v43, v57, s77, v43
	v_and_or_b32 v42, v60, s77, v42
	global_store_dwordx4 v[84:85], v[42:45], off offset:512
	v_mov_b32_e32 v52, v66
	v_mov_b32_e32 v53, v74
	v_mov_b32_e32 v44, v50
	v_mov_b32_e32 v45, v58
	v_mov_b32_e32 v42, v46
	v_mov_b32_e32 v43, v54
	v_pk_mul_f32 v[44:45], v[44:45], v[92:93]
	v_mov_b32_e32 v48, v62
	v_mov_b32_e32 v49, v70
	v_pk_mul_f32 v[52:53], v[52:53], v[90:91]
	v_pk_mul_f32 v[42:43], v[42:43], v[76:77]
	v_pk_mul_f32 v[48:49], v[48:49], v[80:81]
	v_bfe_u32 v50, v45, 16, 1
	v_bfe_u32 v54, v44, 16, 1
	v_add3_u32 v54, v44, v54, s76
	v_add3_u32 v50, v45, v50, s76
	v_bfe_u32 v45, v42, 16, 1
	v_bfe_u32 v46, v43, 16, 1
	v_add3_u32 v43, v43, v46, s76
	v_add3_u32 v42, v42, v45, s76
	v_lshrrev_b32_e32 v42, 16, v42
	v_lshrrev_b32_e32 v43, 16, v43
	v_cvt_pk_bf16_f32 v45, v49, v53
	v_cvt_pk_bf16_f32 v44, v48, v52
	v_and_or_b32 v43, v50, s77, v43
	v_and_or_b32 v42, v54, s77, v42
	v_mov_b32_e32 v58, v51
	v_mov_b32_e32 v74, v67
	global_store_dwordx4 v[84:85], v[42:45], off offset:1024
	v_mov_b32_e32 v54, v47
	v_mov_b32_e32 v70, v63
	v_pk_mul_f32 v[44:45], v[58:59], v[92:93]
	v_pk_mul_f32 v[48:49], v[74:75], v[90:91]
	v_pk_mul_f32 v[42:43], v[54:55], v[76:77]
	v_pk_mul_f32 v[46:47], v[70:71], v[80:81]
	v_bfe_u32 v2, v49, 16, 1
	v_bfe_u32 v50, v48, 16, 1
	v_bfe_u32 v51, v45, 16, 1
	v_bfe_u32 v52, v44, 16, 1
	v_add3_u32 v52, v44, v52, s76
	v_add3_u32 v51, v45, v51, s76
	v_add3_u32 v44, v48, v50, s76
	v_add3_u32 v2, v49, v2, s76
	v_bfe_u32 v45, v42, 16, 1
	v_bfe_u32 v48, v43, 16, 1
	v_bfe_u32 v49, v46, 16, 1
	v_bfe_u32 v50, v47, 16, 1
	v_add3_u32 v47, v47, v50, s76
	v_add3_u32 v46, v46, v49, s76
	v_add3_u32 v43, v43, v48, s76
	v_add3_u32 v42, v42, v45, s76
	v_lshrrev_b32_e32 v42, 16, v42
	v_lshrrev_b32_e32 v43, 16, v43
	v_lshrrev_b32_e32 v46, 16, v46
	v_lshrrev_b32_e32 v45, 16, v47
	v_and_or_b32 v45, v2, s77, v45
	v_and_or_b32 v44, v44, s77, v46
	v_and_or_b32 v43, v51, s77, v43
	v_and_or_b32 v42, v52, s77, v42
	global_store_dwordx4 v[84:85], v[42:45], off offset:1536
	s_waitcnt vmcnt(7)
	v_mov_b32_e32 v46, v28
	s_waitcnt vmcnt(5)
	v_mov_b32_e32 v47, v36
	v_mov_b32_e32 v42, v12
	v_mov_b32_e32 v43, v20
	v_pk_mul_f32 v[42:43], v[42:43], v[4:5]
	v_mov_b32_e32 v44, v8
	v_mov_b32_e32 v45, v16
	v_pk_mul_f32 v[46:47], v[46:47], v[40:41]
	v_mov_b32_e32 v48, v24
	s_waitcnt vmcnt(4)
	v_mov_b32_e32 v49, v32
	v_pk_mul_f32 v[44:45], v[44:45], v[78:79]
	v_pk_mul_f32 v[48:49], v[48:49], v[6:7]
	v_bfe_u32 v24, v43, 16, 1
	v_bfe_u32 v12, v45, 16, 1
	v_add3_u32 v24, v43, v24, s76
	v_add3_u32 v12, v45, v12, s76
	v_lshrrev_b32_e32 v24, 16, v24
	v_cvt_pk_bf16_f32 v45, v47, v49
	v_cvt_pk_bf16_f32 v42, v42, v44
	v_mov_b32_e32 v20, v13
	v_mov_b32_e32 v32, v25
	v_and_or_b32 v43, v12, s77, v24
	v_pk_mul_f32 v[12:13], v[20:21], v[4:5]
	v_mov_b32_e32 v16, v9
	v_pk_mul_f32 v[20:21], v[32:33], v[6:7]
	v_cvt_pk_bf16_f32 v44, v46, v48
	v_pk_mul_f32 v[8:9], v[16:17], v[78:79]
	v_mov_b32_e32 v36, v29
	v_bfe_u32 v2, v21, 16, 1
	v_pk_mul_f32 v[16:17], v[36:37], v[40:41]
	v_add3_u32 v2, v21, v2, s76
	v_bfe_u32 v28, v17, 16, 1
	global_store_dwordx4 v[84:85], v[42:45], off offset:32
	v_add3_u32 v17, v17, v28, s76
	s_nop 1
	v_cvt_pk_bf16_f32 v43, v13, v9
	v_cvt_pk_bf16_f32 v42, v12, v8
	v_mov_b32_e32 v12, v10
	v_mov_b32_e32 v13, v18
	v_lshrrev_b32_e32 v17, 16, v17
	v_cvt_pk_bf16_f32 v44, v16, v20
	v_mov_b32_e32 v8, v14
	v_mov_b32_e32 v9, v22
	v_pk_mul_f32 v[12:13], v[12:13], v[78:79]
	v_mov_b32_e32 v20, v26
	v_mov_b32_e32 v21, v34
	v_and_or_b32 v45, v2, s77, v17
	v_pk_mul_f32 v[8:9], v[8:9], v[4:5]
	v_mov_b32_e32 v16, v30
	v_mov_b32_e32 v17, v38
	v_pk_mul_f32 v[20:21], v[20:21], v[6:7]
	v_bfe_u32 v14, v13, 16, 1
	v_bfe_u32 v18, v12, 16, 1
	v_pk_mul_f32 v[16:17], v[16:17], v[40:41]
	v_add3_u32 v12, v12, v18, s76
	v_add3_u32 v13, v13, v14, s76
	v_bfe_u32 v14, v8, 16, 1
	v_bfe_u32 v18, v9, 16, 1
	v_add3_u32 v9, v9, v18, s76
	v_add3_u32 v8, v8, v14, s76
	v_lshrrev_b32_e32 v8, 16, v8
	v_lshrrev_b32_e32 v9, 16, v9
	v_mov_b32_e32 v18, v11
	v_mov_b32_e32 v34, v27
	global_store_dwordx4 v[84:85], v[42:45], off offset:544
	s_nop 1
	v_and_or_b32 v43, v13, s77, v9
	s_nop 1
	v_and_or_b32 v42, v12, s77, v8
	v_mov_b32_e32 v22, v15
	v_pk_mul_f32 v[8:9], v[18:19], v[78:79]
	v_mov_b32_e32 v38, v31
	v_pk_mul_f32 v[6:7], v[34:35], v[6:7]
	v_cvt_pk_bf16_f32 v45, v17, v21
	v_cvt_pk_bf16_f32 v44, v16, v20
	v_pk_mul_f32 v[4:5], v[22:23], v[4:5]
	v_pk_mul_f32 v[10:11], v[38:39], v[40:41]
	v_bfe_u32 v2, v7, 16, 1
	v_bfe_u32 v14, v8, 16, 1
	v_add3_u32 v8, v8, v14, s76
	v_add3_u32 v2, v7, v2, s76
	v_bfe_u32 v7, v4, 16, 1
	v_bfe_u32 v14, v11, 16, 1
	v_add3_u32 v11, v11, v14, s76
	v_add3_u32 v4, v4, v7, s76
	v_lshrrev_b32_e32 v4, 16, v4
	v_lshrrev_b32_e32 v7, 16, v11
	v_and_or_b32 v7, v2, s77, v7
	v_cvt_pk_bf16_f32 v6, v10, v6
	v_cvt_pk_bf16_f32 v5, v5, v9
	v_and_or_b32 v4, v8, s77, v4
	s_mov_b32 s24, 0x42000
	global_store_dwordx4 v[84:85], v[4:7], off offset:1568
	v_lshl_or_b32 v2, v95, 13, v168
	global_store_dwordx4 v[84:85], v[42:45], off offset:1056
	v_add_co_u32_e32 v6, vcc, s24, v86
	v_lshl_add_u64 v[4:5], v[88:89], 0, v[2:3]
	s_nop 0
	v_addc_co_u32_e32 v7, vcc, 0, v87, vcc
	s_mov_b32 s24, 0x44000
	global_load_dwordx4 v[44:47], v[4:5], off nt
	global_load_dwordx4 v[40:43], v[6:7], off nt
	v_add_co_u32_e32 v4, vcc, s24, v86
	s_mov_b32 s24, 0x48000
	s_nop 0
	v_addc_co_u32_e32 v5, vcc, 0, v87, vcc
	v_add_co_u32_e32 v6, vcc, 0x46000, v86
	v_mov_b32_e32 v76, 1.0
	s_nop 0
	v_addc_co_u32_e32 v7, vcc, 0, v87, vcc
	global_load_dwordx4 v[56:59], v[4:5], off nt
	global_load_dwordx4 v[52:55], v[6:7], off nt
	v_add_co_u32_e32 v4, vcc, s24, v86
	v_mov_b32_e32 v92, 1.0
	s_nop 0
	v_addc_co_u32_e32 v5, vcc, 0, v87, vcc
	v_add_co_u32_e32 v6, vcc, 0x4a000, v86
	v_mov_b32_e32 v77, 1.0
	s_nop 0
	v_addc_co_u32_e32 v7, vcc, 0, v87, vcc
	global_load_dwordx4 v[64:67], v[4:5], off nt
	global_load_dwordx4 v[60:63], v[6:7], off nt
	v_add_co_u32_e32 v4, vcc, 0x4c000, v86
	v_mov_b32_e32 v93, 1.0
	s_nop 0
	v_addc_co_u32_e32 v5, vcc, 0, v87, vcc
	v_add_co_u32_e32 v6, vcc, 0x4e000, v86
	v_mov_b32_e32 v80, 1.0
	s_nop 0
	v_addc_co_u32_e32 v7, vcc, 0, v87, vcc
	global_load_dwordx4 v[72:75], v[4:5], off nt
	global_load_dwordx4 v[68:71], v[6:7], off nt
	v_mov_b32_e32 v4, 1.0
	s_and_b64 vcc, exec, s[16:17]
	v_mov_b32_e32 v90, 1.0
	v_mov_b32_e32 v81, 1.0
	v_mov_b32_e32 v91, 1.0
	s_cbranch_vccnz .LBB0_497
	global_load_dwordx4 v[76:79], v94, s[26:27] offset:128
	global_load_dwordx4 v[80:83], v94, s[26:27] offset:144
	s_waitcnt vmcnt(1)
	v_mov_b32_e32 v92, v77
	v_mov_b32_e32 v77, v78
	v_mov_b32_e32 v93, v79
	s_waitcnt vmcnt(0)
	v_mov_b32_e32 v90, v81
	v_mov_b32_e32 v81, v82
	v_mov_b32_e32 v91, v83

.LBB0_499:
	s_waitcnt vmcnt(15)
	v_mov_b32_e32 v50, v44
	s_waitcnt vmcnt(13)
	v_mov_b32_e32 v51, v56
	v_pk_mul_f32 v[50:51], v[50:51], v[76:77]
	v_mov_b32_e32 v82, v40
	s_waitcnt vmcnt(12)
	v_mov_b32_e32 v83, v52
	s_waitcnt vmcnt(11)
	v_mov_b32_e32 v86, v64
	s_waitcnt vmcnt(9)
	v_mov_b32_e32 v87, v72
	v_pk_mul_f32 v[82:83], v[82:83], v[92:93]
	v_pk_mul_f32 v[86:87], v[86:87], v[80:81]
	v_mov_b32_e32 v88, v60
	s_waitcnt vmcnt(8)
	v_mov_b32_e32 v89, v68
	v_bfe_u32 v56, v50, 16, 1
	v_pk_mul_f32 v[88:89], v[88:89], v[90:91]
	v_bfe_u32 v52, v82, 16, 1
	v_bfe_u32 v64, v86, 16, 1
	v_add3_u32 v50, v50, v56, s76
	v_bfe_u32 v40, v88, 16, 1
	v_add3_u32 v52, v82, v52, s76
	v_add3_u32 v64, v86, v64, s76
	v_lshrrev_b32_e32 v50, 16, v50
	v_add3_u32 v40, v88, v40, s76
	v_lshrrev_b32_e32 v56, 16, v64
	v_and_or_b32 v86, v52, s77, v50
	v_mov_b32_e32 v52, v41
	v_mov_b32_e32 v68, v61
	v_and_or_b32 v88, v40, s77, v56
	v_mov_b32_e32 v56, v45
	v_pk_mul_f32 v[40:41], v[52:53], v[92:93]
	v_mov_b32_e32 v72, v65
	v_pk_mul_f32 v[52:53], v[68:69], v[90:91]
	v_cvt_pk_bf16_f32 v89, v87, v89
	v_cvt_pk_bf16_f32 v87, v51, v83
	v_pk_mul_f32 v[44:45], v[56:57], v[76:77]
	v_pk_mul_f32 v[50:51], v[72:73], v[80:81]
	v_bfe_u32 v2, v53, 16, 1
	v_bfe_u32 v60, v40, 16, 1
	v_add3_u32 v40, v40, v60, s76
	v_add3_u32 v2, v53, v2, s76
	v_bfe_u32 v53, v44, 16, 1
	v_bfe_u32 v60, v51, 16, 1
	v_add3_u32 v51, v51, v60, s76
	v_add3_u32 v44, v44, v53, s76
	v_lshrrev_b32_e32 v44, 16, v44
	v_lshrrev_b32_e32 v51, 16, v51
	v_and_or_b32 v53, v2, s77, v51
	v_cvt_pk_bf16_f32 v52, v50, v52
	v_cvt_pk_bf16_f32 v51, v45, v41
	v_and_or_b32 v50, v40, s77, v44
	global_store_dwordx4 v[84:85], v[50:53], off offset:576
	v_mov_b32_e32 v44, v42
	v_mov_b32_e32 v45, v54
	v_mov_b32_e32 v52, v62
	v_mov_b32_e32 v53, v70
	v_mov_b32_e32 v40, v46
	v_mov_b32_e32 v41, v58
	v_pk_mul_f32 v[44:45], v[44:45], v[92:93]
	v_mov_b32_e32 v50, v66
	v_mov_b32_e32 v51, v74
	v_pk_mul_f32 v[52:53], v[52:53], v[90:91]
	v_pk_mul_f32 v[40:41], v[40:41], v[76:77]
	v_pk_mul_f32 v[50:51], v[50:51], v[80:81]
	v_bfe_u32 v2, v53, 16, 1
	v_bfe_u32 v42, v52, 16, 1
	v_bfe_u32 v46, v45, 16, 1
	v_bfe_u32 v54, v44, 16, 1
	v_add3_u32 v44, v44, v54, s76
	v_add3_u32 v45, v45, v46, s76
	v_add3_u32 v42, v52, v42, s76
	v_add3_u32 v2, v53, v2, s76
	v_bfe_u32 v46, v40, 16, 1
	v_bfe_u32 v52, v41, 16, 1
	v_bfe_u32 v53, v50, 16, 1
	v_bfe_u32 v54, v51, 16, 1
	v_add3_u32 v51, v51, v54, s76
	v_add3_u32 v50, v50, v53, s76
	v_add3_u32 v41, v41, v52, s76
	v_add3_u32 v40, v40, v46, s76
	v_lshrrev_b32_e32 v40, 16, v40
	v_lshrrev_b32_e32 v41, 16, v41
	v_lshrrev_b32_e32 v46, 16, v50
	v_lshrrev_b32_e32 v50, 16, v51
	v_mov_b32_e32 v54, v43
	v_mov_b32_e32 v70, v63
	v_and_or_b32 v53, v2, s77, v50
	v_and_or_b32 v52, v42, s77, v46
	v_and_or_b32 v51, v45, s77, v41
	v_and_or_b32 v50, v44, s77, v40
	v_mov_b32_e32 v58, v47
	v_pk_mul_f32 v[42:43], v[54:55], v[92:93]
	v_mov_b32_e32 v74, v67
	v_pk_mul_f32 v[46:47], v[70:71], v[90:91]
	global_store_dwordx4 v[84:85], v[50:53], off offset:1088
	v_pk_mul_f32 v[40:41], v[58:59], v[76:77]
	v_pk_mul_f32 v[44:45], v[74:75], v[80:81]
	v_bfe_u32 v2, v47, 16, 1
	v_bfe_u32 v50, v46, 16, 1
	v_bfe_u32 v51, v43, 16, 1
	v_bfe_u32 v52, v42, 16, 1
	v_add3_u32 v52, v42, v52, s76
	v_add3_u32 v51, v43, v51, s76
	v_add3_u32 v42, v46, v50, s76
	v_add3_u32 v2, v47, v2, s76
	v_bfe_u32 v43, v40, 16, 1
	v_bfe_u32 v46, v41, 16, 1
	v_bfe_u32 v47, v44, 16, 1
	v_bfe_u32 v50, v45, 16, 1
	v_add3_u32 v45, v45, v50, s76
	v_add3_u32 v44, v44, v47, s76
	v_add3_u32 v41, v41, v46, s76
	v_add3_u32 v40, v40, v43, s76
	v_lshrrev_b32_e32 v40, 16, v40
	v_lshrrev_b32_e32 v41, 16, v41
	v_lshrrev_b32_e32 v44, 16, v44
	v_lshrrev_b32_e32 v43, 16, v45
	v_and_or_b32 v43, v2, s77, v43
	v_and_or_b32 v42, v42, s77, v44
	v_and_or_b32 v41, v51, s77, v41
	v_and_or_b32 v40, v52, s77, v40
	global_store_dwordx4 v[84:85], v[40:43], off offset:1600
	s_waitcnt vmcnt(6)
	v_mov_b32_e32 v44, v28
	s_waitcnt vmcnt(4)
	v_mov_b32_e32 v45, v36
	v_mov_b32_e32 v40, v12
	v_mov_b32_e32 v41, v20
	v_pk_mul_f32 v[40:41], v[40:41], v[4:5]
	v_mov_b32_e32 v42, v8
	v_mov_b32_e32 v43, v16
	v_pk_mul_f32 v[44:45], v[44:45], v[48:49]
	v_mov_b32_e32 v46, v24
	s_waitcnt vmcnt(3)
	v_mov_b32_e32 v47, v32
	v_pk_mul_f32 v[42:43], v[42:43], v[78:79]
	v_pk_mul_f32 v[46:47], v[46:47], v[6:7]
	v_bfe_u32 v24, v41, 16, 1
	v_bfe_u32 v12, v43, 16, 1
	v_add3_u32 v24, v41, v24, s76
	v_add3_u32 v12, v43, v12, s76
	v_lshrrev_b32_e32 v24, 16, v24
	v_cvt_pk_bf16_f32 v43, v45, v47
	v_cvt_pk_bf16_f32 v40, v40, v42
	v_mov_b32_e32 v20, v13
	v_mov_b32_e32 v32, v25
	v_and_or_b32 v41, v12, s77, v24
	v_pk_mul_f32 v[12:13], v[20:21], v[4:5]
	v_mov_b32_e32 v16, v9
	v_pk_mul_f32 v[20:21], v[32:33], v[6:7]
	v_cvt_pk_bf16_f32 v42, v44, v46
	v_pk_mul_f32 v[8:9], v[16:17], v[78:79]
	v_mov_b32_e32 v36, v29
	v_bfe_u32 v2, v21, 16, 1
	v_pk_mul_f32 v[16:17], v[36:37], v[48:49]
	v_add3_u32 v2, v21, v2, s76
	v_bfe_u32 v28, v17, 16, 1
	global_store_dwordx4 v[84:85], v[40:43], off offset:96
	v_add3_u32 v17, v17, v28, s76
	s_nop 1
	v_cvt_pk_bf16_f32 v41, v13, v9
	v_cvt_pk_bf16_f32 v40, v12, v8
	v_mov_b32_e32 v12, v10
	v_mov_b32_e32 v13, v18
	v_lshrrev_b32_e32 v17, 16, v17
	v_cvt_pk_bf16_f32 v42, v16, v20
	v_mov_b32_e32 v8, v14
	v_mov_b32_e32 v9, v22
	v_pk_mul_f32 v[12:13], v[12:13], v[78:79]
	v_mov_b32_e32 v20, v26
	v_mov_b32_e32 v21, v34
	v_and_or_b32 v43, v2, s77, v17
	v_pk_mul_f32 v[8:9], v[8:9], v[4:5]
	v_mov_b32_e32 v16, v30
	v_mov_b32_e32 v17, v38
	v_pk_mul_f32 v[20:21], v[20:21], v[6:7]
	v_bfe_u32 v14, v13, 16, 1
	v_bfe_u32 v18, v12, 16, 1
	v_pk_mul_f32 v[16:17], v[16:17], v[48:49]
	v_add3_u32 v12, v12, v18, s76
	v_add3_u32 v13, v13, v14, s76
	v_bfe_u32 v14, v8, 16, 1
	v_bfe_u32 v18, v9, 16, 1
	v_add3_u32 v9, v9, v18, s76
	v_add3_u32 v8, v8, v14, s76
	v_lshrrev_b32_e32 v8, 16, v8
	v_lshrrev_b32_e32 v9, 16, v9
	v_mov_b32_e32 v18, v11
	v_mov_b32_e32 v34, v27
	global_store_dwordx4 v[84:85], v[40:43], off offset:608
	s_nop 1
	v_and_or_b32 v41, v13, s77, v9
	s_nop 1
	v_and_or_b32 v40, v12, s77, v8
	v_mov_b32_e32 v22, v15
	v_pk_mul_f32 v[8:9], v[18:19], v[78:79]
	v_mov_b32_e32 v38, v31
	v_pk_mul_f32 v[6:7], v[34:35], v[6:7]
	v_cvt_pk_bf16_f32 v43, v17, v21
	v_cvt_pk_bf16_f32 v42, v16, v20
	v_pk_mul_f32 v[4:5], v[22:23], v[4:5]
	v_pk_mul_f32 v[10:11], v[38:39], v[48:49]
	v_bfe_u32 v2, v7, 16, 1
	v_bfe_u32 v14, v8, 16, 1
	v_add3_u32 v8, v8, v14, s76
	v_add3_u32 v2, v7, v2, s76
	v_bfe_u32 v7, v4, 16, 1
	v_bfe_u32 v14, v11, 16, 1
	v_add3_u32 v11, v11, v14, s76
	v_add3_u32 v4, v4, v7, s76
	v_lshrrev_b32_e32 v4, 16, v4
	v_lshrrev_b32_e32 v7, 16, v11
	v_and_or_b32 v7, v2, s77, v7
	v_cvt_pk_bf16_f32 v6, v10, v6
	v_cvt_pk_bf16_f32 v5, v5, v9
	v_and_or_b32 v4, v8, s77, v4
	global_store_dwordx4 v[84:85], v[86:89], off offset:64
	global_store_dwordx4 v[84:85], v[40:43], off offset:1120
	global_store_dwordx4 v[84:85], v[4:7], off offset:1632

.LBB0_507:
	s_waitcnt vmcnt(11)
	v_mov_b32_e32 v94, v64
	s_waitcnt vmcnt(9)
	v_mov_b32_e32 v95, v72
	v_mov_b32_e32 v42, v56
	v_mov_b32_e32 v43, v60
	v_pk_mul_f32 v[94:95], v[94:95], v[80:81]
	v_mov_b32_e32 v96, v52
	s_waitcnt vmcnt(8)
	v_mov_b32_e32 v97, v68
	v_pk_mul_f32 v[42:43], v[42:43], v[76:77]
	v_mov_b32_e32 v86, v44
	v_mov_b32_e32 v87, v48
	v_pk_mul_f32 v[96:97], v[96:97], v[90:91]
	v_pk_mul_f32 v[86:87], v[86:87], v[92:93]
	v_bfe_u32 v60, v42, 16, 1
	v_add3_u32 v42, v42, v60, s76
	v_bfe_u32 v56, v86, 16, 1
	v_cvt_pk_bf16_f32 v96, v94, v96
	v_mov_b32_e32 v48, v45
	v_mov_b32_e32 v68, v53
	v_add3_u32 v56, v86, v56, s76
	v_lshrrev_b32_e32 v42, 16, v42
	v_cvt_pk_bf16_f32 v97, v95, v97
	v_cvt_pk_bf16_f32 v95, v43, v87
	v_mov_b32_e32 v60, v57
	v_pk_mul_f32 v[44:45], v[48:49], v[92:93]
	v_mov_b32_e32 v72, v65
	v_pk_mul_f32 v[52:53], v[68:69], v[90:91]
	v_and_or_b32 v94, v56, s77, v42
	v_pk_mul_f32 v[42:43], v[60:61], v[76:77]
	v_pk_mul_f32 v[48:49], v[72:73], v[80:81]
	v_bfe_u32 v56, v53, 16, 1
	v_bfe_u32 v57, v52, 16, 1
	v_bfe_u32 v60, v45, 16, 1
	v_bfe_u32 v61, v44, 16, 1
	v_add3_u32 v61, v44, v61, s76
	v_add3_u32 v60, v45, v60, s76
	v_add3_u32 v44, v52, v57, s76
	v_add3_u32 v45, v53, v56, s76
	v_bfe_u32 v52, v42, 16, 1
	v_bfe_u32 v53, v43, 16, 1
	v_bfe_u32 v56, v48, 16, 1
	v_bfe_u32 v57, v49, 16, 1
	v_add3_u32 v49, v49, v57, s76
	v_add3_u32 v48, v48, v56, s76
	v_add3_u32 v43, v43, v53, s76
	v_add3_u32 v42, v42, v52, s76
	v_lshrrev_b32_e32 v42, 16, v42
	v_lshrrev_b32_e32 v43, 16, v43
	v_lshrrev_b32_e32 v48, 16, v48
	v_lshrrev_b32_e32 v49, 16, v49
	v_and_or_b32 v45, v45, s77, v49
	v_and_or_b32 v44, v44, s77, v48
	v_and_or_b32 v43, v60, s77, v43
	v_and_or_b32 v42, v61, s77, v42
	global_store_dwordx4 v[84:85], v[42:45], off offset:2048
	v_mov_b32_e32 v52, v54
	v_mov_b32_e32 v53, v70
	v_mov_b32_e32 v44, v46
	v_mov_b32_e32 v45, v50
	v_mov_b32_e32 v42, v58
	v_mov_b32_e32 v43, v62
	v_pk_mul_f32 v[44:45], v[44:45], v[92:93]
	v_mov_b32_e32 v48, v66
	v_mov_b32_e32 v49, v74
	v_pk_mul_f32 v[52:53], v[52:53], v[90:91]
	v_pk_mul_f32 v[42:43], v[42:43], v[76:77]
	v_pk_mul_f32 v[48:49], v[48:49], v[80:81]
	v_bfe_u32 v46, v53, 16, 1
	v_bfe_u32 v50, v52, 16, 1
	v_bfe_u32 v54, v45, 16, 1
	v_bfe_u32 v56, v44, 16, 1
	v_add3_u32 v56, v44, v56, s76
	v_add3_u32 v54, v45, v54, s76
	v_add3_u32 v44, v52, v50, s76
	v_add3_u32 v45, v53, v46, s76
	v_bfe_u32 v46, v42, 16, 1
	v_bfe_u32 v50, v43, 16, 1
	v_bfe_u32 v52, v48, 16, 1
	v_bfe_u32 v53, v49, 16, 1
	v_add3_u32 v49, v49, v53, s76
	v_add3_u32 v48, v48, v52, s76
	v_add3_u32 v43, v43, v50, s76
	v_add3_u32 v42, v42, v46, s76
	v_lshrrev_b32_e32 v42, 16, v42
	v_lshrrev_b32_e32 v43, 16, v43
	v_lshrrev_b32_e32 v46, 16, v48
	v_lshrrev_b32_e32 v48, 16, v49
	v_add_co_u32_e32 v86, vcc, s69, v84
	v_and_or_b32 v45, v45, s77, v48
	v_and_or_b32 v44, v44, s77, v46
	v_and_or_b32 v43, v54, s77, v43
	v_and_or_b32 v42, v56, s77, v42
	v_addc_co_u32_e32 v87, vcc, 0, v85, vcc
	v_mov_b32_e32 v50, v47
	v_mov_b32_e32 v70, v55
	global_store_dwordx4 v[86:87], v[42:45], off
	v_mov_b32_e32 v62, v59
	v_mov_b32_e32 v74, v67
	v_pk_mul_f32 v[44:45], v[50:51], v[92:93]
	v_pk_mul_f32 v[48:49], v[70:71], v[90:91]
	v_pk_mul_f32 v[42:43], v[62:63], v[76:77]
	v_pk_mul_f32 v[46:47], v[74:75], v[80:81]
	v_bfe_u32 v50, v49, 16, 1
	v_bfe_u32 v51, v48, 16, 1
	v_bfe_u32 v52, v45, 16, 1
	v_bfe_u32 v53, v44, 16, 1
	v_add3_u32 v53, v44, v53, s76
	v_add3_u32 v52, v45, v52, s76
	v_add3_u32 v44, v48, v51, s76
	v_add3_u32 v45, v49, v50, s76
	v_bfe_u32 v48, v42, 16, 1
	v_bfe_u32 v49, v43, 16, 1
	v_bfe_u32 v50, v46, 16, 1
	v_bfe_u32 v51, v47, 16, 1
	v_add3_u32 v47, v47, v51, s76
	v_add3_u32 v46, v46, v50, s76
	v_add3_u32 v43, v43, v49, s76
	v_add3_u32 v42, v42, v48, s76
	v_lshrrev_b32_e32 v42, 16, v42
	v_lshrrev_b32_e32 v43, 16, v43
	v_lshrrev_b32_e32 v46, 16, v46
	v_lshrrev_b32_e32 v47, 16, v47
	v_and_or_b32 v45, v45, s77, v47
	v_and_or_b32 v44, v44, s77, v46
	v_and_or_b32 v43, v52, s77, v43
	v_and_or_b32 v42, v53, s77, v42
	s_waitcnt vmcnt(5)
	v_mov_b32_e32 v46, v28
	s_waitcnt vmcnt(3)
	v_mov_b32_e32 v47, v36
	global_store_dwordx4 v[86:87], v[42:45], off offset:2048
	v_pk_mul_f32 v[46:47], v[46:47], v[40:41]
	v_mov_b32_e32 v48, v24
	v_mov_b32_e32 v42, v16
	v_mov_b32_e32 v43, v20
	s_waitcnt vmcnt(3)
	v_mov_b32_e32 v49, v32
	v_pk_mul_f32 v[42:43], v[42:43], v[4:5]
	v_mov_b32_e32 v44, v8
	v_mov_b32_e32 v45, v12
	v_pk_mul_f32 v[48:49], v[48:49], v[78:79]
	v_pk_mul_f32 v[44:45], v[44:45], v[82:83]
	v_bfe_u32 v24, v42, 16, 1
	v_bfe_u32 v20, v44, 16, 1
	v_bfe_u32 v28, v43, 16, 1
	v_add3_u32 v24, v42, v24, s76
	v_bfe_u32 v16, v45, 16, 1
	v_add3_u32 v20, v44, v20, s76
	v_add3_u32 v28, v43, v28, s76
	v_lshrrev_b32_e32 v24, 16, v24
	v_cvt_pk_bf16_f32 v44, v46, v48
	v_mov_b32_e32 v12, v9
	v_add3_u32 v16, v45, v16, s76
	v_lshrrev_b32_e32 v28, 16, v28
	v_cvt_pk_bf16_f32 v45, v47, v49
	v_and_or_b32 v42, v20, s77, v24
	v_mov_b32_e32 v20, v17
	v_pk_mul_f32 v[8:9], v[12:13], v[82:83]
	v_mov_b32_e32 v36, v29
	v_mov_b32_e32 v32, v25
	v_and_or_b32 v43, v16, s77, v28
	v_pk_mul_f32 v[16:17], v[20:21], v[4:5]
	v_pk_mul_f32 v[12:13], v[36:37], v[40:41]
	v_pk_mul_f32 v[20:21], v[32:33], v[78:79]
	global_store_dwordx4 v[84:85], v[42:45], off offset:32
	s_nop 1
	v_cvt_pk_bf16_f32 v45, v13, v21
	s_nop 1
	v_cvt_pk_bf16_f32 v44, v12, v20
	v_mov_b32_e32 v12, v10
	v_mov_b32_e32 v13, v14
	v_mov_b32_e32 v20, v26
	v_mov_b32_e32 v21, v34
	v_cvt_pk_bf16_f32 v43, v17, v9
	v_cvt_pk_bf16_f32 v42, v16, v8
	v_mov_b32_e32 v8, v18
	v_mov_b32_e32 v9, v22
	v_pk_mul_f32 v[12:13], v[12:13], v[82:83]
	v_mov_b32_e32 v16, v30
	v_mov_b32_e32 v17, v38
	v_pk_mul_f32 v[20:21], v[20:21], v[78:79]
	v_pk_mul_f32 v[8:9], v[8:9], v[4:5]
	v_pk_mul_f32 v[16:17], v[16:17], v[40:41]
	v_bfe_u32 v10, v21, 16, 1
	v_bfe_u32 v14, v20, 16, 1
	v_add3_u32 v14, v20, v14, s76
	v_add3_u32 v10, v21, v10, s76
	v_bfe_u32 v18, v8, 16, 1
	v_bfe_u32 v21, v16, 16, 1
	v_bfe_u32 v22, v12, 16, 1
	v_add3_u32 v16, v16, v21, s76
	v_add3_u32 v8, v8, v18, s76
	v_add3_u32 v12, v12, v22, s76
	v_bfe_u32 v22, v17, 16, 1
	v_lshrrev_b32_e32 v8, 16, v8
	v_lshrrev_b32_e32 v16, 16, v16
	v_mov_b32_e32 v34, v27
	global_store_dwordx4 v[84:85], v[42:45], off offset:2080
	v_add3_u32 v17, v17, v22, s76
	v_mov_b32_e32 v22, v19
	v_and_or_b32 v44, v14, s77, v16
	v_cvt_pk_bf16_f32 v43, v9, v13
	v_and_or_b32 v42, v12, s77, v8
	v_mov_b32_e32 v14, v11
	v_pk_mul_f32 v[12:13], v[34:35], v[78:79]
	v_lshrrev_b32_e32 v17, 16, v17
	v_pk_mul_f32 v[4:5], v[22:23], v[4:5]
	v_pk_mul_f32 v[8:9], v[14:15], v[82:83]
	v_mov_b32_e32 v38, v31
	v_and_or_b32 v45, v10, s77, v17
	v_pk_mul_f32 v[10:11], v[38:39], v[40:41]
	v_lshl_add_u64 v[6:7], v[88:89], 0, s[58:59]
	v_cvt_pk_bf16_f32 v8, v4, v8
	v_add_co_u32_e32 v4, vcc, s82, v6
	v_cvt_pk_bf16_f32 v11, v11, v13
	v_cvt_pk_bf16_f32 v10, v10, v12
	v_cvt_pk_bf16_f32 v9, v5, v9
	v_addc_co_u32_e32 v5, vcc, 0, v7, vcc
	s_mov_b32 s24, 0xa000
	global_store_dwordx4 v[86:87], v[8:11], off offset:2080
	global_store_dwordx4 v[84:85], v[94:97], off
	global_store_dwordx4 v[86:87], v[42:45], off offset:32
	v_add_co_u32_e32 v8, vcc, s24, v88
	v_mov_b32_e32 v76, 1.0
	s_nop 0
	v_addc_co_u32_e32 v9, vcc, 0, v89, vcc
	global_load_dwordx4 v[52:55], v[4:5], off nt
	global_load_dwordx4 v[44:47], v[8:9], off offset:1280 nt
	global_load_dwordx4 v[56:59], v[8:9], off offset:2560 nt
	global_load_dwordx4 v[48:51], v[8:9], off offset:3840 nt
	v_add_co_u32_e32 v4, vcc, 0xb000, v88
	v_mov_b32_e32 v92, 1.0
	s_nop 0
	v_addc_co_u32_e32 v5, vcc, 0, v89, vcc
	v_add_co_u32_e32 v8, vcc, 0xc000, v88
	global_load_dwordx4 v[64:67], v[4:5], off offset:1024 nt
	global_load_dwordx4 v[60:63], v[4:5], off offset:2304 nt
	v_addc_co_u32_e32 v9, vcc, 0, v89, vcc
	global_load_dwordx4 v[72:75], v[4:5], off offset:3584 nt
	global_load_dwordx4 v[68:71], v[8:9], off offset:768 nt
	v_mov_b32_e32 v4, 1.0
	s_and_b64 vcc, exec, s[16:17]
	v_mov_b32_e32 v77, 1.0
	v_mov_b32_e32 v93, 1.0
	v_mov_b32_e32 v80, 1.0
	v_mov_b32_e32 v90, 1.0
	v_mov_b32_e32 v81, 1.0
	v_mov_b32_e32 v91, 1.0
	s_cbranch_vccnz .LBB0_509
	global_load_dwordx4 v[76:79], v2, s[60:61] offset:128
	global_load_dwordx4 v[80:83], v2, s[60:61] offset:144
	s_waitcnt vmcnt(1)
	v_mov_b32_e32 v92, v77
	v_mov_b32_e32 v77, v78
	v_mov_b32_e32 v93, v79
	s_waitcnt vmcnt(0)
	v_mov_b32_e32 v90, v81
	v_mov_b32_e32 v81, v82
	v_mov_b32_e32 v91, v83

.LBB0_511:
	s_waitcnt vmcnt(14)
	v_mov_b32_e32 v42, v44
	s_waitcnt vmcnt(12)
	v_mov_b32_e32 v43, v48
	s_waitcnt vmcnt(11)
	v_mov_b32_e32 v88, v64
	s_waitcnt vmcnt(9)
	v_mov_b32_e32 v89, v72
	v_mov_b32_e32 v6, v52
	v_mov_b32_e32 v7, v56
	v_pk_mul_f32 v[42:43], v[42:43], v[92:93]
	v_pk_mul_f32 v[88:89], v[88:89], v[80:81]
	v_mov_b32_e32 v94, v60
	s_waitcnt vmcnt(8)
	v_mov_b32_e32 v95, v68
	v_pk_mul_f32 v[6:7], v[6:7], v[76:77]
	v_pk_mul_f32 v[94:95], v[94:95], v[90:91]
	v_bfe_u32 v48, v43, 16, 1
	v_bfe_u32 v52, v42, 16, 1
	v_add3_u32 v42, v42, v52, s76
	v_add3_u32 v43, v43, v48, s76
	v_bfe_u32 v48, v6, 16, 1
	v_bfe_u32 v52, v7, 16, 1
	v_bfe_u32 v60, v89, 16, 1
	v_add3_u32 v7, v7, v52, s76
	v_add3_u32 v6, v6, v48, s76
	v_bfe_u32 v2, v95, 16, 1
	v_add3_u32 v60, v89, v60, s76
	v_lshrrev_b32_e32 v6, 16, v6
	v_lshrrev_b32_e32 v7, 16, v7
	v_cvt_pk_bf16_f32 v96, v88, v94
	v_mov_b32_e32 v48, v45
	v_mov_b32_e32 v68, v61
	v_add3_u32 v2, v95, v2, s76
	v_lshrrev_b32_e32 v52, 16, v60
	v_and_or_b32 v95, v43, s77, v7
	v_and_or_b32 v94, v42, s77, v6
	v_mov_b32_e32 v56, v53
	v_pk_mul_f32 v[42:43], v[48:49], v[92:93]
	v_mov_b32_e32 v72, v65
	v_pk_mul_f32 v[48:49], v[68:69], v[90:91]
	v_and_or_b32 v97, v2, s77, v52
	v_pk_mul_f32 v[6:7], v[56:57], v[76:77]
	v_pk_mul_f32 v[44:45], v[72:73], v[80:81]
	v_bfe_u32 v2, v49, 16, 1
	v_add3_u32 v2, v49, v2, s76
	v_bfe_u32 v56, v45, 16, 1
	v_add3_u32 v45, v45, v56, s76
	v_lshrrev_b32_e32 v45, 16, v45
	v_and_or_b32 v45, v2, s77, v45
	v_cvt_pk_bf16_f32 v44, v44, v48
	v_cvt_pk_bf16_f32 v43, v7, v43
	v_cvt_pk_bf16_f32 v42, v6, v42
	global_store_dwordx4 v[84:85], v[42:45], off offset:2112
	v_mov_b32_e32 v48, v62
	v_mov_b32_e32 v49, v70
	v_mov_b32_e32 v42, v46
	v_mov_b32_e32 v43, v50
	v_mov_b32_e32 v6, v54
	v_mov_b32_e32 v7, v58
	v_pk_mul_f32 v[42:43], v[42:43], v[92:93]
	v_mov_b32_e32 v44, v66
	v_mov_b32_e32 v45, v74
	v_pk_mul_f32 v[48:49], v[48:49], v[90:91]
	v_pk_mul_f32 v[6:7], v[6:7], v[76:77]
	v_pk_mul_f32 v[44:45], v[44:45], v[80:81]
	v_bfe_u32 v2, v49, 16, 1
	v_bfe_u32 v46, v48, 16, 1
	v_add3_u32 v46, v48, v46, s76
	v_add3_u32 v2, v49, v2, s76
	v_bfe_u32 v50, v44, 16, 1
	v_bfe_u32 v52, v45, 16, 1
	v_add3_u32 v45, v45, v52, s76
	v_add3_u32 v44, v44, v50, s76
	v_lshrrev_b32_e32 v44, 16, v44
	v_lshrrev_b32_e32 v45, 16, v45
	v_and_or_b32 v45, v2, s77, v45
	v_and_or_b32 v44, v46, s77, v44
	v_cvt_pk_bf16_f32 v43, v7, v43
	v_cvt_pk_bf16_f32 v42, v6, v42
	v_mov_b32_e32 v50, v47
	v_mov_b32_e32 v70, v63
	global_store_dwordx4 v[86:87], v[42:45], off offset:64
	v_mov_b32_e32 v58, v55
	v_mov_b32_e32 v74, v67
	v_pk_mul_f32 v[42:43], v[50:51], v[92:93]
	v_pk_mul_f32 v[46:47], v[70:71], v[90:91]
	v_pk_mul_f32 v[6:7], v[58:59], v[76:77]
	v_pk_mul_f32 v[44:45], v[74:75], v[80:81]
	v_bfe_u32 v2, v47, 16, 1
	v_add3_u32 v2, v47, v2, s76
	v_bfe_u32 v50, v45, 16, 1
	v_add3_u32 v45, v45, v50, s76
	v_lshrrev_b32_e32 v45, 16, v45
	v_and_or_b32 v45, v2, s77, v45
	v_cvt_pk_bf16_f32 v44, v44, v46
	v_cvt_pk_bf16_f32 v43, v7, v43
	v_cvt_pk_bf16_f32 v42, v6, v42
	s_waitcnt vmcnt(9)
	v_mov_b32_e32 v6, v32
	s_waitcnt vmcnt(7)
	v_mov_b32_e32 v7, v36
	global_store_dwordx4 v[86:87], v[42:45], off offset:2112
	v_pk_mul_f32 v[6:7], v[6:7], v[4:5]
	s_waitcnt vmcnt(5)
	v_mov_b32_e32 v46, v8
	v_mov_b32_e32 v42, v24
	v_mov_b32_e32 v43, v28
	v_mov_b32_e32 v44, v20
	s_waitcnt vmcnt(4)
	v_mov_b32_e32 v45, v16
	v_pk_mul_f32 v[42:43], v[42:43], v[82:83]
	v_pk_mul_f32 v[44:45], v[44:45], v[40:41]
	s_waitcnt vmcnt(3)
	v_mov_b32_e32 v47, v12
	v_bfe_u32 v24, v7, 16, 1
	v_pk_mul_f32 v[46:47], v[46:47], v[78:79]
	v_bfe_u32 v12, v43, 16, 1
	v_bfe_u32 v28, v44, 16, 1
	v_add3_u32 v7, v7, v24, s76
	v_bfe_u32 v8, v46, 16, 1
	v_add3_u32 v12, v43, v12, s76
	v_add3_u32 v28, v44, v28, s76
	v_lshrrev_b32_e32 v7, 16, v7
	v_add3_u32 v8, v46, v8, s76
	v_lshrrev_b32_e32 v20, 16, v28
	v_and_or_b32 v43, v12, s77, v7
	v_mov_b32_e32 v28, v25
	v_mov_b32_e32 v12, v9
	v_cvt_pk_bf16_f32 v45, v45, v47
	v_and_or_b32 v44, v8, s77, v20
	v_cvt_pk_bf16_f32 v42, v6, v42
	v_mov_b32_e32 v36, v33
	v_pk_mul_f32 v[24:25], v[28:29], v[82:83]
	v_mov_b32_e32 v16, v21
	v_pk_mul_f32 v[8:9], v[12:13], v[78:79]
	v_pk_mul_f32 v[6:7], v[36:37], v[4:5]
	v_pk_mul_f32 v[16:17], v[16:17], v[40:41]
	v_bfe_u32 v2, v9, 16, 1
	v_bfe_u32 v20, v24, 16, 1
	v_add3_u32 v20, v24, v20, s76
	v_add3_u32 v2, v9, v2, s76
	v_bfe_u32 v9, v6, 16, 1
	v_bfe_u32 v24, v17, 16, 1
	v_add3_u32 v17, v17, v24, s76
	v_add3_u32 v6, v6, v9, s76
	v_lshrrev_b32_e32 v6, 16, v6
	v_lshrrev_b32_e32 v9, 16, v17
	v_and_or_b32 v9, v2, s77, v9
	v_cvt_pk_bf16_f32 v8, v16, v8
	v_cvt_pk_bf16_f32 v7, v7, v25
	v_and_or_b32 v6, v20, s77, v6
	global_store_dwordx4 v[84:85], v[6:9], off offset:2144
	v_mov_b32_e32 v16, v10
	v_mov_b32_e32 v17, v14
	v_mov_b32_e32 v8, v26
	v_mov_b32_e32 v9, v30
	v_mov_b32_e32 v6, v34
	v_mov_b32_e32 v7, v38
	v_pk_mul_f32 v[8:9], v[8:9], v[82:83]
	v_mov_b32_e32 v12, v22
	v_mov_b32_e32 v13, v18
	v_pk_mul_f32 v[16:17], v[16:17], v[78:79]
	v_pk_mul_f32 v[6:7], v[6:7], v[4:5]
	v_pk_mul_f32 v[12:13], v[12:13], v[40:41]
	v_bfe_u32 v14, v9, 16, 1
	v_bfe_u32 v18, v8, 16, 1
	v_add3_u32 v18, v8, v18, s76
	v_add3_u32 v14, v9, v14, s76
	v_bfe_u32 v9, v6, 16, 1
	v_bfe_u32 v10, v7, 16, 1
	v_add3_u32 v7, v7, v10, s76
	v_add3_u32 v6, v6, v9, s76
	v_lshrrev_b32_e32 v6, 16, v6
	v_lshrrev_b32_e32 v7, 16, v7
	v_mov_b32_e32 v38, v35
	v_cvt_pk_bf16_f32 v9, v13, v17
	v_cvt_pk_bf16_f32 v8, v12, v16
	v_and_or_b32 v7, v14, s77, v7
	v_and_or_b32 v6, v18, s77, v6
	v_pk_mul_f32 v[4:5], v[38:39], v[4:5]
	v_mov_b32_e32 v30, v27
	global_store_dwordx4 v[86:87], v[6:9], off offset:96
	v_and_b32_sdwa v2, v5, v171 dst_sel:DWORD dst_unused:UNUSED_PAD src0_sel:WORD_1 src1_sel:DWORD
	v_add3_u32 v2, v5, v2, s76
	v_pk_mul_f32 v[6:7], v[30:31], v[82:83]
	v_and_b32_sdwa v8, v4, v171 dst_sel:DWORD dst_unused:UNUSED_PAD src0_sel:WORD_1 src1_sel:DWORD
	v_add3_u32 v4, v4, v8, s76
	v_and_b32_sdwa v8, v6, v171 dst_sel:DWORD dst_unused:UNUSED_PAD src0_sel:WORD_1 src1_sel:DWORD
	v_add3_u32 v6, v6, v8, s76
	v_and_b32_sdwa v5, v7, v171 dst_sel:DWORD dst_unused:UNUSED_PAD src0_sel:WORD_1 src1_sel:DWORD
	v_and_b32_e32 v6, 0xffff0000, v6
	v_add3_u32 v5, v7, v5, s76
	v_or_b32_sdwa v4, v6, v4 dst_sel:DWORD dst_unused:UNUSED_PAD src0_sel:DWORD src1_sel:WORD_1
	v_mov_b32_e32 v10, v23
	v_mov_b32_e32 v6, v40
	v_mov_b32_e32 v7, v78
	v_pk_mul_f32 v[6:7], v[10:11], v[6:7]
	v_and_b32_e32 v5, 0xffff0000, v5
	v_and_b32_sdwa v8, v6, v171 dst_sel:DWORD dst_unused:UNUSED_PAD src0_sel:WORD_1 src1_sel:DWORD
	v_mov_b32_e32 v14, v19
	v_mov_b32_e32 v78, v41
	v_or_b32_sdwa v5, v5, v2 dst_sel:DWORD dst_unused:UNUSED_PAD src0_sel:DWORD src1_sel:WORD_1
	v_and_b32_sdwa v2, v7, v171 dst_sel:DWORD dst_unused:UNUSED_PAD src0_sel:WORD_1 src1_sel:DWORD
	v_add3_u32 v6, v6, v8, s76
	v_pk_mul_f32 v[8:9], v[14:15], v[78:79]
	v_add3_u32 v2, v7, v2, s76
	v_lshrrev_b32_e32 v6, 16, v6
	v_and_b32_sdwa v7, v8, v171 dst_sel:DWORD dst_unused:UNUSED_PAD src0_sel:WORD_1 src1_sel:DWORD
	v_and_or_b32 v6, v2, s77, v6
	v_and_b32_sdwa v2, v9, v171 dst_sel:DWORD dst_unused:UNUSED_PAD src0_sel:WORD_1 src1_sel:DWORD
	v_add3_u32 v7, v8, v7, s76
	v_add3_u32 v2, v9, v2, s76
	v_lshrrev_b32_e32 v7, 16, v7
	v_and_or_b32 v7, v2, s77, v7
	global_store_dwordx4 v[84:85], v[94:97], off offset:64
	global_store_dwordx4 v[84:85], v[42:45], off offset:96

.LBB0_516:
	s_andn2_b64 vcc, exec, s[16:17]
	s_cbranch_vccnz .LBB0_518
	s_mov_b64 s[16:17], s[0:1]
	s_mov_b64 s[26:27], s[0:1]
	s_load_dwordx2 s[16:17], s[16:17], 0x90
	s_lshl_b32 s24, s23, 3
	s_load_dwordx2 s[26:27], s[26:27], 0xa8
	s_addk_i32 s24, 0x100
	s_and_b32 s60, s24, 0x7c0
	s_lshl_b32 s24, s23, 7
	s_and_b32 s24, s24, 0x380
	v_or_b32_e32 v6, s24, v155
	v_lshlrev_b32_e32 v2, 11, v6
	s_waitcnt lgkmcnt(0)
	v_lshl_add_u64 v[4:5], s[26:27], 0, v[2:3]
	s_lshl_b32 s24, s60, 1
	v_lshl_add_u64 v[4:5], v[4:5], 0, s[24:25]
	v_lshlrev_b32_e32 v2, 1, v116
	v_lshl_add_u64 v[70:71], v[4:5], 0, v[2:3]
	v_or_b32_e32 v7, s60, v116
	v_lshlrev_b32_e32 v2, 2, v6
	v_lshl_add_u64 v[4:5], s[16:17], 0, v[2:3]
	v_lshlrev_b32_e32 v2, 12, v7
	v_lshl_add_u64 v[72:73], v[4:5], 0, v[2:3]
	v_add_co_u32_e32 v4, vcc, s81, v72
	global_load_dwordx4 v[36:39], v[72:73], off nt
	s_nop 0
	v_addc_co_u32_e32 v5, vcc, 0, v73, vcc
	global_load_dwordx4 v[52:55], v[4:5], off offset:-4096 nt
	global_load_dwordx4 v[40:43], v[4:5], off nt
	v_add_co_u32_e32 v4, vcc, s70, v72
	s_mov_b64 s[16:17], 0x53c0000
	s_nop 0
	v_addc_co_u32_e32 v5, vcc, 0, v73, vcc
	global_load_dwordx4 v[56:59], v[4:5], off offset:-4096 nt
	global_load_dwordx4 v[44:47], v[4:5], off nt
	v_add_co_u32_e32 v4, vcc, s72, v72
	v_lshl_add_u64 v[68:69], v[70:71], 0, s[16:17]
	s_nop 0
	v_addc_co_u32_e32 v5, vcc, 0, v73, vcc
	global_load_dwordx4 v[60:63], v[4:5], off offset:-4096 nt
	global_load_dwordx4 v[48:51], v[4:5], off nt
	v_add_co_u32_e32 v4, vcc, s73, v72
	s_mov_b32 s16, 0x53c1000
	s_nop 0
	v_addc_co_u32_e32 v5, vcc, 0, v73, vcc
	global_load_dwordx4 v[64:67], v[4:5], off nt
	v_add_co_u32_e32 v4, vcc, s83, v72
	s_waitcnt vmcnt(7)
	v_bfe_u32 v2, v36, 16, 1
	v_addc_co_u32_e32 v5, vcc, 0, v73, vcc
	v_add_co_u32_e32 v6, vcc, s86, v72
	v_add3_u32 v2, v36, v2, s76
	s_nop 0
	v_addc_co_u32_e32 v7, vcc, 0, v73, vcc
	v_add_co_u32_e32 v12, vcc, s87, v72
	s_waitcnt vmcnt(6)
	v_bfe_u32 v36, v52, 16, 1
	v_addc_co_u32_e32 v13, vcc, 0, v73, vcc
	v_add_co_u32_e32 v14, vcc, s88, v72
	s_waitcnt vmcnt(5)
	v_bfe_u32 v74, v40, 16, 1
	v_addc_co_u32_e32 v15, vcc, 0, v73, vcc
	global_load_dwordx4 v[32:35], v[4:5], off offset:-4096 nt
	global_load_dwordx4 v[28:31], v[4:5], off nt
	global_load_dwordx4 v[24:27], v[6:7], off offset:-4096 nt
	global_load_dwordx4 v[16:19], v[6:7], off nt
	global_load_dwordx4 v[8:11], v[12:13], off offset:-4096 nt
	s_nop 0
	global_load_dwordx4 v[4:7], v[12:13], off nt
	global_load_dwordx4 v[20:23], v[14:15], off offset:-4096 nt
	s_nop 0
	global_load_dwordx4 v[12:15], v[14:15], off nt
	s_waitcnt vmcnt(12)
	v_bfe_u32 v75, v56, 16, 1
	s_waitcnt vmcnt(11)
	v_bfe_u32 v76, v44, 16, 1
	v_lshrrev_b32_e32 v2, 16, v2
	v_add3_u32 v36, v52, v36, s76
	v_add3_u32 v40, v40, v74, s76
	s_waitcnt vmcnt(10)
	v_bfe_u32 v77, v60, 16, 1
	s_waitcnt vmcnt(9)
	v_add3_u32 v52, v56, v75, s76
	v_add3_u32 v44, v44, v76, s76
	v_and_or_b32 v74, v36, s77, v2
	v_lshrrev_b32_e32 v2, 16, v40
	s_waitcnt vmcnt(8)
	v_add3_u32 v56, v60, v77, s76
	v_lshrrev_b32_e32 v36, 16, v44
	v_and_or_b32 v75, v52, s77, v2
	v_bfe_u32 v2, v37, 16, 1
	v_and_or_b32 v76, v56, s77, v36
	v_add_co_u32_e32 v70, vcc, s16, v70
	v_add3_u32 v2, v37, v2, s76
	v_bfe_u32 v36, v53, 16, 1
	v_cvt_pk_bf16_f32 v77, v48, v64
	v_addc_co_u32_e32 v71, vcc, 0, v71, vcc
	v_lshrrev_b32_e32 v2, 16, v2
	v_add3_u32 v36, v53, v36, s76
	global_store_dwordx4 v[70:71], v[74:77], off offset:-4096
	s_nop 1
	v_and_or_b32 v74, v36, s77, v2
	s_nop 1
	v_cvt_pk_bf16_f32 v75, v41, v57
	v_cvt_pk_bf16_f32 v76, v45, v61
	v_cvt_pk_bf16_f32 v77, v49, v65
	v_bfe_u32 v2, v38, 16, 1
	v_add3_u32 v2, v38, v2, s76
	v_bfe_u32 v36, v54, 16, 1
	v_lshrrev_b32_e32 v2, 16, v2
	v_add3_u32 v36, v54, v36, s76
	global_store_dwordx4 v[68:69], v[74:77], off offset:2048
	s_nop 1
	v_and_or_b32 v74, v36, s77, v2
	s_nop 1
	v_cvt_pk_bf16_f32 v75, v42, v58
	v_cvt_pk_bf16_f32 v76, v46, v62
	v_cvt_pk_bf16_f32 v77, v50, v66
	v_cvt_pk_bf16_f32 v36, v39, v55
	v_cvt_pk_bf16_f32 v37, v43, v59
	v_cvt_pk_bf16_f32 v38, v47, v63
	v_cvt_pk_bf16_f32 v39, v51, v67
	s_waitcnt vmcnt(9)
	s_waitcnt vmcnt(8)
	global_store_dwordx4 v[70:71], v[36:39], off offset:2048
	global_store_dwordx4 v[70:71], v[74:77], off
	s_nop 0
	v_cvt_pk_bf16_f32 v36, v32, v28
	s_waitcnt vmcnt(9)
	s_waitcnt vmcnt(8)
	v_cvt_pk_bf16_f32 v37, v24, v16
	s_waitcnt vmcnt(7)
	s_waitcnt vmcnt(6)
	v_cvt_pk_bf16_f32 v38, v8, v4
	s_waitcnt vmcnt(5)
	s_waitcnt vmcnt(4)
	v_cvt_pk_bf16_f32 v39, v20, v12
	global_store_dwordx4 v[68:69], v[36:39], off offset:32
	v_add_co_u32_e32 v8, vcc, s75, v72
	s_nop 0
	v_cvt_pk_bf16_f32 v36, v33, v29
	v_cvt_pk_bf16_f32 v37, v25, v17
	v_cvt_pk_bf16_f32 v38, v9, v5
	v_cvt_pk_bf16_f32 v39, v21, v13
	global_store_dwordx4 v[68:69], v[36:39], off offset:2080
	s_nop 1
	v_cvt_pk_bf16_f32 v36, v34, v30
	s_nop 1
	v_cvt_pk_bf16_f32 v37, v26, v18
	v_cvt_pk_bf16_f32 v38, v10, v6
	v_cvt_pk_bf16_f32 v39, v22, v14
	v_cvt_pk_bf16_f32 v4, v35, v31
	v_cvt_pk_bf16_f32 v5, v27, v19
	v_cvt_pk_bf16_f32 v6, v11, v7
	v_cvt_pk_bf16_f32 v7, v23, v15
	global_store_dwordx4 v[70:71], v[36:39], off offset:32
	global_store_dwordx4 v[70:71], v[4:7], off offset:2080
	v_addc_co_u32_e32 v9, vcc, 0, v73, vcc
	global_load_dwordx4 v[4:7], v[8:9], off offset:-4096 nt
	s_nop 0
	global_load_dwordx4 v[8:11], v[8:9], off nt
	v_add_co_u32_e32 v16, vcc, s89, v72
	s_waitcnt vmcnt(1)
	v_addc_co_u32_e32 v17, vcc, 0, v73, vcc
	global_load_dwordx4 v[12:15], v[16:17], off offset:-4096 nt
	s_nop 0
	global_load_dwordx4 v[16:19], v[16:17], off nt
	v_add_co_u32_e32 v24, vcc, s84, v72
	s_nop 0
	v_addc_co_u32_e32 v25, vcc, 0, v73, vcc
	global_load_dwordx4 v[20:23], v[24:25], off offset:-4096 nt
	s_nop 0
	global_load_dwordx4 v[24:27], v[24:25], off nt
	v_add_co_u32_e32 v32, vcc, s85, v72
	s_waitcnt vmcnt(4)
	v_addc_co_u32_e32 v33, vcc, 0, v73, vcc
	global_load_dwordx4 v[28:31], v[32:33], off offset:-4096 nt
	s_nop 0
	global_load_dwordx4 v[32:35], v[32:33], off nt
	v_add_co_u32_e32 v40, vcc, s78, v72
	s_nop 0
	v_addc_co_u32_e32 v41, vcc, 0, v73, vcc
	global_load_dwordx4 v[36:39], v[40:41], off offset:-4096 nt
	s_nop 0
	global_load_dwordx4 v[40:43], v[40:41], off nt
	v_add_co_u32_e32 v48, vcc, s79, v72
	s_nop 0
	v_addc_co_u32_e32 v49, vcc, 0, v73, vcc
	global_load_dwordx4 v[44:47], v[48:49], off offset:-4096 nt
	s_nop 0
	global_load_dwordx4 v[48:51], v[48:49], off nt
	v_add_co_u32_e32 v56, vcc, s90, v72
	s_nop 1
	v_addc_co_u32_e32 v57, vcc, 0, v73, vcc
	global_load_dwordx4 v[52:55], v[56:57], off offset:-4096 nt
	s_nop 0
	global_load_dwordx4 v[56:59], v[56:57], off nt
	v_add_co_u32_e32 v64, vcc, s80, v72
	v_cvt_pk_bf16_f32 v72, v4, v8
	s_nop 0
	v_addc_co_u32_e32 v65, vcc, 0, v73, vcc
	global_load_dwordx4 v[60:63], v[64:65], off offset:-4096 nt
	s_nop 0
	global_load_dwordx4 v[64:67], v[64:65], off nt
	s_waitcnt vmcnt(13)
	s_waitcnt vmcnt(12)
	v_cvt_pk_bf16_f32 v73, v12, v16
	s_waitcnt vmcnt(11)
	s_waitcnt vmcnt(10)
	v_cvt_pk_bf16_f32 v74, v20, v24
	s_waitcnt vmcnt(9)
	s_waitcnt vmcnt(8)
	v_cvt_pk_bf16_f32 v75, v28, v32
	v_bfe_u32 v2, v5, 16, 1
	v_add3_u32 v2, v5, v2, s76
	v_bfe_u32 v4, v9, 16, 1
	v_lshrrev_b32_e32 v2, 16, v2
	v_add3_u32 v4, v9, v4, s76
	global_store_dwordx4 v[68:69], v[72:75], off offset:64
	s_nop 1
	v_and_or_b32 v72, v4, s77, v2
	s_nop 1
	v_cvt_pk_bf16_f32 v73, v13, v17
	v_cvt_pk_bf16_f32 v74, v21, v25
	v_cvt_pk_bf16_f32 v75, v29, v33
	v_bfe_u32 v2, v6, 16, 1
	v_add3_u32 v2, v6, v2, s76
	v_bfe_u32 v4, v10, 16, 1
	v_lshrrev_b32_e32 v2, 16, v2
	v_add3_u32 v4, v10, v4, s76
	global_store_dwordx4 v[68:69], v[72:75], off offset:2112
	s_nop 1
	v_and_or_b32 v72, v4, s77, v2
	s_nop 1
	v_cvt_pk_bf16_f32 v73, v14, v18
	v_cvt_pk_bf16_f32 v74, v22, v26
	v_cvt_pk_bf16_f32 v75, v30, v34
	v_cvt_pk_bf16_f32 v4, v7, v11
	v_cvt_pk_bf16_f32 v5, v15, v19
	v_cvt_pk_bf16_f32 v6, v23, v27
	v_cvt_pk_bf16_f32 v7, v31, v35
	s_waitcnt vmcnt(9)
	global_store_dwordx4 v[70:71], v[4:7], off offset:2112
	s_waitcnt vmcnt(9)
	s_nop 1
	v_cvt_pk_bf16_f32 v4, v36, v40
	s_waitcnt vmcnt(8)
	s_waitcnt vmcnt(7)
	v_cvt_pk_bf16_f32 v5, v44, v48
	s_waitcnt vmcnt(6)
	s_waitcnt vmcnt(5)
	v_cvt_pk_bf16_f32 v6, v52, v56
	s_waitcnt vmcnt(4)
	s_waitcnt vmcnt(3)
	v_cvt_pk_bf16_f32 v7, v60, v64
	global_store_dwordx4 v[68:69], v[4:7], off offset:96
	s_nop 1
	v_cvt_pk_bf16_f32 v4, v37, v41
	s_nop 1
	v_cvt_pk_bf16_f32 v5, v45, v49
	v_cvt_pk_bf16_f32 v6, v53, v57
	v_cvt_pk_bf16_f32 v7, v61, v65
	global_store_dwordx4 v[68:69], v[4:7], off offset:2144
	s_nop 1
	v_cvt_pk_bf16_f32 v4, v38, v42
	s_nop 1
	v_cvt_pk_bf16_f32 v5, v46, v50
	v_cvt_pk_bf16_f32 v6, v54, v58
	v_cvt_pk_bf16_f32 v7, v62, v66
	global_store_dwordx4 v[70:71], v[4:7], off offset:96
	s_nop 1
	v_cvt_pk_bf16_f32 v4, v39, v43
	s_nop 1
	v_cvt_pk_bf16_f32 v5, v47, v51
	v_cvt_pk_bf16_f32 v6, v55, v59
	v_cvt_pk_bf16_f32 v7, v63, v67
	global_store_dwordx4 v[70:71], v[72:75], off offset:64
	global_store_dwordx4 v[70:71], v[4:7], off offset:2144

.LBB0_519:
	s_andn2_b64 vcc, exec, s[16:17]
	s_cbranch_vccnz .LBB0_521
	s_mov_b64 s[16:17], s[0:1]
	s_mov_b64 s[26:27], s[0:1]
	s_load_dwordx2 s[16:17], s[16:17], 0x50
	s_lshl_b32 s24, s23, 3
	s_load_dwordx2 s[26:27], s[26:27], 0xa8
	s_addk_i32 s24, 0x500
	s_and_b32 s60, s24, 0x7c0
	s_lshl_b32 s24, s23, 7
	s_and_b32 s24, s24, 0x380
	v_or_b32_e32 v6, s24, v155
	v_lshlrev_b32_e32 v2, 11, v6
	s_waitcnt lgkmcnt(0)
	v_lshl_add_u64 v[4:5], s[26:27], 0, v[2:3]
	s_lshl_b32 s24, s60, 1
	v_lshl_add_u64 v[4:5], v[4:5], 0, s[24:25]
	v_lshlrev_b32_e32 v2, 1, v116
	v_lshl_add_u64 v[70:71], v[4:5], 0, v[2:3]
	v_or_b32_e32 v7, s60, v116
	v_lshlrev_b32_e32 v2, 2, v6
	v_lshl_add_u64 v[4:5], s[16:17], 0, v[2:3]
	v_lshlrev_b32_e32 v2, 12, v7
	v_lshl_add_u64 v[72:73], v[4:5], 0, v[2:3]
	v_add_co_u32_e32 v4, vcc, s81, v72
	global_load_dwordx4 v[36:39], v[72:73], off nt
	s_nop 0
	v_addc_co_u32_e32 v5, vcc, 0, v73, vcc
	global_load_dwordx4 v[52:55], v[4:5], off offset:-4096 nt
	global_load_dwordx4 v[40:43], v[4:5], off nt
	v_add_co_u32_e32 v4, vcc, s70, v72
	s_mov_b64 s[16:17], 0x4c00000
	s_nop 0
	v_addc_co_u32_e32 v5, vcc, 0, v73, vcc
	global_load_dwordx4 v[56:59], v[4:5], off offset:-4096 nt
	global_load_dwordx4 v[44:47], v[4:5], off nt
	v_add_co_u32_e32 v4, vcc, s72, v72
	v_lshl_add_u64 v[68:69], v[70:71], 0, s[16:17]
	s_nop 0
	v_addc_co_u32_e32 v5, vcc, 0, v73, vcc
	global_load_dwordx4 v[60:63], v[4:5], off offset:-4096 nt
	global_load_dwordx4 v[48:51], v[4:5], off nt
	v_add_co_u32_e32 v4, vcc, s73, v72
	s_mov_b32 s16, 0x4c01000
	s_nop 0
	v_addc_co_u32_e32 v5, vcc, 0, v73, vcc
	global_load_dwordx4 v[64:67], v[4:5], off nt
	v_add_co_u32_e32 v4, vcc, s83, v72
	s_waitcnt vmcnt(7)
	v_bfe_u32 v2, v36, 16, 1
	v_addc_co_u32_e32 v5, vcc, 0, v73, vcc
	v_add_co_u32_e32 v6, vcc, s86, v72
	v_add3_u32 v2, v36, v2, s76
	s_nop 0
	v_addc_co_u32_e32 v7, vcc, 0, v73, vcc
	v_add_co_u32_e32 v12, vcc, s87, v72
	s_waitcnt vmcnt(6)
	v_bfe_u32 v36, v52, 16, 1
	v_addc_co_u32_e32 v13, vcc, 0, v73, vcc
	v_add_co_u32_e32 v14, vcc, s88, v72
	s_waitcnt vmcnt(5)
	v_bfe_u32 v74, v40, 16, 1
	v_addc_co_u32_e32 v15, vcc, 0, v73, vcc
	global_load_dwordx4 v[32:35], v[4:5], off offset:-4096 nt
	global_load_dwordx4 v[28:31], v[4:5], off nt
	global_load_dwordx4 v[24:27], v[6:7], off offset:-4096 nt
	global_load_dwordx4 v[16:19], v[6:7], off nt
	global_load_dwordx4 v[8:11], v[12:13], off offset:-4096 nt
	s_nop 0
	global_load_dwordx4 v[4:7], v[12:13], off nt
	global_load_dwordx4 v[20:23], v[14:15], off offset:-4096 nt
	s_nop 0
	global_load_dwordx4 v[12:15], v[14:15], off nt
	s_waitcnt vmcnt(12)
	v_bfe_u32 v75, v56, 16, 1
	s_waitcnt vmcnt(11)
	v_bfe_u32 v76, v44, 16, 1
	v_lshrrev_b32_e32 v2, 16, v2
	v_add3_u32 v36, v52, v36, s76
	v_add3_u32 v40, v40, v74, s76
	s_waitcnt vmcnt(10)
	v_bfe_u32 v77, v60, 16, 1
	s_waitcnt vmcnt(9)
	v_add3_u32 v52, v56, v75, s76
	v_add3_u32 v44, v44, v76, s76
	v_and_or_b32 v74, v36, s77, v2
	v_lshrrev_b32_e32 v2, 16, v40
	s_waitcnt vmcnt(8)
	v_add3_u32 v56, v60, v77, s76
	v_lshrrev_b32_e32 v36, 16, v44
	v_and_or_b32 v75, v52, s77, v2
	v_bfe_u32 v2, v37, 16, 1
	v_and_or_b32 v76, v56, s77, v36
	v_add_co_u32_e32 v70, vcc, s16, v70
	v_add3_u32 v2, v37, v2, s76
	v_bfe_u32 v36, v53, 16, 1
	v_cvt_pk_bf16_f32 v77, v48, v64
	v_addc_co_u32_e32 v71, vcc, 0, v71, vcc
	v_lshrrev_b32_e32 v2, 16, v2
	v_add3_u32 v36, v53, v36, s76
	global_store_dwordx4 v[70:71], v[74:77], off offset:-4096
	s_nop 1
	v_and_or_b32 v74, v36, s77, v2
	s_nop 1
	v_cvt_pk_bf16_f32 v75, v41, v57
	v_cvt_pk_bf16_f32 v76, v45, v61
	v_cvt_pk_bf16_f32 v77, v49, v65
	v_bfe_u32 v2, v38, 16, 1
	v_add3_u32 v2, v38, v2, s76
	v_bfe_u32 v36, v54, 16, 1
	v_lshrrev_b32_e32 v2, 16, v2
	v_add3_u32 v36, v54, v36, s76
	global_store_dwordx4 v[68:69], v[74:77], off offset:2048
	s_nop 1
	v_and_or_b32 v74, v36, s77, v2
	s_nop 1
	v_cvt_pk_bf16_f32 v75, v42, v58
	v_cvt_pk_bf16_f32 v76, v46, v62
	v_cvt_pk_bf16_f32 v77, v50, v66
	v_cvt_pk_bf16_f32 v36, v39, v55
	v_cvt_pk_bf16_f32 v37, v43, v59
	v_cvt_pk_bf16_f32 v38, v47, v63
	v_cvt_pk_bf16_f32 v39, v51, v67
	s_waitcnt vmcnt(9)
	s_waitcnt vmcnt(8)
	global_store_dwordx4 v[70:71], v[36:39], off offset:2048
	global_store_dwordx4 v[70:71], v[74:77], off
	s_nop 0
	v_cvt_pk_bf16_f32 v36, v32, v28
	s_waitcnt vmcnt(9)
	s_waitcnt vmcnt(8)
	v_cvt_pk_bf16_f32 v37, v24, v16
	s_waitcnt vmcnt(7)
	s_waitcnt vmcnt(6)
	v_cvt_pk_bf16_f32 v38, v8, v4
	s_waitcnt vmcnt(5)
	s_waitcnt vmcnt(4)
	v_cvt_pk_bf16_f32 v39, v20, v12
	global_store_dwordx4 v[68:69], v[36:39], off offset:32
	v_add_co_u32_e32 v8, vcc, s75, v72
	s_nop 0
	v_cvt_pk_bf16_f32 v36, v33, v29
	v_cvt_pk_bf16_f32 v37, v25, v17
	v_cvt_pk_bf16_f32 v38, v9, v5
	v_cvt_pk_bf16_f32 v39, v21, v13
	global_store_dwordx4 v[68:69], v[36:39], off offset:2080
	s_nop 1
	v_cvt_pk_bf16_f32 v36, v34, v30
	s_nop 1
	v_cvt_pk_bf16_f32 v37, v26, v18
	v_cvt_pk_bf16_f32 v38, v10, v6
	v_cvt_pk_bf16_f32 v39, v22, v14
	v_cvt_pk_bf16_f32 v4, v35, v31
	v_cvt_pk_bf16_f32 v5, v27, v19
	v_cvt_pk_bf16_f32 v6, v11, v7
	v_cvt_pk_bf16_f32 v7, v23, v15
	global_store_dwordx4 v[70:71], v[36:39], off offset:32
	global_store_dwordx4 v[70:71], v[4:7], off offset:2080
	v_addc_co_u32_e32 v9, vcc, 0, v73, vcc
	global_load_dwordx4 v[4:7], v[8:9], off offset:-4096 nt
	s_nop 0
	global_load_dwordx4 v[8:11], v[8:9], off nt
	v_add_co_u32_e32 v16, vcc, s89, v72
	s_waitcnt vmcnt(1)
	v_addc_co_u32_e32 v17, vcc, 0, v73, vcc
	global_load_dwordx4 v[12:15], v[16:17], off offset:-4096 nt
	s_nop 0
	global_load_dwordx4 v[16:19], v[16:17], off nt
	v_add_co_u32_e32 v24, vcc, s84, v72
	s_nop 0
	v_addc_co_u32_e32 v25, vcc, 0, v73, vcc
	global_load_dwordx4 v[20:23], v[24:25], off offset:-4096 nt
	s_nop 0
	global_load_dwordx4 v[24:27], v[24:25], off nt
	v_add_co_u32_e32 v32, vcc, s85, v72
	s_waitcnt vmcnt(4)
	v_addc_co_u32_e32 v33, vcc, 0, v73, vcc
	global_load_dwordx4 v[28:31], v[32:33], off offset:-4096 nt
	s_nop 0
	global_load_dwordx4 v[32:35], v[32:33], off nt
	v_add_co_u32_e32 v40, vcc, s78, v72
	s_nop 0
	v_addc_co_u32_e32 v41, vcc, 0, v73, vcc
	global_load_dwordx4 v[36:39], v[40:41], off offset:-4096 nt
	s_nop 0
	global_load_dwordx4 v[40:43], v[40:41], off nt
	v_add_co_u32_e32 v48, vcc, s79, v72
	s_nop 0
	v_addc_co_u32_e32 v49, vcc, 0, v73, vcc
	global_load_dwordx4 v[44:47], v[48:49], off offset:-4096 nt
	s_nop 0
	global_load_dwordx4 v[48:51], v[48:49], off nt
	v_add_co_u32_e32 v56, vcc, s90, v72
	s_nop 1
	v_addc_co_u32_e32 v57, vcc, 0, v73, vcc
	global_load_dwordx4 v[52:55], v[56:57], off offset:-4096 nt
	s_nop 0
	global_load_dwordx4 v[56:59], v[56:57], off nt
	v_add_co_u32_e32 v64, vcc, s80, v72
	v_cvt_pk_bf16_f32 v72, v4, v8
	s_nop 0
	v_addc_co_u32_e32 v65, vcc, 0, v73, vcc
	global_load_dwordx4 v[60:63], v[64:65], off offset:-4096 nt
	s_nop 0
	global_load_dwordx4 v[64:67], v[64:65], off nt
	s_waitcnt vmcnt(13)
	s_waitcnt vmcnt(12)
	v_cvt_pk_bf16_f32 v73, v12, v16
	s_waitcnt vmcnt(11)
	s_waitcnt vmcnt(10)
	v_cvt_pk_bf16_f32 v74, v20, v24
	s_waitcnt vmcnt(9)
	s_waitcnt vmcnt(8)
	v_cvt_pk_bf16_f32 v75, v28, v32
	v_bfe_u32 v2, v5, 16, 1
	v_add3_u32 v2, v5, v2, s76
	v_bfe_u32 v4, v9, 16, 1
	v_lshrrev_b32_e32 v2, 16, v2
	v_add3_u32 v4, v9, v4, s76
	global_store_dwordx4 v[68:69], v[72:75], off offset:64
	s_nop 1
	v_and_or_b32 v72, v4, s77, v2
	s_nop 1
	v_cvt_pk_bf16_f32 v73, v13, v17
	v_cvt_pk_bf16_f32 v74, v21, v25
	v_cvt_pk_bf16_f32 v75, v29, v33
	v_bfe_u32 v2, v6, 16, 1
	v_add3_u32 v2, v6, v2, s76
	v_bfe_u32 v4, v10, 16, 1
	v_lshrrev_b32_e32 v2, 16, v2
	v_add3_u32 v4, v10, v4, s76
	global_store_dwordx4 v[68:69], v[72:75], off offset:2112
	s_nop 1
	v_and_or_b32 v72, v4, s77, v2
	s_nop 1
	v_cvt_pk_bf16_f32 v73, v14, v18
	v_cvt_pk_bf16_f32 v74, v22, v26
	v_cvt_pk_bf16_f32 v75, v30, v34
	v_cvt_pk_bf16_f32 v4, v7, v11
	v_cvt_pk_bf16_f32 v5, v15, v19
	v_cvt_pk_bf16_f32 v6, v23, v27
	v_cvt_pk_bf16_f32 v7, v31, v35
	s_waitcnt vmcnt(9)
	global_store_dwordx4 v[70:71], v[4:7], off offset:2112
	s_waitcnt vmcnt(9)
	s_nop 1
	v_cvt_pk_bf16_f32 v4, v36, v40
	s_waitcnt vmcnt(8)
	s_waitcnt vmcnt(7)
	v_cvt_pk_bf16_f32 v5, v44, v48
	s_waitcnt vmcnt(6)
	s_waitcnt vmcnt(5)
	v_cvt_pk_bf16_f32 v6, v52, v56
	s_waitcnt vmcnt(4)
	s_waitcnt vmcnt(3)
	v_cvt_pk_bf16_f32 v7, v60, v64
	global_store_dwordx4 v[68:69], v[4:7], off offset:96
	s_nop 1
	v_cvt_pk_bf16_f32 v4, v37, v41
	s_nop 1
	v_cvt_pk_bf16_f32 v5, v45, v49
	v_cvt_pk_bf16_f32 v6, v53, v57
	v_cvt_pk_bf16_f32 v7, v61, v65
	global_store_dwordx4 v[68:69], v[4:7], off offset:2144
	s_nop 1
	v_cvt_pk_bf16_f32 v4, v38, v42
	s_nop 1
	v_cvt_pk_bf16_f32 v5, v46, v50
	v_cvt_pk_bf16_f32 v6, v54, v58
	v_cvt_pk_bf16_f32 v7, v62, v66
	global_store_dwordx4 v[70:71], v[4:7], off offset:96
	s_nop 1
	v_cvt_pk_bf16_f32 v4, v39, v43
	s_nop 1
	v_cvt_pk_bf16_f32 v5, v47, v51
	v_cvt_pk_bf16_f32 v6, v55, v59
	v_cvt_pk_bf16_f32 v7, v63, v67
	global_store_dwordx4 v[70:71], v[72:75], off offset:64
	global_store_dwordx4 v[70:71], v[4:7], off offset:2144

.LBB0_527:
	s_mov_b64 s[26:27], s[0:1]
	s_load_dwordx2 s[26:27], s[26:27], 0xa8
	s_lshr_b32 s60, s60, 24
	s_add_i32 s62, s60, 1
	s_mul_i32 s60, s60, 0xfea0
	s_add_i32 s24, s60, s24
	s_mul_i32 s60, s62, 0x580000
	s_waitcnt lgkmcnt(0)
	s_add_u32 s60, s26, s60
	s_sext_i32_i16 s26, s24
	s_addc_u32 s61, s27, 0
	s_bfe_u32 s26, s26, 0x3001c
	s_add_i32 s26, s24, s26
	s_sext_i32_i16 s27, s26
	s_and_b32 s26, s26, 0xfff8
	s_sub_i32 s24, s24, s26
	s_sext_i32_i16 s24, s24
	v_lshl_or_b32 v8, s24, 7, v155
	s_lshl_b32 s26, s27, 3
	v_mul_i32_i24_e32 v4, 0xb00, v8
	s_andn2_b32 s26, s26, 63
	v_ashrrev_i32_e32 v5, 31, v4
	v_lshl_add_u64 v[4:5], v[4:5], 1, s[60:61]
	s_ashr_i32 s27, s26, 31
	v_lshl_add_u64 v[4:5], s[26:27], 1, v[4:5]
	v_lshlrev_b32_e32 v2, 1, v116
	v_lshl_add_u64 v[4:5], v[4:5], 0, v[2:3]
	s_mov_b64 s[60:61], 0x3000000
	v_lshl_add_u64 v[4:5], v[4:5], 0, s[60:61]
	s_cmp_gt_i32 s24, -1
	s_mov_b64 s[60:61], -1
	s_cbranch_scc0 .LBB0_529
	s_load_dwordx2 s[16:17], s[16:17], 0x0
	s_lshr_b32 s24, s62, 1
	v_or_b32_e32 v6, s26, v116
	s_mul_i32 s24, s24, 0xb00000
	v_or_b32_e32 v12, 1, v6
	s_waitcnt lgkmcnt(0)
	s_add_u32 s16, s16, s24
	v_mov_b32_e32 v9, v3
	s_addc_u32 s17, s17, 0
	v_ashrrev_i32_e32 v7, 31, v6
	v_ashrrev_i32_e32 v13, 31, v12
	v_lshl_add_u64 v[8:9], v[8:9], 2, s[16:17]
	v_lshlrev_b64 v[10:11], 12, v[6:7]
	v_lshlrev_b64 v[12:13], 12, v[12:13]
	v_lshl_add_u64 v[10:11], v[8:9], 0, v[10:11]
	v_lshl_add_u64 v[16:17], v[8:9], 0, v[12:13]
	global_load_dwordx4 v[12:15], v[10:11], off nt
	s_nop 0
	global_load_dwordx4 v[16:19], v[16:17], off nt
	v_or_b32_e32 v10, 2, v6
	v_or_b32_e32 v20, 3, v6
	v_ashrrev_i32_e32 v11, 31, v10
	v_ashrrev_i32_e32 v21, 31, v20
	v_lshlrev_b64 v[10:11], 12, v[10:11]
	v_lshlrev_b64 v[20:21], 12, v[20:21]
	v_lshl_add_u64 v[10:11], v[8:9], 0, v[10:11]
	v_lshl_add_u64 v[24:25], v[8:9], 0, v[20:21]
	global_load_dwordx4 v[20:23], v[10:11], off nt
	s_nop 0
	global_load_dwordx4 v[24:27], v[24:25], off nt
	v_or_b32_e32 v10, 4, v6
	v_or_b32_e32 v28, 5, v6
	v_ashrrev_i32_e32 v11, 31, v10
	v_ashrrev_i32_e32 v29, 31, v28
	v_lshlrev_b64 v[10:11], 12, v[10:11]
	v_lshlrev_b64 v[28:29], 12, v[28:29]
	v_lshl_add_u64 v[10:11], v[8:9], 0, v[10:11]
	v_lshl_add_u64 v[32:33], v[8:9], 0, v[28:29]
	global_load_dwordx4 v[28:31], v[10:11], off nt
	s_nop 0
	global_load_dwordx4 v[32:35], v[32:33], off nt
	v_or_b32_e32 v10, 6, v6
	v_ashrrev_i32_e32 v11, 31, v10
	v_lshlrev_b64 v[10:11], 12, v[10:11]
	v_lshl_add_u64 v[10:11], v[8:9], 0, v[10:11]
	global_load_dwordx4 v[36:39], v[10:11], off nt
	v_or_b32_e32 v10, 7, v6
	v_ashrrev_i32_e32 v11, 31, v10
	v_lshlrev_b64 v[10:11], 12, v[10:11]
	v_lshl_add_u64 v[10:11], v[8:9], 0, v[10:11]
	global_load_dwordx4 v[40:43], v[10:11], off nt
	v_or_b32_e32 v10, 16, v6
	v_or_b32_e32 v44, 17, v6
	v_or_b32_e32 v46, 18, v6
	v_or_b32_e32 v48, 19, v6
	v_or_b32_e32 v50, 20, v6
	v_or_b32_e32 v52, 21, v6
	v_or_b32_e32 v54, 22, v6
	v_or_b32_e32 v56, 23, v6
	v_ashrrev_i32_e32 v11, 31, v10
	v_ashrrev_i32_e32 v45, 31, v44
	v_ashrrev_i32_e32 v47, 31, v46
	v_ashrrev_i32_e32 v49, 31, v48
	v_ashrrev_i32_e32 v51, 31, v50
	v_ashrrev_i32_e32 v53, 31, v52
	v_ashrrev_i32_e32 v55, 31, v54
	v_ashrrev_i32_e32 v57, 31, v56
	v_lshlrev_b64 v[10:11], 12, v[10:11]
	v_lshlrev_b64 v[44:45], 12, v[44:45]
	v_lshlrev_b64 v[46:47], 12, v[46:47]
	v_lshlrev_b64 v[48:49], 12, v[48:49]
	v_lshlrev_b64 v[50:51], 12, v[50:51]
	v_lshlrev_b64 v[52:53], 12, v[52:53]
	v_lshlrev_b64 v[54:55], 12, v[54:55]
	v_lshlrev_b64 v[56:57], 12, v[56:57]
	v_lshl_add_u64 v[10:11], v[8:9], 0, v[10:11]
	v_lshl_add_u64 v[58:59], v[8:9], 0, v[44:45]
	v_lshl_add_u64 v[60:61], v[8:9], 0, v[46:47]
	v_lshl_add_u64 v[62:63], v[8:9], 0, v[48:49]
	v_lshl_add_u64 v[64:65], v[8:9], 0, v[50:51]
	v_lshl_add_u64 v[66:67], v[8:9], 0, v[52:53]
	v_lshl_add_u64 v[68:69], v[8:9], 0, v[54:55]
	v_lshl_add_u64 v[72:73], v[8:9], 0, v[56:57]
	global_load_dwordx4 v[44:47], v[10:11], off nt
	global_load_dwordx4 v[48:51], v[58:59], off nt
	global_load_dwordx4 v[52:55], v[60:61], off nt
	s_nop 0
	global_load_dwordx4 v[56:59], v[62:63], off nt
	s_nop 0
	global_load_dwordx4 v[60:63], v[64:65], off nt
	s_nop 0
	global_load_dwordx4 v[64:67], v[66:67], off nt
	s_nop 0
	global_load_dwordx4 v[68:71], v[68:69], off nt
	s_nop 0
	global_load_dwordx4 v[72:75], v[72:73], off nt
	v_add_co_u32_e32 v10, vcc, s69, v4
	s_mov_b64 s[60:61], 0
	s_nop 0
	v_addc_co_u32_e32 v11, vcc, 0, v5, vcc
	s_waitcnt vmcnt(15)
	s_waitcnt vmcnt(14)
	v_cvt_pk_bf16_f32 v76, v12, v16
	v_add_co_u32_e32 v12, vcc, s81, v4
	s_waitcnt vmcnt(13)
	s_waitcnt vmcnt(12)
	v_cvt_pk_bf16_f32 v77, v20, v24
	v_or_b32_e32 v24, 34, v6
	s_waitcnt vmcnt(11)
	s_waitcnt vmcnt(10)
	v_cvt_pk_bf16_f32 v78, v28, v32
	s_waitcnt vmcnt(9)
	v_or_b32_e32 v32, 36, v6
	s_waitcnt vmcnt(8)
	v_cvt_pk_bf16_f32 v79, v36, v40
	v_bfe_u32 v2, v13, 16, 1
	v_add3_u32 v2, v13, v2, s76
	v_bfe_u32 v7, v17, 16, 1
	v_lshrrev_b32_e32 v2, 16, v2
	v_add3_u32 v7, v17, v7, s76
	global_store_dwordx4 v[4:5], v[76:79], off
	v_addc_co_u32_e32 v13, vcc, 0, v5, vcc
	s_nop 0
	v_and_or_b32 v76, v7, s77, v2
	v_cvt_pk_bf16_f32 v77, v21, v25
	v_cvt_pk_bf16_f32 v78, v29, v33
	v_cvt_pk_bf16_f32 v79, v37, v41
	v_bfe_u32 v2, v14, 16, 1
	v_add3_u32 v2, v14, v2, s76
	v_bfe_u32 v7, v18, 16, 1
	v_lshrrev_b32_e32 v2, 16, v2
	v_add3_u32 v7, v18, v7, s76
	global_store_dwordx4 v[10:11], v[76:79], off offset:1536
	v_add_co_u32_e32 v14, vcc, s70, v4
	s_nop 0
	v_and_or_b32 v76, v7, s77, v2
	v_cvt_pk_bf16_f32 v77, v22, v26
	v_cvt_pk_bf16_f32 v78, v30, v34
	v_cvt_pk_bf16_f32 v79, v38, v42
	v_cvt_pk_bf16_f32 v16, v15, v19
	v_cvt_pk_bf16_f32 v17, v23, v27
	v_cvt_pk_bf16_f32 v18, v31, v35
	v_cvt_pk_bf16_f32 v19, v39, v43
	s_waitcnt vmcnt(9)
	s_waitcnt vmcnt(8)
	v_addc_co_u32_e32 v15, vcc, 0, v5, vcc
	global_store_dwordx4 v[14:15], v[16:19], off offset:512
	global_store_dwordx4 v[12:13], v[76:79], off offset:3072
	v_or_b32_e32 v26, 35, v6
	v_cvt_pk_bf16_f32 v16, v44, v48
	s_waitcnt vmcnt(9)
	s_waitcnt vmcnt(8)
	v_cvt_pk_bf16_f32 v17, v52, v56
	s_waitcnt vmcnt(7)
	s_waitcnt vmcnt(6)
	v_cvt_pk_bf16_f32 v18, v60, v64
	s_waitcnt vmcnt(5)
	s_waitcnt vmcnt(4)
	v_cvt_pk_bf16_f32 v19, v68, v72
	global_store_dwordx4 v[4:5], v[16:19], off offset:32
	v_ashrrev_i32_e32 v25, 31, v24
	v_ashrrev_i32_e32 v27, 31, v26
	v_cvt_pk_bf16_f32 v16, v45, v49
	v_cvt_pk_bf16_f32 v17, v53, v57
	v_cvt_pk_bf16_f32 v18, v61, v65
	v_cvt_pk_bf16_f32 v19, v69, v73
	global_store_dwordx4 v[10:11], v[16:19], off offset:1568
	v_lshlrev_b64 v[24:25], 12, v[24:25]
	v_lshlrev_b64 v[26:27], 12, v[26:27]
	v_cvt_pk_bf16_f32 v16, v46, v50
	v_cvt_pk_bf16_f32 v17, v54, v58
	v_cvt_pk_bf16_f32 v18, v62, v66
	v_cvt_pk_bf16_f32 v19, v70, v74
	global_store_dwordx4 v[12:13], v[16:19], off offset:3104
	v_lshl_add_u64 v[24:25], v[8:9], 0, v[24:25]
	v_lshl_add_u64 v[28:29], v[8:9], 0, v[26:27]
	v_cvt_pk_bf16_f32 v16, v47, v51
	v_cvt_pk_bf16_f32 v17, v55, v59
	v_cvt_pk_bf16_f32 v18, v63, v67
	v_cvt_pk_bf16_f32 v19, v71, v75
	global_store_dwordx4 v[14:15], v[16:19], off offset:544
	v_or_b32_e32 v34, 37, v6
	v_ashrrev_i32_e32 v33, 31, v32
	v_or_b32_e32 v16, 32, v6
	v_or_b32_e32 v18, 33, v6
	v_ashrrev_i32_e32 v17, 31, v16
	v_ashrrev_i32_e32 v19, 31, v18
	v_lshlrev_b64 v[16:17], 12, v[16:17]
	v_lshlrev_b64 v[18:19], 12, v[18:19]
	v_lshl_add_u64 v[16:17], v[8:9], 0, v[16:17]
	v_lshl_add_u64 v[20:21], v[8:9], 0, v[18:19]
	global_load_dwordx4 v[16:19], v[16:17], off nt
	s_nop 0
	global_load_dwordx4 v[20:23], v[20:21], off nt
	s_nop 0
	global_load_dwordx4 v[24:27], v[24:25], off nt
	s_nop 0
	global_load_dwordx4 v[28:31], v[28:29], off nt
	v_ashrrev_i32_e32 v35, 31, v34
	v_lshlrev_b64 v[32:33], 12, v[32:33]
	v_lshlrev_b64 v[34:35], 12, v[34:35]
	v_or_b32_e32 v40, 38, v6
	v_lshl_add_u64 v[32:33], v[8:9], 0, v[32:33]
	v_lshl_add_u64 v[36:37], v[8:9], 0, v[34:35]
	v_ashrrev_i32_e32 v41, 31, v40
	v_or_b32_e32 v44, 39, v6
	global_load_dwordx4 v[32:35], v[32:33], off nt
	s_nop 0
	global_load_dwordx4 v[36:39], v[36:37], off nt
	v_lshlrev_b64 v[40:41], 12, v[40:41]
	v_ashrrev_i32_e32 v45, 31, v44
	v_lshl_add_u64 v[40:41], v[8:9], 0, v[40:41]
	v_lshlrev_b64 v[44:45], 12, v[44:45]
	global_load_dwordx4 v[40:43], v[40:41], off nt
	v_lshl_add_u64 v[44:45], v[8:9], 0, v[44:45]
	global_load_dwordx4 v[44:47], v[44:45], off nt
	v_or_b32_e32 v48, 48, v6
	v_or_b32_e32 v50, 49, v6
	v_ashrrev_i32_e32 v49, 31, v48
	v_ashrrev_i32_e32 v51, 31, v50
	v_lshlrev_b64 v[48:49], 12, v[48:49]
	v_lshlrev_b64 v[50:51], 12, v[50:51]
	v_lshl_add_u64 v[48:49], v[8:9], 0, v[48:49]
	v_lshl_add_u64 v[52:53], v[8:9], 0, v[50:51]
	v_or_b32_e32 v56, 50, v6
	v_or_b32_e32 v58, 51, v6
	global_load_dwordx4 v[48:51], v[48:49], off nt
	s_nop 0
	global_load_dwordx4 v[52:55], v[52:53], off nt
	v_ashrrev_i32_e32 v57, 31, v56
	v_ashrrev_i32_e32 v59, 31, v58
	v_lshlrev_b64 v[56:57], 12, v[56:57]
	v_lshlrev_b64 v[58:59], 12, v[58:59]
	v_lshl_add_u64 v[56:57], v[8:9], 0, v[56:57]
	v_lshl_add_u64 v[60:61], v[8:9], 0, v[58:59]
	v_or_b32_e32 v64, 52, v6
	v_or_b32_e32 v66, 53, v6
	global_load_dwordx4 v[56:59], v[56:57], off nt
	s_nop 0
	global_load_dwordx4 v[60:63], v[60:61], off nt
	v_ashrrev_i32_e32 v65, 31, v64
	v_ashrrev_i32_e32 v67, 31, v66
	v_lshlrev_b64 v[64:65], 12, v[64:65]
	v_lshlrev_b64 v[66:67], 12, v[66:67]
	v_lshl_add_u64 v[64:65], v[8:9], 0, v[64:65]
	v_lshl_add_u64 v[68:69], v[8:9], 0, v[66:67]
	v_or_b32_e32 v72, 54, v6
	v_or_b32_e32 v6, 55, v6
	global_load_dwordx4 v[64:67], v[64:65], off nt
	s_nop 0
	global_load_dwordx4 v[68:71], v[68:69], off nt
	v_ashrrev_i32_e32 v73, 31, v72
	v_ashrrev_i32_e32 v7, 31, v6
	v_lshlrev_b64 v[72:73], 12, v[72:73]
	v_lshlrev_b64 v[6:7], 12, v[6:7]
	v_lshl_add_u64 v[72:73], v[8:9], 0, v[72:73]
	v_lshl_add_u64 v[74:75], v[8:9], 0, v[6:7]
	global_load_dwordx4 v[6:9], v[72:73], off nt
	s_nop 0
	global_load_dwordx4 v[72:75], v[74:75], off nt
	s_waitcnt vmcnt(15)
	s_waitcnt vmcnt(14)
	v_cvt_pk_bf16_f32 v76, v16, v20
	s_waitcnt vmcnt(13)
	s_waitcnt vmcnt(12)
	v_cvt_pk_bf16_f32 v77, v24, v28
	s_waitcnt vmcnt(11)
	s_waitcnt vmcnt(10)
	v_cvt_pk_bf16_f32 v78, v32, v36
	s_waitcnt vmcnt(9)
	s_waitcnt vmcnt(8)
	v_cvt_pk_bf16_f32 v79, v40, v44
	v_bfe_u32 v2, v17, 16, 1
	v_add3_u32 v2, v17, v2, s76
	v_bfe_u32 v16, v21, 16, 1
	v_lshrrev_b32_e32 v2, 16, v2
	v_add3_u32 v16, v21, v16, s76
	global_store_dwordx4 v[4:5], v[76:79], off offset:64
	s_nop 1
	v_and_or_b32 v76, v16, s77, v2
	s_nop 1
	v_cvt_pk_bf16_f32 v77, v25, v29
	v_cvt_pk_bf16_f32 v78, v33, v37
	v_cvt_pk_bf16_f32 v79, v41, v45
	v_bfe_u32 v2, v18, 16, 1
	v_add3_u32 v2, v18, v2, s76
	v_bfe_u32 v16, v22, 16, 1
	v_lshrrev_b32_e32 v2, 16, v2
	v_add3_u32 v16, v22, v16, s76
	global_store_dwordx4 v[10:11], v[76:79], off offset:1600
	s_nop 1
	v_and_or_b32 v76, v16, s77, v2
	s_nop 1
	v_cvt_pk_bf16_f32 v77, v26, v30
	v_cvt_pk_bf16_f32 v78, v34, v38
	v_cvt_pk_bf16_f32 v79, v42, v46
	v_cvt_pk_bf16_f32 v16, v19, v23
	v_cvt_pk_bf16_f32 v17, v27, v31
	v_cvt_pk_bf16_f32 v18, v35, v39
	v_cvt_pk_bf16_f32 v19, v43, v47
	s_waitcnt vmcnt(9)
	global_store_dwordx4 v[14:15], v[16:19], off offset:576
	s_waitcnt vmcnt(9)
	s_nop 1
	v_cvt_pk_bf16_f32 v16, v48, v52
	s_waitcnt vmcnt(8)
	s_waitcnt vmcnt(7)
	v_cvt_pk_bf16_f32 v17, v56, v60
	s_waitcnt vmcnt(6)
	s_waitcnt vmcnt(5)
	v_cvt_pk_bf16_f32 v18, v64, v68
	s_waitcnt vmcnt(4)
	s_waitcnt vmcnt(3)
	v_cvt_pk_bf16_f32 v19, v6, v72
	global_store_dwordx4 v[4:5], v[16:19], off offset:96
	global_store_dwordx4 v[12:13], v[76:79], off offset:3136
	s_nop 0
	v_cvt_pk_bf16_f32 v16, v49, v53
	v_cvt_pk_bf16_f32 v17, v57, v61
	v_cvt_pk_bf16_f32 v18, v65, v69
	v_cvt_pk_bf16_f32 v19, v7, v73
	global_store_dwordx4 v[10:11], v[16:19], off offset:1632
	s_nop 1
	v_cvt_pk_bf16_f32 v16, v50, v54
	s_nop 1
	v_cvt_pk_bf16_f32 v17, v58, v62
	v_cvt_pk_bf16_f32 v18, v66, v70
	v_cvt_pk_bf16_f32 v19, v8, v74
	v_cvt_pk_bf16_f32 v6, v51, v55
	v_cvt_pk_bf16_f32 v7, v59, v63
	v_cvt_pk_bf16_f32 v8, v67, v71
	v_cvt_pk_bf16_f32 v9, v9, v75
	global_store_dwordx4 v[12:13], v[16:19], off offset:3168
	global_store_dwordx4 v[14:15], v[6:9], off offset:608

.LBB0_546:
	s_waitcnt vmcnt(15)
	v_mov_b32_e32 v42, v48
	s_waitcnt vmcnt(13)
	v_mov_b32_e32 v43, v60
	v_pk_mul_f32 v[42:43], v[42:43], v[76:77]
	v_mov_b32_e32 v82, v44
	s_waitcnt vmcnt(12)
	v_mov_b32_e32 v83, v52
	s_waitcnt vmcnt(11)
	v_mov_b32_e32 v86, v64
	s_waitcnt vmcnt(9)
	v_mov_b32_e32 v87, v72
	v_pk_mul_f32 v[82:83], v[82:83], v[96:97]
	v_pk_mul_f32 v[86:87], v[86:87], v[80:81]
	v_mov_b32_e32 v98, v56
	s_waitcnt vmcnt(8)
	v_mov_b32_e32 v99, v68
	v_bfe_u32 v56, v42, 16, 1
	v_pk_mul_f32 v[98:99], v[98:99], v[94:95]
	v_bfe_u32 v52, v82, 16, 1
	v_bfe_u32 v64, v86, 16, 1
	v_bfe_u32 v68, v87, 16, 1
	v_add3_u32 v42, v42, v56, s76
	v_bfe_u32 v2, v99, 16, 1
	v_bfe_u32 v44, v98, 16, 1
	v_add3_u32 v52, v82, v52, s76
	v_bfe_u32 v60, v43, 16, 1
	v_add3_u32 v68, v87, v68, s76
	v_add3_u32 v64, v86, v64, s76
	v_lshrrev_b32_e32 v42, 16, v42
	v_bfe_u32 v48, v83, 16, 1
	v_add3_u32 v44, v98, v44, s76
	v_add3_u32 v2, v99, v2, s76
	v_add3_u32 v43, v43, v60, s76
	v_lshrrev_b32_e32 v56, 16, v64
	v_lshrrev_b32_e32 v60, 16, v68
	v_and_or_b32 v98, v52, s77, v42
	v_mov_b32_e32 v52, v45
	v_mov_b32_e32 v68, v57
	v_add3_u32 v48, v83, v48, s76
	v_lshrrev_b32_e32 v43, 16, v43
	v_and_or_b32 v101, v2, s77, v60
	v_and_or_b32 v100, v44, s77, v56
	v_mov_b32_e32 v60, v49
	v_pk_mul_f32 v[44:45], v[52:53], v[96:97]
	v_mov_b32_e32 v72, v65
	v_pk_mul_f32 v[52:53], v[68:69], v[94:95]
	v_and_or_b32 v99, v48, s77, v43
	v_pk_mul_f32 v[42:43], v[60:61], v[76:77]
	v_pk_mul_f32 v[48:49], v[72:73], v[80:81]
	v_bfe_u32 v2, v53, 16, 1
	v_bfe_u32 v56, v52, 16, 1
	v_bfe_u32 v57, v45, 16, 1
	v_bfe_u32 v60, v44, 16, 1
	v_add3_u32 v60, v44, v60, s76
	v_add3_u32 v57, v45, v57, s76
	v_add3_u32 v44, v52, v56, s76
	v_add3_u32 v2, v53, v2, s76
	v_bfe_u32 v45, v42, 16, 1
	v_bfe_u32 v52, v43, 16, 1
	v_bfe_u32 v53, v48, 16, 1
	v_bfe_u32 v56, v49, 16, 1
	v_add3_u32 v49, v49, v56, s76
	v_add3_u32 v48, v48, v53, s76
	v_add3_u32 v43, v43, v52, s76
	v_add3_u32 v42, v42, v45, s76
	v_lshrrev_b32_e32 v42, 16, v42
	v_lshrrev_b32_e32 v43, 16, v43
	v_lshrrev_b32_e32 v48, 16, v48
	v_lshrrev_b32_e32 v45, 16, v49
	v_and_or_b32 v45, v2, s77, v45
	v_and_or_b32 v44, v44, s77, v48
	v_and_or_b32 v43, v57, s77, v43
	v_and_or_b32 v42, v60, s77, v42
	global_store_dwordx4 v[84:85], v[42:45], off offset:2048
	v_mov_b32_e32 v52, v58
	v_mov_b32_e32 v53, v70
	v_mov_b32_e32 v44, v46
	v_mov_b32_e32 v45, v54
	v_mov_b32_e32 v42, v50
	v_mov_b32_e32 v43, v62
	v_pk_mul_f32 v[44:45], v[44:45], v[96:97]
	v_mov_b32_e32 v48, v66
	v_mov_b32_e32 v49, v74
	v_pk_mul_f32 v[52:53], v[52:53], v[94:95]
	v_pk_mul_f32 v[42:43], v[42:43], v[76:77]
	v_pk_mul_f32 v[48:49], v[48:49], v[80:81]
	v_bfe_u32 v50, v45, 16, 1
	v_bfe_u32 v54, v44, 16, 1
	v_add3_u32 v54, v44, v54, s76
	v_add3_u32 v50, v45, v50, s76
	v_bfe_u32 v45, v42, 16, 1
	v_bfe_u32 v46, v43, 16, 1
	v_add3_u32 v43, v43, v46, s76
	v_add3_u32 v42, v42, v45, s76
	v_lshrrev_b32_e32 v42, 16, v42
	v_lshrrev_b32_e32 v43, 16, v43
	v_add_co_u32_e32 v86, vcc, s69, v84
	v_cvt_pk_bf16_f32 v45, v49, v53
	v_cvt_pk_bf16_f32 v44, v48, v52
	v_and_or_b32 v43, v50, s77, v43
	v_and_or_b32 v42, v54, s77, v42
	v_addc_co_u32_e32 v87, vcc, 0, v85, vcc
	v_mov_b32_e32 v54, v47
	v_mov_b32_e32 v70, v59
	global_store_dwordx4 v[86:87], v[42:45], off
	v_mov_b32_e32 v62, v51
	v_mov_b32_e32 v74, v67
	v_pk_mul_f32 v[44:45], v[54:55], v[96:97]
	v_pk_mul_f32 v[48:49], v[70:71], v[94:95]
	v_pk_mul_f32 v[42:43], v[62:63], v[76:77]
	v_pk_mul_f32 v[46:47], v[74:75], v[80:81]
	v_bfe_u32 v2, v49, 16, 1
	v_bfe_u32 v50, v48, 16, 1
	v_bfe_u32 v51, v45, 16, 1
	v_bfe_u32 v52, v44, 16, 1
	v_add3_u32 v52, v44, v52, s76
	v_add3_u32 v51, v45, v51, s76
	v_add3_u32 v44, v48, v50, s76
	v_add3_u32 v2, v49, v2, s76
	v_bfe_u32 v45, v42, 16, 1
	v_bfe_u32 v48, v43, 16, 1
	v_bfe_u32 v49, v46, 16, 1
	v_bfe_u32 v50, v47, 16, 1
	v_add3_u32 v47, v47, v50, s76
	v_add3_u32 v46, v46, v49, s76
	v_add3_u32 v43, v43, v48, s76
	v_add3_u32 v42, v42, v45, s76
	v_lshrrev_b32_e32 v42, 16, v42
	v_lshrrev_b32_e32 v43, 16, v43
	v_lshrrev_b32_e32 v46, 16, v46
	v_lshrrev_b32_e32 v45, 16, v47
	v_and_or_b32 v45, v2, s77, v45
	v_and_or_b32 v44, v44, s77, v46
	v_and_or_b32 v43, v51, s77, v43
	v_and_or_b32 v42, v52, s77, v42
	s_waitcnt vmcnt(5)
	v_mov_b32_e32 v46, v28
	s_waitcnt vmcnt(3)
	v_mov_b32_e32 v47, v36
	global_store_dwordx4 v[86:87], v[42:45], off offset:2048
	v_pk_mul_f32 v[46:47], v[46:47], v[40:41]
	v_mov_b32_e32 v48, v20
	v_mov_b32_e32 v42, v12
	v_mov_b32_e32 v43, v24
	s_waitcnt vmcnt(3)
	v_mov_b32_e32 v49, v32
	v_pk_mul_f32 v[42:43], v[42:43], v[4:5]
	v_mov_b32_e32 v44, v8
	v_mov_b32_e32 v45, v16
	v_pk_mul_f32 v[48:49], v[48:49], v[6:7]
	v_pk_mul_f32 v[44:45], v[44:45], v[78:79]
	v_bfe_u32 v24, v43, 16, 1
	v_bfe_u32 v12, v45, 16, 1
	v_add3_u32 v24, v43, v24, s76
	v_add3_u32 v12, v45, v12, s76
	v_lshrrev_b32_e32 v24, 16, v24
	v_cvt_pk_bf16_f32 v45, v47, v49
	v_mov_b32_e32 v32, v21
	v_and_or_b32 v43, v12, s77, v24
	v_cvt_pk_bf16_f32 v42, v42, v44
	v_mov_b32_e32 v24, v13
	v_mov_b32_e32 v16, v9
	v_pk_mul_f32 v[20:21], v[32:33], v[6:7]
	v_cvt_pk_bf16_f32 v44, v46, v48
	v_pk_mul_f32 v[12:13], v[24:25], v[4:5]
	v_pk_mul_f32 v[8:9], v[16:17], v[78:79]
	v_mov_b32_e32 v36, v29
	v_bfe_u32 v2, v21, 16, 1
	v_pk_mul_f32 v[16:17], v[36:37], v[40:41]
	v_add3_u32 v2, v21, v2, s76
	v_bfe_u32 v28, v17, 16, 1
	global_store_dwordx4 v[84:85], v[42:45], off offset:32
	v_add3_u32 v17, v17, v28, s76
	s_nop 1
	v_cvt_pk_bf16_f32 v43, v13, v9
	v_cvt_pk_bf16_f32 v42, v12, v8
	v_mov_b32_e32 v12, v10
	v_mov_b32_e32 v13, v18
	v_lshrrev_b32_e32 v17, 16, v17
	v_cvt_pk_bf16_f32 v44, v16, v20
	v_mov_b32_e32 v8, v14
	v_mov_b32_e32 v9, v26
	v_pk_mul_f32 v[12:13], v[12:13], v[78:79]
	v_mov_b32_e32 v20, v22
	v_mov_b32_e32 v21, v34
	v_and_or_b32 v45, v2, s77, v17
	v_pk_mul_f32 v[8:9], v[8:9], v[4:5]
	v_mov_b32_e32 v16, v30
	v_mov_b32_e32 v17, v38
	v_pk_mul_f32 v[20:21], v[20:21], v[6:7]
	v_bfe_u32 v14, v13, 16, 1
	v_bfe_u32 v18, v12, 16, 1
	v_pk_mul_f32 v[16:17], v[16:17], v[40:41]
	v_add3_u32 v12, v12, v18, s76
	v_add3_u32 v13, v13, v14, s76
	v_bfe_u32 v14, v8, 16, 1
	v_bfe_u32 v18, v9, 16, 1
	v_add3_u32 v9, v9, v18, s76
	v_add3_u32 v8, v8, v14, s76
	v_lshrrev_b32_e32 v8, 16, v8
	v_lshrrev_b32_e32 v9, 16, v9
	v_mov_b32_e32 v18, v11
	v_mov_b32_e32 v34, v23
	global_store_dwordx4 v[84:85], v[42:45], off offset:2080
	s_nop 1
	v_and_or_b32 v43, v13, s77, v9
	s_nop 1
	v_and_or_b32 v42, v12, s77, v8
	v_mov_b32_e32 v26, v15
	v_pk_mul_f32 v[8:9], v[18:19], v[78:79]
	v_mov_b32_e32 v38, v31
	v_pk_mul_f32 v[6:7], v[34:35], v[6:7]
	v_cvt_pk_bf16_f32 v45, v17, v21
	v_cvt_pk_bf16_f32 v44, v16, v20
	v_pk_mul_f32 v[4:5], v[26:27], v[4:5]
	v_pk_mul_f32 v[10:11], v[38:39], v[40:41]
	v_bfe_u32 v2, v7, 16, 1
	v_bfe_u32 v14, v8, 16, 1
	v_add3_u32 v8, v8, v14, s76
	v_add3_u32 v2, v7, v2, s76
	v_bfe_u32 v7, v4, 16, 1
	v_bfe_u32 v14, v11, 16, 1
	v_add3_u32 v11, v11, v14, s76
	v_add3_u32 v4, v4, v7, s76
	v_lshrrev_b32_e32 v4, 16, v4
	v_lshrrev_b32_e32 v7, 16, v11
	v_and_or_b32 v7, v2, s77, v7
	v_cvt_pk_bf16_f32 v6, v10, v6
	v_cvt_pk_bf16_f32 v5, v5, v9
	v_and_or_b32 v4, v8, s77, v4
	v_or_b32_e32 v2, 32, v88
	global_store_dwordx4 v[86:87], v[4:7], off offset:2080
	global_store_dwordx4 v[84:85], v[98:101], off
	global_store_dwordx4 v[86:87], v[42:45], off offset:32
	v_mad_i64_i32 v[4:5], s[26:27], v2, s91, v[90:91]
	v_or_b32_e32 v2, 33, v88
	v_mad_i64_i32 v[6:7], s[26:27], v2, s91, v[90:91]
	v_or_b32_e32 v2, 34, v88
	global_load_dwordx4 v[48:51], v[4:5], off nt
	global_load_dwordx4 v[44:47], v[6:7], off nt
	v_mad_i64_i32 v[4:5], s[26:27], v2, s91, v[90:91]
	v_or_b32_e32 v2, 35, v88
	v_mad_i64_i32 v[6:7], s[26:27], v2, s91, v[90:91]
	v_or_b32_e32 v2, 36, v88
	global_load_dwordx4 v[60:63], v[4:5], off nt
	global_load_dwordx4 v[52:55], v[6:7], off nt
	v_mad_i64_i32 v[4:5], s[26:27], v2, s91, v[90:91]
	v_or_b32_e32 v2, 37, v88
	v_mad_i64_i32 v[6:7], s[26:27], v2, s91, v[90:91]
	v_or_b32_e32 v2, 38, v88
	global_load_dwordx4 v[64:67], v[4:5], off nt
	global_load_dwordx4 v[56:59], v[6:7], off nt
	v_mad_i64_i32 v[4:5], s[26:27], v2, s91, v[90:91]
	v_or_b32_e32 v2, 39, v88
	v_mad_i64_i32 v[6:7], s[26:27], v2, s91, v[90:91]
	global_load_dwordx4 v[72:75], v[4:5], off nt
	global_load_dwordx4 v[68:71], v[6:7], off nt
	v_mov_b32_e32 v4, 1.0
	s_and_b64 vcc, exec, s[16:17]
	v_mov_b32_e32 v76, 1.0
	v_mov_b32_e32 v96, 1.0
	v_mov_b32_e32 v77, 1.0
	v_mov_b32_e32 v97, 1.0
	v_mov_b32_e32 v80, 1.0
	v_mov_b32_e32 v94, 1.0
	v_mov_b32_e32 v81, 1.0
	v_mov_b32_e32 v95, 1.0
	s_cbranch_vccnz .LBB0_548
	global_load_dwordx4 v[76:79], v[92:93], off offset:128
	global_load_dwordx4 v[80:83], v[92:93], off offset:144
	s_waitcnt vmcnt(1)
	v_mov_b32_e32 v96, v77
	v_mov_b32_e32 v77, v78
	v_mov_b32_e32 v97, v79
	s_waitcnt vmcnt(0)
	v_mov_b32_e32 v94, v81
	v_mov_b32_e32 v81, v82
	v_mov_b32_e32 v95, v83

.LBB0_550:
	s_waitcnt vmcnt(14)
	v_mov_b32_e32 v34, v44
	s_waitcnt vmcnt(12)
	v_mov_b32_e32 v35, v52
	s_waitcnt vmcnt(11)
	v_mov_b32_e32 v88, v64
	s_waitcnt vmcnt(9)
	v_mov_b32_e32 v89, v72
	v_mov_b32_e32 v6, v48
	v_mov_b32_e32 v7, v60
	v_pk_mul_f32 v[34:35], v[34:35], v[96:97]
	v_pk_mul_f32 v[88:89], v[88:89], v[80:81]
	v_mov_b32_e32 v90, v56
	s_waitcnt vmcnt(8)
	v_mov_b32_e32 v91, v68
	v_pk_mul_f32 v[6:7], v[6:7], v[76:77]
	v_pk_mul_f32 v[90:91], v[90:91], v[94:95]
	v_bfe_u32 v48, v35, 16, 1
	v_bfe_u32 v52, v34, 16, 1
	v_add3_u32 v34, v34, v52, s76
	v_add3_u32 v35, v35, v48, s76
	v_bfe_u32 v48, v6, 16, 1
	v_bfe_u32 v52, v7, 16, 1
	v_add3_u32 v7, v7, v52, s76
	v_add3_u32 v6, v6, v48, s76
	v_lshrrev_b32_e32 v6, 16, v6
	v_lshrrev_b32_e32 v7, 16, v7
	v_cvt_pk_bf16_f32 v91, v89, v91
	v_mov_b32_e32 v52, v45
	v_mov_b32_e32 v68, v57
	v_cvt_pk_bf16_f32 v90, v88, v90
	v_and_or_b32 v89, v35, s77, v7
	v_and_or_b32 v88, v34, s77, v6
	v_mov_b32_e32 v60, v49
	v_pk_mul_f32 v[34:35], v[52:53], v[96:97]
	v_mov_b32_e32 v72, v65
	v_pk_mul_f32 v[48:49], v[68:69], v[94:95]
	v_pk_mul_f32 v[6:7], v[60:61], v[76:77]
	v_pk_mul_f32 v[44:45], v[72:73], v[80:81]
	v_bfe_u32 v2, v49, 16, 1
	v_bfe_u32 v56, v34, 16, 1
	v_add3_u32 v2, v49, v2, s76
	v_bfe_u32 v49, v6, 16, 1
	v_add3_u32 v34, v34, v56, s76
	v_bfe_u32 v56, v45, 16, 1
	v_add3_u32 v6, v6, v49, s76
	v_add3_u32 v45, v45, v56, s76
	v_lshrrev_b32_e32 v6, 16, v6
	global_store_dwordx4 v[84:85], v[88:91], off offset:64
	v_lshrrev_b32_e32 v45, 16, v45
	v_mov_b32_e32 v49, v70
	v_cvt_pk_bf16_f32 v90, v44, v48
	v_cvt_pk_bf16_f32 v89, v7, v35
	v_and_or_b32 v88, v34, s77, v6
	v_mov_b32_e32 v34, v46
	v_mov_b32_e32 v35, v54
	v_mov_b32_e32 v48, v58
	v_and_or_b32 v91, v2, s77, v45
	v_mov_b32_e32 v6, v50
	v_mov_b32_e32 v7, v62
	v_pk_mul_f32 v[34:35], v[34:35], v[96:97]
	v_mov_b32_e32 v44, v66
	v_mov_b32_e32 v45, v74
	v_pk_mul_f32 v[48:49], v[48:49], v[94:95]
	v_pk_mul_f32 v[6:7], v[6:7], v[76:77]
	v_pk_mul_f32 v[44:45], v[44:45], v[80:81]
	v_bfe_u32 v46, v48, 16, 1
	v_add3_u32 v46, v48, v46, s76
	v_bfe_u32 v50, v44, 16, 1
	v_add3_u32 v44, v44, v50, s76
	v_lshrrev_b32_e32 v44, 16, v44
	v_mov_b32_e32 v54, v47
	v_mov_b32_e32 v70, v59
	global_store_dwordx4 v[84:85], v[88:91], off offset:2112
	v_mov_b32_e32 v62, v51
	s_nop 1
	v_and_or_b32 v90, v46, s77, v44
	v_cvt_pk_bf16_f32 v89, v7, v35
	v_cvt_pk_bf16_f32 v88, v6, v34
	v_pk_mul_f32 v[34:35], v[54:55], v[96:97]
	v_mov_b32_e32 v74, v67
	v_pk_mul_f32 v[46:47], v[70:71], v[94:95]
	v_cvt_pk_bf16_f32 v91, v45, v49
	v_pk_mul_f32 v[6:7], v[62:63], v[76:77]
	v_pk_mul_f32 v[44:45], v[74:75], v[80:81]
	v_bfe_u32 v2, v47, 16, 1
	v_bfe_u32 v50, v34, 16, 1
	v_add3_u32 v34, v34, v50, s76
	v_add3_u32 v2, v47, v2, s76
	v_bfe_u32 v47, v6, 16, 1
	v_bfe_u32 v50, v45, 16, 1
	v_add3_u32 v45, v45, v50, s76
	v_add3_u32 v6, v6, v47, s76
	v_lshrrev_b32_e32 v6, 16, v6
	v_lshrrev_b32_e32 v45, 16, v45
	v_and_or_b32 v47, v2, s77, v45
	v_cvt_pk_bf16_f32 v46, v44, v46
	v_cvt_pk_bf16_f32 v45, v7, v35
	v_and_or_b32 v44, v34, s77, v6
	global_store_dwordx4 v[86:87], v[44:47], off offset:2112
	s_waitcnt vmcnt(9)
	v_mov_b32_e32 v34, v24
	s_waitcnt vmcnt(7)
	v_mov_b32_e32 v35, v36
	s_waitcnt vmcnt(6)
	v_mov_b32_e32 v44, v20
	s_waitcnt vmcnt(4)
	v_mov_b32_e32 v45, v12
	v_mov_b32_e32 v6, v28
	v_mov_b32_e32 v7, v40
	v_pk_mul_f32 v[34:35], v[34:35], v[82:83]
	v_pk_mul_f32 v[44:45], v[44:45], v[32:33]
	v_mov_b32_e32 v46, v16
	s_waitcnt vmcnt(3)
	v_mov_b32_e32 v47, v8
	v_pk_mul_f32 v[6:7], v[6:7], v[4:5]
	v_pk_mul_f32 v[46:47], v[46:47], v[78:79]
	v_cvt_pk_bf16_f32 v46, v44, v46
	v_mov_b32_e32 v36, v25
	v_mov_b32_e32 v8, v17
	v_cvt_pk_bf16_f32 v47, v45, v47
	v_cvt_pk_bf16_f32 v45, v7, v35
	v_mov_b32_e32 v40, v29
	v_pk_mul_f32 v[24:25], v[36:37], v[82:83]
	v_mov_b32_e32 v12, v21
	v_pk_mul_f32 v[8:9], v[8:9], v[78:79]
	v_cvt_pk_bf16_f32 v44, v6, v34
	v_pk_mul_f32 v[6:7], v[40:41], v[4:5]
	v_pk_mul_f32 v[12:13], v[12:13], v[32:33]
	v_bfe_u32 v2, v9, 16, 1
	v_bfe_u32 v20, v24, 16, 1
	v_add3_u32 v20, v24, v20, s76
	v_add3_u32 v2, v9, v2, s76
	v_bfe_u32 v9, v6, 16, 1
	v_bfe_u32 v24, v13, 16, 1
	v_add3_u32 v13, v13, v24, s76
	v_add3_u32 v6, v6, v9, s76
	v_lshrrev_b32_e32 v6, 16, v6
	v_lshrrev_b32_e32 v9, 16, v13
	v_and_or_b32 v9, v2, s77, v9
	v_cvt_pk_bf16_f32 v8, v12, v8
	v_cvt_pk_bf16_f32 v7, v7, v25
	v_and_or_b32 v6, v20, s77, v6
	global_store_dwordx4 v[84:85], v[6:9], off offset:2144
	v_mov_b32_e32 v16, v18
	v_mov_b32_e32 v17, v10
	v_mov_b32_e32 v8, v26
	v_mov_b32_e32 v9, v38
	v_mov_b32_e32 v6, v30
	v_mov_b32_e32 v7, v42
	v_pk_mul_f32 v[8:9], v[8:9], v[82:83]
	v_mov_b32_e32 v12, v22
	v_mov_b32_e32 v13, v14
	v_pk_mul_f32 v[16:17], v[16:17], v[78:79]
	v_pk_mul_f32 v[6:7], v[6:7], v[4:5]
	v_pk_mul_f32 v[12:13], v[12:13], v[32:33]
	v_bfe_u32 v14, v9, 16, 1
	v_bfe_u32 v18, v8, 16, 1
	v_add3_u32 v18, v8, v18, s76
	v_add3_u32 v14, v9, v14, s76
	v_bfe_u32 v9, v6, 16, 1
	v_bfe_u32 v10, v7, 16, 1
	v_add3_u32 v7, v7, v10, s76
	v_add3_u32 v6, v6, v9, s76
	v_lshrrev_b32_e32 v6, 16, v6
	v_lshrrev_b32_e32 v7, 16, v7
	v_mov_b32_e32 v42, v31
	v_cvt_pk_bf16_f32 v9, v13, v17
	v_cvt_pk_bf16_f32 v8, v12, v16
	v_and_or_b32 v7, v14, s77, v7
	v_and_or_b32 v6, v18, s77, v6
	v_pk_mul_f32 v[4:5], v[42:43], v[4:5]
	v_mov_b32_e32 v38, v27
	global_store_dwordx4 v[86:87], v[6:9], off offset:96
	v_and_b32_sdwa v2, v5, v171 dst_sel:DWORD dst_unused:UNUSED_PAD src0_sel:WORD_1 src1_sel:DWORD
	v_add3_u32 v2, v5, v2, s76
	v_pk_mul_f32 v[6:7], v[38:39], v[82:83]
	v_and_b32_sdwa v8, v4, v171 dst_sel:DWORD dst_unused:UNUSED_PAD src0_sel:WORD_1 src1_sel:DWORD
	v_add3_u32 v4, v4, v8, s76
	v_and_b32_sdwa v8, v6, v171 dst_sel:DWORD dst_unused:UNUSED_PAD src0_sel:WORD_1 src1_sel:DWORD
	v_add3_u32 v6, v6, v8, s76
	v_and_b32_sdwa v5, v7, v171 dst_sel:DWORD dst_unused:UNUSED_PAD src0_sel:WORD_1 src1_sel:DWORD
	v_and_b32_e32 v6, 0xffff0000, v6
	v_add3_u32 v5, v7, v5, s76
	v_or_b32_sdwa v4, v6, v4 dst_sel:DWORD dst_unused:UNUSED_PAD src0_sel:DWORD src1_sel:WORD_1
	v_mov_b32_e32 v18, v23
	v_mov_b32_e32 v6, v32
	v_mov_b32_e32 v7, v78
	v_pk_mul_f32 v[6:7], v[18:19], v[6:7]
	v_and_b32_e32 v5, 0xffff0000, v5
	v_and_b32_sdwa v8, v6, v171 dst_sel:DWORD dst_unused:UNUSED_PAD src0_sel:WORD_1 src1_sel:DWORD
	v_mov_b32_e32 v10, v15
	v_mov_b32_e32 v78, v33
	v_or_b32_sdwa v5, v5, v2 dst_sel:DWORD dst_unused:UNUSED_PAD src0_sel:DWORD src1_sel:WORD_1
	v_and_b32_sdwa v2, v7, v171 dst_sel:DWORD dst_unused:UNUSED_PAD src0_sel:WORD_1 src1_sel:DWORD
	v_add3_u32 v6, v6, v8, s76
	v_pk_mul_f32 v[8:9], v[10:11], v[78:79]
	v_add3_u32 v2, v7, v2, s76
	v_lshrrev_b32_e32 v6, 16, v6
	v_and_b32_sdwa v7, v8, v171 dst_sel:DWORD dst_unused:UNUSED_PAD src0_sel:WORD_1 src1_sel:DWORD
	v_and_or_b32 v6, v2, s77, v6
	v_and_b32_sdwa v2, v9, v171 dst_sel:DWORD dst_unused:UNUSED_PAD src0_sel:WORD_1 src1_sel:DWORD
	v_add3_u32 v7, v8, v7, s76
	v_add3_u32 v2, v9, v2, s76
	v_lshrrev_b32_e32 v7, 16, v7
	v_and_or_b32 v7, v2, s77, v7
	s_mov_b64 s[62:63], 0
	global_store_dwordx4 v[86:87], v[88:91], off offset:64
	global_store_dwordx4 v[84:85], v[44:47], off offset:96

.LBB0_573:
	v_or_b32_e32 v40, s8, v83
	v_mul_u32_u24_e32 v40, 0x300, v40
	v_lshlrev_b32_e32 v84, 1, v40
	v_lshl_add_u64 v[40:41], s[48:49], 0, v[84:85]
	s_lshl_b32 s8, s52, 1
	v_lshl_add_u64 v[40:41], v[40:41], 0, s[8:9]
	v_lshlrev_b32_e32 v84, 1, v82
	v_lshl_add_u64 v[98:99], v[40:41], 0, v[84:85]
	s_waitcnt vmcnt(15)
	v_mov_b32_e32 v40, v46
	s_waitcnt vmcnt(13)
	v_mov_b32_e32 v41, v54
	v_pk_mul_f32 v[40:41], v[40:41], v[74:75]
	v_mov_b32_e32 v108, v42
	s_waitcnt vmcnt(12)
	v_mov_b32_e32 v109, v50
	s_waitcnt vmcnt(11)
	v_mov_b32_e32 v110, v62
	s_waitcnt vmcnt(9)
	v_mov_b32_e32 v111, v70
	v_pk_mul_f32 v[108:109], v[108:109], v[94:95]
	v_pk_mul_f32 v[110:111], v[110:111], v[78:79]
	v_mov_b32_e32 v112, v58
	s_waitcnt vmcnt(8)
	v_mov_b32_e32 v113, v66
	v_bfe_u32 v58, v40, 16, 1
	v_bfe_u32 v62, v41, 16, 1
	v_pk_mul_f32 v[112:113], v[112:113], v[92:93]
	v_bfe_u32 v50, v109, 16, 1
	v_bfe_u32 v54, v108, 16, 1
	v_bfe_u32 v66, v110, 16, 1
	v_add3_u32 v41, v41, v62, s68
	v_add3_u32 v40, v40, v58, s68
	v_bfe_u32 v46, v112, 16, 1
	v_add3_u32 v54, v108, v54, s68
	v_add3_u32 v50, v109, v50, s68
	v_add3_u32 v66, v110, v66, s68
	v_lshrrev_b32_e32 v40, 16, v40
	v_lshrrev_b32_e32 v41, 16, v41
	s_mov_b32 s8, 0x5180000
	v_add3_u32 v46, v112, v46, s68
	v_lshrrev_b32_e32 v58, 16, v66
	v_and_or_b32 v109, v50, s69, v41
	v_and_or_b32 v108, v54, s69, v40
	v_add_co_u32_e32 v40, vcc, s8, v98
	v_mov_b32_e32 v50, v43
	v_mov_b32_e32 v66, v59
	v_cvt_pk_bf16_f32 v111, v111, v113
	v_and_or_b32 v110, v46, s69, v58
	v_addc_co_u32_e32 v41, vcc, 0, v99, vcc
	v_mov_b32_e32 v54, v47
	v_pk_mul_f32 v[42:43], v[50:51], v[94:95]
	v_mov_b32_e32 v70, v63
	v_pk_mul_f32 v[50:51], v[66:67], v[92:93]
	global_store_dwordx4 v[40:41], v[108:111], off
	v_pk_mul_f32 v[40:41], v[54:55], v[74:75]
	v_pk_mul_f32 v[46:47], v[70:71], v[78:79]
	v_bfe_u32 v54, v51, 16, 1
	v_bfe_u32 v55, v50, 16, 1
	v_bfe_u32 v58, v43, 16, 1
	v_bfe_u32 v59, v42, 16, 1
	v_add3_u32 v59, v42, v59, s68
	v_add3_u32 v58, v43, v58, s68
	v_add3_u32 v42, v50, v55, s68
	v_add3_u32 v43, v51, v54, s68
	v_bfe_u32 v50, v40, 16, 1
	v_bfe_u32 v51, v41, 16, 1
	v_bfe_u32 v54, v46, 16, 1
	v_bfe_u32 v55, v47, 16, 1
	v_add3_u32 v47, v47, v55, s68
	v_add3_u32 v46, v46, v54, s68
	v_add3_u32 v41, v41, v51, s68
	v_add3_u32 v40, v40, v50, s68
	s_mov_b64 s[48:49], 0x5180000
	v_lshrrev_b32_e32 v40, 16, v40
	v_lshrrev_b32_e32 v41, 16, v41
	v_lshrrev_b32_e32 v46, 16, v46
	v_lshrrev_b32_e32 v47, 16, v47
	v_lshl_add_u64 v[86:87], v[98:99], 0, s[48:49]
	v_and_or_b32 v43, v43, s69, v47
	v_and_or_b32 v42, v42, s69, v46
	v_and_or_b32 v41, v58, s69, v41
	v_and_or_b32 v40, v59, s69, v40
	global_store_dwordx4 v[86:87], v[40:43], off offset:1536
	v_mov_b32_e32 v50, v60
	v_mov_b32_e32 v51, v68
	v_mov_b32_e32 v42, v44
	v_mov_b32_e32 v43, v52
	v_mov_b32_e32 v40, v48
	v_mov_b32_e32 v41, v56
	v_pk_mul_f32 v[42:43], v[42:43], v[94:95]
	v_mov_b32_e32 v46, v64
	v_mov_b32_e32 v47, v72
	v_pk_mul_f32 v[50:51], v[50:51], v[92:93]
	v_pk_mul_f32 v[40:41], v[40:41], v[74:75]
	v_pk_mul_f32 v[46:47], v[46:47], v[78:79]
	v_bfe_u32 v44, v51, 16, 1
	v_bfe_u32 v48, v50, 16, 1
	v_bfe_u32 v52, v43, 16, 1
	v_bfe_u32 v54, v42, 16, 1
	v_add3_u32 v54, v42, v54, s68
	v_add3_u32 v52, v43, v52, s68
	v_add3_u32 v42, v50, v48, s68
	v_add3_u32 v43, v51, v44, s68
	v_bfe_u32 v44, v40, 16, 1
	v_bfe_u32 v48, v41, 16, 1
	v_bfe_u32 v50, v46, 16, 1
	v_bfe_u32 v51, v47, 16, 1
	v_add3_u32 v47, v47, v51, s68
	v_add3_u32 v46, v46, v50, s68
	v_add3_u32 v41, v41, v48, s68
	v_add3_u32 v40, v40, v44, s68
	v_lshrrev_b32_e32 v40, 16, v40
	v_lshrrev_b32_e32 v41, 16, v41
	v_lshrrev_b32_e32 v44, 16, v46
	v_lshrrev_b32_e32 v46, 16, v47
	v_and_or_b32 v43, v43, s69, v46
	v_and_or_b32 v42, v42, s69, v44
	v_and_or_b32 v41, v52, s69, v41
	v_and_or_b32 v40, v54, s69, v40
	v_mov_b32_e32 v52, v45
	v_mov_b32_e32 v68, v61
	global_store_dwordx4 v[86:87], v[40:43], off offset:3072
	v_mov_b32_e32 v72, v65
	v_pk_mul_f32 v[46:47], v[68:69], v[92:93]
	v_pk_mul_f32 v[42:43], v[52:53], v[94:95]
	v_mov_b32_e32 v56, v49
	v_pk_mul_f32 v[44:45], v[72:73], v[78:79]
	v_bfe_u32 v48, v47, 16, 1
	v_bfe_u32 v50, v43, 16, 1
	v_pk_mul_f32 v[40:41], v[56:57], v[74:75]
	v_bfe_u32 v49, v46, 16, 1
	v_bfe_u32 v51, v42, 16, 1
	v_add3_u32 v50, v43, v50, s68
	v_add3_u32 v43, v47, v48, s68
	v_bfe_u32 v48, v44, 16, 1
	v_add3_u32 v51, v42, v51, s68
	v_add3_u32 v42, v46, v49, s68
	v_bfe_u32 v46, v40, 16, 1
	v_bfe_u32 v47, v41, 16, 1
	v_bfe_u32 v49, v45, 16, 1
	v_add3_u32 v44, v44, v48, s68
	v_add3_u32 v45, v45, v49, s68
	v_add3_u32 v41, v41, v47, s68
	v_add3_u32 v40, v40, v46, s68
	v_lshrrev_b32_e32 v44, 16, v44
	s_mov_b32 s8, 0x5181000
	v_lshrrev_b32_e32 v40, 16, v40
	v_lshrrev_b32_e32 v41, 16, v41
	v_lshrrev_b32_e32 v45, 16, v45
	v_and_or_b32 v42, v42, s69, v44
	v_add_co_u32_e32 v44, vcc, s8, v98
	v_and_or_b32 v43, v43, s69, v45
	v_and_or_b32 v41, v50, s69, v41
	v_and_or_b32 v40, v51, s69, v40
	v_addc_co_u32_e32 v45, vcc, 0, v99, vcc
	global_store_dwordx4 v[44:45], v[40:43], off offset:512
	s_waitcnt vmcnt(7)
	v_mov_b32_e32 v46, v26
	s_waitcnt vmcnt(5)
	v_mov_b32_e32 v47, v34
	v_mov_b32_e32 v40, v10
	v_mov_b32_e32 v41, v18
	v_pk_mul_f32 v[40:41], v[40:41], v[2:3]
	v_mov_b32_e32 v42, v6
	v_mov_b32_e32 v43, v14
	v_pk_mul_f32 v[46:47], v[46:47], v[38:39]
	v_mov_b32_e32 v48, v22
	s_waitcnt vmcnt(4)
	v_mov_b32_e32 v49, v30
	v_pk_mul_f32 v[42:43], v[42:43], v[80:81]
	v_pk_mul_f32 v[48:49], v[48:49], v[76:77]
	v_bfe_u32 v22, v40, 16, 1
	v_bfe_u32 v18, v42, 16, 1
	v_add3_u32 v22, v40, v22, s68
	v_add3_u32 v18, v42, v18, s68
	v_lshrrev_b32_e32 v22, 16, v22
	v_cvt_pk_bf16_f32 v42, v46, v48
	v_cvt_pk_bf16_f32 v41, v41, v43
	v_and_or_b32 v40, v18, s69, v22
	v_mov_b32_e32 v18, v11
	v_mov_b32_e32 v14, v7
	v_mov_b32_e32 v30, v23
	v_cvt_pk_bf16_f32 v43, v47, v49
	v_pk_mul_f32 v[10:11], v[18:19], v[2:3]
	v_pk_mul_f32 v[6:7], v[14:15], v[80:81]
	v_mov_b32_e32 v34, v27
	v_pk_mul_f32 v[18:19], v[30:31], v[76:77]
	v_pk_mul_f32 v[14:15], v[34:35], v[38:39]
	global_store_dwordx4 v[86:87], v[40:43], off offset:32
	s_mov_b64 s[50:51], 0x18000
	v_lshl_add_u64 v[4:5], v[88:89], 0, s[50:51]
	v_cvt_pk_bf16_f32 v43, v15, v19
	v_cvt_pk_bf16_f32 v42, v14, v18
	v_cvt_pk_bf16_f32 v41, v11, v7
	v_cvt_pk_bf16_f32 v40, v10, v6
	v_mov_b32_e32 v10, v8
	v_mov_b32_e32 v11, v16
	v_mov_b32_e32 v18, v24
	v_mov_b32_e32 v19, v32
	v_mov_b32_e32 v6, v12
	v_mov_b32_e32 v7, v20
	v_pk_mul_f32 v[10:11], v[10:11], v[80:81]
	v_pk_mul_f32 v[18:19], v[18:19], v[76:77]
	v_pk_mul_f32 v[6:7], v[6:7], v[2:3]
	v_mov_b32_e32 v14, v28
	v_mov_b32_e32 v15, v36
	v_pk_mul_f32 v[14:15], v[14:15], v[38:39]
	v_mov_b32_e32 v32, v25
	global_store_dwordx4 v[86:87], v[40:43], off offset:1568
	s_nop 1
	v_cvt_pk_bf16_f32 v41, v7, v11
	s_nop 1
	v_cvt_pk_bf16_f32 v40, v6, v10
	v_mov_b32_e32 v20, v13
	v_pk_mul_f32 v[10:11], v[32:33], v[76:77]
	v_cvt_pk_bf16_f32 v42, v14, v18
	v_pk_mul_f32 v[2:3], v[20:21], v[2:3]
	v_mov_b32_e32 v16, v9
	v_pk_mul_f32 v[6:7], v[16:17], v[80:81]
	v_mov_b32_e32 v36, v29
	v_cvt_pk_bf16_f32 v43, v15, v19
	v_pk_mul_f32 v[8:9], v[36:37], v[38:39]
	v_cvt_pk_bf16_f32 v6, v2, v6
	v_add_co_u32_e32 v2, vcc, s66, v4
	v_cvt_pk_bf16_f32 v7, v3, v7
	v_addc_co_u32_e32 v3, vcc, 0, v5, vcc
	v_cvt_pk_bf16_f32 v9, v9, v11
	v_cvt_pk_bf16_f32 v8, v8, v10
	v_add_co_u32_e32 v4, vcc, s70, v88
	global_store_dwordx4 v[86:87], v[40:43], off offset:3104
	global_store_dwordx4 v[44:45], v[6:9], off offset:544
	v_addc_co_u32_e32 v5, vcc, 0, v89, vcc
	global_load_dwordx4 v[46:49], v[2:3], off nt
	global_load_dwordx4 v[42:45], v[4:5], off offset:2048 nt
	v_add_co_u32_e32 v2, vcc, s71, v88
	s_mov_b32 s8, 0x34000
	s_nop 0
	v_addc_co_u32_e32 v3, vcc, 0, v89, vcc
	v_add_co_u32_e32 v4, vcc, s8, v88
	s_mov_b32 s8, 0x36000
	s_nop 0
	v_addc_co_u32_e32 v5, vcc, 0, v89, vcc
	global_load_dwordx4 v[54:57], v[2:3], off nt
	global_load_dwordx4 v[50:53], v[4:5], off offset:2048 nt
	v_add_co_u32_e32 v2, vcc, s8, v88
	v_mov_b32_e32 v74, 1.0
	s_nop 0
	v_addc_co_u32_e32 v3, vcc, 0, v89, vcc
	v_add_co_u32_e32 v4, vcc, 0x37000, v88
	v_mov_b32_e32 v94, 1.0
	s_nop 0
	v_addc_co_u32_e32 v5, vcc, 0, v89, vcc
	global_load_dwordx4 v[62:65], v[2:3], off nt
	global_load_dwordx4 v[58:61], v[4:5], off offset:2048 nt
	v_add_co_u32_e32 v2, vcc, 0x39000, v88
	v_mov_b32_e32 v75, 1.0
	s_nop 0
	v_addc_co_u32_e32 v3, vcc, 0, v89, vcc
	v_add_co_u32_e32 v4, vcc, 0x3a000, v88
	v_mov_b32_e32 v95, 1.0
	s_nop 0
	v_addc_co_u32_e32 v5, vcc, 0, v89, vcc
	global_load_dwordx4 v[70:73], v[2:3], off nt
	global_load_dwordx4 v[66:69], v[4:5], off offset:2048 nt
	v_mov_b32_e32 v2, 1.0
	s_and_b64 vcc, exec, s[6:7]
	v_mov_b32_e32 v78, 1.0
	v_mov_b32_e32 v92, 1.0
	v_mov_b32_e32 v79, 1.0
	v_mov_b32_e32 v93, 1.0
	s_cbranch_vccnz .LBB0_575
	global_load_dwordx4 v[74:77], v96, s[10:11] offset:128
	global_load_dwordx4 v[78:81], v96, s[10:11] offset:144
	s_waitcnt vmcnt(1)
	v_mov_b32_e32 v94, v75
	v_mov_b32_e32 v75, v76
	v_mov_b32_e32 v95, v77
	s_waitcnt vmcnt(0)
	v_mov_b32_e32 v92, v79
	v_mov_b32_e32 v79, v80
	v_mov_b32_e32 v93, v81

.LBB0_577:
	s_waitcnt vmcnt(15)
	v_mov_b32_e32 v40, v46
	s_waitcnt vmcnt(13)
	v_mov_b32_e32 v41, v54
	v_pk_mul_f32 v[40:41], v[40:41], v[74:75]
	v_mov_b32_e32 v80, v42
	s_waitcnt vmcnt(12)
	v_mov_b32_e32 v81, v50
	s_waitcnt vmcnt(11)
	v_mov_b32_e32 v88, v62
	s_waitcnt vmcnt(9)
	v_mov_b32_e32 v89, v70
	v_pk_mul_f32 v[80:81], v[80:81], v[94:95]
	v_pk_mul_f32 v[88:89], v[88:89], v[78:79]
	v_mov_b32_e32 v90, v58
	s_waitcnt vmcnt(8)
	v_mov_b32_e32 v91, v66
	v_bfe_u32 v62, v41, 16, 1
	v_pk_mul_f32 v[90:91], v[90:91], v[92:93]
	v_bfe_u32 v50, v81, 16, 1
	v_bfe_u32 v58, v40, 16, 1
	v_bfe_u32 v66, v88, 16, 1
	v_bfe_u32 v70, v89, 16, 1
	v_add3_u32 v41, v41, v62, s68
	v_bfe_u32 v42, v91, 16, 1
	v_bfe_u32 v54, v80, 16, 1
	v_add3_u32 v50, v81, v50, s68
	v_add3_u32 v70, v89, v70, s68
	v_add3_u32 v66, v88, v66, s68
	v_add3_u32 v40, v40, v58, s68
	v_lshrrev_b32_e32 v41, 16, v41
	v_bfe_u32 v46, v90, 16, 1
	v_add3_u32 v54, v80, v54, s68
	v_add3_u32 v42, v91, v42, s68
	v_lshrrev_b32_e32 v40, 16, v40
	v_lshrrev_b32_e32 v58, 16, v66
	v_lshrrev_b32_e32 v62, 16, v70
	v_and_or_b32 v89, v50, s69, v41
	v_mov_b32_e32 v50, v43
	v_mov_b32_e32 v66, v59
	v_add3_u32 v46, v90, v46, s68
	v_and_or_b32 v91, v42, s69, v62
	v_and_or_b32 v88, v54, s69, v40
	v_mov_b32_e32 v54, v47
	v_pk_mul_f32 v[42:43], v[50:51], v[94:95]
	v_mov_b32_e32 v70, v63
	v_pk_mul_f32 v[50:51], v[66:67], v[92:93]
	v_and_or_b32 v90, v46, s69, v58
	v_pk_mul_f32 v[40:41], v[54:55], v[74:75]
	v_pk_mul_f32 v[46:47], v[70:71], v[78:79]
	v_bfe_u32 v54, v51, 16, 1
	v_bfe_u32 v55, v50, 16, 1
	v_bfe_u32 v58, v43, 16, 1
	v_bfe_u32 v59, v42, 16, 1
	v_add3_u32 v59, v42, v59, s68
	v_add3_u32 v58, v43, v58, s68
	v_add3_u32 v42, v50, v55, s68
	v_add3_u32 v43, v51, v54, s68
	v_bfe_u32 v50, v40, 16, 1
	v_bfe_u32 v51, v41, 16, 1
	v_bfe_u32 v54, v46, 16, 1
	v_bfe_u32 v55, v47, 16, 1
	v_add3_u32 v47, v47, v55, s68
	v_add3_u32 v46, v46, v54, s68
	v_add3_u32 v41, v41, v51, s68
	v_add3_u32 v40, v40, v50, s68
	v_lshrrev_b32_e32 v40, 16, v40
	v_lshrrev_b32_e32 v41, 16, v41
	v_lshrrev_b32_e32 v46, 16, v46
	v_lshrrev_b32_e32 v47, 16, v47
	v_and_or_b32 v43, v43, s69, v47
	v_and_or_b32 v42, v42, s69, v46
	v_and_or_b32 v41, v58, s69, v41
	v_and_or_b32 v40, v59, s69, v40
	global_store_dwordx4 v[86:87], v[40:43], off offset:1600
	v_mov_b32_e32 v50, v60
	v_mov_b32_e32 v51, v68
	v_mov_b32_e32 v42, v44
	v_mov_b32_e32 v43, v52
	v_mov_b32_e32 v40, v48
	v_mov_b32_e32 v41, v56
	v_pk_mul_f32 v[42:43], v[42:43], v[94:95]
	v_mov_b32_e32 v46, v64
	v_mov_b32_e32 v47, v72
	v_pk_mul_f32 v[50:51], v[50:51], v[92:93]
	v_pk_mul_f32 v[40:41], v[40:41], v[74:75]
	v_pk_mul_f32 v[46:47], v[46:47], v[78:79]
	v_bfe_u32 v44, v51, 16, 1
	v_bfe_u32 v48, v50, 16, 1
	v_bfe_u32 v52, v43, 16, 1
	v_bfe_u32 v54, v42, 16, 1
	v_add3_u32 v54, v42, v54, s68
	v_add3_u32 v52, v43, v52, s68
	v_add3_u32 v42, v50, v48, s68
	v_add3_u32 v43, v51, v44, s68
	v_bfe_u32 v44, v40, 16, 1
	v_bfe_u32 v48, v41, 16, 1
	v_bfe_u32 v50, v46, 16, 1
	v_bfe_u32 v51, v47, 16, 1
	v_add3_u32 v47, v47, v51, s68
	v_add3_u32 v46, v46, v50, s68
	v_add3_u32 v41, v41, v48, s68
	v_add3_u32 v40, v40, v44, s68
	v_lshrrev_b32_e32 v40, 16, v40
	v_lshrrev_b32_e32 v41, 16, v41
	v_lshrrev_b32_e32 v44, 16, v46
	v_lshrrev_b32_e32 v46, 16, v47
	v_and_or_b32 v43, v43, s69, v46
	v_and_or_b32 v42, v42, s69, v44
	v_and_or_b32 v41, v52, s69, v41
	v_and_or_b32 v40, v54, s69, v40
	v_mov_b32_e32 v52, v45
	v_mov_b32_e32 v68, v61
	global_store_dwordx4 v[86:87], v[40:43], off offset:3136
	v_mov_b32_e32 v72, v65
	v_pk_mul_f32 v[46:47], v[68:69], v[92:93]
	v_pk_mul_f32 v[42:43], v[52:53], v[94:95]
	v_mov_b32_e32 v56, v49
	v_pk_mul_f32 v[44:45], v[72:73], v[78:79]
	v_bfe_u32 v48, v47, 16, 1
	v_bfe_u32 v50, v43, 16, 1
	v_pk_mul_f32 v[40:41], v[56:57], v[74:75]
	v_bfe_u32 v49, v46, 16, 1
	v_bfe_u32 v51, v42, 16, 1
	v_add3_u32 v50, v43, v50, s68
	v_add3_u32 v43, v47, v48, s68
	v_bfe_u32 v48, v44, 16, 1
	v_add3_u32 v51, v42, v51, s68
	v_add3_u32 v42, v46, v49, s68
	v_bfe_u32 v46, v40, 16, 1
	v_bfe_u32 v47, v41, 16, 1
	v_bfe_u32 v49, v45, 16, 1
	v_add3_u32 v44, v44, v48, s68
	v_add3_u32 v45, v45, v49, s68
	v_add3_u32 v41, v41, v47, s68
	v_add3_u32 v40, v40, v46, s68
	v_lshrrev_b32_e32 v44, 16, v44
	v_lshrrev_b32_e32 v40, 16, v40
	v_lshrrev_b32_e32 v41, 16, v41
	v_lshrrev_b32_e32 v45, 16, v45
	v_and_or_b32 v42, v42, s69, v44
	v_add_co_u32_e32 v44, vcc, s61, v86
	v_and_or_b32 v43, v43, s69, v45
	v_and_or_b32 v41, v50, s69, v41
	v_and_or_b32 v40, v51, s69, v40
	v_addc_co_u32_e32 v45, vcc, 0, v87, vcc
	global_store_dwordx4 v[44:45], v[40:43], off offset:576
	s_waitcnt vmcnt(6)
	v_mov_b32_e32 v46, v26
	s_waitcnt vmcnt(4)
	v_mov_b32_e32 v47, v34
	v_mov_b32_e32 v40, v10
	v_mov_b32_e32 v41, v18
	v_pk_mul_f32 v[40:41], v[40:41], v[2:3]
	v_mov_b32_e32 v42, v6
	v_mov_b32_e32 v43, v14
	v_pk_mul_f32 v[46:47], v[46:47], v[38:39]
	v_mov_b32_e32 v48, v22
	s_waitcnt vmcnt(3)
	v_mov_b32_e32 v49, v30
	v_pk_mul_f32 v[42:43], v[42:43], v[76:77]
	v_pk_mul_f32 v[48:49], v[48:49], v[4:5]
	v_bfe_u32 v22, v40, 16, 1
	v_bfe_u32 v18, v42, 16, 1
	v_add3_u32 v22, v40, v22, s68
	v_add3_u32 v18, v42, v18, s68
	v_lshrrev_b32_e32 v22, 16, v22
	v_cvt_pk_bf16_f32 v42, v46, v48
	v_cvt_pk_bf16_f32 v41, v41, v43
	v_and_or_b32 v40, v18, s69, v22
	v_mov_b32_e32 v18, v11
	v_mov_b32_e32 v14, v7
	v_mov_b32_e32 v30, v23
	v_cvt_pk_bf16_f32 v43, v47, v49
	v_pk_mul_f32 v[10:11], v[18:19], v[2:3]
	v_pk_mul_f32 v[6:7], v[14:15], v[76:77]
	v_mov_b32_e32 v34, v27
	v_pk_mul_f32 v[18:19], v[30:31], v[4:5]
	v_pk_mul_f32 v[14:15], v[34:35], v[38:39]
	global_store_dwordx4 v[86:87], v[40:43], off offset:96
	global_store_dwordx4 v[86:87], v[88:91], off offset:64
	s_mov_b64 s[6:7], 0
	v_cvt_pk_bf16_f32 v43, v15, v19
	v_cvt_pk_bf16_f32 v42, v14, v18
	v_cvt_pk_bf16_f32 v41, v11, v7
	v_cvt_pk_bf16_f32 v40, v10, v6
	v_mov_b32_e32 v10, v8
	v_mov_b32_e32 v11, v16
	v_mov_b32_e32 v18, v24
	v_mov_b32_e32 v19, v32
	v_mov_b32_e32 v6, v12
	v_mov_b32_e32 v7, v20
	v_pk_mul_f32 v[10:11], v[10:11], v[76:77]
	v_pk_mul_f32 v[18:19], v[18:19], v[4:5]
	v_pk_mul_f32 v[6:7], v[6:7], v[2:3]
	v_mov_b32_e32 v14, v28
	v_mov_b32_e32 v15, v36
	v_bfe_u32 v12, v18, 16, 1
	v_bfe_u32 v16, v11, 16, 1
	v_pk_mul_f32 v[14:15], v[14:15], v[38:39]
	v_bfe_u32 v8, v19, 16, 1
	v_bfe_u32 v20, v10, 16, 1
	v_add3_u32 v11, v11, v16, s68
	v_add3_u32 v12, v18, v12, s68
	v_bfe_u32 v16, v6, 16, 1
	v_bfe_u32 v18, v7, 16, 1
	v_add3_u32 v10, v10, v20, s68
	v_add3_u32 v8, v19, v8, s68
	v_bfe_u32 v19, v14, 16, 1
	v_bfe_u32 v20, v15, 16, 1
	v_add3_u32 v7, v7, v18, s68
	v_add3_u32 v6, v6, v16, s68
	v_add3_u32 v15, v15, v20, s68
	v_add3_u32 v14, v14, v19, s68
	v_lshrrev_b32_e32 v6, 16, v6
	v_lshrrev_b32_e32 v7, 16, v7
	v_mov_b32_e32 v16, v9
	v_mov_b32_e32 v32, v25
	global_store_dwordx4 v[86:87], v[40:43], off offset:1632
	v_lshrrev_b32_e32 v14, 16, v14
	v_lshrrev_b32_e32 v15, 16, v15
	v_and_or_b32 v41, v11, s69, v7
	v_and_or_b32 v40, v10, s69, v6
	v_mov_b32_e32 v20, v13
	v_pk_mul_f32 v[6:7], v[16:17], v[76:77]
	v_mov_b32_e32 v36, v29
	v_pk_mul_f32 v[4:5], v[32:33], v[4:5]
	v_and_or_b32 v43, v8, s69, v15
	v_and_or_b32 v42, v12, s69, v14
	v_pk_mul_f32 v[2:3], v[20:21], v[2:3]
	v_pk_mul_f32 v[8:9], v[36:37], v[38:39]
	v_cvt_pk_bf16_f32 v5, v9, v5
	v_cvt_pk_bf16_f32 v4, v8, v4
	v_cvt_pk_bf16_f32 v3, v3, v7
	v_cvt_pk_bf16_f32 v2, v2, v6
	global_store_dwordx4 v[86:87], v[40:43], off offset:3168
	global_store_dwordx4 v[44:45], v[2:5], off offset:608
.LBB0_578:
	s_mov_b32 s8, 0
	s_and_b64 vcc, exec, s[6:7]
	s_cbranch_vccz .LBB0_580
	s_mov_b64 s[6:7], s[0:1]
	s_load_dwordx2 s[10:11], s[6:7], 0x78
	s_mov_b64 s[6:7], s[0:1]
	s_load_dwordx2 s[48:49], s[6:7], 0xa8
	s_mov_b64 s[6:7], s[0:1]
	s_load_dwordx2 s[6:7], s[6:7], 0x20
	s_waitcnt lgkmcnt(0)
	s_add_u32 s6, s6, 0x1000
	s_addc_u32 s7, s7, 0
	s_add_i32 s8, s77, 32
	s_and_b32 s50, s8, 0xff
	s_mulk_i32 s50, 0xab
	s_lshr_b32 s50, s50, 10
	s_mul_i32 s51, s50, 6
	s_sub_i32 s8, s8, s51
	s_and_b32 s8, s8, 0xff
	v_lshl_or_b32 v4, s8, 7, v83
	v_lshlrev_b32_e32 v84, 11, v4
	v_lshl_add_u64 v[2:3], s[48:49], 0, v[84:85]
	s_lshl_b32 s8, s50, 7
	v_lshl_add_u64 v[2:3], v[2:3], 0, s[8:9]
	v_lshlrev_b32_e32 v84, 1, v82
	v_lshl_or_b32 v72, s50, 6, v82
	v_lshl_add_u64 v[98:99], v[2:3], 0, v[84:85]
	v_lshlrev_b32_e32 v84, 2, v4
	v_mul_u32_u24_e32 v4, 0x300, v72
	v_lshl_add_u64 v[70:71], s[10:11], 0, v[84:85]
	v_lshlrev_b32_e32 v84, 2, v4
	v_mad_u64_u32 v[2:3], s[10:11], v72, s73, v[70:71]
	v_lshl_add_u64 v[68:69], v[70:71], 0, v[84:85]
	global_load_dwordx4 v[46:49], v[2:3], off nt
	global_load_dwordx4 v[42:45], v[68:69], off offset:3072 nt
	v_add_co_u32_e32 v2, vcc, s61, v68
	s_mov_b32 s8, 0xc000
	s_nop 0
	v_addc_co_u32_e32 v3, vcc, 0, v69, vcc
	v_add_co_u32_e32 v4, vcc, s74, v68
	v_or_b32_e32 v10, 16, v72
	s_nop 0
	v_addc_co_u32_e32 v5, vcc, 0, v69, vcc
	global_load_dwordx4 v[54:57], v[2:3], off offset:2048 nt
	global_load_dwordx4 v[50:53], v[4:5], off offset:1024 nt
	v_lshlrev_b32_e32 v2, 2, v72
	global_load_dwordx4 v[58:61], v2, s[6:7] offset:16
	global_load_dwordx4 v[74:77], v2, s[6:7]
	v_add_co_u32_e32 v2, vcc, s62, v68
	s_mov_b64 s[10:11], 0x5000000
	s_nop 0
	v_addc_co_u32_e32 v3, vcc, 0, v69, vcc
	global_load_dwordx4 v[78:81], v[2:3], off nt
	global_load_dwordx4 v[62:65], v[2:3], off offset:3072 nt
	v_add_co_u32_e32 v2, vcc, s63, v68
	v_lshlrev_b32_e32 v6, 2, v10
	s_nop 0
	v_addc_co_u32_e32 v3, vcc, 0, v69, vcc
	global_load_dwordx4 v[86:89], v[2:3], off offset:2048 nt
	v_add_co_u32_e32 v2, vcc, s75, v68
	v_lshl_add_u64 v[66:67], v[98:99], 0, s[10:11]
	s_nop 0
	v_addc_co_u32_e32 v3, vcc, 0, v69, vcc
	global_load_dwordx4 v[90:93], v[2:3], off offset:1024 nt
	v_add_co_u32_e32 v12, vcc, s8, v68
	s_mov_b32 s8, 0xd000
	s_nop 0
	v_addc_co_u32_e32 v13, vcc, 0, v69, vcc
	v_add_co_u32_e32 v14, vcc, s8, v68
	s_mov_b32 s8, 0x10000
	s_nop 0
	v_addc_co_u32_e32 v15, vcc, 0, v69, vcc
	v_add_co_u32_e32 v16, vcc, s78, v68
	v_mad_u64_u32 v[10:11], s[10:11], v10, s73, v[70:71]
	s_nop 0
	v_addc_co_u32_e32 v17, vcc, 0, v69, vcc
	v_add_co_u32_e32 v26, vcc, s80, v68
	global_load_dwordx4 v[2:5], v6, s[6:7] offset:16
	s_nop 0
	global_load_dwordx4 v[6:9], v6, s[6:7]
	v_addc_co_u32_e32 v27, vcc, 0, v69, vcc
	v_add_co_u32_e32 v28, vcc, s8, v68
	s_mov_b32 s8, 0x5001000
	s_nop 0
	v_addc_co_u32_e32 v29, vcc, 0, v69, vcc
	v_add_co_u32_e32 v94, vcc, s79, v68
	s_waitcnt vmcnt(10)
	v_mov_b32_e32 v96, v42
	v_addc_co_u32_e32 v95, vcc, 0, v69, vcc
	global_load_dwordx4 v[18:21], v[10:11], off nt
	global_load_dwordx4 v[30:33], v[12:13], off offset:3072 nt
	global_load_dwordx4 v[38:41], v[14:15], off offset:2048 nt
	global_load_dwordx4 v[34:37], v[16:17], off offset:1024 nt
	global_load_dwordx4 v[22:25], v[26:27], off nt
	s_nop 0
	global_load_dwordx4 v[10:13], v[26:27], off offset:3072 nt
	s_nop 0
	global_load_dwordx4 v[26:29], v[28:29], off offset:2048 nt
	s_nop 0
	global_load_dwordx4 v[14:17], v[94:95], off offset:1024 nt
	v_mov_b32_e32 v94, v46
	s_waitcnt vmcnt(17)
	v_mov_b32_e32 v95, v54
	s_waitcnt vmcnt(16)
	v_mov_b32_e32 v97, v50
	s_waitcnt vmcnt(15)
	v_mov_b32_e32 v111, v60
	s_waitcnt vmcnt(14)
	v_mov_b32_e32 v108, v74
	v_mov_b32_e32 v109, v76
	v_mov_b32_e32 v76, v75
	v_mov_b32_e32 v60, v59
	v_pk_mul_f32 v[94:95], v[94:95], v[108:109]
	v_pk_mul_f32 v[74:75], v[96:97], v[76:77]
	s_waitcnt vmcnt(12)
	v_mov_b32_e32 v112, v62
	v_mov_b32_e32 v96, v78
	v_mov_b32_e32 v110, v58
	s_waitcnt vmcnt(11)
	v_mov_b32_e32 v97, v86
	v_pk_mul_f32 v[96:97], v[96:97], v[110:111]
	s_waitcnt vmcnt(10)
	v_mov_b32_e32 v113, v90
	v_pk_mul_f32 v[58:59], v[112:113], v[60:61]
	v_cvt_pk_bf16_f32 v95, v95, v75
	v_cvt_pk_bf16_f32 v94, v94, v74
	v_mov_b32_e32 v54, v47
	v_mov_b32_e32 v50, v43
	v_mov_b32_e32 v90, v63
	v_cvt_pk_bf16_f32 v97, v97, v59
	v_cvt_pk_bf16_f32 v96, v96, v58
	v_pk_mul_f32 v[46:47], v[54:55], v[108:109]
	v_pk_mul_f32 v[42:43], v[50:51], v[76:77]
	v_mov_b32_e32 v86, v79
	v_pk_mul_f32 v[54:55], v[90:91], v[60:61]
	v_pk_mul_f32 v[50:51], v[86:87], v[110:111]
	v_add_co_u32_e32 v58, vcc, s8, v98
	v_addc_co_u32_e32 v59, vcc, 0, v99, vcc
	global_store_dwordx4 v[58:59], v[94:97], off offset:-4096
	s_mov_b32 s8, 0x19000
	s_nop 0
	v_cvt_pk_bf16_f32 v97, v51, v55
	v_cvt_pk_bf16_f32 v96, v50, v54
	v_cvt_pk_bf16_f32 v95, v47, v43
	v_cvt_pk_bf16_f32 v94, v46, v42
	v_mov_b32_e32 v46, v44
	v_mov_b32_e32 v47, v52
	v_mov_b32_e32 v54, v64
	v_mov_b32_e32 v55, v92
	v_pk_mul_f32 v[46:47], v[46:47], v[76:77]
	v_mov_b32_e32 v50, v80
	v_mov_b32_e32 v51, v88
	v_pk_mul_f32 v[54:55], v[54:55], v[60:61]
	v_mov_b32_e32 v42, v48
	v_mov_b32_e32 v43, v56
	v_pk_mul_f32 v[50:51], v[50:51], v[110:111]
	v_bfe_u32 v48, v54, 16, 1
	v_bfe_u32 v52, v47, 16, 1
	v_pk_mul_f32 v[42:43], v[42:43], v[108:109]
	v_bfe_u32 v44, v55, 16, 1
	v_bfe_u32 v56, v46, 16, 1
	v_add3_u32 v48, v54, v48, s68
	v_add3_u32 v47, v47, v52, s68
	v_bfe_u32 v52, v50, 16, 1
	v_bfe_u32 v54, v51, 16, 1
	v_add3_u32 v44, v55, v44, s68
	v_add3_u32 v46, v46, v56, s68
	v_bfe_u32 v55, v42, 16, 1
	v_bfe_u32 v56, v43, 16, 1
	v_add3_u32 v51, v51, v54, s68
	v_add3_u32 v50, v50, v52, s68
	v_add3_u32 v43, v43, v56, s68
	v_add3_u32 v42, v42, v55, s68
	v_lshrrev_b32_e32 v50, 16, v50
	v_lshrrev_b32_e32 v51, 16, v51
	v_mov_b32_e32 v52, v45
	v_mov_b32_e32 v92, v65
	global_store_dwordx4 v[66:67], v[94:97], off offset:2048
	v_lshrrev_b32_e32 v42, 16, v42
	v_lshrrev_b32_e32 v43, 16, v43
	v_and_or_b32 v97, v44, s69, v51
	v_and_or_b32 v96, v48, s69, v50
	v_mov_b32_e32 v56, v49
	v_pk_mul_f32 v[44:45], v[52:53], v[76:77]
	v_mov_b32_e32 v88, v81
	v_pk_mul_f32 v[48:49], v[92:93], v[60:61]
	v_and_or_b32 v95, v47, s69, v43
	v_and_or_b32 v94, v46, s69, v42
	v_pk_mul_f32 v[42:43], v[56:57], v[108:109]
	v_pk_mul_f32 v[46:47], v[88:89], v[110:111]
	v_bfe_u32 v50, v49, 16, 1
	v_bfe_u32 v51, v48, 16, 1
	v_bfe_u32 v52, v45, 16, 1
	v_bfe_u32 v53, v44, 16, 1
	v_add3_u32 v48, v48, v51, s68
	v_add3_u32 v49, v49, v50, s68
	v_add3_u32 v50, v44, v53, s68
	v_add3_u32 v51, v45, v52, s68
	v_bfe_u32 v44, v46, 16, 1
	v_bfe_u32 v45, v47, 16, 1
	v_bfe_u32 v52, v42, 16, 1
	v_bfe_u32 v53, v43, 16, 1
	v_add3_u32 v45, v47, v45, s68
	v_add3_u32 v44, v46, v44, s68
	v_add3_u32 v43, v43, v53, s68
	v_add3_u32 v42, v42, v52, s68
	v_lshrrev_b32_e32 v44, 16, v44
	v_lshrrev_b32_e32 v45, 16, v45
	v_lshrrev_b32_e32 v42, 16, v42
	v_lshrrev_b32_e32 v43, 16, v43
	v_and_or_b32 v45, v49, s69, v45
	v_and_or_b32 v44, v48, s69, v44
	v_and_or_b32 v43, v51, s69, v43
	v_and_or_b32 v42, v50, s69, v42
	global_store_dwordx4 v[58:59], v[42:45], off offset:2048
	s_waitcnt vmcnt(11)
	v_mov_b32_e32 v47, v8
	v_mov_b32_e32 v8, v7
	s_waitcnt vmcnt(9)
	v_mov_b32_e32 v44, v30
	s_waitcnt vmcnt(7)
	v_mov_b32_e32 v45, v34
	v_mov_b32_e32 v49, v4
	s_waitcnt vmcnt(5)
	v_mov_b32_e32 v50, v10
	s_waitcnt vmcnt(3)
	v_mov_b32_e32 v51, v14
	v_mov_b32_e32 v4, v3
	v_mov_b32_e32 v42, v18
	v_mov_b32_e32 v43, v38
	v_mov_b32_e32 v46, v6
	v_pk_mul_f32 v[6:7], v[44:45], v[8:9]
	v_mov_b32_e32 v44, v22
	v_mov_b32_e32 v45, v26
	v_mov_b32_e32 v48, v2
	v_pk_mul_f32 v[2:3], v[50:51], v[4:5]
	v_pk_mul_f32 v[42:43], v[42:43], v[46:47]
	v_pk_mul_f32 v[44:45], v[44:45], v[48:49]
	v_bfe_u32 v14, v2, 16, 1
	v_bfe_u32 v18, v7, 16, 1
	v_bfe_u32 v10, v3, 16, 1
	v_add3_u32 v7, v7, v18, s68
	v_add3_u32 v2, v2, v14, s68
	v_bfe_u32 v14, v45, 16, 1
	v_bfe_u32 v22, v43, 16, 1
	v_add3_u32 v3, v3, v10, s68
	v_bfe_u32 v10, v44, 16, 1
	v_add3_u32 v14, v45, v14, s68
	v_add3_u32 v22, v43, v22, s68
	v_add3_u32 v10, v44, v10, s68
	v_lshrrev_b32_e32 v14, 16, v14
	v_lshrrev_b32_e32 v22, 16, v22
	v_mov_b32_e32 v34, v31
	v_lshrrev_b32_e32 v10, 16, v10
	v_and_or_b32 v45, v3, s69, v14
	v_and_or_b32 v43, v7, s69, v22
	v_cvt_pk_bf16_f32 v42, v42, v6
	v_mov_b32_e32 v38, v19
	v_pk_mul_f32 v[6:7], v[34:35], v[8:9]
	v_mov_b32_e32 v14, v11
	v_and_or_b32 v44, v2, s69, v10
	v_pk_mul_f32 v[2:3], v[38:39], v[46:47]
	v_mov_b32_e32 v26, v23
	v_pk_mul_f32 v[10:11], v[14:15], v[4:5]
	v_pk_mul_f32 v[18:19], v[26:27], v[48:49]
	v_bfe_u32 v14, v11, 16, 1
	v_add3_u32 v11, v11, v14, s68
	v_bfe_u32 v15, v19, 16, 1
	v_add3_u32 v15, v19, v15, s68
	global_store_dwordx4 v[66:67], v[42:45], off offset:32
	v_lshrrev_b32_e32 v15, 16, v15
	s_nop 1
	v_cvt_pk_bf16_f32 v43, v3, v7
	v_cvt_pk_bf16_f32 v42, v2, v6
	v_mov_b32_e32 v6, v32
	v_mov_b32_e32 v7, v36
	v_and_or_b32 v45, v11, s69, v15
	v_cvt_pk_bf16_f32 v44, v18, v10
	v_mov_b32_e32 v2, v20
	v_mov_b32_e32 v3, v40
	v_pk_mul_f32 v[6:7], v[6:7], v[8:9]
	v_mov_b32_e32 v14, v12
	v_mov_b32_e32 v15, v16
	v_pk_mul_f32 v[2:3], v[2:3], v[46:47]
	v_mov_b32_e32 v10, v24
	v_mov_b32_e32 v11, v28
	v_pk_mul_f32 v[14:15], v[14:15], v[4:5]
	v_pk_mul_f32 v[10:11], v[10:11], v[48:49]
	v_bfe_u32 v12, v15, 16, 1
	v_add3_u32 v12, v15, v12, s68
	v_bfe_u32 v16, v11, 16, 1
	v_add3_u32 v11, v11, v16, s68
	v_mov_b32_e32 v36, v33
	v_mov_b32_e32 v16, v13
	global_store_dwordx4 v[66:67], v[42:45], off offset:2080
	v_lshrrev_b32_e32 v11, 16, v11
	s_nop 1
	v_cvt_pk_bf16_f32 v43, v3, v7
	v_cvt_pk_bf16_f32 v42, v2, v6
	v_mov_b32_e32 v40, v21
	v_pk_mul_f32 v[6:7], v[36:37], v[8:9]
	v_mov_b32_e32 v28, v25
	v_pk_mul_f32 v[4:5], v[16:17], v[4:5]
	v_and_or_b32 v45, v12, s69, v11
	v_cvt_pk_bf16_f32 v44, v10, v14
	v_pk_mul_f32 v[2:3], v[40:41], v[46:47]
	v_pk_mul_f32 v[8:9], v[28:29], v[48:49]
	v_cvt_pk_bf16_f32 v5, v9, v5
	v_cvt_pk_bf16_f32 v4, v8, v4
	v_cvt_pk_bf16_f32 v3, v3, v7
	v_cvt_pk_bf16_f32 v2, v2, v6
	global_store_dwordx4 v[58:59], v[2:5], off offset:2080
	v_or_b32_e32 v6, 32, v72
	global_store_dwordx4 v[58:59], v[94:97], off
	v_add_co_u32_e32 v4, vcc, s66, v68
	global_store_dwordx4 v[58:59], v[42:45], off offset:32
	v_mad_u64_u32 v[2:3], s[10:11], v6, s73, v[70:71]
	v_addc_co_u32_e32 v5, vcc, 0, v69, vcc
	global_load_dwordx4 v[42:45], v[2:3], off nt
	global_load_dwordx4 v[46:49], v[4:5], off offset:3072 nt
	v_add_co_u32_e32 v2, vcc, s8, v68
	s_mov_b32 s8, 0x1a000
	s_nop 0
	v_addc_co_u32_e32 v3, vcc, 0, v69, vcc
	v_add_co_u32_e32 v4, vcc, s8, v68
	s_mov_b32 s8, 0x1b000
	s_nop 0
	v_addc_co_u32_e32 v5, vcc, 0, v69, vcc
	global_load_dwordx4 v[50:53], v[2:3], off offset:2048 nt
	global_load_dwordx4 v[54:57], v[4:5], off offset:1024 nt
	v_lshlrev_b32_e32 v2, 2, v6
	global_load_dwordx4 v[60:63], v2, s[6:7] offset:16
	global_load_dwordx4 v[74:77], v2, s[6:7]
	v_add_co_u32_e32 v2, vcc, s8, v68
	s_mov_b32 s8, 0x1c000
	s_nop 0
	v_addc_co_u32_e32 v3, vcc, 0, v69, vcc
	global_load_dwordx4 v[78:81], v[2:3], off nt
	global_load_dwordx4 v[86:89], v[2:3], off offset:3072 nt
	v_add_co_u32_e32 v2, vcc, s8, v68
	v_or_b32_e32 v34, 48, v72
	s_nop 0
	v_addc_co_u32_e32 v3, vcc, 0, v69, vcc
	global_load_dwordx4 v[90:93], v[2:3], off offset:2048 nt
	v_add_co_u32_e32 v2, vcc, s82, v68
	v_lshlrev_b32_e32 v38, 2, v34
	s_nop 0
	v_addc_co_u32_e32 v3, vcc, 0, v69, vcc
	global_load_dwordx4 v[94:97], v[2:3], off offset:1024 nt
	v_add_co_u32_e32 v4, vcc, s83, v68
	v_mad_u64_u32 v[2:3], s[10:11], v34, s73, v[70:71]
	s_nop 0
	v_addc_co_u32_e32 v5, vcc, 0, v69, vcc
	v_add_co_u32_e32 v10, vcc, s84, v68
	global_load_dwordx4 v[6:9], v[2:3], off nt
	s_nop 0
	global_load_dwordx4 v[2:5], v[4:5], off offset:3072 nt
	v_addc_co_u32_e32 v11, vcc, 0, v69, vcc
	v_add_co_u32_e32 v12, vcc, s85, v68
	s_mov_b32 s8, 4
	s_nop 0
	v_addc_co_u32_e32 v13, vcc, 0, v69, vcc
	v_add_co_u32_e32 v14, vcc, s86, v68
	global_load_dwordx4 v[18:21], v[10:11], off offset:2048 nt
	s_nop 0
	global_load_dwordx4 v[10:13], v[12:13], off offset:1024 nt
	v_addc_co_u32_e32 v15, vcc, 0, v69, vcc
	v_add_co_u32_e32 v26, vcc, s87, v68
	global_load_dwordx4 v[22:25], v[14:15], off nt
	s_nop 0
	global_load_dwordx4 v[14:17], v[14:15], off offset:3072 nt
	v_addc_co_u32_e32 v27, vcc, 0, v69, vcc
	v_add_co_u32_e32 v28, vcc, s88, v68
	s_waitcnt vmcnt(15)
	v_mov_b32_e32 v64, v42
	v_addc_co_u32_e32 v29, vcc, 0, v69, vcc
	global_load_dwordx4 v[30:33], v[26:27], off offset:2048 nt
	s_nop 0
	global_load_dwordx4 v[26:29], v[28:29], off offset:1024 nt
	s_nop 0
	global_load_dwordx4 v[34:37], v38, s[6:7] offset:16
	s_nop 0
	global_load_dwordx4 v[38:41], v38, s[6:7]
	s_waitcnt vmcnt(18)
	v_mov_b32_e32 v68, v46
	s_waitcnt vmcnt(17)
	v_mov_b32_e32 v65, v50
	s_waitcnt vmcnt(16)
	v_mov_b32_e32 v69, v54
	s_waitcnt vmcnt(14)
	v_mov_b32_e32 v73, v76
	v_mov_b32_e32 v76, v75
	v_mov_b32_e32 v72, v74
	v_pk_mul_f32 v[68:69], v[68:69], v[76:77]
	v_mov_b32_e32 v75, v62
	v_mov_b32_e32 v62, v61
	s_waitcnt vmcnt(12)
	v_mov_b32_e32 v98, v86
	v_pk_mul_f32 v[64:65], v[64:65], v[72:73]
	v_mov_b32_e32 v70, v78
	v_mov_b32_e32 v74, v60
	s_waitcnt vmcnt(11)
	v_mov_b32_e32 v71, v90
	v_pk_mul_f32 v[70:71], v[70:71], v[74:75]
	s_waitcnt vmcnt(10)
	v_mov_b32_e32 v99, v94
	v_pk_mul_f32 v[60:61], v[98:99], v[62:63]
	v_cvt_pk_bf16_f32 v68, v64, v68
	v_mov_b32_e32 v54, v47
	v_mov_b32_e32 v94, v87
	v_cvt_pk_bf16_f32 v70, v70, v60
	v_cvt_pk_bf16_f32 v69, v65, v69
	v_mov_b32_e32 v50, v43
	v_pk_mul_f32 v[46:47], v[54:55], v[76:77]
	v_mov_b32_e32 v90, v79
	v_pk_mul_f32 v[54:55], v[94:95], v[62:63]
	v_cvt_pk_bf16_f32 v71, v71, v61
	v_pk_mul_f32 v[42:43], v[50:51], v[72:73]
	v_pk_mul_f32 v[50:51], v[90:91], v[74:75]
	global_store_dwordx4 v[66:67], v[68:71], off offset:64
	s_nop 1
	v_cvt_pk_bf16_f32 v71, v51, v55
	v_cvt_pk_bf16_f32 v70, v50, v54
	v_cvt_pk_bf16_f32 v69, v43, v47
	v_cvt_pk_bf16_f32 v68, v42, v46
	v_mov_b32_e32 v46, v48
	v_mov_b32_e32 v47, v56
	v_mov_b32_e32 v54, v88
	v_mov_b32_e32 v55, v96
	v_pk_mul_f32 v[46:47], v[46:47], v[76:77]
	v_mov_b32_e32 v50, v80
	v_mov_b32_e32 v51, v92
	v_pk_mul_f32 v[54:55], v[54:55], v[62:63]
	v_mov_b32_e32 v42, v44
	v_mov_b32_e32 v43, v52
	v_pk_mul_f32 v[50:51], v[50:51], v[74:75]
	v_bfe_u32 v48, v54, 16, 1
	v_bfe_u32 v52, v47, 16, 1
	v_pk_mul_f32 v[42:43], v[42:43], v[72:73]
	v_bfe_u32 v44, v55, 16, 1
	v_add3_u32 v47, v47, v52, s68
	v_add3_u32 v48, v54, v48, s68
	v_bfe_u32 v52, v50, 16, 1
	v_bfe_u32 v54, v51, 16, 1
	v_add3_u32 v44, v55, v44, s68
	v_bfe_u32 v56, v43, 16, 1
	v_add3_u32 v51, v51, v54, s68
	v_add3_u32 v50, v50, v52, s68
	v_add3_u32 v43, v43, v56, s68
	v_lshrrev_b32_e32 v50, 16, v50
	v_lshrrev_b32_e32 v51, 16, v51
	v_mov_b32_e32 v56, v49
	v_mov_b32_e32 v96, v89
	global_store_dwordx4 v[66:67], v[68:71], off offset:2112
	v_lshrrev_b32_e32 v43, 16, v43
	s_nop 1
	v_and_or_b32 v71, v44, s69, v51
	v_and_or_b32 v70, v48, s69, v50
	v_mov_b32_e32 v52, v45
	v_pk_mul_f32 v[44:45], v[56:57], v[76:77]
	v_mov_b32_e32 v92, v81
	v_pk_mul_f32 v[48:49], v[96:97], v[62:63]
	v_and_or_b32 v69, v47, s69, v43
	v_cvt_pk_bf16_f32 v68, v42, v46
	v_pk_mul_f32 v[42:43], v[52:53], v[72:73]
	v_pk_mul_f32 v[46:47], v[92:93], v[74:75]
	v_bfe_u32 v52, v45, 16, 1
	v_bfe_u32 v53, v44, 16, 1
	v_add3_u32 v53, v44, v53, s68
	v_add3_u32 v52, v45, v52, s68
	v_bfe_u32 v50, v42, 16, 1
	v_bfe_u32 v51, v43, 16, 1
	v_add3_u32 v43, v43, v51, s68
	v_add3_u32 v42, v42, v50, s68
	v_lshrrev_b32_e32 v42, 16, v42
	v_lshrrev_b32_e32 v43, 16, v43
	v_cvt_pk_bf16_f32 v45, v47, v49
	v_cvt_pk_bf16_f32 v44, v46, v48
	v_and_or_b32 v43, v52, s69, v43
	v_and_or_b32 v42, v53, s69, v42
	global_store_dwordx4 v[58:59], v[42:45], off offset:2112
	s_waitcnt vmcnt(3)
	v_mov_b32_e32 v46, v38
	v_mov_b32_e32 v47, v40
	v_mov_b32_e32 v42, v6
	v_mov_b32_e32 v43, v18
	v_mov_b32_e32 v44, v2
	v_mov_b32_e32 v45, v10
	v_mov_b32_e32 v40, v39
	v_pk_mul_f32 v[42:43], v[42:43], v[46:47]
	v_pk_mul_f32 v[38:39], v[44:45], v[40:41]
	v_mov_b32_e32 v44, v22
	v_mov_b32_e32 v45, v30
	v_mov_b32_e32 v48, v34
	v_mov_b32_e32 v49, v36
	v_pk_mul_f32 v[44:45], v[44:45], v[48:49]
	v_mov_b32_e32 v50, v14
	v_mov_b32_e32 v51, v26
	v_mov_b32_e32 v36, v35
	v_pk_mul_f32 v[34:35], v[50:51], v[36:37]
	v_cvt_pk_bf16_f32 v43, v43, v39
	v_cvt_pk_bf16_f32 v42, v42, v38
	v_mov_b32_e32 v10, v3
	v_mov_b32_e32 v26, v15
	v_cvt_pk_bf16_f32 v45, v45, v35
	v_cvt_pk_bf16_f32 v44, v44, v34
	v_mov_b32_e32 v18, v7
	v_pk_mul_f32 v[2:3], v[10:11], v[40:41]
	v_mov_b32_e32 v30, v23
	v_pk_mul_f32 v[14:15], v[26:27], v[36:37]
	v_pk_mul_f32 v[6:7], v[18:19], v[46:47]
	v_pk_mul_f32 v[10:11], v[30:31], v[48:49]
	global_store_dwordx4 v[66:67], v[42:45], off offset:96
	global_store_dwordx4 v[58:59], v[68:71], off offset:64
	s_nop 0
	v_cvt_pk_bf16_f32 v45, v11, v15
	v_cvt_pk_bf16_f32 v44, v10, v14
	v_cvt_pk_bf16_f32 v43, v7, v3
	v_cvt_pk_bf16_f32 v42, v6, v2
	v_mov_b32_e32 v6, v4
	v_mov_b32_e32 v7, v12
	v_mov_b32_e32 v14, v16
	v_mov_b32_e32 v15, v28
	v_pk_mul_f32 v[6:7], v[6:7], v[40:41]
	v_mov_b32_e32 v10, v24
	v_mov_b32_e32 v11, v32
	v_pk_mul_f32 v[14:15], v[14:15], v[36:37]
	v_mov_b32_e32 v2, v8
	v_mov_b32_e32 v3, v20
	v_pk_mul_f32 v[10:11], v[10:11], v[48:49]
	v_bfe_u32 v8, v14, 16, 1
	v_pk_mul_f32 v[2:3], v[2:3], v[46:47]
	v_bfe_u32 v4, v15, 16, 1
	v_add3_u32 v8, v14, v8, s68
	v_bfe_u32 v12, v10, 16, 1
	v_bfe_u32 v14, v11, 16, 1
	v_add3_u32 v4, v15, v4, s68
	v_add3_u32 v11, v11, v14, s68
	v_add3_u32 v10, v10, v12, s68
	v_lshrrev_b32_e32 v10, 16, v10
	v_lshrrev_b32_e32 v11, 16, v11
	v_mov_b32_e32 v12, v5
	v_mov_b32_e32 v28, v17
	global_store_dwordx4 v[66:67], v[42:45], off offset:2144
	s_nop 1
	v_and_or_b32 v45, v4, s69, v11
	s_nop 1
	v_and_or_b32 v44, v8, s69, v10
	v_mov_b32_e32 v20, v9
	v_pk_mul_f32 v[4:5], v[12:13], v[40:41]
	v_mov_b32_e32 v32, v25
	v_pk_mul_f32 v[8:9], v[28:29], v[36:37]
	v_cvt_pk_bf16_f32 v43, v3, v7
	v_cvt_pk_bf16_f32 v42, v2, v6
	v_pk_mul_f32 v[2:3], v[20:21], v[46:47]
	v_pk_mul_f32 v[6:7], v[32:33], v[48:49]
	v_bfe_u32 v12, v5, 16, 1
	v_bfe_u32 v13, v4, 16, 1
	v_add3_u32 v13, v4, v13, s68
	v_add3_u32 v12, v5, v12, s68
	v_bfe_u32 v10, v2, 16, 1
	v_bfe_u32 v11, v3, 16, 1
	v_add3_u32 v3, v3, v11, s68
	v_add3_u32 v2, v2, v10, s68
	v_lshrrev_b32_e32 v2, 16, v2
	v_lshrrev_b32_e32 v3, 16, v3
	v_cvt_pk_bf16_f32 v5, v7, v9
	v_cvt_pk_bf16_f32 v4, v6, v8
	v_and_or_b32 v3, v12, s69, v3
	v_and_or_b32 v2, v13, s69, v2
	global_store_dwordx4 v[58:59], v[42:45], off offset:96
	global_store_dwordx4 v[58:59], v[2:5], off offset:2144

.LBB0_586:
	v_lshlrev_b32_e32 v84, 9, v86
	s_waitcnt vmcnt(15)
	v_mov_b32_e32 v80, v42
	s_waitcnt vmcnt(13)
	v_mov_b32_e32 v81, v50
	s_waitcnt vmcnt(11)
	v_mov_b32_e32 v108, v58
	s_waitcnt vmcnt(9)
	v_mov_b32_e32 v109, v66
	s_waitcnt lgkmcnt(0)
	v_lshl_add_u64 v[40:41], s[50:51], 0, v[84:85]
	s_lshl_b32 s8, s8, 1
	v_pk_mul_f32 v[80:81], v[80:81], v[74:75]
	v_mov_b32_e32 v98, v46
	v_mov_b32_e32 v99, v54
	v_pk_mul_f32 v[108:109], v[108:109], v[78:79]
	v_mov_b32_e32 v110, v62
	s_waitcnt vmcnt(8)
	v_mov_b32_e32 v111, v70
	v_lshl_add_u64 v[40:41], v[40:41], 0, s[8:9]
	v_lshlrev_b32_e32 v84, 1, v82
	v_pk_mul_f32 v[98:99], v[98:99], v[94:95]
	v_pk_mul_f32 v[110:111], v[110:111], v[92:93]
	v_lshl_add_u64 v[40:41], v[40:41], 0, v[84:85]
	v_lshl_add_u64 v[86:87], v[40:41], 0, s[12:13]
	v_add_co_u32_e32 v40, vcc, s89, v40
	v_cvt_pk_bf16_f32 v111, v109, v111
	v_cvt_pk_bf16_f32 v110, v108, v110
	v_cvt_pk_bf16_f32 v109, v81, v99
	v_cvt_pk_bf16_f32 v108, v80, v98
	v_addc_co_u32_e32 v41, vcc, 0, v41, vcc
	v_mov_b32_e32 v50, v43
	v_mov_b32_e32 v54, v47
	v_mov_b32_e32 v70, v63
	global_store_dwordx4 v[40:41], v[108:111], off
	v_pk_mul_f32 v[40:41], v[50:51], v[74:75]
	v_pk_mul_f32 v[42:43], v[54:55], v[94:95]
	v_mov_b32_e32 v66, v59
	v_pk_mul_f32 v[50:51], v[70:71], v[92:93]
	v_pk_mul_f32 v[46:47], v[66:67], v[78:79]
	v_bfe_u32 v54, v51, 16, 1
	v_bfe_u32 v55, v50, 16, 1
	v_bfe_u32 v58, v43, 16, 1
	v_bfe_u32 v59, v42, 16, 1
	v_add3_u32 v59, v42, v59, s68
	v_add3_u32 v58, v43, v58, s68
	v_add3_u32 v42, v50, v55, s68
	v_add3_u32 v43, v51, v54, s68
	v_bfe_u32 v50, v40, 16, 1
	v_bfe_u32 v51, v41, 16, 1
	v_bfe_u32 v54, v46, 16, 1
	v_bfe_u32 v55, v47, 16, 1
	v_add3_u32 v47, v47, v55, s68
	v_add3_u32 v46, v46, v54, s68
	v_add3_u32 v41, v41, v51, s68
	v_add3_u32 v40, v40, v50, s68
	v_lshrrev_b32_e32 v40, 16, v40
	v_lshrrev_b32_e32 v41, 16, v41
	v_lshrrev_b32_e32 v46, 16, v46
	v_lshrrev_b32_e32 v47, 16, v47
	v_and_or_b32 v43, v43, s69, v47
	v_and_or_b32 v42, v42, s69, v46
	v_and_or_b32 v41, v58, s69, v41
	v_and_or_b32 v40, v59, s69, v40
	global_store_dwordx4 v[86:87], v[40:43], off offset:512
	v_mov_b32_e32 v50, v64
	v_mov_b32_e32 v51, v72
	v_mov_b32_e32 v42, v48
	v_mov_b32_e32 v43, v56
	v_mov_b32_e32 v40, v44
	v_mov_b32_e32 v41, v52
	v_pk_mul_f32 v[42:43], v[42:43], v[94:95]
	v_mov_b32_e32 v46, v60
	v_mov_b32_e32 v47, v68
	v_pk_mul_f32 v[50:51], v[50:51], v[92:93]
	v_pk_mul_f32 v[40:41], v[40:41], v[74:75]
	v_pk_mul_f32 v[46:47], v[46:47], v[78:79]
	v_bfe_u32 v44, v51, 16, 1
	v_bfe_u32 v48, v50, 16, 1
	v_bfe_u32 v52, v43, 16, 1
	v_bfe_u32 v54, v42, 16, 1
	v_add3_u32 v54, v42, v54, s68
	v_add3_u32 v52, v43, v52, s68
	v_add3_u32 v42, v50, v48, s68
	v_add3_u32 v43, v51, v44, s68
	v_bfe_u32 v44, v40, 16, 1
	v_bfe_u32 v48, v41, 16, 1
	v_bfe_u32 v50, v46, 16, 1
	v_bfe_u32 v51, v47, 16, 1
	v_add3_u32 v47, v47, v51, s68
	v_add3_u32 v46, v46, v50, s68
	v_add3_u32 v41, v41, v48, s68
	v_add3_u32 v40, v40, v44, s68
	v_lshrrev_b32_e32 v40, 16, v40
	v_lshrrev_b32_e32 v41, 16, v41
	v_lshrrev_b32_e32 v44, 16, v46
	v_lshrrev_b32_e32 v46, 16, v47
	v_and_or_b32 v43, v43, s69, v46
	v_and_or_b32 v42, v42, s69, v44
	v_and_or_b32 v41, v52, s69, v41
	v_and_or_b32 v40, v54, s69, v40
	v_mov_b32_e32 v56, v49
	v_mov_b32_e32 v72, v65
	global_store_dwordx4 v[86:87], v[40:43], off offset:1024
	v_mov_b32_e32 v52, v45
	v_mov_b32_e32 v68, v61
	v_pk_mul_f32 v[42:43], v[56:57], v[94:95]
	v_pk_mul_f32 v[46:47], v[72:73], v[92:93]
	v_pk_mul_f32 v[40:41], v[52:53], v[74:75]
	v_pk_mul_f32 v[44:45], v[68:69], v[78:79]
	v_bfe_u32 v48, v47, 16, 1
	v_bfe_u32 v49, v46, 16, 1
	v_bfe_u32 v50, v43, 16, 1
	v_bfe_u32 v51, v42, 16, 1
	v_add3_u32 v51, v42, v51, s68
	v_add3_u32 v50, v43, v50, s68
	v_add3_u32 v42, v46, v49, s68
	v_add3_u32 v43, v47, v48, s68
	v_bfe_u32 v46, v40, 16, 1
	v_bfe_u32 v47, v41, 16, 1
	v_bfe_u32 v48, v44, 16, 1
	v_bfe_u32 v49, v45, 16, 1
	v_add3_u32 v45, v45, v49, s68
	v_add3_u32 v44, v44, v48, s68
	v_add3_u32 v41, v41, v47, s68
	v_add3_u32 v40, v40, v46, s68
	v_lshrrev_b32_e32 v40, 16, v40
	v_lshrrev_b32_e32 v41, 16, v41
	v_lshrrev_b32_e32 v44, 16, v44
	v_lshrrev_b32_e32 v45, 16, v45
	v_and_or_b32 v43, v43, s69, v45
	v_and_or_b32 v42, v42, s69, v44
	v_and_or_b32 v41, v50, s69, v41
	v_and_or_b32 v40, v51, s69, v40
	global_store_dwordx4 v[86:87], v[40:43], off offset:1536
	s_waitcnt vmcnt(7)
	v_mov_b32_e32 v44, v26
	s_waitcnt vmcnt(5)
	v_mov_b32_e32 v45, v34
	v_mov_b32_e32 v40, v10
	v_mov_b32_e32 v41, v18
	v_pk_mul_f32 v[40:41], v[40:41], v[2:3]
	v_mov_b32_e32 v42, v6
	v_mov_b32_e32 v43, v14
	v_pk_mul_f32 v[44:45], v[44:45], v[38:39]
	v_mov_b32_e32 v46, v22
	s_waitcnt vmcnt(4)
	v_mov_b32_e32 v47, v30
	v_pk_mul_f32 v[42:43], v[42:43], v[76:77]
	v_pk_mul_f32 v[46:47], v[46:47], v[4:5]
	v_bfe_u32 v22, v40, 16, 1
	v_bfe_u32 v18, v42, 16, 1
	v_add3_u32 v22, v40, v22, s68
	v_add3_u32 v18, v42, v18, s68
	v_lshrrev_b32_e32 v22, 16, v22
	v_cvt_pk_bf16_f32 v42, v44, v46
	v_cvt_pk_bf16_f32 v41, v41, v43
	v_and_or_b32 v40, v18, s69, v22
	v_mov_b32_e32 v18, v11
	v_mov_b32_e32 v14, v7
	v_mov_b32_e32 v30, v23
	v_cvt_pk_bf16_f32 v43, v45, v47
	v_pk_mul_f32 v[10:11], v[18:19], v[2:3]
	v_pk_mul_f32 v[6:7], v[14:15], v[76:77]
	v_mov_b32_e32 v34, v27
	v_pk_mul_f32 v[18:19], v[30:31], v[4:5]
	v_pk_mul_f32 v[14:15], v[34:35], v[38:39]
	global_store_dwordx4 v[86:87], v[40:43], off offset:32
	v_lshl_or_b32 v84, v97, 13, v104
	s_mov_b32 s8, 0x48000
	v_cvt_pk_bf16_f32 v43, v15, v19
	v_cvt_pk_bf16_f32 v42, v14, v18
	v_cvt_pk_bf16_f32 v41, v11, v7
	v_cvt_pk_bf16_f32 v40, v10, v6
	v_mov_b32_e32 v10, v8
	v_mov_b32_e32 v11, v16
	v_mov_b32_e32 v18, v24
	v_mov_b32_e32 v19, v32
	v_mov_b32_e32 v6, v12
	v_mov_b32_e32 v7, v20
	v_pk_mul_f32 v[10:11], v[10:11], v[76:77]
	v_pk_mul_f32 v[18:19], v[18:19], v[4:5]
	v_pk_mul_f32 v[6:7], v[6:7], v[2:3]
	v_mov_b32_e32 v14, v28
	v_mov_b32_e32 v15, v36
	v_bfe_u32 v12, v18, 16, 1
	v_bfe_u32 v16, v11, 16, 1
	v_pk_mul_f32 v[14:15], v[14:15], v[38:39]
	v_bfe_u32 v8, v19, 16, 1
	v_bfe_u32 v20, v10, 16, 1
	v_add3_u32 v11, v11, v16, s68
	v_add3_u32 v12, v18, v12, s68
	v_bfe_u32 v16, v6, 16, 1
	v_bfe_u32 v18, v7, 16, 1
	v_add3_u32 v10, v10, v20, s68
	v_add3_u32 v8, v19, v8, s68
	v_bfe_u32 v19, v14, 16, 1
	v_bfe_u32 v20, v15, 16, 1
	v_add3_u32 v7, v7, v18, s68
	v_add3_u32 v6, v6, v16, s68
	v_add3_u32 v15, v15, v20, s68
	v_add3_u32 v14, v14, v19, s68
	v_lshrrev_b32_e32 v6, 16, v6
	v_lshrrev_b32_e32 v7, 16, v7
	v_mov_b32_e32 v16, v9
	v_mov_b32_e32 v32, v25
	global_store_dwordx4 v[86:87], v[40:43], off offset:544
	v_lshrrev_b32_e32 v14, 16, v14
	v_lshrrev_b32_e32 v15, 16, v15
	v_and_or_b32 v41, v11, s69, v7
	v_and_or_b32 v40, v10, s69, v6
	v_mov_b32_e32 v20, v13
	v_pk_mul_f32 v[6:7], v[16:17], v[76:77]
	v_mov_b32_e32 v36, v29
	v_pk_mul_f32 v[4:5], v[32:33], v[4:5]
	v_and_or_b32 v43, v8, s69, v15
	v_and_or_b32 v42, v12, s69, v14
	v_pk_mul_f32 v[2:3], v[20:21], v[2:3]
	v_pk_mul_f32 v[8:9], v[36:37], v[38:39]
	v_cvt_pk_bf16_f32 v5, v9, v5
	v_cvt_pk_bf16_f32 v4, v8, v4
	v_cvt_pk_bf16_f32 v3, v3, v7
	v_cvt_pk_bf16_f32 v2, v2, v6
	global_store_dwordx4 v[86:87], v[2:5], off offset:1568
	global_store_dwordx4 v[86:87], v[40:43], off offset:1056
	v_mov_b32_e32 v74, 1.0
	v_add_co_u32_e32 v4, vcc, s90, v88
	v_lshl_add_u64 v[2:3], v[90:91], 0, v[84:85]
	s_nop 0
	v_addc_co_u32_e32 v5, vcc, 0, v89, vcc
	global_load_dwordx4 v[46:49], v[2:3], off nt
	global_load_dwordx4 v[38:41], v[4:5], off nt
	v_add_co_u32_e32 v2, vcc, s91, v88
	v_mov_b32_e32 v94, 1.0
	s_nop 0
	v_addc_co_u32_e32 v3, vcc, 0, v89, vcc
	v_add_co_u32_e32 v4, vcc, 0x46000, v88
	v_mov_b32_e32 v75, 1.0
	s_nop 0
	v_addc_co_u32_e32 v5, vcc, 0, v89, vcc
	global_load_dwordx4 v[54:57], v[2:3], off nt
	global_load_dwordx4 v[50:53], v[4:5], off nt
	v_add_co_u32_e32 v2, vcc, s8, v88
	v_mov_b32_e32 v95, 1.0
	s_nop 0
	v_addc_co_u32_e32 v3, vcc, 0, v89, vcc
	v_add_co_u32_e32 v4, vcc, 0x4a000, v88
	v_mov_b32_e32 v78, 1.0
	s_nop 0
	v_addc_co_u32_e32 v5, vcc, 0, v89, vcc
	global_load_dwordx4 v[62:65], v[2:3], off nt
	global_load_dwordx4 v[58:61], v[4:5], off nt
	v_add_co_u32_e32 v2, vcc, 0x4c000, v88
	v_mov_b32_e32 v92, 1.0
	s_nop 0
	v_addc_co_u32_e32 v3, vcc, 0, v89, vcc
	v_add_co_u32_e32 v4, vcc, 0x4e000, v88
	v_mov_b32_e32 v79, 1.0
	s_nop 0
	v_addc_co_u32_e32 v5, vcc, 0, v89, vcc
	global_load_dwordx4 v[70:73], v[2:3], off nt
	global_load_dwordx4 v[66:69], v[4:5], off nt
	v_mov_b32_e32 v2, 1.0
	s_and_b64 vcc, exec, s[6:7]
	v_mov_b32_e32 v93, 1.0
	s_cbranch_vccnz .LBB0_588
	global_load_dwordx4 v[74:77], v96, s[10:11] offset:128
	global_load_dwordx4 v[78:81], v96, s[10:11] offset:144
	s_waitcnt vmcnt(1)
	v_mov_b32_e32 v94, v75
	v_mov_b32_e32 v75, v76
	v_mov_b32_e32 v95, v77
	s_waitcnt vmcnt(0)
	v_mov_b32_e32 v92, v79
	v_mov_b32_e32 v79, v80
	v_mov_b32_e32 v93, v81

.LBB0_590:
	s_waitcnt vmcnt(15)
	v_mov_b32_e32 v44, v46
	s_waitcnt vmcnt(13)
	v_mov_b32_e32 v45, v54
	v_pk_mul_f32 v[44:45], v[44:45], v[74:75]
	v_mov_b32_e32 v80, v38
	s_waitcnt vmcnt(12)
	v_mov_b32_e32 v81, v50
	s_waitcnt vmcnt(11)
	v_mov_b32_e32 v88, v62
	s_waitcnt vmcnt(9)
	v_mov_b32_e32 v89, v70
	v_pk_mul_f32 v[80:81], v[80:81], v[94:95]
	v_pk_mul_f32 v[88:89], v[88:89], v[78:79]
	v_mov_b32_e32 v90, v58
	s_waitcnt vmcnt(8)
	v_mov_b32_e32 v91, v66
	v_bfe_u32 v62, v45, 16, 1
	v_pk_mul_f32 v[90:91], v[90:91], v[92:93]
	v_bfe_u32 v50, v81, 16, 1
	v_bfe_u32 v58, v44, 16, 1
	v_bfe_u32 v66, v88, 16, 1
	v_bfe_u32 v70, v89, 16, 1
	v_add3_u32 v45, v45, v62, s68
	v_bfe_u32 v38, v91, 16, 1
	v_bfe_u32 v54, v80, 16, 1
	v_add3_u32 v50, v81, v50, s68
	v_add3_u32 v70, v89, v70, s68
	v_add3_u32 v66, v88, v66, s68
	v_add3_u32 v44, v44, v58, s68
	v_lshrrev_b32_e32 v45, 16, v45
	v_bfe_u32 v46, v90, 16, 1
	v_add3_u32 v54, v80, v54, s68
	v_add3_u32 v38, v91, v38, s68
	v_lshrrev_b32_e32 v44, 16, v44
	v_lshrrev_b32_e32 v58, 16, v66
	v_lshrrev_b32_e32 v62, 16, v70
	v_and_or_b32 v89, v50, s69, v45
	v_mov_b32_e32 v50, v39
	v_mov_b32_e32 v66, v59
	v_add3_u32 v46, v90, v46, s68
	v_and_or_b32 v91, v38, s69, v62
	v_and_or_b32 v88, v54, s69, v44
	v_mov_b32_e32 v54, v47
	v_pk_mul_f32 v[38:39], v[50:51], v[94:95]
	v_mov_b32_e32 v70, v63
	v_pk_mul_f32 v[50:51], v[66:67], v[92:93]
	v_and_or_b32 v90, v46, s69, v58
	v_pk_mul_f32 v[44:45], v[54:55], v[74:75]
	v_pk_mul_f32 v[46:47], v[70:71], v[78:79]
	v_cvt_pk_bf16_f32 v47, v47, v51
	v_cvt_pk_bf16_f32 v46, v46, v50
	v_cvt_pk_bf16_f32 v45, v45, v39
	v_cvt_pk_bf16_f32 v44, v44, v38
	global_store_dwordx4 v[86:87], v[44:47], off offset:576
	v_mov_b32_e32 v50, v60
	v_mov_b32_e32 v51, v68
	v_mov_b32_e32 v44, v40
	v_mov_b32_e32 v45, v52
	v_mov_b32_e32 v38, v48
	v_mov_b32_e32 v39, v56
	v_pk_mul_f32 v[44:45], v[44:45], v[94:95]
	v_mov_b32_e32 v46, v64
	v_mov_b32_e32 v47, v72
	v_pk_mul_f32 v[50:51], v[50:51], v[92:93]
	v_pk_mul_f32 v[38:39], v[38:39], v[74:75]
	v_pk_mul_f32 v[46:47], v[46:47], v[78:79]
	v_bfe_u32 v40, v51, 16, 1
	v_bfe_u32 v48, v50, 16, 1
	v_add3_u32 v48, v50, v48, s68
	v_add3_u32 v40, v51, v40, s68
	v_bfe_u32 v52, v46, 16, 1
	v_bfe_u32 v54, v47, 16, 1
	v_add3_u32 v47, v47, v54, s68
	v_add3_u32 v46, v46, v52, s68
	v_lshrrev_b32_e32 v46, 16, v46
	v_lshrrev_b32_e32 v47, 16, v47
	v_and_or_b32 v47, v40, s69, v47
	v_and_or_b32 v46, v48, s69, v46
	v_cvt_pk_bf16_f32 v45, v39, v45
	v_cvt_pk_bf16_f32 v44, v38, v44
	v_mov_b32_e32 v52, v41
	v_mov_b32_e32 v68, v61
	global_store_dwordx4 v[86:87], v[44:47], off offset:1088
	v_mov_b32_e32 v56, v49
	v_pk_mul_f32 v[40:41], v[52:53], v[94:95]
	v_mov_b32_e32 v72, v65
	v_pk_mul_f32 v[46:47], v[68:69], v[92:93]
	v_pk_mul_f32 v[38:39], v[56:57], v[74:75]
	v_pk_mul_f32 v[44:45], v[72:73], v[78:79]
	v_bfe_u32 v48, v47, 16, 1
	v_bfe_u32 v49, v46, 16, 1
	v_bfe_u32 v50, v41, 16, 1
	v_bfe_u32 v51, v40, 16, 1
	v_add3_u32 v51, v40, v51, s68
	v_add3_u32 v50, v41, v50, s68
	v_add3_u32 v40, v46, v49, s68
	v_add3_u32 v41, v47, v48, s68
	v_bfe_u32 v46, v38, 16, 1
	v_bfe_u32 v47, v39, 16, 1
	v_bfe_u32 v48, v44, 16, 1
	v_bfe_u32 v49, v45, 16, 1
	v_add3_u32 v45, v45, v49, s68
	v_add3_u32 v44, v44, v48, s68
	v_add3_u32 v39, v39, v47, s68
	v_add3_u32 v38, v38, v46, s68
	v_lshrrev_b32_e32 v38, 16, v38
	v_lshrrev_b32_e32 v39, 16, v39
	v_lshrrev_b32_e32 v44, 16, v44
	v_lshrrev_b32_e32 v45, 16, v45
	v_and_or_b32 v41, v41, s69, v45
	v_and_or_b32 v40, v40, s69, v44
	v_and_or_b32 v39, v50, s69, v39
	v_and_or_b32 v38, v51, s69, v38
	global_store_dwordx4 v[86:87], v[38:41], off offset:1600
	s_waitcnt vmcnt(6)
	v_mov_b32_e32 v44, v26
	s_waitcnt vmcnt(4)
	v_mov_b32_e32 v45, v34
	v_mov_b32_e32 v38, v10
	v_mov_b32_e32 v39, v18
	v_pk_mul_f32 v[38:39], v[38:39], v[2:3]
	v_mov_b32_e32 v40, v6
	v_mov_b32_e32 v41, v14
	v_pk_mul_f32 v[44:45], v[44:45], v[42:43]
	v_mov_b32_e32 v46, v22
	s_waitcnt vmcnt(3)
	v_mov_b32_e32 v47, v30
	v_pk_mul_f32 v[40:41], v[40:41], v[76:77]
	v_pk_mul_f32 v[46:47], v[46:47], v[4:5]
	v_bfe_u32 v22, v38, 16, 1
	v_bfe_u32 v18, v40, 16, 1
	v_add3_u32 v22, v38, v22, s68
	v_add3_u32 v18, v40, v18, s68
	v_lshrrev_b32_e32 v22, 16, v22
	v_cvt_pk_bf16_f32 v40, v44, v46
	v_cvt_pk_bf16_f32 v39, v39, v41
	v_and_or_b32 v38, v18, s69, v22
	v_mov_b32_e32 v18, v11
	v_mov_b32_e32 v14, v7
	v_mov_b32_e32 v30, v23
	v_cvt_pk_bf16_f32 v41, v45, v47
	v_pk_mul_f32 v[10:11], v[18:19], v[2:3]
	v_pk_mul_f32 v[6:7], v[14:15], v[76:77]
	v_mov_b32_e32 v34, v27
	v_pk_mul_f32 v[18:19], v[30:31], v[4:5]
	v_pk_mul_f32 v[14:15], v[34:35], v[42:43]
	global_store_dwordx4 v[86:87], v[38:41], off offset:96
	s_mov_b32 s8, 4
	global_store_dwordx4 v[86:87], v[88:91], off offset:64
	v_cvt_pk_bf16_f32 v41, v15, v19
	v_cvt_pk_bf16_f32 v40, v14, v18
	v_cvt_pk_bf16_f32 v39, v11, v7
	v_cvt_pk_bf16_f32 v38, v10, v6
	v_mov_b32_e32 v10, v8
	v_mov_b32_e32 v11, v16
	v_mov_b32_e32 v18, v24
	v_mov_b32_e32 v19, v32
	v_mov_b32_e32 v6, v12
	v_mov_b32_e32 v7, v20
	v_pk_mul_f32 v[10:11], v[10:11], v[76:77]
	v_pk_mul_f32 v[18:19], v[18:19], v[4:5]
	v_pk_mul_f32 v[6:7], v[6:7], v[2:3]
	v_mov_b32_e32 v14, v28
	v_mov_b32_e32 v15, v36
	v_bfe_u32 v12, v18, 16, 1
	v_bfe_u32 v16, v11, 16, 1
	v_pk_mul_f32 v[14:15], v[14:15], v[42:43]
	v_bfe_u32 v8, v19, 16, 1
	v_bfe_u32 v20, v10, 16, 1
	v_add3_u32 v11, v11, v16, s68
	v_add3_u32 v12, v18, v12, s68
	v_bfe_u32 v16, v6, 16, 1
	v_bfe_u32 v18, v7, 16, 1
	v_add3_u32 v10, v10, v20, s68
	v_add3_u32 v8, v19, v8, s68
	v_bfe_u32 v19, v14, 16, 1
	v_bfe_u32 v20, v15, 16, 1
	v_add3_u32 v7, v7, v18, s68
	v_add3_u32 v6, v6, v16, s68
	v_add3_u32 v15, v15, v20, s68
	v_add3_u32 v14, v14, v19, s68
	v_lshrrev_b32_e32 v6, 16, v6
	v_lshrrev_b32_e32 v7, 16, v7
	v_mov_b32_e32 v16, v9
	v_mov_b32_e32 v32, v25
	global_store_dwordx4 v[86:87], v[38:41], off offset:608
	v_lshrrev_b32_e32 v14, 16, v14
	v_lshrrev_b32_e32 v15, 16, v15
	v_and_or_b32 v39, v11, s69, v7
	v_and_or_b32 v38, v10, s69, v6
	v_mov_b32_e32 v20, v13
	v_pk_mul_f32 v[6:7], v[16:17], v[76:77]
	v_mov_b32_e32 v36, v29
	v_pk_mul_f32 v[4:5], v[32:33], v[4:5]
	v_and_or_b32 v41, v8, s69, v15
	v_and_or_b32 v40, v12, s69, v14
	v_pk_mul_f32 v[2:3], v[20:21], v[2:3]
	v_pk_mul_f32 v[8:9], v[36:37], v[42:43]
	v_cvt_pk_bf16_f32 v5, v9, v5
	v_cvt_pk_bf16_f32 v4, v8, v4
	v_cvt_pk_bf16_f32 v3, v3, v7
	v_cvt_pk_bf16_f32 v2, v2, v6
	global_store_dwordx4 v[86:87], v[38:41], off offset:1120
	global_store_dwordx4 v[86:87], v[2:5], off offset:1632

.LBB0_598:
	s_waitcnt vmcnt(11)
	v_mov_b32_e32 v96, v62
	s_waitcnt vmcnt(9)
	v_mov_b32_e32 v97, v70
	v_mov_b32_e32 v40, v54
	v_mov_b32_e32 v41, v58
	v_pk_mul_f32 v[96:97], v[96:97], v[78:79]
	v_mov_b32_e32 v98, v50
	s_waitcnt vmcnt(8)
	v_mov_b32_e32 v99, v66
	v_pk_mul_f32 v[40:41], v[40:41], v[74:75]
	v_mov_b32_e32 v88, v42
	v_mov_b32_e32 v89, v46
	v_pk_mul_f32 v[98:99], v[98:99], v[92:93]
	v_pk_mul_f32 v[88:89], v[88:89], v[94:95]
	v_bfe_u32 v58, v40, 16, 1
	v_add3_u32 v40, v40, v58, s68
	v_bfe_u32 v54, v88, 16, 1
	v_cvt_pk_bf16_f32 v98, v96, v98
	v_mov_b32_e32 v46, v43
	v_mov_b32_e32 v66, v51
	v_add3_u32 v54, v88, v54, s68
	v_lshrrev_b32_e32 v40, 16, v40
	v_cvt_pk_bf16_f32 v99, v97, v99
	v_cvt_pk_bf16_f32 v97, v41, v89
	v_mov_b32_e32 v58, v55
	v_pk_mul_f32 v[42:43], v[46:47], v[94:95]
	v_mov_b32_e32 v70, v63
	v_pk_mul_f32 v[50:51], v[66:67], v[92:93]
	v_and_or_b32 v96, v54, s69, v40
	v_pk_mul_f32 v[40:41], v[58:59], v[74:75]
	v_pk_mul_f32 v[46:47], v[70:71], v[78:79]
	v_bfe_u32 v54, v51, 16, 1
	v_bfe_u32 v55, v50, 16, 1
	v_bfe_u32 v58, v43, 16, 1
	v_bfe_u32 v59, v42, 16, 1
	v_add3_u32 v59, v42, v59, s68
	v_add3_u32 v58, v43, v58, s68
	v_add3_u32 v42, v50, v55, s68
	v_add3_u32 v43, v51, v54, s68
	v_bfe_u32 v50, v40, 16, 1
	v_bfe_u32 v51, v41, 16, 1
	v_bfe_u32 v54, v46, 16, 1
	v_bfe_u32 v55, v47, 16, 1
	v_add3_u32 v47, v47, v55, s68
	v_add3_u32 v46, v46, v54, s68
	v_add3_u32 v41, v41, v51, s68
	v_add3_u32 v40, v40, v50, s68
	v_lshrrev_b32_e32 v40, 16, v40
	v_lshrrev_b32_e32 v41, 16, v41
	v_lshrrev_b32_e32 v46, 16, v46
	v_lshrrev_b32_e32 v47, 16, v47
	v_and_or_b32 v43, v43, s69, v47
	v_and_or_b32 v42, v42, s69, v46
	v_and_or_b32 v41, v58, s69, v41
	v_and_or_b32 v40, v59, s69, v40
	global_store_dwordx4 v[86:87], v[40:43], off offset:2048
	v_mov_b32_e32 v50, v52
	v_mov_b32_e32 v51, v68
	v_mov_b32_e32 v42, v44
	v_mov_b32_e32 v43, v48
	v_mov_b32_e32 v40, v56
	v_mov_b32_e32 v41, v60
	v_pk_mul_f32 v[42:43], v[42:43], v[94:95]
	v_mov_b32_e32 v46, v64
	v_mov_b32_e32 v47, v72
	v_pk_mul_f32 v[50:51], v[50:51], v[92:93]
	v_pk_mul_f32 v[40:41], v[40:41], v[74:75]
	v_pk_mul_f32 v[46:47], v[46:47], v[78:79]
	v_bfe_u32 v44, v51, 16, 1
	v_bfe_u32 v48, v50, 16, 1
	v_bfe_u32 v52, v43, 16, 1
	v_bfe_u32 v54, v42, 16, 1
	v_add3_u32 v54, v42, v54, s68
	v_add3_u32 v52, v43, v52, s68
	v_add3_u32 v42, v50, v48, s68
	v_add3_u32 v43, v51, v44, s68
	v_bfe_u32 v44, v40, 16, 1
	v_bfe_u32 v48, v41, 16, 1
	v_bfe_u32 v50, v46, 16, 1
	v_bfe_u32 v51, v47, 16, 1
	v_add3_u32 v47, v47, v51, s68
	v_add3_u32 v46, v46, v50, s68
	v_add3_u32 v41, v41, v48, s68
	v_add3_u32 v40, v40, v44, s68
	v_lshrrev_b32_e32 v40, 16, v40
	v_lshrrev_b32_e32 v41, 16, v41
	v_lshrrev_b32_e32 v44, 16, v46
	v_lshrrev_b32_e32 v46, 16, v47
	v_add_co_u32_e32 v88, vcc, s61, v86
	v_and_or_b32 v43, v43, s69, v46
	v_and_or_b32 v42, v42, s69, v44
	v_and_or_b32 v41, v52, s69, v41
	v_and_or_b32 v40, v54, s69, v40
	v_addc_co_u32_e32 v89, vcc, 0, v87, vcc
	v_mov_b32_e32 v48, v45
	v_mov_b32_e32 v68, v53
	global_store_dwordx4 v[88:89], v[40:43], off
	v_mov_b32_e32 v60, v57
	v_mov_b32_e32 v72, v65
	v_pk_mul_f32 v[42:43], v[48:49], v[94:95]
	v_pk_mul_f32 v[46:47], v[68:69], v[92:93]
	v_pk_mul_f32 v[40:41], v[60:61], v[74:75]
	v_pk_mul_f32 v[44:45], v[72:73], v[78:79]
	v_bfe_u32 v48, v47, 16, 1
	v_bfe_u32 v49, v46, 16, 1
	v_bfe_u32 v50, v43, 16, 1
	v_bfe_u32 v51, v42, 16, 1
	v_add3_u32 v51, v42, v51, s68
	v_add3_u32 v50, v43, v50, s68
	v_add3_u32 v42, v46, v49, s68
	v_add3_u32 v43, v47, v48, s68
	v_bfe_u32 v46, v40, 16, 1
	v_bfe_u32 v47, v41, 16, 1
	v_bfe_u32 v48, v44, 16, 1
	v_bfe_u32 v49, v45, 16, 1
	v_add3_u32 v45, v45, v49, s68
	v_add3_u32 v44, v44, v48, s68
	v_add3_u32 v41, v41, v47, s68
	v_add3_u32 v40, v40, v46, s68
	v_lshrrev_b32_e32 v40, 16, v40
	v_lshrrev_b32_e32 v41, 16, v41
	v_lshrrev_b32_e32 v44, 16, v44
	v_lshrrev_b32_e32 v45, 16, v45
	v_and_or_b32 v43, v43, s69, v45
	v_and_or_b32 v42, v42, s69, v44
	v_and_or_b32 v41, v50, s69, v41
	v_and_or_b32 v40, v51, s69, v40
	s_waitcnt vmcnt(5)
	v_mov_b32_e32 v44, v26
	s_waitcnt vmcnt(3)
	v_mov_b32_e32 v45, v34
	global_store_dwordx4 v[88:89], v[40:43], off offset:2048
	v_pk_mul_f32 v[44:45], v[44:45], v[38:39]
	v_mov_b32_e32 v46, v22
	v_mov_b32_e32 v40, v14
	v_mov_b32_e32 v41, v18
	s_waitcnt vmcnt(3)
	v_mov_b32_e32 v47, v30
	v_pk_mul_f32 v[40:41], v[40:41], v[2:3]
	v_mov_b32_e32 v42, v6
	v_mov_b32_e32 v43, v10
	v_pk_mul_f32 v[46:47], v[46:47], v[76:77]
	v_pk_mul_f32 v[42:43], v[42:43], v[80:81]
	v_bfe_u32 v22, v40, 16, 1
	v_bfe_u32 v18, v42, 16, 1
	v_bfe_u32 v26, v41, 16, 1
	v_add3_u32 v22, v40, v22, s68
	v_bfe_u32 v14, v43, 16, 1
	v_add3_u32 v18, v42, v18, s68
	v_add3_u32 v26, v41, v26, s68
	v_lshrrev_b32_e32 v22, 16, v22
	v_cvt_pk_bf16_f32 v42, v44, v46
	v_mov_b32_e32 v10, v7
	v_add3_u32 v14, v43, v14, s68
	v_lshrrev_b32_e32 v26, 16, v26
	v_cvt_pk_bf16_f32 v43, v45, v47
	v_and_or_b32 v40, v18, s69, v22
	v_mov_b32_e32 v18, v15
	v_pk_mul_f32 v[6:7], v[10:11], v[80:81]
	v_mov_b32_e32 v34, v27
	v_mov_b32_e32 v30, v23
	v_and_or_b32 v41, v14, s69, v26
	v_pk_mul_f32 v[14:15], v[18:19], v[2:3]
	v_pk_mul_f32 v[10:11], v[34:35], v[38:39]
	v_pk_mul_f32 v[18:19], v[30:31], v[76:77]
	global_store_dwordx4 v[86:87], v[40:43], off offset:32
	s_nop 1
	v_cvt_pk_bf16_f32 v43, v11, v19
	s_nop 1
	v_cvt_pk_bf16_f32 v42, v10, v18
	v_mov_b32_e32 v10, v8
	v_mov_b32_e32 v11, v12
	v_mov_b32_e32 v18, v24
	v_mov_b32_e32 v19, v32
	v_cvt_pk_bf16_f32 v41, v15, v7
	v_cvt_pk_bf16_f32 v40, v14, v6
	v_mov_b32_e32 v6, v16
	v_mov_b32_e32 v7, v20
	v_pk_mul_f32 v[10:11], v[10:11], v[80:81]
	v_mov_b32_e32 v14, v28
	v_mov_b32_e32 v15, v36
	v_pk_mul_f32 v[18:19], v[18:19], v[76:77]
	v_pk_mul_f32 v[6:7], v[6:7], v[2:3]
	v_pk_mul_f32 v[14:15], v[14:15], v[38:39]
	v_bfe_u32 v8, v19, 16, 1
	v_bfe_u32 v12, v18, 16, 1
	v_add3_u32 v12, v18, v12, s68
	v_add3_u32 v8, v19, v8, s68
	v_bfe_u32 v16, v6, 16, 1
	v_bfe_u32 v19, v14, 16, 1
	v_bfe_u32 v20, v10, 16, 1
	v_add3_u32 v14, v14, v19, s68
	v_add3_u32 v6, v6, v16, s68
	v_add3_u32 v10, v10, v20, s68
	v_bfe_u32 v20, v15, 16, 1
	v_lshrrev_b32_e32 v6, 16, v6
	v_lshrrev_b32_e32 v14, 16, v14
	v_mov_b32_e32 v32, v25
	global_store_dwordx4 v[86:87], v[40:43], off offset:2080
	v_add3_u32 v15, v15, v20, s68
	v_mov_b32_e32 v20, v17
	v_and_or_b32 v42, v12, s69, v14
	v_cvt_pk_bf16_f32 v41, v7, v11
	v_and_or_b32 v40, v10, s69, v6
	v_mov_b32_e32 v12, v9
	v_pk_mul_f32 v[10:11], v[32:33], v[76:77]
	v_lshrrev_b32_e32 v15, 16, v15
	v_pk_mul_f32 v[2:3], v[20:21], v[2:3]
	v_pk_mul_f32 v[6:7], v[12:13], v[80:81]
	v_mov_b32_e32 v36, v29
	v_and_or_b32 v43, v8, s69, v15
	v_pk_mul_f32 v[8:9], v[36:37], v[38:39]
	v_lshl_add_u64 v[4:5], v[90:91], 0, s[16:17]
	v_cvt_pk_bf16_f32 v6, v2, v6
	v_add_co_u32_e32 v2, vcc, s75, v4
	v_cvt_pk_bf16_f32 v9, v9, v11
	v_cvt_pk_bf16_f32 v8, v8, v10
	v_cvt_pk_bf16_f32 v7, v3, v7
	v_addc_co_u32_e32 v3, vcc, 0, v5, vcc
	s_mov_b32 s8, 0xa000
	global_store_dwordx4 v[88:89], v[6:9], off offset:2080
	global_store_dwordx4 v[86:87], v[96:99], off
	global_store_dwordx4 v[88:89], v[40:43], off offset:32
	v_add_co_u32_e32 v6, vcc, s8, v90
	v_mov_b32_e32 v74, 1.0
	s_nop 0
	v_addc_co_u32_e32 v7, vcc, 0, v91, vcc
	global_load_dwordx4 v[50:53], v[2:3], off nt
	global_load_dwordx4 v[42:45], v[6:7], off offset:1280 nt
	global_load_dwordx4 v[54:57], v[6:7], off offset:2560 nt
	global_load_dwordx4 v[46:49], v[6:7], off offset:3840 nt
	v_add_co_u32_e32 v2, vcc, 0xb000, v90
	v_mov_b32_e32 v94, 1.0
	s_nop 0
	v_addc_co_u32_e32 v3, vcc, 0, v91, vcc
	v_add_co_u32_e32 v6, vcc, 0xc000, v90
	global_load_dwordx4 v[62:65], v[2:3], off offset:1024 nt
	global_load_dwordx4 v[58:61], v[2:3], off offset:2304 nt
	v_addc_co_u32_e32 v7, vcc, 0, v91, vcc
	global_load_dwordx4 v[70:73], v[2:3], off offset:3584 nt
	global_load_dwordx4 v[66:69], v[6:7], off offset:768 nt
	v_mov_b32_e32 v2, 1.0
	s_and_b64 vcc, exec, s[6:7]
	v_mov_b32_e32 v75, 1.0
	v_mov_b32_e32 v95, 1.0
	v_mov_b32_e32 v78, 1.0
	v_mov_b32_e32 v92, 1.0
	v_mov_b32_e32 v79, 1.0
	v_mov_b32_e32 v93, 1.0
	s_cbranch_vccnz .LBB0_600
	global_load_dwordx4 v[74:77], v84, s[48:49] offset:128
	global_load_dwordx4 v[78:81], v84, s[48:49] offset:144
	s_waitcnt vmcnt(1)
	v_mov_b32_e32 v94, v75
	v_mov_b32_e32 v75, v76
	v_mov_b32_e32 v95, v77
	s_waitcnt vmcnt(0)
	v_mov_b32_e32 v92, v79
	v_mov_b32_e32 v79, v80
	v_mov_b32_e32 v93, v81

.LBB0_602:
	s_waitcnt vmcnt(14)
	v_mov_b32_e32 v40, v42
	s_waitcnt vmcnt(12)
	v_mov_b32_e32 v41, v46
	s_waitcnt vmcnt(11)
	v_mov_b32_e32 v90, v62
	s_waitcnt vmcnt(9)
	v_mov_b32_e32 v91, v70
	v_mov_b32_e32 v4, v50
	v_mov_b32_e32 v5, v54
	v_pk_mul_f32 v[40:41], v[40:41], v[94:95]
	v_pk_mul_f32 v[90:91], v[90:91], v[78:79]
	v_mov_b32_e32 v96, v58
	s_waitcnt vmcnt(8)
	v_mov_b32_e32 v97, v66
	v_pk_mul_f32 v[4:5], v[4:5], v[74:75]
	v_pk_mul_f32 v[96:97], v[96:97], v[92:93]
	v_cvt_pk_bf16_f32 v98, v90, v96
	v_mov_b32_e32 v46, v43
	v_mov_b32_e32 v66, v59
	v_cvt_pk_bf16_f32 v99, v91, v97
	v_cvt_pk_bf16_f32 v97, v5, v41
	v_cvt_pk_bf16_f32 v96, v4, v40
	v_mov_b32_e32 v54, v51
	v_pk_mul_f32 v[40:41], v[46:47], v[94:95]
	v_mov_b32_e32 v70, v63
	v_pk_mul_f32 v[46:47], v[66:67], v[92:93]
	v_pk_mul_f32 v[4:5], v[54:55], v[74:75]
	v_pk_mul_f32 v[42:43], v[70:71], v[78:79]
	v_cvt_pk_bf16_f32 v43, v43, v47
	v_cvt_pk_bf16_f32 v42, v42, v46
	v_cvt_pk_bf16_f32 v41, v5, v41
	v_cvt_pk_bf16_f32 v40, v4, v40
	global_store_dwordx4 v[86:87], v[40:43], off offset:2112
	v_mov_b32_e32 v46, v60
	v_mov_b32_e32 v47, v68
	v_mov_b32_e32 v40, v44
	v_mov_b32_e32 v41, v48
	v_mov_b32_e32 v4, v52
	v_mov_b32_e32 v5, v56
	v_pk_mul_f32 v[40:41], v[40:41], v[94:95]
	v_mov_b32_e32 v42, v64
	v_mov_b32_e32 v43, v72
	v_pk_mul_f32 v[46:47], v[46:47], v[92:93]
	v_pk_mul_f32 v[4:5], v[4:5], v[74:75]
	v_pk_mul_f32 v[42:43], v[42:43], v[78:79]
	v_bfe_u32 v44, v47, 16, 1
	v_add3_u32 v44, v47, v44, s68
	v_bfe_u32 v51, v43, 16, 1
	v_add3_u32 v43, v43, v51, s68
	v_lshrrev_b32_e32 v43, 16, v43
	v_and_or_b32 v43, v44, s69, v43
	v_cvt_pk_bf16_f32 v42, v42, v46
	v_cvt_pk_bf16_f32 v41, v5, v41
	v_cvt_pk_bf16_f32 v40, v4, v40
	v_mov_b32_e32 v48, v45
	v_mov_b32_e32 v68, v61
	global_store_dwordx4 v[88:89], v[40:43], off offset:64
	v_mov_b32_e32 v56, v53
	v_mov_b32_e32 v72, v65
	v_pk_mul_f32 v[40:41], v[48:49], v[94:95]
	v_pk_mul_f32 v[44:45], v[68:69], v[92:93]
	v_pk_mul_f32 v[4:5], v[56:57], v[74:75]
	v_pk_mul_f32 v[42:43], v[72:73], v[78:79]
	v_cvt_pk_bf16_f32 v43, v43, v45
	v_cvt_pk_bf16_f32 v42, v42, v44
	v_cvt_pk_bf16_f32 v41, v5, v41
	v_cvt_pk_bf16_f32 v40, v4, v40
	global_store_dwordx4 v[88:89], v[40:43], off offset:2112
	s_waitcnt vmcnt(10)
	v_mov_b32_e32 v4, v30
	s_waitcnt vmcnt(8)
	v_mov_b32_e32 v5, v34
	s_waitcnt vmcnt(6)
	v_mov_b32_e32 v42, v18
	s_waitcnt vmcnt(4)
	v_mov_b32_e32 v43, v14
	v_pk_mul_f32 v[42:43], v[42:43], v[38:39]
	v_mov_b32_e32 v44, v6
	s_waitcnt vmcnt(3)
	v_mov_b32_e32 v45, v10
	v_pk_mul_f32 v[4:5], v[4:5], v[2:3]
	v_mov_b32_e32 v40, v22
	v_mov_b32_e32 v41, v26
	v_pk_mul_f32 v[44:45], v[44:45], v[76:77]
	v_pk_mul_f32 v[40:41], v[40:41], v[80:81]
	v_bfe_u32 v22, v4, 16, 1
	v_bfe_u32 v26, v5, 16, 1
	v_bfe_u32 v14, v41, 16, 1
	v_add3_u32 v5, v5, v26, s68
	v_add3_u32 v4, v4, v22, s68
	v_bfe_u32 v18, v40, 16, 1
	v_add3_u32 v14, v41, v14, s68
	v_lshrrev_b32_e32 v5, 16, v5
	v_cvt_pk_bf16_f32 v43, v43, v45
	v_cvt_pk_bf16_f32 v42, v42, v44
	v_mov_b32_e32 v26, v23
	v_mov_b32_e32 v10, v7
	v_add3_u32 v18, v40, v18, s68
	v_lshrrev_b32_e32 v4, 16, v4
	v_and_or_b32 v41, v14, s69, v5
	v_mov_b32_e32 v34, v31
	v_pk_mul_f32 v[22:23], v[26:27], v[80:81]
	v_mov_b32_e32 v14, v19
	v_pk_mul_f32 v[6:7], v[10:11], v[76:77]
	v_and_or_b32 v40, v18, s69, v4
	v_pk_mul_f32 v[4:5], v[34:35], v[2:3]
	v_pk_mul_f32 v[14:15], v[14:15], v[38:39]
	v_bfe_u32 v10, v7, 16, 1
	v_bfe_u32 v18, v23, 16, 1
	v_add3_u32 v18, v23, v18, s68
	v_add3_u32 v7, v7, v10, s68
	v_bfe_u32 v11, v5, 16, 1
	v_bfe_u32 v23, v15, 16, 1
	v_add3_u32 v15, v15, v23, s68
	v_add3_u32 v5, v5, v11, s68
	v_lshrrev_b32_e32 v5, 16, v5
	v_lshrrev_b32_e32 v11, 16, v15
	v_and_or_b32 v7, v7, s69, v11
	v_cvt_pk_bf16_f32 v6, v14, v6
	v_and_or_b32 v5, v18, s69, v5
	v_cvt_pk_bf16_f32 v4, v4, v22
	global_store_dwordx4 v[86:87], v[4:7], off offset:2144
	v_mov_b32_e32 v14, v8
	v_mov_b32_e32 v15, v12
	v_mov_b32_e32 v6, v24
	v_mov_b32_e32 v7, v28
	v_mov_b32_e32 v4, v32
	v_mov_b32_e32 v5, v36
	v_pk_mul_f32 v[6:7], v[6:7], v[80:81]
	v_mov_b32_e32 v10, v20
	v_mov_b32_e32 v11, v16
	v_pk_mul_f32 v[14:15], v[14:15], v[76:77]
	v_pk_mul_f32 v[4:5], v[4:5], v[2:3]
	v_pk_mul_f32 v[10:11], v[10:11], v[38:39]
	v_bfe_u32 v8, v15, 16, 1
	v_bfe_u32 v12, v14, 16, 1
	v_bfe_u32 v16, v7, 16, 1
	v_bfe_u32 v18, v6, 16, 1
	v_add3_u32 v18, v6, v18, s68
	v_add3_u32 v16, v7, v16, s68
	v_add3_u32 v6, v14, v12, s68
	v_add3_u32 v7, v15, v8, s68
	v_bfe_u32 v8, v4, 16, 1
	v_bfe_u32 v12, v5, 16, 1
	v_bfe_u32 v14, v10, 16, 1
	v_bfe_u32 v15, v11, 16, 1
	v_add3_u32 v11, v11, v15, s68
	v_add3_u32 v10, v10, v14, s68
	v_add3_u32 v5, v5, v12, s68
	v_add3_u32 v4, v4, v8, s68
	v_lshrrev_b32_e32 v4, 16, v4
	v_lshrrev_b32_e32 v5, 16, v5
	v_lshrrev_b32_e32 v8, 16, v10
	v_lshrrev_b32_e32 v10, 16, v11
	v_mov_b32_e32 v36, v33
	v_and_or_b32 v7, v7, s69, v10
	v_and_or_b32 v6, v6, s69, v8
	v_and_or_b32 v5, v16, s69, v5
	v_and_or_b32 v4, v18, s69, v4
	v_pk_mul_f32 v[2:3], v[36:37], v[2:3]
	v_mov_b32_e32 v28, v25
	global_store_dwordx4 v[88:89], v[4:7], off offset:96
	v_mov_b32_e32 v8, v21
	v_mov_b32_e32 v12, v17
	v_pk_mul_f32 v[4:5], v[28:29], v[80:81]
	v_and_b32_sdwa v6, v3, v107 dst_sel:DWORD dst_unused:UNUSED_PAD src0_sel:WORD_1 src1_sel:DWORD
	v_and_b32_sdwa v7, v2, v107 dst_sel:DWORD dst_unused:UNUSED_PAD src0_sel:WORD_1 src1_sel:DWORD
	v_add3_u32 v2, v2, v7, s68
	v_add3_u32 v3, v3, v6, s68
	v_and_b32_sdwa v6, v5, v107 dst_sel:DWORD dst_unused:UNUSED_PAD src0_sel:WORD_1 src1_sel:DWORD
	v_and_b32_sdwa v7, v4, v107 dst_sel:DWORD dst_unused:UNUSED_PAD src0_sel:WORD_1 src1_sel:DWORD
	v_add3_u32 v5, v5, v6, s68
	v_add3_u32 v4, v4, v7, s68
	v_and_b32_e32 v5, 0xffff0000, v5
	v_and_b32_e32 v4, 0xffff0000, v4
	v_or_b32_sdwa v3, v5, v3 dst_sel:DWORD dst_unused:UNUSED_PAD src0_sel:DWORD src1_sel:WORD_1
	v_or_b32_sdwa v2, v4, v2 dst_sel:DWORD dst_unused:UNUSED_PAD src0_sel:DWORD src1_sel:WORD_1
	v_mov_b32_e32 v4, v38
	v_mov_b32_e32 v5, v76
	v_pk_mul_f32 v[4:5], v[8:9], v[4:5]
	v_mov_b32_e32 v76, v39
	v_and_b32_sdwa v6, v5, v107 dst_sel:DWORD dst_unused:UNUSED_PAD src0_sel:WORD_1 src1_sel:DWORD
	v_and_b32_sdwa v7, v4, v107 dst_sel:DWORD dst_unused:UNUSED_PAD src0_sel:WORD_1 src1_sel:DWORD
	v_add3_u32 v5, v5, v6, s68
	v_add3_u32 v4, v4, v7, s68
	v_pk_mul_f32 v[6:7], v[12:13], v[76:77]
	v_lshrrev_b32_e32 v4, 16, v4
	v_and_b32_sdwa v8, v6, v107 dst_sel:DWORD dst_unused:UNUSED_PAD src0_sel:WORD_1 src1_sel:DWORD
	v_and_or_b32 v4, v5, s69, v4
	v_and_b32_sdwa v5, v7, v107 dst_sel:DWORD dst_unused:UNUSED_PAD src0_sel:WORD_1 src1_sel:DWORD
	v_add3_u32 v6, v6, v8, s68
	v_add3_u32 v5, v7, v5, s68
	v_lshrrev_b32_e32 v6, 16, v6
	v_and_or_b32 v5, v5, s69, v6
	global_store_dwordx4 v[86:87], v[96:99], off offset:64
	global_store_dwordx4 v[86:87], v[40:43], off offset:96

.LBB0_607:
	s_andn2_b64 vcc, exec, s[6:7]
	s_cbranch_vccnz .LBB0_609
	s_mov_b64 s[6:7], s[0:1]
	s_mov_b64 s[10:11], s[0:1]
	s_load_dwordx2 s[6:7], s[6:7], 0x90
	s_load_dwordx2 s[10:11], s[10:11], 0xa8
	s_add_i32 s8, s3, 0xfffffc00
	s_and_b32 s48, s8, 0x7c0
	s_and_b32 s8, s56, 0x380
	v_or_b32_e32 v4, s8, v83
	v_lshlrev_b32_e32 v84, 11, v4
	s_waitcnt lgkmcnt(0)
	v_lshl_add_u64 v[2:3], s[10:11], 0, v[84:85]
	s_lshl_b32 s8, s48, 1
	v_lshl_add_u64 v[2:3], v[2:3], 0, s[8:9]
	v_lshlrev_b32_e32 v84, 1, v82
	v_lshl_add_u64 v[2:3], v[2:3], 0, v[84:85]
	v_or_b32_e32 v6, s48, v82
	v_lshlrev_b32_e32 v84, 2, v4
	v_lshl_add_u64 v[4:5], s[6:7], 0, v[84:85]
	v_lshlrev_b32_e32 v84, 12, v6
	v_lshl_add_u64 v[38:39], v[4:5], 0, v[84:85]
	v_add_co_u32_e32 v4, vcc, s74, v38
	global_load_dwordx4 v[40:43], v[38:39], off nt
	s_nop 0
	v_addc_co_u32_e32 v5, vcc, 0, v39, vcc
	global_load_dwordx4 v[44:47], v[4:5], off offset:-4096 nt
	global_load_dwordx4 v[48:51], v[4:5], off nt
	v_add_co_u32_e32 v4, vcc, s63, v38
	v_lshl_add_u64 v[36:37], v[2:3], 0, s[24:25]
	s_nop 0
	v_addc_co_u32_e32 v5, vcc, 0, v39, vcc
	global_load_dwordx4 v[52:55], v[4:5], off offset:-4096 nt
	global_load_dwordx4 v[56:59], v[4:5], off nt
	v_add_co_u32_e32 v4, vcc, s64, v38
	s_mov_b32 s8, 4
	s_nop 0
	v_addc_co_u32_e32 v5, vcc, 0, v39, vcc
	global_load_dwordx4 v[60:63], v[4:5], off offset:-4096 nt
	global_load_dwordx4 v[64:67], v[4:5], off nt
	v_add_co_u32_e32 v4, vcc, s65, v38
	s_waitcnt vmcnt(3)
	v_addc_co_u32_e32 v5, vcc, 0, v39, vcc
	global_load_dwordx4 v[68:71], v[4:5], off nt
	v_add_co_u32_e32 v34, vcc, s95, v2
	s_waitcnt vmcnt(3)
	v_addc_co_u32_e32 v35, vcc, 0, v3, vcc
	v_add_co_u32_e32 v2, vcc, s79, v38
	s_waitcnt vmcnt(1)
	v_addc_co_u32_e32 v3, vcc, 0, v39, vcc
	v_add_co_u32_e32 v4, vcc, s92, v38
	s_nop 0
	v_addc_co_u32_e32 v5, vcc, 0, v39, vcc
	v_add_co_u32_e32 v6, vcc, s93, v38
	s_nop 0
	v_addc_co_u32_e32 v7, vcc, 0, v39, vcc
	v_add_co_u32_e32 v72, vcc, s94, v38
	s_nop 0
	v_addc_co_u32_e32 v73, vcc, 0, v39, vcc
	global_load_dwordx4 v[30:33], v[2:3], off offset:-4096 nt
	global_load_dwordx4 v[26:29], v[2:3], off nt
	global_load_dwordx4 v[22:25], v[4:5], off offset:-4096 nt
	global_load_dwordx4 v[18:21], v[4:5], off nt
	global_load_dwordx4 v[14:17], v[6:7], off offset:-4096 nt
	global_load_dwordx4 v[10:13], v[6:7], off nt
	s_nop 0
	global_load_dwordx4 v[6:9], v[72:73], off offset:-4096 nt
	global_load_dwordx4 v[2:5], v[72:73], off nt
	v_cvt_pk_bf16_f32 v72, v40, v44
	v_cvt_pk_bf16_f32 v73, v48, v52
	v_cvt_pk_bf16_f32 v74, v56, v60
	s_waitcnt vmcnt(8)
	v_cvt_pk_bf16_f32 v75, v64, v68
	global_store_dwordx4 v[34:35], v[72:75], off offset:-4096
	s_nop 1
	v_cvt_pk_bf16_f32 v72, v41, v45
	s_nop 1
	v_cvt_pk_bf16_f32 v73, v49, v53
	v_cvt_pk_bf16_f32 v74, v57, v61
	v_cvt_pk_bf16_f32 v75, v65, v69
	v_bfe_u32 v40, v42, 16, 1
	v_add3_u32 v40, v42, v40, s68
	v_bfe_u32 v41, v46, 16, 1
	v_lshrrev_b32_e32 v40, 16, v40
	v_add3_u32 v41, v46, v41, s68
	global_store_dwordx4 v[36:37], v[72:75], off offset:2048
	s_nop 1
	v_and_or_b32 v72, v41, s69, v40
	s_nop 1
	v_cvt_pk_bf16_f32 v73, v50, v54
	v_cvt_pk_bf16_f32 v74, v58, v62
	v_cvt_pk_bf16_f32 v75, v66, v70
	v_cvt_pk_bf16_f32 v40, v43, v47
	v_cvt_pk_bf16_f32 v41, v51, v55
	v_cvt_pk_bf16_f32 v42, v59, v63
	v_cvt_pk_bf16_f32 v43, v67, v71
	global_store_dwordx4 v[34:35], v[40:43], off offset:2048
	global_store_dwordx4 v[34:35], v[72:75], off
	s_waitcnt vmcnt(11)
	s_waitcnt vmcnt(10)
	v_cvt_pk_bf16_f32 v40, v30, v26
	s_waitcnt vmcnt(9)
	s_waitcnt vmcnt(8)
	v_cvt_pk_bf16_f32 v41, v22, v18
	s_waitcnt vmcnt(7)
	s_waitcnt vmcnt(6)
	v_cvt_pk_bf16_f32 v42, v14, v10
	s_waitcnt vmcnt(5)
	s_waitcnt vmcnt(4)
	v_cvt_pk_bf16_f32 v43, v6, v2
	global_store_dwordx4 v[36:37], v[40:43], off offset:32
	s_nop 1
	v_cvt_pk_bf16_f32 v40, v31, v27
	v_cvt_pk_bf16_f32 v41, v23, v19
	v_cvt_pk_bf16_f32 v42, v15, v11
	v_cvt_pk_bf16_f32 v43, v7, v3
	global_store_dwordx4 v[36:37], v[40:43], off offset:2080
	s_nop 1
	v_cvt_pk_bf16_f32 v40, v32, v28
	s_nop 1
	v_cvt_pk_bf16_f32 v41, v24, v20
	v_cvt_pk_bf16_f32 v42, v16, v12
	v_cvt_pk_bf16_f32 v43, v8, v4
	v_cvt_pk_bf16_f32 v2, v33, v29
	v_cvt_pk_bf16_f32 v3, v25, v21
	v_cvt_pk_bf16_f32 v4, v17, v13
	v_cvt_pk_bf16_f32 v5, v9, v5
	v_add_co_u32_e32 v6, vcc, s67, v38
	global_store_dwordx4 v[34:35], v[40:43], off offset:32
	global_store_dwordx4 v[34:35], v[2:5], off offset:2080
	v_addc_co_u32_e32 v7, vcc, 0, v39, vcc
	global_load_dwordx4 v[2:5], v[6:7], off offset:-4096 nt
	s_nop 0
	global_load_dwordx4 v[6:9], v[6:7], off nt
	v_add_co_u32_e32 v14, vcc, s96, v38
	s_nop 1
	v_addc_co_u32_e32 v15, vcc, 0, v39, vcc
	global_load_dwordx4 v[10:13], v[14:15], off offset:-4096 nt
	s_nop 0
	global_load_dwordx4 v[14:17], v[14:15], off nt
	v_add_co_u32_e32 v22, vcc, s84, v38
	s_nop 1
	v_addc_co_u32_e32 v23, vcc, 0, v39, vcc
	global_load_dwordx4 v[18:21], v[22:23], off offset:-4096 nt
	s_nop 0
	global_load_dwordx4 v[22:25], v[22:23], off nt
	v_add_co_u32_e32 v30, vcc, s86, v38
	s_nop 1
	v_addc_co_u32_e32 v31, vcc, 0, v39, vcc
	global_load_dwordx4 v[26:29], v[30:31], off offset:-4096 nt
	s_nop 0
	global_load_dwordx4 v[30:33], v[30:31], off nt
	v_add_co_u32_e32 v44, vcc, s70, v38
	s_nop 1
	v_addc_co_u32_e32 v45, vcc, 0, v39, vcc
	global_load_dwordx4 v[40:43], v[44:45], off offset:-4096 nt
	s_nop 0
	global_load_dwordx4 v[44:47], v[44:45], off nt
	v_add_co_u32_e32 v52, vcc, s71, v38
	s_nop 1
	v_addc_co_u32_e32 v53, vcc, 0, v39, vcc
	global_load_dwordx4 v[48:51], v[52:53], off offset:-4096 nt
	s_nop 0
	global_load_dwordx4 v[52:55], v[52:53], off nt
	v_add_co_u32_e32 v60, vcc, s97, v38
	s_nop 1
	v_addc_co_u32_e32 v61, vcc, 0, v39, vcc
	global_load_dwordx4 v[56:59], v[60:61], off offset:-4096 nt
	s_nop 0
	global_load_dwordx4 v[60:63], v[60:61], off nt
	v_add_co_u32_e32 v38, vcc, s72, v38
	s_nop 1
	v_addc_co_u32_e32 v39, vcc, 0, v39, vcc
	global_load_dwordx4 v[64:67], v[38:39], off offset:-4096 nt
	global_load_dwordx4 v[68:71], v[38:39], off nt
	s_waitcnt vmcnt(15)
	s_waitcnt vmcnt(14)
	v_cvt_pk_bf16_f32 v72, v2, v6
	s_waitcnt vmcnt(13)
	s_waitcnt vmcnt(12)
	v_cvt_pk_bf16_f32 v73, v10, v14
	s_waitcnt vmcnt(11)
	s_waitcnt vmcnt(10)
	v_cvt_pk_bf16_f32 v74, v18, v22
	s_waitcnt vmcnt(9)
	s_waitcnt vmcnt(8)
	v_cvt_pk_bf16_f32 v75, v26, v30
	global_store_dwordx4 v[36:37], v[72:75], off offset:64
	s_nop 1
	v_cvt_pk_bf16_f32 v72, v3, v7
	s_nop 1
	v_cvt_pk_bf16_f32 v73, v11, v15
	v_cvt_pk_bf16_f32 v74, v19, v23
	v_cvt_pk_bf16_f32 v75, v27, v31
	v_bfe_u32 v2, v4, 16, 1
	v_add3_u32 v2, v4, v2, s68
	v_bfe_u32 v3, v8, 16, 1
	v_lshrrev_b32_e32 v2, 16, v2
	v_add3_u32 v3, v8, v3, s68
	global_store_dwordx4 v[36:37], v[72:75], off offset:2112
	s_nop 1
	v_and_or_b32 v72, v3, s69, v2
	s_nop 1
	v_cvt_pk_bf16_f32 v73, v12, v16
	v_cvt_pk_bf16_f32 v74, v20, v24
	v_cvt_pk_bf16_f32 v75, v28, v32
	v_cvt_pk_bf16_f32 v2, v5, v9
	v_cvt_pk_bf16_f32 v3, v13, v17
	v_cvt_pk_bf16_f32 v4, v21, v25
	v_cvt_pk_bf16_f32 v5, v29, v33
	global_store_dwordx4 v[34:35], v[2:5], off offset:2112
	s_waitcnt vmcnt(3)
	s_nop 1
	v_cvt_pk_bf16_f32 v2, v40, v44
	v_cvt_pk_bf16_f32 v3, v48, v52
	v_cvt_pk_bf16_f32 v4, v56, v60
	v_cvt_pk_bf16_f32 v5, v64, v68
	global_store_dwordx4 v[36:37], v[2:5], off offset:96
	s_nop 1
	v_cvt_pk_bf16_f32 v2, v41, v45
	s_nop 1
	v_cvt_pk_bf16_f32 v3, v49, v53
	v_cvt_pk_bf16_f32 v4, v57, v61
	v_cvt_pk_bf16_f32 v5, v65, v69
	global_store_dwordx4 v[36:37], v[2:5], off offset:2144
	s_nop 1
	v_cvt_pk_bf16_f32 v2, v42, v46
	s_nop 1
	v_cvt_pk_bf16_f32 v3, v50, v54
	v_cvt_pk_bf16_f32 v4, v58, v62
	v_cvt_pk_bf16_f32 v5, v66, v70
	global_store_dwordx4 v[34:35], v[2:5], off offset:96
	s_nop 1
	v_cvt_pk_bf16_f32 v2, v43, v47
	s_nop 1
	v_cvt_pk_bf16_f32 v3, v51, v55
	v_cvt_pk_bf16_f32 v4, v59, v63
	v_cvt_pk_bf16_f32 v5, v67, v71
	global_store_dwordx4 v[34:35], v[72:75], off offset:64
	global_store_dwordx4 v[34:35], v[2:5], off offset:2144

.LBB0_610:
	s_andn2_b64 vcc, exec, s[6:7]
	s_cbranch_vccnz .LBB0_612
	s_mov_b64 s[6:7], s[0:1]
	s_mov_b64 s[10:11], s[0:1]
	s_load_dwordx2 s[6:7], s[6:7], 0x50
	s_load_dwordx2 s[10:11], s[10:11], 0xa8
	s_and_b32 s8, s56, 0x380
	v_or_b32_e32 v4, s8, v83
	s_and_b32 s48, s3, 0x7c0
	v_lshlrev_b32_e32 v84, 11, v4
	s_waitcnt lgkmcnt(0)
	v_lshl_add_u64 v[2:3], s[10:11], 0, v[84:85]
	s_lshl_b32 s8, s48, 1
	v_lshl_add_u64 v[2:3], v[2:3], 0, s[8:9]
	v_lshlrev_b32_e32 v84, 1, v82
	v_lshl_add_u64 v[2:3], v[2:3], 0, v[84:85]
	v_or_b32_e32 v6, s48, v82
	v_lshlrev_b32_e32 v84, 2, v4
	v_lshl_add_u64 v[4:5], s[6:7], 0, v[84:85]
	v_lshlrev_b32_e32 v84, 12, v6
	v_lshl_add_u64 v[38:39], v[4:5], 0, v[84:85]
	v_add_co_u32_e32 v4, vcc, s74, v38
	global_load_dwordx4 v[40:43], v[38:39], off nt
	s_nop 0
	v_addc_co_u32_e32 v5, vcc, 0, v39, vcc
	global_load_dwordx4 v[44:47], v[4:5], off offset:-4096 nt
	global_load_dwordx4 v[48:51], v[4:5], off nt
	v_add_co_u32_e32 v4, vcc, s63, v38
	v_lshl_add_u64 v[36:37], v[2:3], 0, s[26:27]
	s_nop 0
	v_addc_co_u32_e32 v5, vcc, 0, v39, vcc
	global_load_dwordx4 v[52:55], v[4:5], off offset:-4096 nt
	global_load_dwordx4 v[56:59], v[4:5], off nt
	v_add_co_u32_e32 v4, vcc, s64, v38
	s_mov_b32 s8, 4
	s_nop 0
	v_addc_co_u32_e32 v5, vcc, 0, v39, vcc
	global_load_dwordx4 v[60:63], v[4:5], off offset:-4096 nt
	global_load_dwordx4 v[64:67], v[4:5], off nt
	v_add_co_u32_e32 v4, vcc, s65, v38
	s_waitcnt vmcnt(6)
	v_addc_co_u32_e32 v5, vcc, 0, v39, vcc
	global_load_dwordx4 v[68:71], v[4:5], off nt
	v_add_co_u32_e32 v34, vcc, s23, v2
	s_waitcnt vmcnt(4)
	v_bfe_u32 v74, v52, 16, 1
	v_addc_co_u32_e32 v35, vcc, 0, v3, vcc
	v_add_co_u32_e32 v2, vcc, s79, v38
	s_waitcnt vmcnt(3)
	v_addc_co_u32_e32 v3, vcc, 0, v39, vcc
	v_add_co_u32_e32 v4, vcc, s92, v38
	s_waitcnt vmcnt(1)
	v_addc_co_u32_e32 v5, vcc, 0, v39, vcc
	v_add_co_u32_e32 v6, vcc, s93, v38
	s_nop 0
	v_addc_co_u32_e32 v7, vcc, 0, v39, vcc
	v_add_co_u32_e32 v72, vcc, s94, v38
	v_add3_u32 v52, v52, v74, s68
	s_nop 0
	v_addc_co_u32_e32 v73, vcc, 0, v39, vcc
	global_load_dwordx4 v[30:33], v[2:3], off offset:-4096 nt
	global_load_dwordx4 v[26:29], v[2:3], off nt
	global_load_dwordx4 v[22:25], v[4:5], off offset:-4096 nt
	global_load_dwordx4 v[18:21], v[4:5], off nt
	global_load_dwordx4 v[14:17], v[6:7], off offset:-4096 nt
	global_load_dwordx4 v[10:13], v[6:7], off nt
	s_nop 0
	global_load_dwordx4 v[6:9], v[72:73], off offset:-4096 nt
	global_load_dwordx4 v[2:5], v[72:73], off nt
	v_bfe_u32 v73, v48, 16, 1
	v_add3_u32 v48, v48, v73, s68
	v_cvt_pk_bf16_f32 v72, v40, v44
	v_lshrrev_b32_e32 v40, 16, v48
	v_and_or_b32 v73, v52, s69, v40
	v_cvt_pk_bf16_f32 v74, v56, v60
	s_waitcnt vmcnt(8)
	v_cvt_pk_bf16_f32 v75, v64, v68
	global_store_dwordx4 v[34:35], v[72:75], off offset:-4096
	s_nop 1
	v_cvt_pk_bf16_f32 v72, v41, v45
	s_nop 1
	v_cvt_pk_bf16_f32 v73, v49, v53
	v_cvt_pk_bf16_f32 v74, v57, v61
	v_cvt_pk_bf16_f32 v75, v65, v69
	v_bfe_u32 v40, v42, 16, 1
	v_add3_u32 v40, v42, v40, s68
	v_bfe_u32 v41, v46, 16, 1
	v_lshrrev_b32_e32 v40, 16, v40
	v_add3_u32 v41, v46, v41, s68
	global_store_dwordx4 v[36:37], v[72:75], off offset:2048
	s_nop 1
	v_and_or_b32 v72, v41, s69, v40
	s_nop 1
	v_cvt_pk_bf16_f32 v73, v50, v54
	v_cvt_pk_bf16_f32 v74, v58, v62
	v_cvt_pk_bf16_f32 v75, v66, v70
	v_cvt_pk_bf16_f32 v40, v43, v47
	v_cvt_pk_bf16_f32 v41, v51, v55
	v_cvt_pk_bf16_f32 v42, v59, v63
	v_cvt_pk_bf16_f32 v43, v67, v71
	global_store_dwordx4 v[34:35], v[40:43], off offset:2048
	global_store_dwordx4 v[34:35], v[72:75], off
	s_waitcnt vmcnt(11)
	s_waitcnt vmcnt(10)
	v_cvt_pk_bf16_f32 v40, v30, v26
	s_waitcnt vmcnt(9)
	s_waitcnt vmcnt(8)
	v_cvt_pk_bf16_f32 v41, v22, v18
	s_waitcnt vmcnt(7)
	s_waitcnt vmcnt(6)
	v_cvt_pk_bf16_f32 v42, v14, v10
	s_waitcnt vmcnt(5)
	s_waitcnt vmcnt(4)
	v_cvt_pk_bf16_f32 v43, v6, v2
	global_store_dwordx4 v[36:37], v[40:43], off offset:32
	s_nop 1
	v_cvt_pk_bf16_f32 v40, v31, v27
	v_cvt_pk_bf16_f32 v41, v23, v19
	v_cvt_pk_bf16_f32 v42, v15, v11
	v_cvt_pk_bf16_f32 v43, v7, v3
	global_store_dwordx4 v[36:37], v[40:43], off offset:2080
	s_nop 1
	v_cvt_pk_bf16_f32 v40, v32, v28
	s_nop 1
	v_cvt_pk_bf16_f32 v41, v24, v20
	v_cvt_pk_bf16_f32 v42, v16, v12
	v_cvt_pk_bf16_f32 v43, v8, v4
	v_cvt_pk_bf16_f32 v2, v33, v29
	v_cvt_pk_bf16_f32 v3, v25, v21
	v_cvt_pk_bf16_f32 v4, v17, v13
	v_cvt_pk_bf16_f32 v5, v9, v5
	v_add_co_u32_e32 v6, vcc, s67, v38
	global_store_dwordx4 v[34:35], v[40:43], off offset:32
	global_store_dwordx4 v[34:35], v[2:5], off offset:2080
	v_addc_co_u32_e32 v7, vcc, 0, v39, vcc
	global_load_dwordx4 v[2:5], v[6:7], off offset:-4096 nt
	s_nop 0
	global_load_dwordx4 v[6:9], v[6:7], off nt
	v_add_co_u32_e32 v14, vcc, s96, v38
	s_nop 1
	v_addc_co_u32_e32 v15, vcc, 0, v39, vcc
	global_load_dwordx4 v[10:13], v[14:15], off offset:-4096 nt
	s_nop 0
	global_load_dwordx4 v[14:17], v[14:15], off nt
	v_add_co_u32_e32 v22, vcc, s84, v38
	s_nop 1
	v_addc_co_u32_e32 v23, vcc, 0, v39, vcc
	global_load_dwordx4 v[18:21], v[22:23], off offset:-4096 nt
	s_nop 0
	global_load_dwordx4 v[22:25], v[22:23], off nt
	v_add_co_u32_e32 v30, vcc, s86, v38
	s_nop 1
	v_addc_co_u32_e32 v31, vcc, 0, v39, vcc
	global_load_dwordx4 v[26:29], v[30:31], off offset:-4096 nt
	s_nop 0
	global_load_dwordx4 v[30:33], v[30:31], off nt
	v_add_co_u32_e32 v44, vcc, s70, v38
	s_nop 1
	v_addc_co_u32_e32 v45, vcc, 0, v39, vcc
	global_load_dwordx4 v[40:43], v[44:45], off offset:-4096 nt
	s_nop 0
	global_load_dwordx4 v[44:47], v[44:45], off nt
	v_add_co_u32_e32 v52, vcc, s71, v38
	s_nop 1
	v_addc_co_u32_e32 v53, vcc, 0, v39, vcc
	global_load_dwordx4 v[48:51], v[52:53], off offset:-4096 nt
	s_nop 0
	global_load_dwordx4 v[52:55], v[52:53], off nt
	v_add_co_u32_e32 v60, vcc, s97, v38
	s_nop 1
	v_addc_co_u32_e32 v61, vcc, 0, v39, vcc
	global_load_dwordx4 v[56:59], v[60:61], off offset:-4096 nt
	s_nop 0
	global_load_dwordx4 v[60:63], v[60:61], off nt
	v_add_co_u32_e32 v38, vcc, s72, v38
	s_nop 1
	v_addc_co_u32_e32 v39, vcc, 0, v39, vcc
	global_load_dwordx4 v[64:67], v[38:39], off offset:-4096 nt
	global_load_dwordx4 v[68:71], v[38:39], off nt
	s_waitcnt vmcnt(15)
	s_waitcnt vmcnt(14)
	v_cvt_pk_bf16_f32 v72, v2, v6
	s_waitcnt vmcnt(13)
	s_waitcnt vmcnt(12)
	v_cvt_pk_bf16_f32 v73, v10, v14
	s_waitcnt vmcnt(11)
	s_waitcnt vmcnt(10)
	v_cvt_pk_bf16_f32 v74, v18, v22
	s_waitcnt vmcnt(9)
	s_waitcnt vmcnt(8)
	v_cvt_pk_bf16_f32 v75, v26, v30
	global_store_dwordx4 v[36:37], v[72:75], off offset:64
	s_nop 1
	v_cvt_pk_bf16_f32 v72, v3, v7
	s_nop 1
	v_cvt_pk_bf16_f32 v73, v11, v15
	v_cvt_pk_bf16_f32 v74, v19, v23
	v_cvt_pk_bf16_f32 v75, v27, v31
	v_bfe_u32 v2, v4, 16, 1
	v_add3_u32 v2, v4, v2, s68
	v_bfe_u32 v3, v8, 16, 1
	v_lshrrev_b32_e32 v2, 16, v2
	v_add3_u32 v3, v8, v3, s68
	global_store_dwordx4 v[36:37], v[72:75], off offset:2112
	s_nop 1
	v_and_or_b32 v72, v3, s69, v2
	s_nop 1
	v_cvt_pk_bf16_f32 v73, v12, v16
	v_cvt_pk_bf16_f32 v74, v20, v24
	v_cvt_pk_bf16_f32 v75, v28, v32
	v_cvt_pk_bf16_f32 v2, v5, v9
	v_cvt_pk_bf16_f32 v3, v13, v17
	v_cvt_pk_bf16_f32 v4, v21, v25
	v_cvt_pk_bf16_f32 v5, v29, v33
	global_store_dwordx4 v[34:35], v[2:5], off offset:2112
	s_waitcnt vmcnt(3)
	s_nop 1
	v_cvt_pk_bf16_f32 v2, v40, v44
	v_cvt_pk_bf16_f32 v3, v48, v52
	v_cvt_pk_bf16_f32 v4, v56, v60
	v_cvt_pk_bf16_f32 v5, v64, v68
	global_store_dwordx4 v[36:37], v[2:5], off offset:96
	s_nop 1
	v_cvt_pk_bf16_f32 v2, v41, v45
	s_nop 1
	v_cvt_pk_bf16_f32 v3, v49, v53
	v_cvt_pk_bf16_f32 v4, v57, v61
	v_cvt_pk_bf16_f32 v5, v65, v69
	global_store_dwordx4 v[36:37], v[2:5], off offset:2144
	s_nop 1
	v_cvt_pk_bf16_f32 v2, v42, v46
	s_nop 1
	v_cvt_pk_bf16_f32 v3, v50, v54
	v_cvt_pk_bf16_f32 v4, v58, v62
	v_cvt_pk_bf16_f32 v5, v66, v70
	global_store_dwordx4 v[34:35], v[2:5], off offset:96
	s_nop 1
	v_cvt_pk_bf16_f32 v2, v43, v47
	s_nop 1
	v_cvt_pk_bf16_f32 v3, v51, v55
	v_cvt_pk_bf16_f32 v4, v59, v63
	v_cvt_pk_bf16_f32 v5, v67, v71
	global_store_dwordx4 v[34:35], v[72:75], off offset:64
	global_store_dwordx4 v[34:35], v[2:5], off offset:2144

.LBB0_618:
	s_mov_b64 s[10:11], s[0:1]
	s_load_dwordx2 s[10:11], s[10:11], 0xa8
	s_lshr_b32 s48, s48, 24
	s_mul_hi_u32 s8, s8, 0xba2e8c
	s_mul_i32 s49, s8, 0xfea0
	s_add_i32 s8, s48, 1
	s_add_i32 s50, s31, s49
	s_mul_i32 s48, s8, 0x580000
	s_waitcnt lgkmcnt(0)
	s_add_u32 s48, s10, s48
	s_sext_i32_i16 s10, s50
	s_addc_u32 s49, s11, 0
	s_bfe_u32 s10, s10, 0x3001c
	s_add_i32 s10, s50, s10
	s_sext_i32_i16 s11, s10
	s_and_b32 s10, s10, 0xfff8
	s_sub_i32 s10, s50, s10
	s_sext_i32_i16 s50, s10
	v_lshl_or_b32 v6, s50, 7, v83
	s_lshl_b32 s10, s11, 3
	v_mul_i32_i24_e32 v2, 0xb00, v6
	s_andn2_b32 s10, s10, 63
	v_ashrrev_i32_e32 v3, 31, v2
	v_lshl_add_u64 v[2:3], v[2:3], 1, s[48:49]
	s_ashr_i32 s11, s10, 31
	v_lshl_add_u64 v[2:3], s[10:11], 1, v[2:3]
	v_lshlrev_b32_e32 v84, 1, v82
	v_lshl_add_u64 v[2:3], v[2:3], 0, v[84:85]
	v_lshl_add_u64 v[2:3], v[2:3], 0, s[44:45]
	s_cmp_gt_i32 s50, -1
	s_mov_b64 s[48:49], -1
	s_cbranch_scc0 .LBB0_620
	s_load_dwordx2 s[6:7], s[6:7], 0x0
	s_lshr_b32 s8, s8, 1
	v_or_b32_e32 v4, s10, v82
	s_mul_i32 s8, s8, 0xb00000
	v_or_b32_e32 v10, 1, v4
	s_waitcnt lgkmcnt(0)
	s_add_u32 s6, s6, s8
	v_mov_b32_e32 v7, v85
	s_addc_u32 s7, s7, 0
	v_ashrrev_i32_e32 v5, 31, v4
	v_ashrrev_i32_e32 v11, 31, v10
	v_lshl_add_u64 v[6:7], v[6:7], 2, s[6:7]
	v_lshlrev_b64 v[8:9], 12, v[4:5]
	v_lshlrev_b64 v[10:11], 12, v[10:11]
	v_lshl_add_u64 v[8:9], v[6:7], 0, v[8:9]
	v_lshl_add_u64 v[14:15], v[6:7], 0, v[10:11]
	global_load_dwordx4 v[10:13], v[8:9], off nt
	s_nop 0
	global_load_dwordx4 v[14:17], v[14:15], off nt
	v_or_b32_e32 v8, 2, v4
	v_or_b32_e32 v18, 3, v4
	v_ashrrev_i32_e32 v9, 31, v8
	v_ashrrev_i32_e32 v19, 31, v18
	v_lshlrev_b64 v[8:9], 12, v[8:9]
	v_lshlrev_b64 v[18:19], 12, v[18:19]
	v_lshl_add_u64 v[8:9], v[6:7], 0, v[8:9]
	v_lshl_add_u64 v[22:23], v[6:7], 0, v[18:19]
	global_load_dwordx4 v[18:21], v[8:9], off nt
	s_nop 0
	global_load_dwordx4 v[22:25], v[22:23], off nt
	v_or_b32_e32 v8, 4, v4
	v_or_b32_e32 v26, 5, v4
	v_ashrrev_i32_e32 v9, 31, v8
	v_ashrrev_i32_e32 v27, 31, v26
	v_lshlrev_b64 v[8:9], 12, v[8:9]
	v_lshlrev_b64 v[26:27], 12, v[26:27]
	v_lshl_add_u64 v[8:9], v[6:7], 0, v[8:9]
	v_lshl_add_u64 v[30:31], v[6:7], 0, v[26:27]
	global_load_dwordx4 v[26:29], v[8:9], off nt
	s_nop 0
	global_load_dwordx4 v[30:33], v[30:31], off nt
	v_or_b32_e32 v8, 6, v4
	v_ashrrev_i32_e32 v9, 31, v8
	v_lshlrev_b64 v[8:9], 12, v[8:9]
	v_lshl_add_u64 v[8:9], v[6:7], 0, v[8:9]
	global_load_dwordx4 v[34:37], v[8:9], off nt
	v_or_b32_e32 v8, 7, v4
	v_ashrrev_i32_e32 v9, 31, v8
	v_lshlrev_b64 v[8:9], 12, v[8:9]
	v_lshl_add_u64 v[8:9], v[6:7], 0, v[8:9]
	global_load_dwordx4 v[38:41], v[8:9], off nt
	v_or_b32_e32 v8, 16, v4
	v_or_b32_e32 v42, 17, v4
	v_or_b32_e32 v44, 18, v4
	v_or_b32_e32 v46, 19, v4
	v_or_b32_e32 v48, 20, v4
	v_or_b32_e32 v50, 21, v4
	v_or_b32_e32 v52, 22, v4
	v_or_b32_e32 v54, 23, v4
	v_ashrrev_i32_e32 v9, 31, v8
	v_ashrrev_i32_e32 v43, 31, v42
	v_ashrrev_i32_e32 v45, 31, v44
	v_ashrrev_i32_e32 v47, 31, v46
	v_ashrrev_i32_e32 v49, 31, v48
	v_ashrrev_i32_e32 v51, 31, v50
	v_ashrrev_i32_e32 v53, 31, v52
	v_ashrrev_i32_e32 v55, 31, v54
	v_lshlrev_b64 v[8:9], 12, v[8:9]
	v_lshlrev_b64 v[42:43], 12, v[42:43]
	v_lshlrev_b64 v[44:45], 12, v[44:45]
	v_lshlrev_b64 v[46:47], 12, v[46:47]
	v_lshlrev_b64 v[48:49], 12, v[48:49]
	v_lshlrev_b64 v[50:51], 12, v[50:51]
	v_lshlrev_b64 v[52:53], 12, v[52:53]
	v_lshlrev_b64 v[54:55], 12, v[54:55]
	v_lshl_add_u64 v[8:9], v[6:7], 0, v[8:9]
	v_lshl_add_u64 v[56:57], v[6:7], 0, v[42:43]
	v_lshl_add_u64 v[58:59], v[6:7], 0, v[44:45]
	v_lshl_add_u64 v[60:61], v[6:7], 0, v[46:47]
	v_lshl_add_u64 v[62:63], v[6:7], 0, v[48:49]
	v_lshl_add_u64 v[64:65], v[6:7], 0, v[50:51]
	v_lshl_add_u64 v[66:67], v[6:7], 0, v[52:53]
	v_lshl_add_u64 v[70:71], v[6:7], 0, v[54:55]
	global_load_dwordx4 v[42:45], v[8:9], off nt
	global_load_dwordx4 v[46:49], v[56:57], off nt
	global_load_dwordx4 v[50:53], v[58:59], off nt
	s_nop 0
	global_load_dwordx4 v[54:57], v[60:61], off nt
	s_nop 0
	global_load_dwordx4 v[58:61], v[62:63], off nt
	s_nop 0
	global_load_dwordx4 v[62:65], v[64:65], off nt
	s_nop 0
	global_load_dwordx4 v[66:69], v[66:67], off nt
	s_nop 0
	global_load_dwordx4 v[70:73], v[70:71], off nt
	s_mov_b64 s[48:49], 0
	s_waitcnt vmcnt(15)
	s_waitcnt vmcnt(14)
	v_cvt_pk_bf16_f32 v74, v10, v14
	v_bfe_u32 v10, v16, 16, 1
	v_add3_u32 v10, v16, v10, s68
	s_waitcnt vmcnt(13)
	s_waitcnt vmcnt(12)
	v_cvt_pk_bf16_f32 v75, v18, v22
	v_or_b32_e32 v22, 34, v4
	s_waitcnt vmcnt(11)
	s_waitcnt vmcnt(10)
	v_cvt_pk_bf16_f32 v76, v26, v30
	s_waitcnt vmcnt(9)
	v_or_b32_e32 v30, 36, v4
	s_waitcnt vmcnt(8)
	v_cvt_pk_bf16_f32 v77, v34, v38
	global_store_dwordx4 v[2:3], v[74:77], off
	v_or_b32_e32 v38, 38, v4
	s_nop 0
	v_cvt_pk_bf16_f32 v74, v11, v15
	v_cvt_pk_bf16_f32 v75, v19, v23
	v_cvt_pk_bf16_f32 v76, v27, v31
	v_cvt_pk_bf16_f32 v77, v35, v39
	v_bfe_u32 v5, v12, 16, 1
	v_add_co_u32_e32 v8, vcc, s61, v2
	v_add3_u32 v5, v12, v5, s68
	s_nop 0
	v_addc_co_u32_e32 v9, vcc, 0, v3, vcc
	v_lshrrev_b32_e32 v5, 16, v5
	global_store_dwordx4 v[8:9], v[74:77], off offset:1536
	s_nop 1
	v_and_or_b32 v74, v10, s69, v5
	s_nop 1
	v_cvt_pk_bf16_f32 v75, v20, v24
	v_cvt_pk_bf16_f32 v76, v28, v32
	v_cvt_pk_bf16_f32 v77, v36, v40
	v_cvt_pk_bf16_f32 v14, v13, v17
	v_cvt_pk_bf16_f32 v15, v21, v25
	v_cvt_pk_bf16_f32 v16, v29, v33
	v_add_co_u32_e32 v10, vcc, s74, v2
	v_addc_co_u32_e32 v11, vcc, 0, v3, vcc
	v_cvt_pk_bf16_f32 v17, v37, v41
	v_add_co_u32_e32 v12, vcc, s63, v2
	s_waitcnt vmcnt(9)
	v_addc_co_u32_e32 v13, vcc, 0, v3, vcc
	global_store_dwordx4 v[12:13], v[14:17], off offset:512
	s_waitcnt vmcnt(9)
	s_nop 1
	v_cvt_pk_bf16_f32 v14, v42, v46
	s_waitcnt vmcnt(8)
	s_waitcnt vmcnt(7)
	v_cvt_pk_bf16_f32 v15, v50, v54
	s_waitcnt vmcnt(6)
	s_waitcnt vmcnt(5)
	v_cvt_pk_bf16_f32 v16, v58, v62
	s_waitcnt vmcnt(4)
	s_waitcnt vmcnt(3)
	v_cvt_pk_bf16_f32 v17, v66, v70
	global_store_dwordx4 v[2:3], v[14:17], off offset:32
	s_nop 1
	v_cvt_pk_bf16_f32 v14, v43, v47
	s_nop 1
	v_cvt_pk_bf16_f32 v15, v51, v55
	v_cvt_pk_bf16_f32 v16, v59, v63
	v_cvt_pk_bf16_f32 v17, v67, v71
	global_store_dwordx4 v[8:9], v[14:17], off offset:1568
	s_nop 1
	v_cvt_pk_bf16_f32 v14, v44, v48
	s_nop 1
	v_cvt_pk_bf16_f32 v15, v52, v56
	v_cvt_pk_bf16_f32 v16, v60, v64
	v_cvt_pk_bf16_f32 v17, v68, v72
	global_store_dwordx4 v[10:11], v[14:17], off offset:3104
	s_nop 1
	v_cvt_pk_bf16_f32 v14, v45, v49
	s_nop 1
	v_cvt_pk_bf16_f32 v15, v53, v57
	v_cvt_pk_bf16_f32 v16, v61, v65
	v_cvt_pk_bf16_f32 v17, v69, v73
	global_store_dwordx4 v[12:13], v[14:17], off offset:544
	global_store_dwordx4 v[10:11], v[74:77], off offset:3072
	v_or_b32_e32 v24, 35, v4
	v_or_b32_e32 v14, 32, v4
	v_or_b32_e32 v16, 33, v4
	v_ashrrev_i32_e32 v15, 31, v14
	v_ashrrev_i32_e32 v17, 31, v16
	v_lshlrev_b64 v[14:15], 12, v[14:15]
	v_lshlrev_b64 v[16:17], 12, v[16:17]
	v_lshl_add_u64 v[14:15], v[6:7], 0, v[14:15]
	v_lshl_add_u64 v[18:19], v[6:7], 0, v[16:17]
	global_load_dwordx4 v[14:17], v[14:15], off nt
	s_nop 0
	global_load_dwordx4 v[18:21], v[18:19], off nt
	v_ashrrev_i32_e32 v23, 31, v22
	v_ashrrev_i32_e32 v25, 31, v24
	v_lshlrev_b64 v[22:23], 12, v[22:23]
	v_lshlrev_b64 v[24:25], 12, v[24:25]
	v_lshl_add_u64 v[22:23], v[6:7], 0, v[22:23]
	v_lshl_add_u64 v[26:27], v[6:7], 0, v[24:25]
	v_or_b32_e32 v32, 37, v4
	global_load_dwordx4 v[22:25], v[22:23], off nt
	s_nop 0
	global_load_dwordx4 v[26:29], v[26:27], off nt
	v_ashrrev_i32_e32 v31, 31, v30
	v_ashrrev_i32_e32 v33, 31, v32
	v_lshlrev_b64 v[30:31], 12, v[30:31]
	v_lshlrev_b64 v[32:33], 12, v[32:33]
	v_lshl_add_u64 v[30:31], v[6:7], 0, v[30:31]
	v_lshl_add_u64 v[34:35], v[6:7], 0, v[32:33]
	v_ashrrev_i32_e32 v39, 31, v38
	v_or_b32_e32 v42, 39, v4
	global_load_dwordx4 v[30:33], v[30:31], off nt
	s_nop 0
	global_load_dwordx4 v[34:37], v[34:35], off nt
	v_lshlrev_b64 v[38:39], 12, v[38:39]
	v_ashrrev_i32_e32 v43, 31, v42
	v_lshl_add_u64 v[38:39], v[6:7], 0, v[38:39]
	v_lshlrev_b64 v[42:43], 12, v[42:43]
	global_load_dwordx4 v[38:41], v[38:39], off nt
	v_lshl_add_u64 v[42:43], v[6:7], 0, v[42:43]
	global_load_dwordx4 v[42:45], v[42:43], off nt
	v_or_b32_e32 v46, 48, v4
	v_or_b32_e32 v48, 49, v4
	v_ashrrev_i32_e32 v47, 31, v46
	v_ashrrev_i32_e32 v49, 31, v48
	v_lshlrev_b64 v[46:47], 12, v[46:47]
	v_lshlrev_b64 v[48:49], 12, v[48:49]
	v_lshl_add_u64 v[46:47], v[6:7], 0, v[46:47]
	v_lshl_add_u64 v[50:51], v[6:7], 0, v[48:49]
	v_or_b32_e32 v54, 50, v4
	v_or_b32_e32 v56, 51, v4
	global_load_dwordx4 v[46:49], v[46:47], off nt
	s_nop 0
	global_load_dwordx4 v[50:53], v[50:51], off nt
	v_ashrrev_i32_e32 v55, 31, v54
	v_ashrrev_i32_e32 v57, 31, v56
	v_lshlrev_b64 v[54:55], 12, v[54:55]
	v_lshlrev_b64 v[56:57], 12, v[56:57]
	v_lshl_add_u64 v[54:55], v[6:7], 0, v[54:55]
	v_lshl_add_u64 v[58:59], v[6:7], 0, v[56:57]
	v_or_b32_e32 v62, 52, v4
	v_or_b32_e32 v64, 53, v4
	global_load_dwordx4 v[54:57], v[54:55], off nt
	s_nop 0
	global_load_dwordx4 v[58:61], v[58:59], off nt
	v_ashrrev_i32_e32 v63, 31, v62
	v_ashrrev_i32_e32 v65, 31, v64
	v_lshlrev_b64 v[62:63], 12, v[62:63]
	v_lshlrev_b64 v[64:65], 12, v[64:65]
	v_lshl_add_u64 v[62:63], v[6:7], 0, v[62:63]
	v_lshl_add_u64 v[66:67], v[6:7], 0, v[64:65]
	v_or_b32_e32 v70, 54, v4
	v_or_b32_e32 v4, 55, v4
	global_load_dwordx4 v[62:65], v[62:63], off nt
	s_nop 0
	global_load_dwordx4 v[66:69], v[66:67], off nt
	v_ashrrev_i32_e32 v71, 31, v70
	v_ashrrev_i32_e32 v5, 31, v4
	v_lshlrev_b64 v[70:71], 12, v[70:71]
	v_lshlrev_b64 v[4:5], 12, v[4:5]
	v_lshl_add_u64 v[70:71], v[6:7], 0, v[70:71]
	v_lshl_add_u64 v[72:73], v[6:7], 0, v[4:5]
	global_load_dwordx4 v[4:7], v[70:71], off nt
	s_nop 0
	global_load_dwordx4 v[70:73], v[72:73], off nt
	s_waitcnt vmcnt(15)
	s_waitcnt vmcnt(14)
	v_cvt_pk_bf16_f32 v74, v14, v18
	s_waitcnt vmcnt(13)
	s_waitcnt vmcnt(12)
	v_cvt_pk_bf16_f32 v75, v22, v26
	s_waitcnt vmcnt(11)
	s_waitcnt vmcnt(10)
	v_cvt_pk_bf16_f32 v76, v30, v34
	s_waitcnt vmcnt(9)
	s_waitcnt vmcnt(8)
	v_cvt_pk_bf16_f32 v77, v38, v42
	global_store_dwordx4 v[2:3], v[74:77], off offset:64
	s_nop 1
	v_cvt_pk_bf16_f32 v74, v15, v19
	s_nop 1
	v_cvt_pk_bf16_f32 v75, v23, v27
	v_cvt_pk_bf16_f32 v76, v31, v35
	v_cvt_pk_bf16_f32 v77, v39, v43
	v_bfe_u32 v14, v16, 16, 1
	v_add3_u32 v14, v16, v14, s68
	v_bfe_u32 v15, v20, 16, 1
	v_lshrrev_b32_e32 v14, 16, v14
	v_add3_u32 v15, v20, v15, s68
	global_store_dwordx4 v[8:9], v[74:77], off offset:1600
	s_nop 1
	v_and_or_b32 v74, v15, s69, v14
	s_nop 1
	v_cvt_pk_bf16_f32 v75, v24, v28
	v_cvt_pk_bf16_f32 v76, v32, v36
	v_cvt_pk_bf16_f32 v77, v40, v44
	v_cvt_pk_bf16_f32 v14, v17, v21
	v_cvt_pk_bf16_f32 v15, v25, v29
	v_cvt_pk_bf16_f32 v16, v33, v37
	v_cvt_pk_bf16_f32 v17, v41, v45
	global_store_dwordx4 v[12:13], v[14:17], off offset:576
	global_store_dwordx4 v[10:11], v[74:77], off offset:3136
	s_waitcnt vmcnt(11)
	s_waitcnt vmcnt(10)
	v_cvt_pk_bf16_f32 v14, v46, v50
	s_waitcnt vmcnt(9)
	s_waitcnt vmcnt(8)
	v_cvt_pk_bf16_f32 v15, v54, v58
	s_waitcnt vmcnt(7)
	s_waitcnt vmcnt(6)
	v_cvt_pk_bf16_f32 v16, v62, v66
	s_waitcnt vmcnt(5)
	s_waitcnt vmcnt(4)
	v_cvt_pk_bf16_f32 v17, v4, v70
	global_store_dwordx4 v[2:3], v[14:17], off offset:96
	s_nop 1
	v_cvt_pk_bf16_f32 v14, v47, v51
	s_nop 1
	v_cvt_pk_bf16_f32 v15, v55, v59
	v_cvt_pk_bf16_f32 v16, v63, v67
	v_cvt_pk_bf16_f32 v17, v5, v71
	global_store_dwordx4 v[8:9], v[14:17], off offset:1632
	s_nop 1
	v_cvt_pk_bf16_f32 v14, v48, v52
	s_nop 1
	v_cvt_pk_bf16_f32 v15, v56, v60
	v_cvt_pk_bf16_f32 v16, v64, v68
	v_cvt_pk_bf16_f32 v17, v6, v72
	v_cvt_pk_bf16_f32 v4, v49, v53
	v_cvt_pk_bf16_f32 v5, v57, v61
	v_cvt_pk_bf16_f32 v6, v65, v69
	v_cvt_pk_bf16_f32 v7, v7, v73
	global_store_dwordx4 v[10:11], v[14:17], off offset:3168
	global_store_dwordx4 v[12:13], v[4:7], off offset:608

.LBB0_638:
	s_waitcnt vmcnt(15)
	v_mov_b32_e32 v40, v46
	s_waitcnt vmcnt(13)
	v_mov_b32_e32 v41, v58
	v_pk_mul_f32 v[40:41], v[40:41], v[74:75]
	v_mov_b32_e32 v80, v42
	s_waitcnt vmcnt(12)
	v_mov_b32_e32 v81, v50
	s_waitcnt vmcnt(11)
	v_mov_b32_e32 v88, v62
	s_waitcnt vmcnt(9)
	v_mov_b32_e32 v89, v70
	v_pk_mul_f32 v[80:81], v[80:81], v[98:99]
	v_pk_mul_f32 v[88:89], v[88:89], v[78:79]
	v_mov_b32_e32 v108, v54
	s_waitcnt vmcnt(8)
	v_mov_b32_e32 v109, v66
	v_bfe_u32 v62, v41, 16, 1
	v_pk_mul_f32 v[108:109], v[108:109], v[96:97]
	v_bfe_u32 v50, v81, 16, 1
	v_bfe_u32 v66, v88, 16, 1
	v_bfe_u32 v70, v89, 16, 1
	v_add3_u32 v41, v41, v62, s68
	v_bfe_u32 v42, v109, 16, 1
	v_bfe_u32 v46, v108, 16, 1
	v_add3_u32 v50, v81, v50, s68
	v_bfe_u32 v58, v40, 16, 1
	v_add3_u32 v70, v89, v70, s68
	v_add3_u32 v66, v88, v66, s68
	v_lshrrev_b32_e32 v41, 16, v41
	v_bfe_u32 v54, v80, 16, 1
	v_add3_u32 v46, v108, v46, s68
	v_add3_u32 v42, v109, v42, s68
	v_add3_u32 v40, v40, v58, s68
	v_lshrrev_b32_e32 v58, 16, v66
	v_lshrrev_b32_e32 v62, 16, v70
	v_and_or_b32 v109, v50, s69, v41
	v_mov_b32_e32 v50, v43
	v_mov_b32_e32 v66, v55
	v_add3_u32 v54, v80, v54, s68
	v_lshrrev_b32_e32 v40, 16, v40
	v_and_or_b32 v111, v42, s69, v62
	v_and_or_b32 v110, v46, s69, v58
	v_mov_b32_e32 v58, v47
	v_pk_mul_f32 v[42:43], v[50:51], v[98:99]
	v_mov_b32_e32 v70, v63
	v_pk_mul_f32 v[50:51], v[66:67], v[96:97]
	v_and_or_b32 v108, v54, s69, v40
	v_pk_mul_f32 v[40:41], v[58:59], v[74:75]
	v_pk_mul_f32 v[46:47], v[70:71], v[78:79]
	v_bfe_u32 v54, v51, 16, 1
	v_bfe_u32 v55, v50, 16, 1
	v_bfe_u32 v58, v43, 16, 1
	v_bfe_u32 v59, v42, 16, 1
	v_add3_u32 v59, v42, v59, s68
	v_add3_u32 v58, v43, v58, s68
	v_add3_u32 v42, v50, v55, s68
	v_add3_u32 v43, v51, v54, s68
	v_bfe_u32 v50, v40, 16, 1
	v_bfe_u32 v51, v41, 16, 1
	v_bfe_u32 v54, v46, 16, 1
	v_bfe_u32 v55, v47, 16, 1
	v_add3_u32 v47, v47, v55, s68
	v_add3_u32 v46, v46, v54, s68
	v_add3_u32 v41, v41, v51, s68
	v_add3_u32 v40, v40, v50, s68
	v_lshrrev_b32_e32 v40, 16, v40
	v_lshrrev_b32_e32 v41, 16, v41
	v_lshrrev_b32_e32 v46, 16, v46
	v_lshrrev_b32_e32 v47, 16, v47
	v_and_or_b32 v43, v43, s69, v47
	v_and_or_b32 v42, v42, s69, v46
	v_and_or_b32 v41, v58, s69, v41
	v_and_or_b32 v40, v59, s69, v40
	global_store_dwordx4 v[86:87], v[40:43], off offset:2048
	v_mov_b32_e32 v50, v56
	v_mov_b32_e32 v51, v68
	v_mov_b32_e32 v42, v44
	v_mov_b32_e32 v43, v52
	v_mov_b32_e32 v40, v48
	v_mov_b32_e32 v41, v60
	v_pk_mul_f32 v[42:43], v[42:43], v[98:99]
	v_mov_b32_e32 v46, v64
	v_mov_b32_e32 v47, v72
	v_pk_mul_f32 v[50:51], v[50:51], v[96:97]
	v_pk_mul_f32 v[40:41], v[40:41], v[74:75]
	v_pk_mul_f32 v[46:47], v[46:47], v[78:79]
	v_bfe_u32 v44, v51, 16, 1
	v_bfe_u32 v48, v50, 16, 1
	v_bfe_u32 v52, v43, 16, 1
	v_bfe_u32 v54, v42, 16, 1
	v_add3_u32 v54, v42, v54, s68
	v_add3_u32 v52, v43, v52, s68
	v_add3_u32 v42, v50, v48, s68
	v_add3_u32 v43, v51, v44, s68
	v_bfe_u32 v44, v40, 16, 1
	v_bfe_u32 v48, v41, 16, 1
	v_bfe_u32 v50, v46, 16, 1
	v_bfe_u32 v51, v47, 16, 1
	v_add3_u32 v47, v47, v51, s68
	v_add3_u32 v46, v46, v50, s68
	v_add3_u32 v41, v41, v48, s68
	v_add3_u32 v40, v40, v44, s68
	v_lshrrev_b32_e32 v40, 16, v40
	v_lshrrev_b32_e32 v41, 16, v41
	v_lshrrev_b32_e32 v44, 16, v46
	v_lshrrev_b32_e32 v46, 16, v47
	v_add_co_u32_e32 v88, vcc, s61, v86
	v_and_or_b32 v43, v43, s69, v46
	v_and_or_b32 v42, v42, s69, v44
	v_and_or_b32 v41, v52, s69, v41
	v_and_or_b32 v40, v54, s69, v40
	v_addc_co_u32_e32 v89, vcc, 0, v87, vcc
	v_mov_b32_e32 v52, v45
	v_mov_b32_e32 v68, v57
	global_store_dwordx4 v[88:89], v[40:43], off
	v_mov_b32_e32 v60, v49
	v_mov_b32_e32 v72, v65
	v_pk_mul_f32 v[42:43], v[52:53], v[98:99]
	v_pk_mul_f32 v[46:47], v[68:69], v[96:97]
	v_pk_mul_f32 v[40:41], v[60:61], v[74:75]
	v_pk_mul_f32 v[44:45], v[72:73], v[78:79]
	v_bfe_u32 v48, v47, 16, 1
	v_bfe_u32 v49, v46, 16, 1
	v_bfe_u32 v50, v43, 16, 1
	v_bfe_u32 v51, v42, 16, 1
	v_add3_u32 v51, v42, v51, s68
	v_add3_u32 v50, v43, v50, s68
	v_add3_u32 v42, v46, v49, s68
	v_add3_u32 v43, v47, v48, s68
	v_bfe_u32 v46, v40, 16, 1
	v_bfe_u32 v47, v41, 16, 1
	v_bfe_u32 v48, v44, 16, 1
	v_bfe_u32 v49, v45, 16, 1
	v_add3_u32 v45, v45, v49, s68
	v_add3_u32 v44, v44, v48, s68
	v_add3_u32 v41, v41, v47, s68
	v_add3_u32 v40, v40, v46, s68
	v_lshrrev_b32_e32 v40, 16, v40
	v_lshrrev_b32_e32 v41, 16, v41
	v_lshrrev_b32_e32 v44, 16, v44
	v_lshrrev_b32_e32 v45, 16, v45
	v_and_or_b32 v43, v43, s69, v45
	v_and_or_b32 v42, v42, s69, v44
	v_and_or_b32 v41, v50, s69, v41
	v_and_or_b32 v40, v51, s69, v40
	global_store_dwordx4 v[88:89], v[40:43], off offset:2048
	s_waitcnt vmcnt(6)
	v_mov_b32_e32 v44, v26
	s_waitcnt vmcnt(4)
	v_mov_b32_e32 v45, v34
	v_mov_b32_e32 v40, v10
	v_mov_b32_e32 v41, v22
	v_pk_mul_f32 v[40:41], v[40:41], v[2:3]
	v_mov_b32_e32 v42, v6
	v_mov_b32_e32 v43, v14
	v_pk_mul_f32 v[44:45], v[44:45], v[38:39]
	v_mov_b32_e32 v46, v18
	s_waitcnt vmcnt(3)
	v_mov_b32_e32 v47, v30
	v_pk_mul_f32 v[42:43], v[42:43], v[76:77]
	v_pk_mul_f32 v[46:47], v[46:47], v[4:5]
	v_bfe_u32 v22, v40, 16, 1
	v_bfe_u32 v18, v42, 16, 1
	v_add3_u32 v22, v40, v22, s68
	v_add3_u32 v18, v42, v18, s68
	v_lshrrev_b32_e32 v22, 16, v22
	v_cvt_pk_bf16_f32 v42, v44, v46
	v_cvt_pk_bf16_f32 v41, v41, v43
	v_mov_b32_e32 v14, v7
	v_mov_b32_e32 v30, v19
	v_cvt_pk_bf16_f32 v43, v45, v47
	v_and_or_b32 v40, v18, s69, v22
	v_mov_b32_e32 v22, v11
	v_pk_mul_f32 v[6:7], v[14:15], v[76:77]
	v_mov_b32_e32 v34, v27
	v_pk_mul_f32 v[18:19], v[30:31], v[4:5]
	v_pk_mul_f32 v[10:11], v[22:23], v[2:3]
	v_pk_mul_f32 v[14:15], v[34:35], v[38:39]
	global_store_dwordx4 v[86:87], v[40:43], off offset:32
	global_store_dwordx4 v[86:87], v[108:111], off
	s_and_b64 vcc, exec, s[6:7]
	v_cvt_pk_bf16_f32 v43, v15, v19
	v_cvt_pk_bf16_f32 v42, v14, v18
	v_cvt_pk_bf16_f32 v41, v11, v7
	v_cvt_pk_bf16_f32 v40, v10, v6
	v_mov_b32_e32 v10, v8
	v_mov_b32_e32 v11, v16
	v_mov_b32_e32 v18, v20
	v_mov_b32_e32 v19, v32
	v_mov_b32_e32 v6, v12
	v_mov_b32_e32 v7, v24
	v_pk_mul_f32 v[10:11], v[10:11], v[76:77]
	v_pk_mul_f32 v[18:19], v[18:19], v[4:5]
	v_pk_mul_f32 v[6:7], v[6:7], v[2:3]
	v_mov_b32_e32 v14, v28
	v_mov_b32_e32 v15, v36
	v_bfe_u32 v12, v18, 16, 1
	v_bfe_u32 v16, v11, 16, 1
	v_pk_mul_f32 v[14:15], v[14:15], v[38:39]
	v_bfe_u32 v8, v19, 16, 1
	v_bfe_u32 v20, v10, 16, 1
	v_add3_u32 v11, v11, v16, s68
	v_add3_u32 v12, v18, v12, s68
	v_bfe_u32 v16, v6, 16, 1
	v_bfe_u32 v18, v7, 16, 1
	v_add3_u32 v10, v10, v20, s68
	v_add3_u32 v8, v19, v8, s68
	v_bfe_u32 v19, v14, 16, 1
	v_bfe_u32 v20, v15, 16, 1
	v_add3_u32 v7, v7, v18, s68
	v_add3_u32 v6, v6, v16, s68
	v_add3_u32 v15, v15, v20, s68
	v_add3_u32 v14, v14, v19, s68
	v_lshrrev_b32_e32 v6, 16, v6
	v_lshrrev_b32_e32 v7, 16, v7
	v_mov_b32_e32 v16, v9
	v_mov_b32_e32 v32, v21
	global_store_dwordx4 v[86:87], v[40:43], off offset:2080
	v_lshrrev_b32_e32 v14, 16, v14
	v_lshrrev_b32_e32 v15, 16, v15
	v_and_or_b32 v41, v11, s69, v7
	v_and_or_b32 v40, v10, s69, v6
	v_mov_b32_e32 v24, v13
	v_pk_mul_f32 v[6:7], v[16:17], v[76:77]
	v_mov_b32_e32 v36, v29
	v_pk_mul_f32 v[4:5], v[32:33], v[4:5]
	v_and_or_b32 v43, v8, s69, v15
	v_and_or_b32 v42, v12, s69, v14
	v_pk_mul_f32 v[2:3], v[24:25], v[2:3]
	v_pk_mul_f32 v[8:9], v[36:37], v[38:39]
	v_cvt_pk_bf16_f32 v5, v9, v5
	v_cvt_pk_bf16_f32 v4, v8, v4
	v_cvt_pk_bf16_f32 v3, v3, v7
	v_cvt_pk_bf16_f32 v2, v2, v6
	global_store_dwordx4 v[88:89], v[2:5], off offset:2080
	global_store_dwordx4 v[88:89], v[40:43], off offset:32
	v_mov_b32_e32 v74, 1.0
	v_or_b32_e32 v2, 32, v90
	v_mad_i64_i32 v[2:3], s[10:11], v2, s76, v[92:93]
	v_or_b32_e32 v4, 33, v90
	v_mad_i64_i32 v[4:5], s[10:11], v4, s76, v[92:93]
	global_load_dwordx4 v[46:49], v[2:3], off nt
	global_load_dwordx4 v[42:45], v[4:5], off nt
	v_or_b32_e32 v2, 34, v90
	v_mad_i64_i32 v[2:3], s[10:11], v2, s76, v[92:93]
	v_or_b32_e32 v4, 35, v90
	v_mad_i64_i32 v[4:5], s[10:11], v4, s76, v[92:93]
	global_load_dwordx4 v[58:61], v[2:3], off nt
	global_load_dwordx4 v[50:53], v[4:5], off nt
	v_or_b32_e32 v2, 36, v90
	v_mad_i64_i32 v[2:3], s[10:11], v2, s76, v[92:93]
	v_or_b32_e32 v4, 37, v90
	v_mad_i64_i32 v[4:5], s[10:11], v4, s76, v[92:93]
	global_load_dwordx4 v[62:65], v[2:3], off nt
	global_load_dwordx4 v[54:57], v[4:5], off nt
	v_or_b32_e32 v2, 38, v90
	v_mad_i64_i32 v[2:3], s[10:11], v2, s76, v[92:93]
	v_or_b32_e32 v4, 39, v90
	v_mad_i64_i32 v[4:5], s[10:11], v4, s76, v[92:93]
	global_load_dwordx4 v[70:73], v[2:3], off nt
	global_load_dwordx4 v[66:69], v[4:5], off nt
	v_mov_b32_e32 v2, 1.0
	v_mov_b32_e32 v98, 1.0
	v_mov_b32_e32 v75, 1.0
	v_mov_b32_e32 v99, 1.0
	v_mov_b32_e32 v78, 1.0
	v_mov_b32_e32 v96, 1.0
	v_mov_b32_e32 v79, 1.0
	v_mov_b32_e32 v97, 1.0
	s_cbranch_vccnz .LBB0_640
	global_load_dwordx4 v[74:77], v[94:95], off offset:128
	global_load_dwordx4 v[78:81], v[94:95], off offset:144
	s_waitcnt vmcnt(1)
	v_mov_b32_e32 v98, v75
	v_mov_b32_e32 v75, v76
	v_mov_b32_e32 v99, v77
	s_waitcnt vmcnt(0)
	v_mov_b32_e32 v96, v79
	v_mov_b32_e32 v79, v80
	v_mov_b32_e32 v97, v81

.LBB0_642:
	s_waitcnt vmcnt(14)
	v_mov_b32_e32 v32, v42
	s_waitcnt vmcnt(12)
	v_mov_b32_e32 v33, v50
	s_waitcnt vmcnt(11)
	v_mov_b32_e32 v90, v62
	s_waitcnt vmcnt(9)
	v_mov_b32_e32 v91, v70
	v_mov_b32_e32 v4, v46
	v_mov_b32_e32 v5, v58
	v_pk_mul_f32 v[32:33], v[32:33], v[98:99]
	v_pk_mul_f32 v[90:91], v[90:91], v[78:79]
	v_mov_b32_e32 v92, v54
	s_waitcnt vmcnt(8)
	v_mov_b32_e32 v93, v66
	v_pk_mul_f32 v[4:5], v[4:5], v[74:75]
	v_pk_mul_f32 v[92:93], v[92:93], v[96:97]
	v_bfe_u32 v50, v33, 16, 1
	v_bfe_u32 v54, v32, 16, 1
	v_add3_u32 v32, v32, v54, s68
	v_add3_u32 v33, v33, v50, s68
	v_bfe_u32 v50, v4, 16, 1
	v_bfe_u32 v54, v5, 16, 1
	v_bfe_u32 v62, v91, 16, 1
	v_add3_u32 v5, v5, v54, s68
	v_add3_u32 v4, v4, v50, s68
	v_bfe_u32 v42, v93, 16, 1
	v_add3_u32 v62, v91, v62, s68
	v_lshrrev_b32_e32 v4, 16, v4
	v_lshrrev_b32_e32 v5, 16, v5
	v_cvt_pk_bf16_f32 v92, v90, v92
	v_mov_b32_e32 v50, v43
	v_mov_b32_e32 v66, v55
	v_add3_u32 v42, v93, v42, s68
	v_lshrrev_b32_e32 v54, 16, v62
	v_and_or_b32 v91, v33, s69, v5
	v_and_or_b32 v90, v32, s69, v4
	v_mov_b32_e32 v58, v47
	v_pk_mul_f32 v[32:33], v[50:51], v[98:99]
	v_mov_b32_e32 v70, v63
	v_pk_mul_f32 v[46:47], v[66:67], v[96:97]
	v_and_or_b32 v93, v42, s69, v54
	v_pk_mul_f32 v[4:5], v[58:59], v[74:75]
	v_pk_mul_f32 v[42:43], v[70:71], v[78:79]
	global_store_dwordx4 v[86:87], v[90:93], off offset:64
	s_mov_b64 s[50:51], 0
	s_nop 0
	v_cvt_pk_bf16_f32 v93, v43, v47
	v_cvt_pk_bf16_f32 v92, v42, v46
	v_cvt_pk_bf16_f32 v91, v5, v33
	v_cvt_pk_bf16_f32 v90, v4, v32
	v_mov_b32_e32 v32, v44
	v_mov_b32_e32 v33, v52
	v_mov_b32_e32 v46, v56
	v_mov_b32_e32 v47, v68
	v_mov_b32_e32 v4, v48
	v_mov_b32_e32 v5, v60
	v_pk_mul_f32 v[32:33], v[32:33], v[98:99]
	v_mov_b32_e32 v42, v64
	v_mov_b32_e32 v43, v72
	v_pk_mul_f32 v[46:47], v[46:47], v[96:97]
	v_pk_mul_f32 v[4:5], v[4:5], v[74:75]
	v_pk_mul_f32 v[42:43], v[42:43], v[78:79]
	v_bfe_u32 v44, v47, 16, 1
	v_add3_u32 v44, v47, v44, s68
	v_bfe_u32 v51, v43, 16, 1
	v_add3_u32 v43, v43, v51, s68
	v_lshrrev_b32_e32 v43, 16, v43
	v_mov_b32_e32 v52, v45
	v_mov_b32_e32 v68, v57
	global_store_dwordx4 v[86:87], v[90:93], off offset:2112
	v_mov_b32_e32 v60, v49
	s_nop 1
	v_and_or_b32 v93, v44, s69, v43
	v_cvt_pk_bf16_f32 v91, v5, v33
	v_cvt_pk_bf16_f32 v90, v4, v32
	v_pk_mul_f32 v[32:33], v[52:53], v[98:99]
	v_mov_b32_e32 v72, v65
	v_pk_mul_f32 v[44:45], v[68:69], v[96:97]
	v_cvt_pk_bf16_f32 v92, v42, v46
	v_pk_mul_f32 v[4:5], v[60:61], v[74:75]
	v_pk_mul_f32 v[42:43], v[72:73], v[78:79]
	v_cvt_pk_bf16_f32 v45, v43, v45
	v_cvt_pk_bf16_f32 v44, v42, v44
	v_cvt_pk_bf16_f32 v43, v5, v33
	v_cvt_pk_bf16_f32 v42, v4, v32
	s_waitcnt vmcnt(8)
	v_mov_b32_e32 v32, v22
	s_waitcnt vmcnt(6)
	v_mov_b32_e32 v33, v34
	global_store_dwordx4 v[88:89], v[42:45], off offset:2112
	v_pk_mul_f32 v[32:33], v[32:33], v[80:81]
	v_mov_b32_e32 v4, v26
	s_waitcnt vmcnt(6)
	v_mov_b32_e32 v42, v18
	s_waitcnt vmcnt(4)
	v_mov_b32_e32 v43, v10
	v_mov_b32_e32 v5, v38
	v_pk_mul_f32 v[42:43], v[42:43], v[30:31]
	v_mov_b32_e32 v44, v14
	s_waitcnt vmcnt(3)
	v_mov_b32_e32 v45, v6
	v_pk_mul_f32 v[4:5], v[4:5], v[2:3]
	v_pk_mul_f32 v[44:45], v[44:45], v[76:77]
	v_bfe_u32 v18, v32, 16, 1
	v_add3_u32 v18, v32, v18, s68
	v_bfe_u32 v22, v4, 16, 1
	v_add3_u32 v4, v4, v22, s68
	v_cvt_pk_bf16_f32 v45, v43, v45
	v_mov_b32_e32 v34, v23
	v_mov_b32_e32 v6, v15
	v_lshrrev_b32_e32 v4, 16, v4
	v_cvt_pk_bf16_f32 v44, v42, v44
	v_mov_b32_e32 v38, v27
	v_pk_mul_f32 v[22:23], v[34:35], v[80:81]
	v_mov_b32_e32 v10, v19
	v_pk_mul_f32 v[6:7], v[6:7], v[76:77]
	v_cvt_pk_bf16_f32 v43, v5, v33
	v_and_or_b32 v42, v18, s69, v4
	v_pk_mul_f32 v[4:5], v[38:39], v[2:3]
	v_pk_mul_f32 v[10:11], v[10:11], v[30:31]
	v_cvt_pk_bf16_f32 v7, v11, v7
	v_cvt_pk_bf16_f32 v6, v10, v6
	v_cvt_pk_bf16_f32 v5, v5, v23
	v_cvt_pk_bf16_f32 v4, v4, v22
	global_store_dwordx4 v[86:87], v[4:7], off offset:2144
	v_mov_b32_e32 v14, v16
	v_mov_b32_e32 v15, v8
	v_mov_b32_e32 v6, v24
	v_mov_b32_e32 v7, v36
	v_mov_b32_e32 v4, v28
	v_mov_b32_e32 v5, v40
	v_pk_mul_f32 v[6:7], v[6:7], v[80:81]
	v_mov_b32_e32 v10, v20
	v_mov_b32_e32 v11, v12
	v_pk_mul_f32 v[14:15], v[14:15], v[76:77]
	v_pk_mul_f32 v[4:5], v[4:5], v[2:3]
	v_pk_mul_f32 v[10:11], v[10:11], v[30:31]
	v_bfe_u32 v8, v15, 16, 1
	v_bfe_u32 v12, v14, 16, 1
	v_bfe_u32 v16, v7, 16, 1
	v_bfe_u32 v18, v6, 16, 1
	v_add3_u32 v18, v6, v18, s68
	v_add3_u32 v16, v7, v16, s68
	v_add3_u32 v6, v14, v12, s68
	v_add3_u32 v7, v15, v8, s68
	v_bfe_u32 v8, v4, 16, 1
	v_bfe_u32 v12, v5, 16, 1
	v_bfe_u32 v14, v10, 16, 1
	v_bfe_u32 v15, v11, 16, 1
	v_add3_u32 v11, v11, v15, s68
	v_add3_u32 v10, v10, v14, s68
	v_add3_u32 v5, v5, v12, s68
	v_add3_u32 v4, v4, v8, s68
	v_lshrrev_b32_e32 v4, 16, v4
	v_lshrrev_b32_e32 v5, 16, v5
	v_lshrrev_b32_e32 v8, 16, v10
	v_lshrrev_b32_e32 v10, 16, v11
	v_mov_b32_e32 v40, v29
	v_and_or_b32 v7, v7, s69, v10
	v_and_or_b32 v6, v6, s69, v8
	v_and_or_b32 v5, v16, s69, v5
	v_and_or_b32 v4, v18, s69, v4
	v_pk_mul_f32 v[2:3], v[40:41], v[2:3]
	v_mov_b32_e32 v36, v25
	global_store_dwordx4 v[88:89], v[4:7], off offset:96
	v_mov_b32_e32 v16, v21
	v_mov_b32_e32 v8, v13
	v_pk_mul_f32 v[4:5], v[36:37], v[80:81]
	v_and_b32_sdwa v6, v3, v107 dst_sel:DWORD dst_unused:UNUSED_PAD src0_sel:WORD_1 src1_sel:DWORD
	v_and_b32_sdwa v7, v2, v107 dst_sel:DWORD dst_unused:UNUSED_PAD src0_sel:WORD_1 src1_sel:DWORD
	v_add3_u32 v2, v2, v7, s68
	v_add3_u32 v3, v3, v6, s68
	v_and_b32_sdwa v6, v5, v107 dst_sel:DWORD dst_unused:UNUSED_PAD src0_sel:WORD_1 src1_sel:DWORD
	v_and_b32_sdwa v7, v4, v107 dst_sel:DWORD dst_unused:UNUSED_PAD src0_sel:WORD_1 src1_sel:DWORD
	v_add3_u32 v5, v5, v6, s68
	v_add3_u32 v4, v4, v7, s68
	v_and_b32_e32 v5, 0xffff0000, v5
	v_and_b32_e32 v4, 0xffff0000, v4
	v_or_b32_sdwa v3, v5, v3 dst_sel:DWORD dst_unused:UNUSED_PAD src0_sel:DWORD src1_sel:WORD_1
	v_or_b32_sdwa v2, v4, v2 dst_sel:DWORD dst_unused:UNUSED_PAD src0_sel:DWORD src1_sel:WORD_1
	v_mov_b32_e32 v4, v30
	v_mov_b32_e32 v5, v76
	v_pk_mul_f32 v[4:5], v[16:17], v[4:5]
	v_mov_b32_e32 v76, v31
	v_and_b32_sdwa v6, v5, v107 dst_sel:DWORD dst_unused:UNUSED_PAD src0_sel:WORD_1 src1_sel:DWORD
	v_and_b32_sdwa v7, v4, v107 dst_sel:DWORD dst_unused:UNUSED_PAD src0_sel:WORD_1 src1_sel:DWORD
	v_add3_u32 v5, v5, v6, s68
	v_add3_u32 v4, v4, v7, s68
	v_pk_mul_f32 v[6:7], v[8:9], v[76:77]
	v_lshrrev_b32_e32 v4, 16, v4
	v_and_b32_sdwa v8, v6, v107 dst_sel:DWORD dst_unused:UNUSED_PAD src0_sel:WORD_1 src1_sel:DWORD
	v_and_or_b32 v4, v5, s69, v4
	v_and_b32_sdwa v5, v7, v107 dst_sel:DWORD dst_unused:UNUSED_PAD src0_sel:WORD_1 src1_sel:DWORD
	v_add3_u32 v6, v6, v8, s68
	v_add3_u32 v5, v7, v5, s68
	v_lshrrev_b32_e32 v6, 16, v6
	v_and_or_b32 v5, v5, s69, v6
	global_store_dwordx4 v[88:89], v[90:93], off offset:64
	global_store_dwordx4 v[86:87], v[42:45], off offset:96
